# LN-folded epilogues (QKV, SwiGLU-LN x2, PLE x2, SGU-in): column-vector and residual loads issued before the row-statistics round trip; producer temps in statistics registers
# baseline (speedup 1.0000x reference)
; __device__ __forceinline__ void load_row_stats(const float* sp, int row0, RowStats& r) {
;     ...
;         for (int m = 0; m < 4; ++m) { const float* p = sp + (size_t)(row0 + ai * HALF + m * 16) * 8; const f32x4 a = *(const f32x4*)p, b = *(const f32x4*)(p + 4);
;             const float s1 = (a[0] + a[2]) + (b[0] + b[2]), s2 = (a[1] + a[3]) + (b[1] + b[3]); const float mu = s1 * (1.f / 1024.f); const float var = s2 * (1.f / 1024.f) - mu * mu;
;             r.mu[ai][m] = mu; r.rs[ai][m] = __builtin_amdgcn_rsqf(__builtin_fmaxf(var, 0.f) + 1e-5f); } }
;     __device__ __forceinline__ void operator()(const f32x4 (&acc)[2][2][4][2], const Unit& u, int wr, int wc, int fr_in, int fq_in) const {
;     ...
;         const int row0 = u.pm * BM + wr * 64 + fr; const int t = u.pn >> 2; bf16_t* base = O + (size_t)t * split_stride; const float sc = (t == 0) ? scale0 : 1.f;
;         const int col0 = (u.pn & 3) * BM + wc * 32 + 8 * fq, n0 = u.pn * BM + wc * 32 + 8 * fq;
;         RowStats rst; load_row_stats(sp, row0, rst); f32x4 csv[2][2], cbv[2][2];
; #pragma unroll
;         for (int bj = 0; bj < 2; ++bj)
; #pragma unroll
;             for (int n = 0; n < 2; ++n) { csv[bj][n] = *(const f32x4*)(cs + n0 + bj * HALF + 4 * n); cbv[bj][n] = *(const f32x4*)(cb + n0 + bj * HALF + 4 * n); }
;         const bool kb = (u.pn == 4 || u.pn == 5);
;         f32x4 ks[2][2];
; #pragma unroll
;         for (int bj = 0; bj < 2; ++bj)
; #pragma unroll
;             for (int n = 0; n < 2; ++n) ks[bj][n] = (f32x4){0.f, 0.f, 0.f, 0.f};
; #pragma unroll
;         for (int ai = 0; ai < 2; ++ai)
; #pragma unroll
;             for (int m = 0; m < 4; ++m) { bf16_t* rowp = base + (size_t)(row0 + ai * HALF + m * 16) * 1024 + col0;
; #pragma unroll
;                 for (int bj = 0; bj < 2; ++bj) { const f32x4 v0r = ln_fix(acc[ai][bj][m][0], rst.mu[ai][m], rst.rs[ai][m], csv[bj][0], cbv[bj][0]), v1r = ln_fix(acc[ai][bj][m][1], rst.mu[ai][m], rst.rs[ai][m], csv[bj][1], cbv[bj][1]);
;                     ks[bj][0] += v0r; ks[bj][1] += v1r; const f32x4 v0 = v0r * sc, v1 = v1r * sc;
;                     u32x4 w; w.x = cvt_pk_bf16(v0[0], v0[1]); w.y = cvt_pk_bf16(v0[2], v0[3]); w.z = cvt_pk_bf16(v1[0], v1[1]); w.w = cvt_pk_bf16(v1[2], v1[3]);
;                     *(u32x4*)(rowp + bj * HALF) = w; } }
.LBB0_436:
	s_lshl_b32 s8, s46, 8
	v_mov_b32_e32 v228, v183
	v_mov_b32_e32 v128, v189
	s_add_i32 s8, s8, s49
	s_nop 0
	v_add_u32_e32 v220, s8, v228
	v_ashrrev_i32_e32 v221, 31, v220
	v_and_b32_e32 v216, 0xffffff00, v220
	v_and_b32_e32 v179, 0xff, v220
	v_lshlrev_b32_e32 v179, 3, v179
	v_add_u32_e32 v179, 0x22400, v179
	v_add_u32_e32 v222, 16, v220
	v_ashrrev_i32_e32 v223, 31, v222
	v_add_u32_e32 v214, 32, v220
	v_ashrrev_i32_e32 v215, 31, v214
	v_add_u32_e32 v210, 48, v220
	v_ashrrev_i32_e32 v211, 31, v210
	v_add_u32_e32 v206, 0x80, v220
	v_ashrrev_i32_e32 v207, 31, v206
	v_add_u32_e32 v200, 0x90, v220
	v_ashrrev_i32_e32 v201, 31, v200
	v_add_u32_e32 v192, 0xa0, v220
	v_ashrrev_i32_e32 v193, 31, v192
	v_add_u32_e32 v186, 0xb0, v220
	v_ashrrev_i32_e32 v187, 31, v186
	s_ashr_i32 s8, s48, 2
	s_ashr_i32 s9, s8, 31
	s_lshl_b64 s[8:9], s[8:9], 26
	s_add_u32 s50, s57, s8
	s_addc_u32 s51, s58, s9
	s_lshl_b32 s8, s48, 8
	v_lshlrev_b32_e32 v229, 3, v128
	s_or_b32 s9, s8, s56
	v_add_u32_e32 v128, s9, v229
	s_cmp_lt_u32 s48, 4
	s_cselect_b64 vcc, -1, 0
	s_and_b32 s9, s8, 0x300
	s_or_b32 s9, s9, s56
	v_add_u32_e32 v226, s9, v229
	v_cndmask_b32_e32 v224, 1.0, v219, vcc
	v_ashrrev_i32_e32 v227, 31, v226
	v_lshl_add_u64 v[226:227], v[226:227], 1, s[50:51]
	v_lshlrev_b64 v[220:221], 11, v[220:221]
	v_lshl_add_u64 v[220:221], v[226:227], 0, v[220:221]
	s_and_b32 s9, s48, -2
	s_cmp_lg_u32 s9, 4
	s_nop 0
	v_ashrrev_i32_e32 v129, 31, v128
	v_lshlrev_b64 v[128:129], 2, v[128:129]
	v_lshl_add_u64 v[132:133], s[22:23], 0, v[128:129]
	v_lshl_add_u64 v[136:137], s[24:25], 0, v[128:129]
	global_load_dwordx4 v[148:151], v[132:133], off offset:16
	global_load_dwordx4 v[156:159], v[132:133], off
	global_load_dwordx4 v[144:147], v[136:137], off offset:16
	global_load_dwordx4 v[152:155], v[136:137], off
	global_load_dwordx4 v[128:131], v[132:133], off offset:528
	global_load_dwordx4 v[140:143], v[132:133], off offset:512
	s_nop 0
	global_load_dwordx4 v[132:135], v[136:137], off offset:528
	s_nop 0
	global_load_dwordx4 v[136:139], v[136:137], off offset:512
	s_cselect_b32 s99, 1, 0
	v_readfirstlane_b32 s98, v254
	s_nop 0
	s_cmpk_lt_u32 s98, 0x100
	s_cbranch_scc0 .Lrs0_skip
	v_add_u32_e32 v216, v216, v254
	v_mov_b32_e32 v217, 0
	v_lshlrev_b64 v[216:217], 5, v[216:217]
	v_lshl_add_u64 v[216:217], s[12:13], 0, v[216:217]
	global_load_dwordx2 v[208:209], v[216:217], off offset:16
	global_load_dwordx2 v[202:203], v[216:217], off offset:24
	global_load_dwordx2 v[196:197], v[216:217], off
	global_load_dwordx2 v[190:191], v[216:217], off offset:8
	s_waitcnt vmcnt(0)
	v_pk_add_f32 v[208:209], v[208:209], v[202:203]
	v_pk_add_f32 v[196:197], v[196:197], v[190:191]
	s_nop 0
	v_pk_add_f32 v[208:209], v[196:197], v[208:209]
	s_nop 0
	v_pk_mul_f32 v[208:209], v[208:209], s[34:35] op_sel_hi:[1,0]
	v_lshlrev_b32_e32 v184, 3, v254
	v_add_u32_e32 v184, 0x22400, v184
	ds_write_b64 v184, v[208:209]
.Lrs0_skip:
	s_waitcnt vmcnt(0) lgkmcnt(0)
	s_barrier
	ds_read_b64 v[216:217], v179
	ds_read_b64 v[208:209], v179 offset:128
	ds_read_b64 v[202:203], v179 offset:256
	ds_read_b64 v[196:197], v179 offset:384
	ds_read_b64 v[190:191], v179 offset:1024
	ds_read_b64 v[184:185], v179 offset:1152
	ds_read_b64 v[180:181], v179 offset:1280
	ds_read_b64 v[178:179], v179 offset:1408
	s_cmp_lg_u32 s99, 0
	s_waitcnt lgkmcnt(0)
	v_fma_f32 v218, -v216, v216, v217
	v_max_f32_e32 v218, 0, v218
	v_add_f32_e32 v218, 0x3727c5ac, v218
	v_rsq_f32_e32 v218, v218
	v_fma_f32 v212, -v208, v208, v209
	v_max_f32_e32 v212, 0, v212
	v_add_f32_e32 v212, 0x3727c5ac, v212
	v_rsq_f32_e32 v212, v212
	v_fma_f32 v204, -v202, v202, v203
	v_max_f32_e32 v204, 0, v204
	v_add_f32_e32 v204, 0x3727c5ac, v204
	v_rsq_f32_e32 v204, v204
	v_fma_f32 v198, -v196, v196, v197
	v_max_f32_e32 v198, 0, v198
	v_add_f32_e32 v198, 0x3727c5ac, v198
	v_rsq_f32_e32 v198, v198
	v_fma_f32 v194, -v190, v190, v191
	v_max_f32_e32 v194, 0, v194
	v_add_f32_e32 v194, 0x3727c5ac, v194
	v_rsq_f32_e32 v194, v194
	v_fma_f32 v188, -v184, v184, v185
	v_max_f32_e32 v188, 0, v188
	v_add_f32_e32 v188, 0x3727c5ac, v188
	v_rsq_f32_e32 v188, v188
	v_fma_f32 v182, -v180, v180, v181
	v_max_f32_e32 v182, 0, v182
	v_add_f32_e32 v182, 0x3727c5ac, v182
	v_rsq_f32_e32 v182, v182
	v_fma_f32 v168, -v178, v178, v179
	v_max_f32_e32 v168, 0, v168
	v_add_f32_e32 v168, 0x3727c5ac, v168
	v_rsq_f32_e32 v168, v168
	s_waitcnt vmcnt(6)
	v_pk_fma_f32 v[230:231], v[216:217], v[156:157], v[124:125] op_sel_hi:[0,1,1] neg_lo:[1,0,0] neg_hi:[1,0,0]
	v_pk_fma_f32 v[124:125], v[216:217], v[158:159], v[126:127] op_sel_hi:[0,1,1] neg_lo:[1,0,0] neg_hi:[1,0,0]
	s_waitcnt vmcnt(4)
	v_pk_fma_f32 v[126:127], v[218:219], v[230:231], v[152:153] op_sel_hi:[0,1,1]
	v_pk_fma_f32 v[230:231], v[216:217], v[148:149], v[120:121] op_sel_hi:[0,1,1] neg_lo:[1,0,0] neg_hi:[1,0,0]
	v_pk_fma_f32 v[124:125], v[218:219], v[124:125], v[154:155] op_sel_hi:[0,1,1]
	v_pk_fma_f32 v[120:121], v[216:217], v[150:151], v[122:123] op_sel_hi:[0,1,1] neg_lo:[1,0,0] neg_hi:[1,0,0]
	v_pk_fma_f32 v[122:123], v[218:219], v[230:231], v[144:145] op_sel_hi:[0,1,1]
	v_pk_mul_f32 v[230:231], v[224:225], v[126:127] op_sel_hi:[0,1]
	v_pk_fma_f32 v[120:121], v[218:219], v[120:121], v[146:147] op_sel_hi:[0,1,1]
	v_pk_mul_f32 v[232:233], v[224:225], v[124:125] op_sel_hi:[0,1]
	v_cvt_pk_bf16_f32 v230, v230, v231
	v_cvt_pk_bf16_f32 v231, v232, v233
	v_pk_mul_f32 v[234:235], v[224:225], v[120:121] op_sel_hi:[0,1]
	v_pk_mul_f32 v[236:237], v[224:225], v[122:123] op_sel_hi:[0,1]
	v_cvt_pk_bf16_f32 v232, v236, v237
	v_cvt_pk_bf16_f32 v233, v234, v235
	global_store_dwordx4 v[220:221], v[230:233], off
	v_pk_fma_f32 v[12:13], v[156:157], v[178:179], v[12:13] op_sel_hi:[1,0,1] neg_lo:[1,0,0] neg_hi:[1,0,0]
	s_waitcnt vmcnt(3)
; __device__ __forceinline__ unsigned cvt_pk_bf16(float lo, float hi) { unsigned r; asm("v_cvt_pk_bf16_f32 %0, %1, %2" : "=v"(r) : "v"(lo), "v"(hi)); return r; }
; __device__ __forceinline__ f32x4 ln_fix(const f32x4& a, float mu, float rs, const f32x4& cs, const f32x4& cb) { return (a - cs * mu) * rs + cb; }
;     __device__ __forceinline__ void operator()(const f32x4 (&acc)[2][2][4][2], const Unit& u, int wr, int wc, int fr_in, int fq_in) const {
;     ...
;             for (int m = 0; m < 4; ++m) { bf16_t* rowp = base + (size_t)(row0 + ai * HALF + m * 16) * 1024 + col0;
; #pragma unroll
;                 for (int bj = 0; bj < 2; ++bj) { const f32x4 v0r = ln_fix(acc[ai][bj][m][0], rst.mu[ai][m], rst.rs[ai][m], csv[bj][0], cbv[bj][0]), v1r = ln_fix(acc[ai][bj][m][1], rst.mu[ai][m], rst.rs[ai][m], csv[bj][1], cbv[bj][1]);
;                     ks[bj][0] += v0r; ks[bj][1] += v1r; const f32x4 v0 = v0r * sc, v1 = v1r * sc;
;                     u32x4 w; w.x = cvt_pk_bf16(v0[0], v0[1]); w.y = cvt_pk_bf16(v0[2], v0[3]); w.z = cvt_pk_bf16(v1[0], v1[1]); w.w = cvt_pk_bf16(v1[2], v1[3]);
;                     *(u32x4*)(rowp + bj * HALF) = w; } }
	v_pk_fma_f32 v[230:231], v[216:217], v[140:141], v[116:117] op_sel_hi:[0,1,1] neg_lo:[1,0,0] neg_hi:[1,0,0]
	v_pk_fma_f32 v[116:117], v[216:217], v[142:143], v[118:119] op_sel_hi:[0,1,1] neg_lo:[1,0,0] neg_hi:[1,0,0]
	s_waitcnt vmcnt(1)
	v_pk_fma_f32 v[118:119], v[218:219], v[230:231], v[136:137] op_sel_hi:[0,1,1]
	v_pk_fma_f32 v[230:231], v[216:217], v[128:129], v[112:113] op_sel_hi:[0,1,1] neg_lo:[1,0,0] neg_hi:[1,0,0]
	v_pk_fma_f32 v[112:113], v[216:217], v[130:131], v[114:115] op_sel_hi:[0,1,1] neg_lo:[1,0,0] neg_hi:[1,0,0]
	v_pk_fma_f32 v[114:115], v[218:219], v[230:231], v[132:133] op_sel_hi:[0,1,1]
	v_pk_fma_f32 v[116:117], v[218:219], v[116:117], v[138:139] op_sel_hi:[0,1,1]
	v_pk_fma_f32 v[112:113], v[218:219], v[112:113], v[134:135] op_sel_hi:[0,1,1]
	v_pk_mul_f32 v[230:231], v[224:225], v[118:119] op_sel_hi:[0,1]
	v_pk_mul_f32 v[232:233], v[224:225], v[114:115] op_sel_hi:[0,1]
	v_pk_mul_f32 v[216:217], v[224:225], v[116:117] op_sel_hi:[0,1]
	v_pk_mul_f32 v[234:235], v[224:225], v[112:113] op_sel_hi:[0,1]
	v_cvt_pk_bf16_f32 v230, v230, v231
	v_cvt_pk_bf16_f32 v231, v216, v217
	v_cvt_pk_bf16_f32 v232, v232, v233
	v_cvt_pk_bf16_f32 v233, v234, v235
	global_store_dwordx4 v[220:221], v[230:233], off offset:256
	v_pk_fma_f32 v[220:221], v[208:209], v[156:157], v[108:109] op_sel_hi:[0,1,1] neg_lo:[1,0,0] neg_hi:[1,0,0]
	v_pk_fma_f32 v[108:109], v[208:209], v[158:159], v[110:111] op_sel_hi:[0,1,1] neg_lo:[1,0,0] neg_hi:[1,0,0]
	v_pk_fma_f32 v[110:111], v[212:213], v[220:221], v[152:153] op_sel_hi:[0,1,1]
	v_pk_fma_f32 v[220:221], v[208:209], v[148:149], v[104:105] op_sel_hi:[0,1,1] neg_lo:[1,0,0] neg_hi:[1,0,0]
	v_lshlrev_b64 v[216:217], 11, v[222:223]
	v_pk_fma_f32 v[108:109], v[212:213], v[108:109], v[154:155] op_sel_hi:[0,1,1]
	v_pk_fma_f32 v[104:105], v[208:209], v[150:151], v[106:107] op_sel_hi:[0,1,1] neg_lo:[1,0,0] neg_hi:[1,0,0]
	v_pk_fma_f32 v[106:107], v[212:213], v[220:221], v[144:145] op_sel_hi:[0,1,1]
	v_pk_mul_f32 v[220:221], v[224:225], v[110:111] op_sel_hi:[0,1]
	v_lshl_add_u64 v[216:217], v[226:227], 0, v[216:217]
	v_pk_fma_f32 v[104:105], v[212:213], v[104:105], v[146:147] op_sel_hi:[0,1,1]
	v_pk_mul_f32 v[222:223], v[224:225], v[108:109] op_sel_hi:[0,1]
	v_cvt_pk_bf16_f32 v220, v220, v221
	v_cvt_pk_bf16_f32 v221, v222, v223
	v_pk_mul_f32 v[230:231], v[224:225], v[104:105] op_sel_hi:[0,1]
	v_pk_mul_f32 v[232:233], v[224:225], v[106:107] op_sel_hi:[0,1]
	v_cvt_pk_bf16_f32 v222, v232, v233
	v_cvt_pk_bf16_f32 v223, v230, v231
	global_store_dwordx4 v[216:217], v[220:223], off
	v_pk_fma_f32 v[12:13], v[12:13], v[168:169], v[152:153] op_sel_hi:[1,0,1]
	s_nop 0
	v_pk_fma_f32 v[220:221], v[208:209], v[140:141], v[100:101] op_sel_hi:[0,1,1] neg_lo:[1,0,0] neg_hi:[1,0,0]
	v_pk_fma_f32 v[100:101], v[208:209], v[142:143], v[102:103] op_sel_hi:[0,1,1] neg_lo:[1,0,0] neg_hi:[1,0,0]
	v_pk_fma_f32 v[100:101], v[212:213], v[100:101], v[138:139] op_sel_hi:[0,1,1]
	v_pk_fma_f32 v[102:103], v[212:213], v[220:221], v[136:137] op_sel_hi:[0,1,1]
	v_pk_fma_f32 v[220:221], v[208:209], v[128:129], v[96:97] op_sel_hi:[0,1,1] neg_lo:[1,0,0] neg_hi:[1,0,0]
	v_pk_fma_f32 v[96:97], v[208:209], v[130:131], v[98:99] op_sel_hi:[0,1,1] neg_lo:[1,0,0] neg_hi:[1,0,0]
	v_pk_fma_f32 v[98:99], v[212:213], v[220:221], v[132:133] op_sel_hi:[0,1,1]
	v_pk_mul_f32 v[208:209], v[224:225], v[100:101] op_sel_hi:[0,1]
	v_pk_mul_f32 v[220:221], v[224:225], v[102:103] op_sel_hi:[0,1]
	v_cvt_pk_bf16_f32 v220, v220, v221
	v_cvt_pk_bf16_f32 v221, v208, v209
	v_lshlrev_b64 v[208:209], 11, v[214:215]
	v_pk_fma_f32 v[214:215], v[202:203], v[156:157], v[92:93] op_sel_hi:[0,1,1] neg_lo:[1,0,0] neg_hi:[1,0,0]
	v_pk_fma_f32 v[92:93], v[202:203], v[158:159], v[94:95] op_sel_hi:[0,1,1] neg_lo:[1,0,0] neg_hi:[1,0,0]
	v_pk_fma_f32 v[94:95], v[204:205], v[214:215], v[152:153] op_sel_hi:[0,1,1]
	v_pk_fma_f32 v[214:215], v[202:203], v[148:149], v[88:89] op_sel_hi:[0,1,1] neg_lo:[1,0,0] neg_hi:[1,0,0]
	v_pk_fma_f32 v[96:97], v[212:213], v[96:97], v[134:135] op_sel_hi:[0,1,1]
	v_pk_mul_f32 v[222:223], v[224:225], v[98:99] op_sel_hi:[0,1]
	v_pk_fma_f32 v[92:93], v[204:205], v[92:93], v[154:155] op_sel_hi:[0,1,1]
	v_pk_fma_f32 v[88:89], v[202:203], v[150:151], v[90:91] op_sel_hi:[0,1,1] neg_lo:[1,0,0] neg_hi:[1,0,0]
	v_pk_fma_f32 v[90:91], v[204:205], v[214:215], v[144:145] op_sel_hi:[0,1,1]
	v_pk_mul_f32 v[214:215], v[224:225], v[94:95] op_sel_hi:[0,1]
	v_pk_mul_f32 v[230:231], v[224:225], v[96:97] op_sel_hi:[0,1]
	v_cvt_pk_bf16_f32 v222, v222, v223
	v_cvt_pk_bf16_f32 v223, v230, v231
	global_store_dwordx4 v[216:217], v[220:223], off offset:256
	v_lshl_add_u64 v[208:209], v[226:227], 0, v[208:209]
	v_pk_fma_f32 v[88:89], v[204:205], v[88:89], v[146:147] op_sel_hi:[0,1,1]
	v_pk_mul_f32 v[216:217], v[224:225], v[92:93] op_sel_hi:[0,1]
	v_cvt_pk_bf16_f32 v214, v214, v215
	v_cvt_pk_bf16_f32 v215, v216, v217
	v_pk_mul_f32 v[220:221], v[224:225], v[88:89] op_sel_hi:[0,1]
	v_pk_mul_f32 v[222:223], v[224:225], v[90:91] op_sel_hi:[0,1]
	v_cvt_pk_bf16_f32 v216, v222, v223
	v_cvt_pk_bf16_f32 v217, v220, v221
	global_store_dwordx4 v[208:209], v[214:217], off
	s_nop 1
	v_pk_fma_f32 v[214:215], v[202:203], v[140:141], v[84:85] op_sel_hi:[0,1,1] neg_lo:[1,0,0] neg_hi:[1,0,0]
	v_pk_fma_f32 v[84:85], v[202:203], v[142:143], v[86:87] op_sel_hi:[0,1,1] neg_lo:[1,0,0] neg_hi:[1,0,0]
	v_pk_fma_f32 v[86:87], v[204:205], v[214:215], v[136:137] op_sel_hi:[0,1,1]
	v_pk_fma_f32 v[214:215], v[202:203], v[128:129], v[80:81] op_sel_hi:[0,1,1] neg_lo:[1,0,0] neg_hi:[1,0,0]
	v_pk_fma_f32 v[80:81], v[202:203], v[130:131], v[82:83] op_sel_hi:[0,1,1] neg_lo:[1,0,0] neg_hi:[1,0,0]
; __device__ __forceinline__ unsigned cvt_pk_bf16(float lo, float hi) { unsigned r; asm("v_cvt_pk_bf16_f32 %0, %1, %2" : "=v"(r) : "v"(lo), "v"(hi)); return r; }
; __device__ __forceinline__ f32x4 ln_fix(const f32x4& a, float mu, float rs, const f32x4& cs, const f32x4& cb) { return (a - cs * mu) * rs + cb; }
;     __device__ __forceinline__ void operator()(const f32x4 (&acc)[2][2][4][2], const Unit& u, int wr, int wc, int fr_in, int fq_in) const {
;     ...
;             for (int m = 0; m < 4; ++m) { bf16_t* rowp = base + (size_t)(row0 + ai * HALF + m * 16) * 1024 + col0;
; #pragma unroll
;                 for (int bj = 0; bj < 2; ++bj) { const f32x4 v0r = ln_fix(acc[ai][bj][m][0], rst.mu[ai][m], rst.rs[ai][m], csv[bj][0], cbv[bj][0]), v1r = ln_fix(acc[ai][bj][m][1], rst.mu[ai][m], rst.rs[ai][m], csv[bj][1], cbv[bj][1]);
;                     ks[bj][0] += v0r; ks[bj][1] += v1r; const f32x4 v0 = v0r * sc, v1 = v1r * sc;
;                     u32x4 w; w.x = cvt_pk_bf16(v0[0], v0[1]); w.y = cvt_pk_bf16(v0[2], v0[3]); w.z = cvt_pk_bf16(v1[0], v1[1]); w.w = cvt_pk_bf16(v1[2], v1[3]);
;                     *(u32x4*)(rowp + bj * HALF) = w; } }
	v_pk_fma_f32 v[82:83], v[204:205], v[214:215], v[132:133] op_sel_hi:[0,1,1]
	v_pk_fma_f32 v[84:85], v[204:205], v[84:85], v[138:139] op_sel_hi:[0,1,1]
	v_pk_fma_f32 v[80:81], v[204:205], v[80:81], v[134:135] op_sel_hi:[0,1,1]
	v_pk_mul_f32 v[214:215], v[224:225], v[86:87] op_sel_hi:[0,1]
	v_pk_mul_f32 v[216:217], v[224:225], v[82:83] op_sel_hi:[0,1]
	v_pk_mul_f32 v[202:203], v[224:225], v[84:85] op_sel_hi:[0,1]
	v_pk_mul_f32 v[220:221], v[224:225], v[80:81] op_sel_hi:[0,1]
	v_cvt_pk_bf16_f32 v214, v214, v215
	v_cvt_pk_bf16_f32 v215, v202, v203
	v_cvt_pk_bf16_f32 v216, v216, v217
	v_cvt_pk_bf16_f32 v217, v220, v221
	global_store_dwordx4 v[208:209], v[214:217], off offset:256
	v_pk_fma_f32 v[208:209], v[196:197], v[156:157], v[76:77] op_sel_hi:[0,1,1] neg_lo:[1,0,0] neg_hi:[1,0,0]
	v_pk_fma_f32 v[76:77], v[196:197], v[158:159], v[78:79] op_sel_hi:[0,1,1] neg_lo:[1,0,0] neg_hi:[1,0,0]
	v_pk_fma_f32 v[78:79], v[198:199], v[208:209], v[152:153] op_sel_hi:[0,1,1]
	v_pk_fma_f32 v[208:209], v[196:197], v[148:149], v[72:73] op_sel_hi:[0,1,1] neg_lo:[1,0,0] neg_hi:[1,0,0]
	v_lshlrev_b64 v[202:203], 11, v[210:211]
	v_pk_fma_f32 v[76:77], v[198:199], v[76:77], v[154:155] op_sel_hi:[0,1,1]
	v_pk_fma_f32 v[72:73], v[196:197], v[150:151], v[74:75] op_sel_hi:[0,1,1] neg_lo:[1,0,0] neg_hi:[1,0,0]
	v_pk_fma_f32 v[74:75], v[198:199], v[208:209], v[144:145] op_sel_hi:[0,1,1]
	v_pk_mul_f32 v[208:209], v[224:225], v[78:79] op_sel_hi:[0,1]
	v_lshl_add_u64 v[202:203], v[226:227], 0, v[202:203]
	v_pk_fma_f32 v[72:73], v[198:199], v[72:73], v[146:147] op_sel_hi:[0,1,1]
	v_pk_mul_f32 v[210:211], v[224:225], v[76:77] op_sel_hi:[0,1]
	v_cvt_pk_bf16_f32 v208, v208, v209
	v_cvt_pk_bf16_f32 v209, v210, v211
	v_pk_mul_f32 v[214:215], v[224:225], v[72:73] op_sel_hi:[0,1]
	v_pk_mul_f32 v[216:217], v[224:225], v[74:75] op_sel_hi:[0,1]
	v_cvt_pk_bf16_f32 v210, v216, v217
	v_cvt_pk_bf16_f32 v211, v214, v215
	global_store_dwordx4 v[202:203], v[208:211], off
	s_nop 1
	v_pk_fma_f32 v[208:209], v[196:197], v[140:141], v[68:69] op_sel_hi:[0,1,1] neg_lo:[1,0,0] neg_hi:[1,0,0]
	v_pk_fma_f32 v[68:69], v[196:197], v[142:143], v[70:71] op_sel_hi:[0,1,1] neg_lo:[1,0,0] neg_hi:[1,0,0]
	v_pk_fma_f32 v[70:71], v[198:199], v[208:209], v[136:137] op_sel_hi:[0,1,1]
	v_pk_fma_f32 v[208:209], v[196:197], v[128:129], v[64:65] op_sel_hi:[0,1,1] neg_lo:[1,0,0] neg_hi:[1,0,0]
	v_pk_fma_f32 v[64:65], v[196:197], v[130:131], v[66:67] op_sel_hi:[0,1,1] neg_lo:[1,0,0] neg_hi:[1,0,0]
	v_pk_fma_f32 v[66:67], v[198:199], v[208:209], v[132:133] op_sel_hi:[0,1,1]
	v_pk_fma_f32 v[68:69], v[198:199], v[68:69], v[138:139] op_sel_hi:[0,1,1]
	v_pk_fma_f32 v[64:65], v[198:199], v[64:65], v[134:135] op_sel_hi:[0,1,1]
	v_pk_mul_f32 v[208:209], v[224:225], v[70:71] op_sel_hi:[0,1]
	v_pk_mul_f32 v[210:211], v[224:225], v[66:67] op_sel_hi:[0,1]
	v_pk_mul_f32 v[196:197], v[224:225], v[68:69] op_sel_hi:[0,1]
	v_pk_mul_f32 v[214:215], v[224:225], v[64:65] op_sel_hi:[0,1]
	v_cvt_pk_bf16_f32 v208, v208, v209
	v_cvt_pk_bf16_f32 v209, v196, v197
	v_cvt_pk_bf16_f32 v210, v210, v211
	v_cvt_pk_bf16_f32 v211, v214, v215
	global_store_dwordx4 v[202:203], v[208:211], off offset:256
	v_pk_fma_f32 v[202:203], v[190:191], v[156:157], v[60:61] op_sel_hi:[0,1,1] neg_lo:[1,0,0] neg_hi:[1,0,0]
	v_pk_fma_f32 v[60:61], v[190:191], v[158:159], v[62:63] op_sel_hi:[0,1,1] neg_lo:[1,0,0] neg_hi:[1,0,0]
	v_pk_fma_f32 v[60:61], v[60:61], v[194:195], v[154:155] op_sel_hi:[1,0,1]
	v_pk_fma_f32 v[62:63], v[202:203], v[194:195], v[152:153] op_sel_hi:[1,0,1]
	v_pk_fma_f32 v[202:203], v[190:191], v[148:149], v[56:57] op_sel_hi:[0,1,1] neg_lo:[1,0,0] neg_hi:[1,0,0]
	v_lshlrev_b64 v[196:197], 11, v[206:207]
	v_pk_fma_f32 v[56:57], v[190:191], v[150:151], v[58:59] op_sel_hi:[0,1,1] neg_lo:[1,0,0] neg_hi:[1,0,0]
	v_pk_fma_f32 v[58:59], v[202:203], v[194:195], v[144:145] op_sel_hi:[1,0,1]
	v_pk_mul_f32 v[202:203], v[224:225], v[60:61] op_sel_hi:[0,1]
	v_pk_mul_f32 v[206:207], v[224:225], v[62:63] op_sel_hi:[0,1]
	v_cvt_pk_bf16_f32 v206, v206, v207
	v_cvt_pk_bf16_f32 v207, v202, v203
	v_pk_fma_f32 v[202:203], v[190:191], v[140:141], v[52:53] op_sel_hi:[0,1,1] neg_lo:[1,0,0] neg_hi:[1,0,0]
	v_pk_fma_f32 v[56:57], v[56:57], v[194:195], v[146:147] op_sel_hi:[1,0,1]
	v_pk_mul_f32 v[208:209], v[224:225], v[58:59] op_sel_hi:[0,1]
	v_pk_fma_f32 v[52:53], v[190:191], v[142:143], v[54:55] op_sel_hi:[0,1,1] neg_lo:[1,0,0] neg_hi:[1,0,0]
	v_pk_fma_f32 v[54:55], v[194:195], v[202:203], v[136:137] op_sel_hi:[0,1,1]
	v_pk_fma_f32 v[202:203], v[190:191], v[128:129], v[48:49] op_sel_hi:[0,1,1] neg_lo:[1,0,0] neg_hi:[1,0,0]
	v_lshl_add_u64 v[196:197], v[226:227], 0, v[196:197]
	v_pk_mul_f32 v[210:211], v[224:225], v[56:57] op_sel_hi:[0,1]
	v_cvt_pk_bf16_f32 v208, v208, v209
	v_cvt_pk_bf16_f32 v209, v210, v211
	v_pk_fma_f32 v[48:49], v[190:191], v[130:131], v[50:51] op_sel_hi:[0,1,1] neg_lo:[1,0,0] neg_hi:[1,0,0]
	v_pk_fma_f32 v[50:51], v[194:195], v[202:203], v[132:133] op_sel_hi:[0,1,1]
	global_store_dwordx4 v[196:197], v[206:209], off
	v_pk_fma_f32 v[52:53], v[194:195], v[52:53], v[138:139] op_sel_hi:[0,1,1]
	v_pk_fma_f32 v[48:49], v[194:195], v[48:49], v[134:135] op_sel_hi:[0,1,1]
	v_pk_mul_f32 v[208:209], v[224:225], v[50:51] op_sel_hi:[0,1]
	v_xor_b32_e32 v159, 0x80000000, v159
	v_xor_b32_e32 v158, 0x80000000, v158
	v_pk_mul_f32 v[190:191], v[224:225], v[52:53] op_sel_hi:[0,1]
	v_pk_mul_f32 v[202:203], v[224:225], v[54:55] op_sel_hi:[0,1]
	v_pk_mul_f32 v[210:211], v[224:225], v[48:49] op_sel_hi:[0,1]
	v_cvt_pk_bf16_f32 v206, v202, v203
	v_cvt_pk_bf16_f32 v207, v190, v191
	v_cvt_pk_bf16_f32 v208, v208, v209
	v_cvt_pk_bf16_f32 v209, v210, v211
; __device__ __forceinline__ unsigned cvt_pk_bf16(float lo, float hi) { unsigned r; asm("v_cvt_pk_bf16_f32 %0, %1, %2" : "=v"(r) : "v"(lo), "v"(hi)); return r; }
; __device__ __forceinline__ f32x4 ln_fix(const f32x4& a, float mu, float rs, const f32x4& cs, const f32x4& cb) { return (a - cs * mu) * rs + cb; }
;     __device__ __forceinline__ void operator()(const f32x4 (&acc)[2][2][4][2], const Unit& u, int wr, int wc, int fr_in, int fq_in) const {
;     ...
;             for (int m = 0; m < 4; ++m) { bf16_t* rowp = base + (size_t)(row0 + ai * HALF + m * 16) * 1024 + col0;
; #pragma unroll
;                 for (int bj = 0; bj < 2; ++bj) { const f32x4 v0r = ln_fix(acc[ai][bj][m][0], rst.mu[ai][m], rst.rs[ai][m], csv[bj][0], cbv[bj][0]), v1r = ln_fix(acc[ai][bj][m][1], rst.mu[ai][m], rst.rs[ai][m], csv[bj][1], cbv[bj][1]);
;                     ks[bj][0] += v0r; ks[bj][1] += v1r; const f32x4 v0 = v0r * sc, v1 = v1r * sc;
;                     u32x4 w; w.x = cvt_pk_bf16(v0[0], v0[1]); w.y = cvt_pk_bf16(v0[2], v0[3]); w.z = cvt_pk_bf16(v1[0], v1[1]); w.w = cvt_pk_bf16(v1[2], v1[3]);
;                     *(u32x4*)(rowp + bj * HALF) = w; } }
	global_store_dwordx4 v[196:197], v[206:209], off offset:256
	v_pk_fma_f32 v[196:197], v[156:157], v[184:185], v[44:45] op_sel_hi:[1,0,1] neg_lo:[1,0,0] neg_hi:[1,0,0]
	v_pk_fma_f32 v[44:45], v[158:159], v[184:185], v[46:47] op_sel_hi:[1,0,1]
	v_pk_fma_f32 v[46:47], v[196:197], v[188:189], v[152:153] op_sel_hi:[1,0,1]
	v_pk_fma_f32 v[44:45], v[44:45], v[188:189], v[154:155] op_sel_hi:[1,0,1]
	v_pk_fma_f32 v[196:197], v[184:185], v[148:149], v[40:41] op_sel_hi:[0,1,1] neg_lo:[1,0,0] neg_hi:[1,0,0]
	v_lshlrev_b64 v[190:191], 11, v[200:201]
	v_pk_fma_f32 v[40:41], v[184:185], v[150:151], v[42:43] op_sel_hi:[0,1,1] neg_lo:[1,0,0] neg_hi:[1,0,0]
	v_pk_fma_f32 v[42:43], v[196:197], v[188:189], v[144:145] op_sel_hi:[1,0,1]
	v_pk_mul_f32 v[196:197], v[224:225], v[44:45] op_sel_hi:[0,1]
	v_pk_mul_f32 v[200:201], v[224:225], v[46:47] op_sel_hi:[0,1]
	v_cvt_pk_bf16_f32 v200, v200, v201
	v_cvt_pk_bf16_f32 v201, v196, v197
	v_pk_fma_f32 v[196:197], v[184:185], v[140:141], v[36:37] op_sel_hi:[0,1,1] neg_lo:[1,0,0] neg_hi:[1,0,0]
	v_pk_fma_f32 v[40:41], v[40:41], v[188:189], v[146:147] op_sel_hi:[1,0,1]
	v_pk_mul_f32 v[202:203], v[224:225], v[42:43] op_sel_hi:[0,1]
	v_pk_fma_f32 v[36:37], v[184:185], v[142:143], v[38:39] op_sel_hi:[0,1,1] neg_lo:[1,0,0] neg_hi:[1,0,0]
	v_pk_fma_f32 v[38:39], v[196:197], v[188:189], v[136:137] op_sel_hi:[1,0,1]
	v_pk_fma_f32 v[196:197], v[184:185], v[128:129], v[32:33] op_sel_hi:[0,1,1] neg_lo:[1,0,0] neg_hi:[1,0,0]
	v_lshl_add_u64 v[190:191], v[226:227], 0, v[190:191]
	v_pk_mul_f32 v[206:207], v[224:225], v[40:41] op_sel_hi:[0,1]
	v_cvt_pk_bf16_f32 v202, v202, v203
	v_cvt_pk_bf16_f32 v203, v206, v207
	v_pk_fma_f32 v[32:33], v[184:185], v[130:131], v[34:35] op_sel_hi:[0,1,1] neg_lo:[1,0,0] neg_hi:[1,0,0]
	v_pk_fma_f32 v[34:35], v[188:189], v[196:197], v[132:133] op_sel_hi:[0,1,1]
	global_store_dwordx4 v[190:191], v[200:203], off
	v_pk_fma_f32 v[36:37], v[36:37], v[188:189], v[138:139] op_sel_hi:[1,0,1]
	v_pk_fma_f32 v[32:33], v[188:189], v[32:33], v[134:135] op_sel_hi:[0,1,1]
	v_pk_mul_f32 v[202:203], v[224:225], v[34:35] op_sel_hi:[0,1]
	v_pk_mul_f32 v[184:185], v[224:225], v[36:37] op_sel_hi:[0,1]
	v_pk_mul_f32 v[196:197], v[224:225], v[38:39] op_sel_hi:[0,1]
	v_pk_mul_f32 v[206:207], v[224:225], v[32:33] op_sel_hi:[0,1]
	v_cvt_pk_bf16_f32 v200, v196, v197
	v_cvt_pk_bf16_f32 v201, v184, v185
	v_cvt_pk_bf16_f32 v202, v202, v203
	v_cvt_pk_bf16_f32 v203, v206, v207
	global_store_dwordx4 v[190:191], v[200:203], off offset:256
	v_pk_fma_f32 v[190:191], v[156:157], v[180:181], v[28:29] op_sel_hi:[1,0,1] neg_lo:[1,0,0] neg_hi:[1,0,0]
	v_pk_fma_f32 v[28:29], v[158:159], v[180:181], v[30:31] op_sel_hi:[1,0,1]
	v_pk_fma_f32 v[30:31], v[190:191], v[182:183], v[152:153] op_sel_hi:[1,0,1]
	v_pk_fma_f32 v[190:191], v[148:149], v[180:181], v[24:25] op_sel_hi:[1,0,1] neg_lo:[1,0,0] neg_hi:[1,0,0]
	v_xor_b32_e32 v151, 0x80000000, v151
	v_xor_b32_e32 v150, 0x80000000, v150
	v_lshlrev_b64 v[184:185], 11, v[192:193]
	v_pk_fma_f32 v[28:29], v[28:29], v[182:183], v[154:155] op_sel_hi:[1,0,1]
	v_pk_fma_f32 v[24:25], v[150:151], v[180:181], v[26:27] op_sel_hi:[1,0,1]
	v_pk_fma_f32 v[26:27], v[190:191], v[182:183], v[144:145] op_sel_hi:[1,0,1]
	v_pk_mul_f32 v[190:191], v[224:225], v[30:31] op_sel_hi:[0,1]
	v_lshl_add_u64 v[184:185], v[226:227], 0, v[184:185]
	v_pk_fma_f32 v[24:25], v[24:25], v[182:183], v[146:147] op_sel_hi:[1,0,1]
	v_pk_mul_f32 v[192:193], v[224:225], v[28:29] op_sel_hi:[0,1]
	v_cvt_pk_bf16_f32 v190, v190, v191
	v_cvt_pk_bf16_f32 v191, v192, v193
	v_pk_mul_f32 v[196:197], v[224:225], v[24:25] op_sel_hi:[0,1]
	v_pk_mul_f32 v[200:201], v[224:225], v[26:27] op_sel_hi:[0,1]
	v_cvt_pk_bf16_f32 v192, v200, v201
	v_cvt_pk_bf16_f32 v193, v196, v197
	global_store_dwordx4 v[184:185], v[190:193], off
	v_pk_fma_f32 v[14:15], v[158:159], v[178:179], v[14:15] op_sel_hi:[1,0,1]
	v_pk_fma_f32 v[148:149], v[148:149], v[178:179], v[8:9] op_sel_hi:[1,0,1] neg_lo:[1,0,0] neg_hi:[1,0,0]
	v_pk_fma_f32 v[190:191], v[180:181], v[140:141], v[20:21] op_sel_hi:[0,1,1] neg_lo:[1,0,0] neg_hi:[1,0,0]
	v_pk_fma_f32 v[20:21], v[180:181], v[142:143], v[22:23] op_sel_hi:[0,1,1] neg_lo:[1,0,0] neg_hi:[1,0,0]
	v_pk_fma_f32 v[20:21], v[20:21], v[182:183], v[138:139] op_sel_hi:[1,0,1]
	v_pk_fma_f32 v[22:23], v[190:191], v[182:183], v[136:137] op_sel_hi:[1,0,1]
	v_pk_fma_f32 v[190:191], v[180:181], v[128:129], v[16:17] op_sel_hi:[0,1,1] neg_lo:[1,0,0] neg_hi:[1,0,0]
	v_pk_fma_f32 v[140:141], v[140:141], v[178:179], v[4:5] op_sel_hi:[1,0,1] neg_lo:[1,0,0] neg_hi:[1,0,0]
; __device__ __forceinline__ unsigned cvt_pk_bf16(float lo, float hi) { unsigned r; asm("v_cvt_pk_bf16_f32 %0, %1, %2" : "=v"(r) : "v"(lo), "v"(hi)); return r; }
; __device__ __forceinline__ f32x4 ln_fix(const f32x4& a, float mu, float rs, const f32x4& cs, const f32x4& cb) { return (a - cs * mu) * rs + cb; }
;     __device__ __forceinline__ void operator()(const f32x4 (&acc)[2][2][4][2], const Unit& u, int wr, int wc, int fr_in, int fq_in) const {
;     ...
;                 for (int bj = 0; bj < 2; ++bj) { const f32x4 v0r = ln_fix(acc[ai][bj][m][0], rst.mu[ai][m], rst.rs[ai][m], csv[bj][0], cbv[bj][0]), v1r = ln_fix(acc[ai][bj][m][1], rst.mu[ai][m], rst.rs[ai][m], csv[bj][1], cbv[bj][1]);
;                     ks[bj][0] += v0r; ks[bj][1] += v1r; const f32x4 v0 = v0r * sc, v1 = v1r * sc;
;                     u32x4 w; w.x = cvt_pk_bf16(v0[0], v0[1]); w.y = cvt_pk_bf16(v0[2], v0[3]); w.z = cvt_pk_bf16(v1[0], v1[1]); w.w = cvt_pk_bf16(v1[2], v1[3]);
;                     *(u32x4*)(rowp + bj * HALF) = w; } }
;         if (kb) {
;             const int colt = (u.pn - 4) * BM + wc * 32 + 8 * fq; const int b = u.pm >> 5, blk = u.pm & 31;
; #pragma unroll
;             for (int bj = 0; bj < 2; ++bj)
; #pragma unroll
;                 for (int n = 0; n < 2; ++n)
; #pragma unroll
;                     for (int j = 0; j < 4; ++j) { float s = ks[bj][n][j];
;                         s += __shfl_xor(s, 1); s += __shfl_xor(s, 2); s += __shfl_xor(s, 4); s += __shfl_xor(s, 8);
;                         if (fr == 0) { const int col = colt + bj * HALF + 4 * n + j; atomicAdd(kbar + ((size_t)((b * 8 + (col >> 6)) * 32 + blk)) * 64 + (col & 63), s); } }
	v_xor_b32_e32 v5, 0x80000000, v143
	v_xor_b32_e32 v4, 0x80000000, v142
	v_pk_fma_f32 v[16:17], v[180:181], v[130:131], v[18:19] op_sel_hi:[0,1,1] neg_lo:[1,0,0] neg_hi:[1,0,0]
	v_pk_fma_f32 v[18:19], v[190:191], v[182:183], v[132:133] op_sel_hi:[1,0,1]
	v_pk_mul_f32 v[180:181], v[224:225], v[20:21] op_sel_hi:[0,1]
	v_pk_mul_f32 v[190:191], v[224:225], v[22:23] op_sel_hi:[0,1]
	v_pk_fma_f32 v[4:5], v[4:5], v[178:179], v[6:7] op_sel_hi:[1,0,1]
	v_cvt_pk_bf16_f32 v190, v190, v191
	v_cvt_pk_bf16_f32 v191, v180, v181
	v_lshlrev_b64 v[180:181], 11, v[186:187]
	v_pk_fma_f32 v[14:15], v[14:15], v[168:169], v[154:155] op_sel_hi:[1,0,1]
	v_pk_fma_f32 v[8:9], v[150:151], v[178:179], v[10:11] op_sel_hi:[1,0,1]
	v_pk_fma_f32 v[4:5], v[4:5], v[168:169], v[138:139] op_sel_hi:[1,0,1]
	v_pk_fma_f32 v[6:7], v[140:141], v[168:169], v[136:137] op_sel_hi:[1,0,1]
	v_pk_fma_f32 v[128:129], v[178:179], v[128:129], v[0:1] op_sel_hi:[0,1,1] neg_lo:[1,0,0] neg_hi:[1,0,0]
	v_pk_fma_f32 v[0:1], v[178:179], v[130:131], v[2:3] op_sel_hi:[0,1,1] neg_lo:[1,0,0] neg_hi:[1,0,0]
	v_pk_fma_f32 v[16:17], v[16:17], v[182:183], v[134:135] op_sel_hi:[1,0,1]
	v_pk_mul_f32 v[192:193], v[224:225], v[18:19] op_sel_hi:[0,1]
	v_lshl_add_u64 v[180:181], v[226:227], 0, v[180:181]
	v_pk_fma_f32 v[8:9], v[8:9], v[168:169], v[146:147] op_sel_hi:[1,0,1]
	v_pk_fma_f32 v[10:11], v[148:149], v[168:169], v[144:145] op_sel_hi:[1,0,1]
	v_pk_mul_f32 v[146:147], v[224:225], v[14:15] op_sel_hi:[0,1]
	v_pk_mul_f32 v[144:145], v[224:225], v[12:13] op_sel_hi:[0,1]
	v_pk_fma_f32 v[0:1], v[0:1], v[168:169], v[134:135] op_sel_hi:[1,0,1]
	v_pk_fma_f32 v[2:3], v[128:129], v[168:169], v[132:133] op_sel_hi:[1,0,1]
	v_pk_mul_f32 v[130:131], v[224:225], v[4:5] op_sel_hi:[0,1]
	v_pk_mul_f32 v[128:129], v[224:225], v[6:7] op_sel_hi:[0,1]
	v_pk_mul_f32 v[196:197], v[224:225], v[16:17] op_sel_hi:[0,1]
	v_cvt_pk_bf16_f32 v192, v192, v193
	v_cvt_pk_bf16_f32 v193, v196, v197
	global_store_dwordx4 v[184:185], v[190:193], off offset:256
	v_pk_mul_f32 v[148:149], v[224:225], v[8:9] op_sel_hi:[0,1]
	v_pk_mul_f32 v[150:151], v[224:225], v[10:11] op_sel_hi:[0,1]
	v_cvt_pk_bf16_f32 v144, v144, v145
	v_cvt_pk_bf16_f32 v145, v146, v147
	v_cvt_pk_bf16_f32 v146, v150, v151
	v_cvt_pk_bf16_f32 v147, v148, v149
	global_store_dwordx4 v[180:181], v[144:147], off
	v_pk_mul_f32 v[132:133], v[224:225], v[0:1] op_sel_hi:[0,1]
	v_pk_mul_f32 v[134:135], v[224:225], v[2:3] op_sel_hi:[0,1]
	v_cvt_pk_bf16_f32 v128, v128, v129
	v_cvt_pk_bf16_f32 v129, v130, v131
	v_cvt_pk_bf16_f32 v130, v134, v135
	v_cvt_pk_bf16_f32 v131, v132, v133
	global_store_dwordx4 v[180:181], v[128:131], off offset:256
	s_cbranch_scc1 .LBB0_470
	v_pk_add_f32 v[126:127], v[126:127], 0 op_sel_hi:[1,0]
	s_add_i32 s8, s62, s8
	v_pk_add_f32 v[110:111], v[110:111], v[126:127]
	s_and_b32 s37, s46, 31
	v_pk_add_f32 v[94:95], v[94:95], v[110:111]
	s_nop 0
	v_pk_add_f32 v[78:79], v[78:79], v[94:95]
	s_nop 0
	v_pk_add_f32 v[62:63], v[62:63], v[78:79]
	s_nop 0
	v_pk_add_f32 v[46:47], v[62:63], v[46:47]
	v_add_u32_e32 v63, s8, v229
	v_pk_add_f32 v[30:31], v[46:47], v[30:31]
	s_ashr_i32 s8, s46, 2
	v_pk_add_f32 v[30:31], v[30:31], v[12:13]
	v_and_b32_e32 v13, 64, v225
	v_xor_b32_e32 v12, 1, v225
	v_add_u32_e32 v13, 64, v13
	v_cmp_lt_i32_e32 vcc, v12, v13
	s_and_b32 s41, s8, -8
	v_and_b32_e32 v94, 56, v63
	v_cndmask_b32_e32 v12, v225, v12, vcc
	v_lshlrev_b32_e32 v46, 2, v12
	v_xor_b32_e32 v12, 2, v225
	v_cmp_lt_i32_e32 vcc, v12, v13
	ds_bpermute_b32 v78, v46, v30
	v_lshlrev_b32_e32 v168, 2, v94
	v_cndmask_b32_e32 v12, v225, v12, vcc
	v_lshlrev_b32_e32 v47, 2, v12
	v_xor_b32_e32 v12, 4, v225
	v_cmp_lt_i32_e32 vcc, v12, v13
	s_nop 1
	v_cndmask_b32_e32 v12, v225, v12, vcc
	v_lshlrev_b32_e32 v62, 2, v12
	v_xor_b32_e32 v12, 8, v225
	v_cmp_lt_i32_e32 vcc, v12, v13
	s_waitcnt lgkmcnt(0)
	v_add_f32_e32 v13, v30, v78
	ds_bpermute_b32 v78, v47, v13
	v_cndmask_b32_e32 v12, v225, v12, vcc
	v_lshlrev_b32_e32 v30, 2, v12
	v_ashrrev_i32_e32 v12, 6, v63
	v_add_u32_e32 v12, s41, v12
	s_waitcnt lgkmcnt(0)
	v_add_f32_e32 v13, v13, v78
	ds_bpermute_b32 v78, v62, v13
	v_lshl_or_b32 v12, v12, 5, s37
	v_cmp_eq_u32_e32 vcc, 0, v228
	s_waitcnt lgkmcnt(0)
	v_add_f32_e32 v78, v13, v78
	ds_bpermute_b32 v79, v30, v78
	v_ashrrev_i32_e32 v13, 31, v12
	v_lshlrev_b64 v[12:13], 8, v[12:13]
	v_lshl_add_u64 v[12:13], s[10:11], 0, v[12:13]
	s_and_saveexec_b64 s[46:47], vcc
	s_cbranch_execz .LBB0_439
	v_lshl_add_u64 v[94:95], v[12:13], 0, v[168:169]
	s_waitcnt lgkmcnt(0)
	v_add_f32_e32 v78, v78, v79
	global_atomic_add_f32 v[94:95], v78, off

; __device__ __forceinline__ void load_row_stats(const float* sp, int row0, RowStats& r) {
;     ...
;         for (int m = 0; m < 4; ++m) { const float* p = sp + (size_t)(row0 + ai * HALF + m * 16) * 8; const f32x4 a = *(const f32x4*)p, b = *(const f32x4*)(p + 4);
;             const float s1 = (a[0] + a[2]) + (b[0] + b[2]), s2 = (a[1] + a[3]) + (b[1] + b[3]); const float mu = s1 * (1.f / 1024.f); const float var = s2 * (1.f / 1024.f) - mu * mu;
;             r.mu[ai][m] = mu; r.rs[ai][m] = __builtin_amdgcn_rsqf(__builtin_fmaxf(var, 0.f) + 1e-5f); } }
;     __device__ __forceinline__ void operator()(const f32x4 (&acc)[2][2][4][2], const Unit& u, int wr, int wc, int fr_in, int fq_in) const {
;     ...
;         const int row0 = u.pm * BM + wr * 64 + fr, n0 = u.pn * BM + wc * 32 + 8 * fq; const int kt = u.pn * 2 + (wc >> 1), cin = (wc & 1) * 32 + 8 * fq;
;         RowStats rst; f32x4 csv[2][2], cbv[2][2];
;         if constexpr (LN) { load_row_stats(sp, row0, rst);
; #pragma unroll
;             for (int bj = 0; bj < 2; ++bj)
; #pragma unroll
;                 for (int n = 0; n < 2; ++n) { csv[bj][n] = *(const f32x4*)(cs + n0 + bj * HALF + 4 * n); cbv[bj][n] = *(const f32x4*)(cb + n0 + bj * HALF + 4 * n); } }
.LBB0_1260:
	s_lshl_b32 s35, s44, 8
	v_mov_b32_e32 v112, v185
	v_mov_b32_e32 v113, v179
	s_add_i32 s35, s35, s54
	s_andn2_b64 vcc, exec, s[38:39]
	v_add_u32_e32 v192, s35, v113
	v_ashrrev_i32_e32 v193, 31, v192
	v_and_b32_e32 v226, 0xffffff00, v192
	v_and_b32_e32 v177, 0xff, v192
	v_lshlrev_b32_e32 v177, 3, v177
	v_add_u32_e32 v177, 0x22400, v177
	v_add_u32_e32 v224, 16, v192
	v_ashrrev_i32_e32 v225, 31, v224
	v_add_u32_e32 v218, 32, v192
	v_ashrrev_i32_e32 v219, 31, v218
	v_add_u32_e32 v212, 48, v192
	v_ashrrev_i32_e32 v213, 31, v212
	v_add_u32_e32 v204, 0x80, v192
	v_ashrrev_i32_e32 v205, 31, v204
	v_add_u32_e32 v196, 0x90, v192
	v_ashrrev_i32_e32 v197, 31, v196
	v_add_u32_e32 v188, 0xa0, v192
	v_ashrrev_i32_e32 v189, 31, v188
	v_add_u32_e32 v182, 0xb0, v192
	v_ashrrev_i32_e32 v183, 31, v182
	s_lshl_b32 s35, s45, 8
	s_or_b32 s35, s35, s55
	v_lshlrev_b32_e32 v206, 3, v112
	v_add_u32_e32 v112, s35, v206
	s_lshl_b32 s35, s45, 1
	s_or_b32 s44, s35, s59
	s_ashr_i32 s45, s44, 31
	s_lshl_b64 s[44:45], s[44:45], 15
	v_lshl_add_u64 v[192:193], s[44:45], 0, v[192:193]
	v_lshlrev_b64 v[192:193], 7, v[192:193]
	v_add_u32_e32 v230, s60, v206
	v_lshl_add_u64 v[232:233], s[6:7], 0, v[192:193]
	v_mov_b32_e32 v192, v144
	v_mov_b32_e32 v193, v140
	v_mov_b32_e32 v140, v145
	v_ashrrev_i32_e32 v231, 31, v230
	s_nop 0
	v_ashrrev_i32_e32 v113, 31, v112
	v_lshlrev_b64 v[112:113], 2, v[112:113]
	v_lshl_add_u64 v[136:137], s[12:13], 0, v[112:113]
	v_lshl_add_u64 v[156:157], s[22:23], 0, v[112:113]
	global_load_dwordx4 v[112:115], v[136:137], off offset:16
	global_load_dwordx4 v[128:131], v[136:137], off
	global_load_dwordx4 v[116:119], v[156:157], off offset:16
	global_load_dwordx4 v[132:135], v[156:157], off
	global_load_dwordx4 v[148:151], v[136:137], off offset:528
	s_nop 0
	global_load_dwordx4 v[136:139], v[136:137], off offset:512
	s_nop 0
	global_load_dwordx4 v[152:155], v[156:157], off offset:528
	s_nop 0
	global_load_dwordx4 v[156:159], v[156:157], off offset:512
	s_cselect_b32 s99, 1, 0
	v_readfirstlane_b32 s98, v254
	s_nop 0
	s_cmpk_lt_u32 s98, 0x100
	s_cbranch_scc0 .Lrs2_skip
	v_add_u32_e32 v226, v226, v254
	v_mov_b32_e32 v227, 0
	v_lshlrev_b64 v[226:227], 5, v[226:227]
	v_lshl_add_u64 v[226:227], s[10:11], 0, v[226:227]
	global_load_dwordx2 v[220:221], v[226:227], off offset:16
	global_load_dwordx2 v[214:215], v[226:227], off offset:24
	global_load_dwordx2 v[200:201], v[226:227], off
	global_load_dwordx2 v[194:195], v[226:227], off offset:8
	s_waitcnt vmcnt(0)
	v_pk_add_f32 v[220:221], v[220:221], v[214:215]
	v_pk_add_f32 v[200:201], v[200:201], v[194:195]
	s_nop 0
	v_pk_add_f32 v[220:221], v[200:201], v[220:221]
	s_nop 0
	v_pk_mul_f32 v[220:221], v[220:221], s[30:31] op_sel_hi:[1,0]
	v_lshlrev_b32_e32 v186, 3, v254
	v_add_u32_e32 v186, 0x22400, v186
	ds_write_b64 v186, v[220:221]
.Lrs2_skip:
	s_waitcnt vmcnt(0) lgkmcnt(0)
	s_barrier
	ds_read_b64 v[226:227], v177
	ds_read_b64 v[220:221], v177 offset:128
	ds_read_b64 v[214:215], v177 offset:256
	ds_read_b64 v[200:201], v177 offset:384
	ds_read_b64 v[194:195], v177 offset:1024
	ds_read_b64 v[186:187], v177 offset:1152
	ds_read_b64 v[180:181], v177 offset:1280
	ds_read_b64 v[176:177], v177 offset:1408
	s_cmp_lg_u32 s99, 0
	s_waitcnt lgkmcnt(0)
	v_fma_f32 v228, -v226, v226, v227
	v_max_f32_e32 v228, 0, v228
	v_add_f32_e32 v228, 0x3727c5ac, v228
	v_rsq_f32_e32 v228, v228
	v_fma_f32 v222, -v220, v220, v221
	v_max_f32_e32 v222, 0, v222
	v_add_f32_e32 v222, 0x3727c5ac, v222
	v_rsq_f32_e32 v222, v222
	v_fma_f32 v216, -v214, v214, v215
	v_max_f32_e32 v216, 0, v216
	v_add_f32_e32 v216, 0x3727c5ac, v216
	v_rsq_f32_e32 v216, v216
	v_fma_f32 v202, -v200, v200, v201
	v_max_f32_e32 v202, 0, v202
	v_add_f32_e32 v202, 0x3727c5ac, v202
	v_rsq_f32_e32 v202, v202
	v_fma_f32 v198, -v194, v194, v195
	v_max_f32_e32 v198, 0, v198
	v_add_f32_e32 v198, 0x3727c5ac, v198
	v_rsq_f32_e32 v198, v198
	v_fma_f32 v190, -v186, v186, v187
	v_max_f32_e32 v190, 0, v190
	v_add_f32_e32 v190, 0x3727c5ac, v190
	v_rsq_f32_e32 v190, v190
	v_fma_f32 v184, -v180, v180, v181
	v_max_f32_e32 v184, 0, v184
	v_add_f32_e32 v184, 0x3727c5ac, v184
	v_rsq_f32_e32 v184, v184
	v_fma_f32 v178, -v176, v176, v177
	v_max_f32_e32 v178, 0, v178
	v_add_f32_e32 v178, 0x3727c5ac, v178
	v_rsq_f32_e32 v178, v178
	s_waitcnt vmcnt(0)
; __device__ __forceinline__ unsigned cvt_pk_bf16(float lo, float hi) { unsigned r; asm("v_cvt_pk_bf16_f32 %0, %1, %2" : "=v"(r) : "v"(lo), "v"(hi)); return r; }
; __device__ __forceinline__ float fast_sigmoid(float v) { return __builtin_amdgcn_rcpf(1.0f + __builtin_amdgcn_exp2f(-1.4426950408889634f * v)); }
; __device__ __forceinline__ f32x4 ln_fix(const f32x4& a, float mu, float rs, const f32x4& cs, const f32x4& cb) { return (a - cs * mu) * rs + cb; }
;     __device__ __forceinline__ void operator()(const f32x4 (&acc)[2][2][4][2], const Unit& u, int wr, int wc, int fr_in, int fq_in) const {
;     ...
;         for (int ai = 0; ai < 2; ++ai)
; #pragma unroll
;             for (int m = 0; m < 4; ++m) { bf16_t* rowp = H + ((size_t)kt * mrows + (row0 + ai * HALF + m * 16)) * 64 + cin;
;                 float h[8];
; #pragma unroll
;                 for (int n = 0; n < 2; ++n) { f32x4 g = acc[ai][0][m][n], uu = acc[ai][1][m][n];
;                     if constexpr (LN) { g = ln_fix(g, rst.mu[ai][m], rst.rs[ai][m], csv[0][n], cbv[0][n]); uu = ln_fix(uu, rst.mu[ai][m], rst.rs[ai][m], csv[1][n], cbv[1][n]); }
; #pragma unroll
;                     for (int j = 0; j < 4; ++j) h[4 * n + j] = g[j] * fast_sigmoid(g[j]) * uu[j]; }
;                 u32x4 w; w.x = cvt_pk_bf16(h[0], h[1]); w.y = cvt_pk_bf16(h[2], h[3]); w.z = cvt_pk_bf16(h[4], h[5]); w.w = cvt_pk_bf16(h[6], h[7]);
;                 *(u32x4*)rowp = w; }
	v_mov_b32_e32 v207, v128
	v_mov_b32_e32 v211, v131
	v_mov_b32_e32 v206, v136
	v_pk_fma_f32 v[208:209], v[226:227], v[206:207], v[192:193] op_sel_hi:[0,1,1] neg_lo:[1,0,0] neg_hi:[1,0,0]
	v_mov_b32_e32 v192, v156
	v_mov_b32_e32 v193, v132
	v_pk_fma_f32 v[208:209], v[228:229], v[208:209], v[192:193] op_sel_hi:[0,1,1]
	v_mul_f32_e32 v132, 0xbfb8aa3b, v209
	v_exp_f32_e32 v132, v132
	v_mov_b32_e32 v156, v138
	v_mov_b32_e32 v210, v139
	v_add_f32_e32 v132, 1.0, v132
	v_rcp_f32_e32 v132, v132
	s_nop 0
	v_mul_f32_e32 v132, v209, v132
	v_mul_f32_e32 v223, v208, v132
	v_mov_b32_e32 v208, v137
	v_mov_b32_e32 v209, v129
	v_pk_fma_f32 v[140:141], v[226:227], v[208:209], v[140:141] op_sel_hi:[0,1,1] neg_lo:[1,0,0] neg_hi:[1,0,0]
	v_mov_b32_e32 v132, v157
	v_pk_fma_f32 v[140:141], v[228:229], v[140:141], v[132:133] op_sel_hi:[0,1,1]
	v_mul_f32_e32 v144, 0xbfb8aa3b, v141
	v_exp_f32_e32 v144, v144
	v_mov_b32_e32 v157, v130
	v_add_f32_e32 v144, 1.0, v144
	v_rcp_f32_e32 v144, v144
	s_nop 0
	v_mul_f32_e32 v141, v141, v144
	v_mul_f32_e32 v229, v140, v141
	v_mov_b32_e32 v140, v146
	v_mov_b32_e32 v141, v142
	v_pk_fma_f32 v[144:145], v[226:227], v[156:157], v[140:141] op_sel_hi:[0,1,1] neg_lo:[1,0,0] neg_hi:[1,0,0]
	v_mov_b32_e32 v140, v158
	v_mov_b32_e32 v141, v134
	v_pk_fma_f32 v[144:145], v[228:229], v[144:145], v[140:141] op_sel_hi:[0,1,1]
	v_mul_f32_e32 v134, 0xbfb8aa3b, v145
	v_exp_f32_e32 v134, v134
	v_mov_b32_e32 v142, v147
	v_pk_fma_f32 v[142:143], v[226:227], v[210:211], v[142:143] op_sel_hi:[0,1,1] neg_lo:[1,0,0] neg_hi:[1,0,0]
	v_add_f32_e32 v134, 1.0, v134
	v_rcp_f32_e32 v134, v134
	s_nop 0
	v_mul_f32_e32 v134, v145, v134
	v_mul_f32_e32 v158, v144, v134
	v_mov_b32_e32 v134, v159
	v_pk_fma_f32 v[142:143], v[228:229], v[142:143], v[134:135] op_sel_hi:[0,1,1]
	v_mul_f32_e32 v144, 0xbfb8aa3b, v143
	v_exp_f32_e32 v144, v144
	v_mov_b32_e32 v145, v120
	v_mov_b32_e32 v120, v125
	v_mov_b32_e32 v125, v122
	v_add_f32_e32 v144, 1.0, v144
	v_rcp_f32_e32 v144, v144
	v_mov_b32_e32 v122, v127
	v_mul_f32_e32 v143, v143, v144
	v_mul_f32_e32 v159, v142, v143
	v_mov_b32_e32 v142, v148
	v_mov_b32_e32 v143, v112
	v_mov_b32_e32 v144, v124
	v_pk_fma_f32 v[146:147], v[226:227], v[142:143], v[144:145] op_sel_hi:[0,1,1] neg_lo:[1,0,0] neg_hi:[1,0,0]
	v_mov_b32_e32 v144, v152
	v_mov_b32_e32 v145, v116
	v_pk_fma_f32 v[146:147], v[228:229], v[146:147], v[144:145] op_sel_hi:[0,1,1]
	v_mul_f32_e32 v112, 0xbfb8aa3b, v147
	v_exp_f32_e32 v112, v112
	v_mov_b32_e32 v116, v153
	v_add_f32_e32 v112, 1.0, v112
	v_rcp_f32_e32 v112, v112
	s_nop 0
	v_mul_f32_e32 v112, v147, v112
	v_mul_f32_e32 v148, v146, v112
	v_mov_b32_e32 v112, v149
	v_pk_fma_f32 v[120:121], v[226:227], v[112:113], v[120:121] op_sel_hi:[0,1,1] neg_lo:[1,0,0] neg_hi:[1,0,0]
	v_pk_fma_f32 v[120:121], v[228:229], v[120:121], v[116:117] op_sel_hi:[0,1,1]
	v_mul_f32_e32 v124, 0xbfb8aa3b, v121
	v_exp_f32_e32 v124, v124
	s_nop 0
	v_add_f32_e32 v124, 1.0, v124
	v_rcp_f32_e32 v124, v124
	s_nop 0
	v_mul_f32_e32 v121, v121, v124
	v_mul_f32_e32 v149, v120, v121
	v_mov_b32_e32 v120, v150
	v_mov_b32_e32 v121, v114
	v_mov_b32_e32 v124, v126
	v_pk_fma_f32 v[146:147], v[226:227], v[120:121], v[124:125] op_sel_hi:[0,1,1] neg_lo:[1,0,0] neg_hi:[1,0,0]
	v_mov_b32_e32 v124, v154
	v_mov_b32_e32 v125, v118
	v_pk_fma_f32 v[146:147], v[228:229], v[146:147], v[124:125] op_sel_hi:[0,1,1]
	v_mul_f32_e32 v114, 0xbfb8aa3b, v147
	v_exp_f32_e32 v114, v114
	v_mov_b32_e32 v118, v155
	v_cvt_pk_bf16_f32 v148, v148, v149
	v_add_f32_e32 v114, 1.0, v114
	v_rcp_f32_e32 v114, v114
	s_nop 0
	v_mul_f32_e32 v114, v147, v114
	v_mul_f32_e32 v150, v146, v114
	v_mov_b32_e32 v114, v151
	v_pk_fma_f32 v[122:123], v[226:227], v[114:115], v[122:123] op_sel_hi:[0,1,1] neg_lo:[1,0,0] neg_hi:[1,0,0]
	v_pk_fma_f32 v[122:123], v[228:229], v[122:123], v[118:119] op_sel_hi:[0,1,1]
	v_mul_f32_e32 v126, 0xbfb8aa3b, v123
	v_exp_f32_e32 v126, v126
	v_cvt_pk_bf16_f32 v146, v223, v229
	v_cvt_pk_bf16_f32 v147, v158, v159
	s_nop 0
	v_add_f32_e32 v126, 1.0, v126
	v_rcp_f32_e32 v126, v126
	s_nop 0
	v_mul_f32_e32 v123, v123, v126
	v_mul_f32_e32 v151, v122, v123
	v_lshlrev_b64 v[122:123], 1, v[230:231]
	v_lshl_add_u64 v[126:127], v[232:233], 0, v[122:123]
	v_cvt_pk_bf16_f32 v149, v150, v151
	global_store_dwordx4 v[126:127], v[146:149], off
	v_lshl_add_u64 v[126:127], s[44:45], 0, v[224:225]
	v_lshlrev_b64 v[126:127], 7, v[126:127]
	v_mov_b32_e32 v146, v108
	v_mov_b32_e32 v147, v104
	v_pk_fma_f32 v[146:147], v[220:221], v[206:207], v[146:147] op_sel_hi:[0,1,1] neg_lo:[1,0,0] neg_hi:[1,0,0]
	v_pk_fma_f32 v[146:147], v[222:223], v[146:147], v[192:193] op_sel_hi:[0,1,1]
	v_mul_f32_e32 v104, 0xbfb8aa3b, v147
	v_exp_f32_e32 v104, v104
	v_lshl_add_u64 v[126:127], s[6:7], 0, v[126:127]
	v_add_f32_e32 v104, 1.0, v104
	v_rcp_f32_e32 v104, v104
	s_nop 0
	v_mul_f32_e32 v104, v147, v104
	v_mul_f32_e32 v108, v146, v104
	v_mov_b32_e32 v104, v109
	v_pk_fma_f32 v[104:105], v[220:221], v[208:209], v[104:105] op_sel_hi:[0,1,1] neg_lo:[1,0,0] neg_hi:[1,0,0]
	v_pk_fma_f32 v[104:105], v[222:223], v[104:105], v[132:133] op_sel_hi:[0,1,1]
	v_mul_f32_e32 v109, 0xbfb8aa3b, v105
	v_exp_f32_e32 v109, v109
	s_nop 0
	v_add_f32_e32 v109, 1.0, v109
	v_rcp_f32_e32 v109, v109
	s_nop 0
	v_mul_f32_e32 v105, v105, v109
	v_mul_f32_e32 v109, v104, v105
	v_mov_b32_e32 v104, v110
	v_mov_b32_e32 v105, v106
	v_pk_fma_f32 v[104:105], v[220:221], v[156:157], v[104:105] op_sel_hi:[0,1,1] neg_lo:[1,0,0] neg_hi:[1,0,0]
	v_pk_fma_f32 v[104:105], v[222:223], v[104:105], v[140:141] op_sel_hi:[0,1,1]
	v_mul_f32_e32 v106, 0xbfb8aa3b, v105
	v_exp_f32_e32 v106, v106
	s_nop 0
	v_add_f32_e32 v106, 1.0, v106
	v_rcp_f32_e32 v106, v106
	s_nop 0
; __device__ __forceinline__ unsigned cvt_pk_bf16(float lo, float hi) { unsigned r; asm("v_cvt_pk_bf16_f32 %0, %1, %2" : "=v"(r) : "v"(lo), "v"(hi)); return r; }
; __device__ __forceinline__ float fast_sigmoid(float v) { return __builtin_amdgcn_rcpf(1.0f + __builtin_amdgcn_exp2f(-1.4426950408889634f * v)); }
; __device__ __forceinline__ f32x4 ln_fix(const f32x4& a, float mu, float rs, const f32x4& cs, const f32x4& cb) { return (a - cs * mu) * rs + cb; }
;     __device__ __forceinline__ void operator()(const f32x4 (&acc)[2][2][4][2], const Unit& u, int wr, int wc, int fr_in, int fq_in) const {
;     ...
;         for (int ai = 0; ai < 2; ++ai)
; #pragma unroll
;             for (int m = 0; m < 4; ++m) { bf16_t* rowp = H + ((size_t)kt * mrows + (row0 + ai * HALF + m * 16)) * 64 + cin;
;                 float h[8];
; #pragma unroll
;                 for (int n = 0; n < 2; ++n) { f32x4 g = acc[ai][0][m][n], uu = acc[ai][1][m][n];
;                     if constexpr (LN) { g = ln_fix(g, rst.mu[ai][m], rst.rs[ai][m], csv[0][n], cbv[0][n]); uu = ln_fix(uu, rst.mu[ai][m], rst.rs[ai][m], csv[1][n], cbv[1][n]); }
; #pragma unroll
;                     for (int j = 0; j < 4; ++j) h[4 * n + j] = g[j] * fast_sigmoid(g[j]) * uu[j]; }
;                 u32x4 w; w.x = cvt_pk_bf16(h[0], h[1]); w.y = cvt_pk_bf16(h[2], h[3]); w.z = cvt_pk_bf16(h[4], h[5]); w.w = cvt_pk_bf16(h[6], h[7]);
;                 *(u32x4*)rowp = w; }
	v_mul_f32_e32 v105, v105, v106
	v_mov_b32_e32 v106, v111
	v_mul_f32_e32 v110, v104, v105
	v_pk_fma_f32 v[104:105], v[220:221], v[210:211], v[106:107] op_sel_hi:[0,1,1] neg_lo:[1,0,0] neg_hi:[1,0,0]
	v_pk_fma_f32 v[104:105], v[222:223], v[104:105], v[134:135] op_sel_hi:[0,1,1]
	v_mul_f32_e32 v106, 0xbfb8aa3b, v105
	v_exp_f32_e32 v106, v106
	s_nop 0
	v_add_f32_e32 v106, 1.0, v106
	v_rcp_f32_e32 v106, v106
	s_nop 0
	v_mul_f32_e32 v105, v105, v106
	v_mul_f32_e32 v106, v104, v105
	v_mov_b32_e32 v104, v100
	v_mov_b32_e32 v105, v96
	v_pk_fma_f32 v[104:105], v[220:221], v[142:143], v[104:105] op_sel_hi:[0,1,1] neg_lo:[1,0,0] neg_hi:[1,0,0]
	v_pk_fma_f32 v[104:105], v[222:223], v[104:105], v[144:145] op_sel_hi:[0,1,1]
	v_mul_f32_e32 v96, 0xbfb8aa3b, v105
	v_exp_f32_e32 v96, v96
	s_nop 0
	v_add_f32_e32 v96, 1.0, v96
	v_rcp_f32_e32 v96, v96
	s_nop 0
	v_mul_f32_e32 v96, v105, v96
	v_mul_f32_e32 v104, v104, v96
	v_mov_b32_e32 v96, v101
	v_pk_fma_f32 v[96:97], v[220:221], v[112:113], v[96:97] op_sel_hi:[0,1,1] neg_lo:[1,0,0] neg_hi:[1,0,0]
	v_pk_fma_f32 v[96:97], v[222:223], v[96:97], v[116:117] op_sel_hi:[0,1,1]
	v_mul_f32_e32 v100, 0xbfb8aa3b, v97
	v_exp_f32_e32 v100, v100
	s_nop 0
	v_add_f32_e32 v100, 1.0, v100
	v_rcp_f32_e32 v100, v100
	s_nop 0
	v_mul_f32_e32 v97, v97, v100
	v_mul_f32_e32 v105, v96, v97
	v_mov_b32_e32 v96, v102
	v_mov_b32_e32 v97, v98
	v_pk_fma_f32 v[96:97], v[220:221], v[120:121], v[96:97] op_sel_hi:[0,1,1] neg_lo:[1,0,0] neg_hi:[1,0,0]
	v_pk_fma_f32 v[96:97], v[222:223], v[96:97], v[124:125] op_sel_hi:[0,1,1]
	v_mul_f32_e32 v98, 0xbfb8aa3b, v97
	v_exp_f32_e32 v98, v98
	v_lshl_add_u64 v[100:101], v[126:127], 0, v[122:123]
	v_add_f32_e32 v98, 1.0, v98
	v_rcp_f32_e32 v98, v98
	s_nop 0
	v_mul_f32_e32 v97, v97, v98
	v_mov_b32_e32 v98, v103
	v_mul_f32_e32 v102, v96, v97
	v_pk_fma_f32 v[96:97], v[220:221], v[114:115], v[98:99] op_sel_hi:[0,1,1] neg_lo:[1,0,0] neg_hi:[1,0,0]
	v_pk_fma_f32 v[96:97], v[222:223], v[96:97], v[118:119] op_sel_hi:[0,1,1]
	v_mul_f32_e32 v98, 0xbfb8aa3b, v97
	v_exp_f32_e32 v98, v98
	s_nop 0
	v_add_f32_e32 v98, 1.0, v98
	v_rcp_f32_e32 v98, v98
	s_nop 0
	v_mul_f32_e32 v97, v97, v98
	v_mul_f32_e32 v99, v96, v97
	v_cvt_pk_bf16_f32 v98, v104, v105
	v_cvt_pk_bf16_f32 v99, v102, v99
	v_cvt_pk_bf16_f32 v96, v108, v109
	v_cvt_pk_bf16_f32 v97, v110, v106
	global_store_dwordx4 v[100:101], v[96:99], off
	s_nop 1
	v_mov_b32_e32 v98, v92
	v_mov_b32_e32 v99, v88
	v_pk_fma_f32 v[98:99], v[214:215], v[206:207], v[98:99] op_sel_hi:[0,1,1] neg_lo:[1,0,0] neg_hi:[1,0,0]
	v_pk_fma_f32 v[98:99], v[216:217], v[98:99], v[192:193] op_sel_hi:[0,1,1]
	v_mul_f32_e32 v88, 0xbfb8aa3b, v99
	v_exp_f32_e32 v88, v88
	v_lshl_add_u64 v[96:97], s[44:45], 0, v[218:219]
	v_lshlrev_b64 v[96:97], 7, v[96:97]
	v_lshl_add_u64 v[96:97], s[6:7], 0, v[96:97]
	v_add_f32_e32 v88, 1.0, v88
	v_rcp_f32_e32 v88, v88
	s_nop 0
	v_mul_f32_e32 v88, v99, v88
	v_mul_f32_e32 v92, v98, v88
	v_mov_b32_e32 v88, v93
	v_pk_fma_f32 v[88:89], v[214:215], v[208:209], v[88:89] op_sel_hi:[0,1,1] neg_lo:[1,0,0] neg_hi:[1,0,0]
	v_pk_fma_f32 v[88:89], v[216:217], v[88:89], v[132:133] op_sel_hi:[0,1,1]
	v_mul_f32_e32 v93, 0xbfb8aa3b, v89
	v_exp_f32_e32 v93, v93
	s_nop 0
	v_add_f32_e32 v93, 1.0, v93
	v_rcp_f32_e32 v93, v93
	s_nop 0
	v_mul_f32_e32 v89, v89, v93
	v_mul_f32_e32 v93, v88, v89
	v_mov_b32_e32 v88, v94
	v_mov_b32_e32 v89, v90
	v_pk_fma_f32 v[88:89], v[214:215], v[156:157], v[88:89] op_sel_hi:[0,1,1] neg_lo:[1,0,0] neg_hi:[1,0,0]
	v_pk_fma_f32 v[88:89], v[216:217], v[88:89], v[140:141] op_sel_hi:[0,1,1]
	v_mul_f32_e32 v90, 0xbfb8aa3b, v89
	v_exp_f32_e32 v90, v90
	s_nop 0
	v_add_f32_e32 v90, 1.0, v90
	v_rcp_f32_e32 v90, v90
	s_nop 0
	v_mul_f32_e32 v89, v89, v90
	v_mov_b32_e32 v90, v95
	v_mul_f32_e32 v94, v88, v89
	v_pk_fma_f32 v[88:89], v[214:215], v[210:211], v[90:91] op_sel_hi:[0,1,1] neg_lo:[1,0,0] neg_hi:[1,0,0]
	v_pk_fma_f32 v[88:89], v[216:217], v[88:89], v[134:135] op_sel_hi:[0,1,1]
	v_mul_f32_e32 v90, 0xbfb8aa3b, v89
	v_exp_f32_e32 v90, v90
	s_nop 0
	v_add_f32_e32 v90, 1.0, v90
	v_rcp_f32_e32 v90, v90
	s_nop 0
	v_mul_f32_e32 v89, v89, v90
	v_mul_f32_e32 v90, v88, v89
	v_mov_b32_e32 v88, v84
	v_mov_b32_e32 v89, v80
	v_pk_fma_f32 v[88:89], v[214:215], v[142:143], v[88:89] op_sel_hi:[0,1,1] neg_lo:[1,0,0] neg_hi:[1,0,0]
	v_pk_fma_f32 v[88:89], v[216:217], v[88:89], v[144:145] op_sel_hi:[0,1,1]
	v_mul_f32_e32 v80, 0xbfb8aa3b, v89
	v_exp_f32_e32 v80, v80
	s_nop 0
	v_add_f32_e32 v80, 1.0, v80
	v_rcp_f32_e32 v80, v80
	s_nop 0
	v_mul_f32_e32 v80, v89, v80
	v_mul_f32_e32 v88, v88, v80
	v_mov_b32_e32 v80, v85
	v_pk_fma_f32 v[80:81], v[214:215], v[112:113], v[80:81] op_sel_hi:[0,1,1] neg_lo:[1,0,0] neg_hi:[1,0,0]
	v_pk_fma_f32 v[80:81], v[216:217], v[80:81], v[116:117] op_sel_hi:[0,1,1]
	v_mul_f32_e32 v84, 0xbfb8aa3b, v81
	v_exp_f32_e32 v84, v84
	s_nop 0
	v_add_f32_e32 v84, 1.0, v84
	v_rcp_f32_e32 v84, v84
	s_nop 0
	v_mul_f32_e32 v81, v81, v84
	v_mul_f32_e32 v89, v80, v81
	v_mov_b32_e32 v80, v86
	v_mov_b32_e32 v81, v82
	v_pk_fma_f32 v[80:81], v[214:215], v[120:121], v[80:81] op_sel_hi:[0,1,1] neg_lo:[1,0,0] neg_hi:[1,0,0]
	v_pk_fma_f32 v[80:81], v[216:217], v[80:81], v[124:125] op_sel_hi:[0,1,1]
	v_mul_f32_e32 v82, 0xbfb8aa3b, v81
	v_exp_f32_e32 v82, v82
	v_lshl_add_u64 v[84:85], v[96:97], 0, v[122:123]
	v_add_f32_e32 v82, 1.0, v82
	v_rcp_f32_e32 v82, v82
	s_nop 0
	v_mul_f32_e32 v81, v81, v82
	v_mov_b32_e32 v82, v87
	v_mul_f32_e32 v86, v80, v81
	v_pk_fma_f32 v[80:81], v[214:215], v[114:115], v[82:83] op_sel_hi:[0,1,1] neg_lo:[1,0,0] neg_hi:[1,0,0]
	v_pk_fma_f32 v[80:81], v[216:217], v[80:81], v[118:119] op_sel_hi:[0,1,1]
	v_mul_f32_e32 v82, 0xbfb8aa3b, v81
	v_exp_f32_e32 v82, v82
; __device__ __forceinline__ unsigned cvt_pk_bf16(float lo, float hi) { unsigned r; asm("v_cvt_pk_bf16_f32 %0, %1, %2" : "=v"(r) : "v"(lo), "v"(hi)); return r; }
; __device__ __forceinline__ float fast_sigmoid(float v) { return __builtin_amdgcn_rcpf(1.0f + __builtin_amdgcn_exp2f(-1.4426950408889634f * v)); }
; __device__ __forceinline__ f32x4 ln_fix(const f32x4& a, float mu, float rs, const f32x4& cs, const f32x4& cb) { return (a - cs * mu) * rs + cb; }
;     __device__ __forceinline__ void operator()(const f32x4 (&acc)[2][2][4][2], const Unit& u, int wr, int wc, int fr_in, int fq_in) const {
;     ...
;         for (int ai = 0; ai < 2; ++ai)
; #pragma unroll
;             for (int m = 0; m < 4; ++m) { bf16_t* rowp = H + ((size_t)kt * mrows + (row0 + ai * HALF + m * 16)) * 64 + cin;
;                 float h[8];
; #pragma unroll
;                 for (int n = 0; n < 2; ++n) { f32x4 g = acc[ai][0][m][n], uu = acc[ai][1][m][n];
;                     if constexpr (LN) { g = ln_fix(g, rst.mu[ai][m], rst.rs[ai][m], csv[0][n], cbv[0][n]); uu = ln_fix(uu, rst.mu[ai][m], rst.rs[ai][m], csv[1][n], cbv[1][n]); }
; #pragma unroll
;                     for (int j = 0; j < 4; ++j) h[4 * n + j] = g[j] * fast_sigmoid(g[j]) * uu[j]; }
;                 u32x4 w; w.x = cvt_pk_bf16(h[0], h[1]); w.y = cvt_pk_bf16(h[2], h[3]); w.z = cvt_pk_bf16(h[4], h[5]); w.w = cvt_pk_bf16(h[6], h[7]);
;                 *(u32x4*)rowp = w; }
	s_nop 0
	v_add_f32_e32 v82, 1.0, v82
	v_rcp_f32_e32 v82, v82
	s_nop 0
	v_mul_f32_e32 v81, v81, v82
	v_mul_f32_e32 v83, v80, v81
	v_cvt_pk_bf16_f32 v82, v88, v89
	v_cvt_pk_bf16_f32 v83, v86, v83
	v_cvt_pk_bf16_f32 v80, v92, v93
	v_cvt_pk_bf16_f32 v81, v94, v90
	global_store_dwordx4 v[84:85], v[80:83], off
	s_nop 1
	v_mov_b32_e32 v82, v76
	v_mov_b32_e32 v83, v72
	v_pk_fma_f32 v[82:83], v[200:201], v[206:207], v[82:83] op_sel_hi:[0,1,1] neg_lo:[1,0,0] neg_hi:[1,0,0]
	v_pk_fma_f32 v[82:83], v[202:203], v[82:83], v[192:193] op_sel_hi:[0,1,1]
	v_mul_f32_e32 v72, 0xbfb8aa3b, v83
	v_exp_f32_e32 v72, v72
	v_lshl_add_u64 v[80:81], s[44:45], 0, v[212:213]
	v_lshlrev_b64 v[80:81], 7, v[80:81]
	v_lshl_add_u64 v[80:81], s[6:7], 0, v[80:81]
	v_add_f32_e32 v72, 1.0, v72
	v_rcp_f32_e32 v72, v72
	s_nop 0
	v_mul_f32_e32 v72, v83, v72
	v_mul_f32_e32 v76, v82, v72
	v_mov_b32_e32 v72, v77
	v_pk_fma_f32 v[72:73], v[200:201], v[208:209], v[72:73] op_sel_hi:[0,1,1] neg_lo:[1,0,0] neg_hi:[1,0,0]
	v_pk_fma_f32 v[72:73], v[202:203], v[72:73], v[132:133] op_sel_hi:[0,1,1]
	v_mul_f32_e32 v77, 0xbfb8aa3b, v73
	v_exp_f32_e32 v77, v77
	s_nop 0
	v_add_f32_e32 v77, 1.0, v77
	v_rcp_f32_e32 v77, v77
	s_nop 0
	v_mul_f32_e32 v73, v73, v77
	v_mul_f32_e32 v77, v72, v73
	v_mov_b32_e32 v72, v78
	v_mov_b32_e32 v73, v74
	v_pk_fma_f32 v[72:73], v[200:201], v[156:157], v[72:73] op_sel_hi:[0,1,1] neg_lo:[1,0,0] neg_hi:[1,0,0]
	v_pk_fma_f32 v[72:73], v[202:203], v[72:73], v[140:141] op_sel_hi:[0,1,1]
	v_mul_f32_e32 v74, 0xbfb8aa3b, v73
	v_exp_f32_e32 v74, v74
	s_nop 0
	v_add_f32_e32 v74, 1.0, v74
	v_rcp_f32_e32 v74, v74
	s_nop 0
	v_mul_f32_e32 v73, v73, v74
	v_mov_b32_e32 v74, v79
	v_mul_f32_e32 v78, v72, v73
	v_pk_fma_f32 v[72:73], v[200:201], v[210:211], v[74:75] op_sel_hi:[0,1,1] neg_lo:[1,0,0] neg_hi:[1,0,0]
	v_pk_fma_f32 v[72:73], v[202:203], v[72:73], v[134:135] op_sel_hi:[0,1,1]
	v_mul_f32_e32 v74, 0xbfb8aa3b, v73
	v_exp_f32_e32 v74, v74
	s_nop 0
	v_add_f32_e32 v74, 1.0, v74
	v_rcp_f32_e32 v74, v74
	s_nop 0
	v_mul_f32_e32 v73, v73, v74
	v_mul_f32_e32 v74, v72, v73
	v_mov_b32_e32 v72, v68
	v_mov_b32_e32 v73, v64
	v_pk_fma_f32 v[72:73], v[200:201], v[142:143], v[72:73] op_sel_hi:[0,1,1] neg_lo:[1,0,0] neg_hi:[1,0,0]
	v_pk_fma_f32 v[72:73], v[202:203], v[72:73], v[144:145] op_sel_hi:[0,1,1]
	v_mul_f32_e32 v64, 0xbfb8aa3b, v73
	v_exp_f32_e32 v64, v64
	s_nop 0
	v_add_f32_e32 v64, 1.0, v64
	v_rcp_f32_e32 v64, v64
	s_nop 0
	v_mul_f32_e32 v64, v73, v64
	v_mul_f32_e32 v72, v72, v64
	v_mov_b32_e32 v64, v69
	v_pk_fma_f32 v[64:65], v[200:201], v[112:113], v[64:65] op_sel_hi:[0,1,1] neg_lo:[1,0,0] neg_hi:[1,0,0]
	v_pk_fma_f32 v[64:65], v[202:203], v[64:65], v[116:117] op_sel_hi:[0,1,1]
	v_mul_f32_e32 v68, 0xbfb8aa3b, v65
	v_exp_f32_e32 v68, v68
	s_nop 0
	v_add_f32_e32 v68, 1.0, v68
	v_rcp_f32_e32 v68, v68
	s_nop 0
	v_mul_f32_e32 v65, v65, v68
	v_mul_f32_e32 v73, v64, v65
	v_mov_b32_e32 v64, v70
	v_mov_b32_e32 v65, v66
	v_pk_fma_f32 v[64:65], v[200:201], v[120:121], v[64:65] op_sel_hi:[0,1,1] neg_lo:[1,0,0] neg_hi:[1,0,0]
	v_pk_fma_f32 v[64:65], v[202:203], v[64:65], v[124:125] op_sel_hi:[0,1,1]
	v_mul_f32_e32 v66, 0xbfb8aa3b, v65
	v_exp_f32_e32 v66, v66
	v_lshl_add_u64 v[68:69], v[80:81], 0, v[122:123]
	v_add_f32_e32 v66, 1.0, v66
	v_rcp_f32_e32 v66, v66
	s_nop 0
	v_mul_f32_e32 v65, v65, v66
	v_mov_b32_e32 v66, v71
	v_mul_f32_e32 v70, v64, v65
	v_pk_fma_f32 v[64:65], v[200:201], v[114:115], v[66:67] op_sel_hi:[0,1,1] neg_lo:[1,0,0] neg_hi:[1,0,0]
	v_pk_fma_f32 v[64:65], v[202:203], v[64:65], v[118:119] op_sel_hi:[0,1,1]
	v_mul_f32_e32 v66, 0xbfb8aa3b, v65
	v_exp_f32_e32 v66, v66
	s_nop 0
	v_add_f32_e32 v66, 1.0, v66
	v_rcp_f32_e32 v66, v66
	s_nop 0
	v_mul_f32_e32 v65, v65, v66
	v_mul_f32_e32 v67, v64, v65
	v_cvt_pk_bf16_f32 v66, v72, v73
	v_cvt_pk_bf16_f32 v67, v70, v67
	v_cvt_pk_bf16_f32 v64, v76, v77
	v_cvt_pk_bf16_f32 v65, v78, v74
	global_store_dwordx4 v[68:69], v[64:67], off
	s_nop 1
	v_mov_b32_e32 v66, v60
	v_mov_b32_e32 v67, v56
	v_pk_fma_f32 v[66:67], v[194:195], v[206:207], v[66:67] op_sel_hi:[0,1,1] neg_lo:[1,0,0] neg_hi:[1,0,0]
	v_pk_fma_f32 v[66:67], v[198:199], v[66:67], v[192:193] op_sel_hi:[0,1,1]
	v_mul_f32_e32 v56, 0xbfb8aa3b, v67
	v_exp_f32_e32 v56, v56
	v_lshl_add_u64 v[64:65], s[44:45], 0, v[204:205]
	v_lshlrev_b64 v[64:65], 7, v[64:65]
	v_lshl_add_u64 v[64:65], s[6:7], 0, v[64:65]
	v_add_f32_e32 v56, 1.0, v56
	v_rcp_f32_e32 v56, v56
	s_nop 0
	v_mul_f32_e32 v56, v67, v56
	v_mul_f32_e32 v60, v66, v56
	v_mov_b32_e32 v56, v61
	v_pk_fma_f32 v[56:57], v[194:195], v[208:209], v[56:57] op_sel_hi:[0,1,1] neg_lo:[1,0,0] neg_hi:[1,0,0]
	v_pk_fma_f32 v[56:57], v[198:199], v[56:57], v[132:133] op_sel_hi:[0,1,1]
	v_mul_f32_e32 v61, 0xbfb8aa3b, v57
	v_exp_f32_e32 v61, v61
	s_nop 0
	v_add_f32_e32 v61, 1.0, v61
	v_rcp_f32_e32 v61, v61
	s_nop 0
	v_mul_f32_e32 v57, v57, v61
	v_mul_f32_e32 v61, v56, v57
	v_mov_b32_e32 v56, v62
	v_mov_b32_e32 v57, v58
	v_pk_fma_f32 v[56:57], v[194:195], v[156:157], v[56:57] op_sel_hi:[0,1,1] neg_lo:[1,0,0] neg_hi:[1,0,0]
	v_pk_fma_f32 v[56:57], v[198:199], v[56:57], v[140:141] op_sel_hi:[0,1,1]
	v_mul_f32_e32 v58, 0xbfb8aa3b, v57
	v_exp_f32_e32 v58, v58
	s_nop 0
	v_add_f32_e32 v58, 1.0, v58
	v_rcp_f32_e32 v58, v58
	s_nop 0
	v_mul_f32_e32 v57, v57, v58
	v_mov_b32_e32 v58, v63
	v_mul_f32_e32 v62, v56, v57
	v_pk_fma_f32 v[56:57], v[194:195], v[210:211], v[58:59] op_sel_hi:[0,1,1] neg_lo:[1,0,0] neg_hi:[1,0,0]
	v_pk_fma_f32 v[56:57], v[198:199], v[56:57], v[134:135] op_sel_hi:[0,1,1]
	v_mul_f32_e32 v58, 0xbfb8aa3b, v57
	v_exp_f32_e32 v58, v58
	s_nop 0
	v_add_f32_e32 v58, 1.0, v58
	v_rcp_f32_e32 v58, v58
	s_nop 0
	v_mul_f32_e32 v57, v57, v58
	v_mul_f32_e32 v58, v56, v57
; __device__ __forceinline__ unsigned cvt_pk_bf16(float lo, float hi) { unsigned r; asm("v_cvt_pk_bf16_f32 %0, %1, %2" : "=v"(r) : "v"(lo), "v"(hi)); return r; }
; __device__ __forceinline__ float fast_sigmoid(float v) { return __builtin_amdgcn_rcpf(1.0f + __builtin_amdgcn_exp2f(-1.4426950408889634f * v)); }
; __device__ __forceinline__ f32x4 ln_fix(const f32x4& a, float mu, float rs, const f32x4& cs, const f32x4& cb) { return (a - cs * mu) * rs + cb; }
;     __device__ __forceinline__ void operator()(const f32x4 (&acc)[2][2][4][2], const Unit& u, int wr, int wc, int fr_in, int fq_in) const {
;     ...
;         for (int ai = 0; ai < 2; ++ai)
; #pragma unroll
;             for (int m = 0; m < 4; ++m) { bf16_t* rowp = H + ((size_t)kt * mrows + (row0 + ai * HALF + m * 16)) * 64 + cin;
;                 float h[8];
; #pragma unroll
;                 for (int n = 0; n < 2; ++n) { f32x4 g = acc[ai][0][m][n], uu = acc[ai][1][m][n];
;                     if constexpr (LN) { g = ln_fix(g, rst.mu[ai][m], rst.rs[ai][m], csv[0][n], cbv[0][n]); uu = ln_fix(uu, rst.mu[ai][m], rst.rs[ai][m], csv[1][n], cbv[1][n]); }
; #pragma unroll
;                     for (int j = 0; j < 4; ++j) h[4 * n + j] = g[j] * fast_sigmoid(g[j]) * uu[j]; }
;                 u32x4 w; w.x = cvt_pk_bf16(h[0], h[1]); w.y = cvt_pk_bf16(h[2], h[3]); w.z = cvt_pk_bf16(h[4], h[5]); w.w = cvt_pk_bf16(h[6], h[7]);
;                 *(u32x4*)rowp = w; }
	v_mov_b32_e32 v56, v52
	v_mov_b32_e32 v57, v48
	v_pk_fma_f32 v[56:57], v[194:195], v[142:143], v[56:57] op_sel_hi:[0,1,1] neg_lo:[1,0,0] neg_hi:[1,0,0]
	v_pk_fma_f32 v[56:57], v[198:199], v[56:57], v[144:145] op_sel_hi:[0,1,1]
	v_mul_f32_e32 v48, 0xbfb8aa3b, v57
	v_exp_f32_e32 v48, v48
	s_nop 0
	v_add_f32_e32 v48, 1.0, v48
	v_rcp_f32_e32 v48, v48
	s_nop 0
	v_mul_f32_e32 v48, v57, v48
	v_mul_f32_e32 v56, v56, v48
	v_mov_b32_e32 v48, v53
	v_pk_fma_f32 v[48:49], v[194:195], v[112:113], v[48:49] op_sel_hi:[0,1,1] neg_lo:[1,0,0] neg_hi:[1,0,0]
	v_pk_fma_f32 v[48:49], v[198:199], v[48:49], v[116:117] op_sel_hi:[0,1,1]
	v_mul_f32_e32 v52, 0xbfb8aa3b, v49
	v_exp_f32_e32 v52, v52
	s_nop 0
	v_add_f32_e32 v52, 1.0, v52
	v_rcp_f32_e32 v52, v52
	s_nop 0
	v_mul_f32_e32 v49, v49, v52
	v_mul_f32_e32 v57, v48, v49
	v_mov_b32_e32 v48, v54
	v_mov_b32_e32 v49, v50
	v_pk_fma_f32 v[48:49], v[194:195], v[120:121], v[48:49] op_sel_hi:[0,1,1] neg_lo:[1,0,0] neg_hi:[1,0,0]
	v_pk_fma_f32 v[48:49], v[198:199], v[48:49], v[124:125] op_sel_hi:[0,1,1]
	v_mul_f32_e32 v50, 0xbfb8aa3b, v49
	v_exp_f32_e32 v50, v50
	v_lshl_add_u64 v[52:53], v[64:65], 0, v[122:123]
	v_add_f32_e32 v50, 1.0, v50
	v_rcp_f32_e32 v50, v50
	s_nop 0
	v_mul_f32_e32 v49, v49, v50
	v_mov_b32_e32 v50, v55
	v_mul_f32_e32 v54, v48, v49
	v_pk_fma_f32 v[48:49], v[194:195], v[114:115], v[50:51] op_sel_hi:[0,1,1] neg_lo:[1,0,0] neg_hi:[1,0,0]
	v_pk_fma_f32 v[48:49], v[198:199], v[48:49], v[118:119] op_sel_hi:[0,1,1]
	v_mul_f32_e32 v50, 0xbfb8aa3b, v49
	v_exp_f32_e32 v50, v50
	s_nop 0
	v_add_f32_e32 v50, 1.0, v50
	v_rcp_f32_e32 v50, v50
	s_nop 0
	v_mul_f32_e32 v49, v49, v50
	v_mul_f32_e32 v51, v48, v49
	v_cvt_pk_bf16_f32 v50, v56, v57
	v_cvt_pk_bf16_f32 v51, v54, v51
	v_cvt_pk_bf16_f32 v48, v60, v61
	v_cvt_pk_bf16_f32 v49, v62, v58
	global_store_dwordx4 v[52:53], v[48:51], off
	s_nop 1
	v_mov_b32_e32 v50, v44
	v_mov_b32_e32 v51, v40
	v_pk_fma_f32 v[50:51], v[186:187], v[206:207], v[50:51] op_sel_hi:[0,1,1] neg_lo:[1,0,0] neg_hi:[1,0,0]
	v_pk_fma_f32 v[50:51], v[190:191], v[50:51], v[192:193] op_sel_hi:[0,1,1]
	v_mul_f32_e32 v40, 0xbfb8aa3b, v51
	v_exp_f32_e32 v40, v40
	v_lshl_add_u64 v[48:49], s[44:45], 0, v[196:197]
	v_lshlrev_b64 v[48:49], 7, v[48:49]
	v_lshl_add_u64 v[48:49], s[6:7], 0, v[48:49]
	v_add_f32_e32 v40, 1.0, v40
	v_rcp_f32_e32 v40, v40
	s_nop 0
	v_mul_f32_e32 v40, v51, v40
	v_mul_f32_e32 v44, v50, v40
	v_mov_b32_e32 v40, v45
	v_pk_fma_f32 v[40:41], v[186:187], v[208:209], v[40:41] op_sel_hi:[0,1,1] neg_lo:[1,0,0] neg_hi:[1,0,0]
	v_pk_fma_f32 v[40:41], v[190:191], v[40:41], v[132:133] op_sel_hi:[0,1,1]
	v_mul_f32_e32 v45, 0xbfb8aa3b, v41
	v_exp_f32_e32 v45, v45
	s_nop 0
	v_add_f32_e32 v45, 1.0, v45
	v_rcp_f32_e32 v45, v45
	s_nop 0
	v_mul_f32_e32 v41, v41, v45
	v_mul_f32_e32 v45, v40, v41
	v_mov_b32_e32 v40, v46
	v_mov_b32_e32 v41, v42
	v_pk_fma_f32 v[40:41], v[186:187], v[156:157], v[40:41] op_sel_hi:[0,1,1] neg_lo:[1,0,0] neg_hi:[1,0,0]
	v_pk_fma_f32 v[40:41], v[190:191], v[40:41], v[140:141] op_sel_hi:[0,1,1]
	v_mul_f32_e32 v42, 0xbfb8aa3b, v41
	v_exp_f32_e32 v42, v42
	s_nop 0
	v_add_f32_e32 v42, 1.0, v42
	v_rcp_f32_e32 v42, v42
	s_nop 0
	v_mul_f32_e32 v41, v41, v42
	v_mov_b32_e32 v42, v47
	v_mul_f32_e32 v46, v40, v41
	v_pk_fma_f32 v[40:41], v[186:187], v[210:211], v[42:43] op_sel_hi:[0,1,1] neg_lo:[1,0,0] neg_hi:[1,0,0]
	v_pk_fma_f32 v[40:41], v[190:191], v[40:41], v[134:135] op_sel_hi:[0,1,1]
	v_mul_f32_e32 v42, 0xbfb8aa3b, v41
	v_exp_f32_e32 v42, v42
	s_nop 0
	v_add_f32_e32 v42, 1.0, v42
	v_rcp_f32_e32 v42, v42
	s_nop 0
	v_mul_f32_e32 v41, v41, v42
	v_mul_f32_e32 v42, v40, v41
	v_mov_b32_e32 v40, v36
	v_mov_b32_e32 v41, v32
	v_pk_fma_f32 v[40:41], v[186:187], v[142:143], v[40:41] op_sel_hi:[0,1,1] neg_lo:[1,0,0] neg_hi:[1,0,0]
	v_pk_fma_f32 v[40:41], v[190:191], v[40:41], v[144:145] op_sel_hi:[0,1,1]
	v_mul_f32_e32 v32, 0xbfb8aa3b, v41
	v_exp_f32_e32 v32, v32
	s_nop 0
	v_add_f32_e32 v32, 1.0, v32
	v_rcp_f32_e32 v32, v32
	s_nop 0
	v_mul_f32_e32 v32, v41, v32
	v_mul_f32_e32 v40, v40, v32
	v_mov_b32_e32 v32, v37
	v_pk_fma_f32 v[32:33], v[186:187], v[112:113], v[32:33] op_sel_hi:[0,1,1] neg_lo:[1,0,0] neg_hi:[1,0,0]
	v_pk_fma_f32 v[32:33], v[190:191], v[32:33], v[116:117] op_sel_hi:[0,1,1]
	v_mul_f32_e32 v36, 0xbfb8aa3b, v33
	v_exp_f32_e32 v36, v36
	s_nop 0
	v_add_f32_e32 v36, 1.0, v36
	v_rcp_f32_e32 v36, v36
	s_nop 0
	v_mul_f32_e32 v33, v33, v36
	v_mul_f32_e32 v41, v32, v33
	v_mov_b32_e32 v32, v38
	v_mov_b32_e32 v33, v34
	v_pk_fma_f32 v[32:33], v[186:187], v[120:121], v[32:33] op_sel_hi:[0,1,1] neg_lo:[1,0,0] neg_hi:[1,0,0]
	v_pk_fma_f32 v[32:33], v[190:191], v[32:33], v[124:125] op_sel_hi:[0,1,1]
	v_mul_f32_e32 v34, 0xbfb8aa3b, v33
	v_exp_f32_e32 v34, v34
	v_lshl_add_u64 v[36:37], v[48:49], 0, v[122:123]
	v_add_f32_e32 v34, 1.0, v34
	v_rcp_f32_e32 v34, v34
	s_nop 0
	v_mul_f32_e32 v33, v33, v34
	v_mov_b32_e32 v34, v39
	v_mul_f32_e32 v38, v32, v33
	v_pk_fma_f32 v[32:33], v[186:187], v[114:115], v[34:35] op_sel_hi:[0,1,1] neg_lo:[1,0,0] neg_hi:[1,0,0]
	v_pk_fma_f32 v[32:33], v[190:191], v[32:33], v[118:119] op_sel_hi:[0,1,1]
	v_mul_f32_e32 v34, 0xbfb8aa3b, v33
	v_exp_f32_e32 v34, v34
	s_nop 0
	v_add_f32_e32 v34, 1.0, v34
	v_rcp_f32_e32 v34, v34
	s_nop 0
	v_mul_f32_e32 v33, v33, v34
	v_mul_f32_e32 v35, v32, v33
	v_cvt_pk_bf16_f32 v34, v40, v41
	v_cvt_pk_bf16_f32 v35, v38, v35
	v_cvt_pk_bf16_f32 v32, v44, v45
	v_cvt_pk_bf16_f32 v33, v46, v42
	global_store_dwordx4 v[36:37], v[32:35], off
	s_nop 1
	v_mov_b32_e32 v34, v28
	v_mov_b32_e32 v35, v24
	v_pk_fma_f32 v[34:35], v[180:181], v[206:207], v[34:35] op_sel_hi:[0,1,1] neg_lo:[1,0,0] neg_hi:[1,0,0]
	v_pk_fma_f32 v[34:35], v[184:185], v[34:35], v[192:193] op_sel_hi:[0,1,1]
; __device__ __forceinline__ unsigned cvt_pk_bf16(float lo, float hi) { unsigned r; asm("v_cvt_pk_bf16_f32 %0, %1, %2" : "=v"(r) : "v"(lo), "v"(hi)); return r; }
; __device__ __forceinline__ float fast_sigmoid(float v) { return __builtin_amdgcn_rcpf(1.0f + __builtin_amdgcn_exp2f(-1.4426950408889634f * v)); }
; __device__ __forceinline__ f32x4 ln_fix(const f32x4& a, float mu, float rs, const f32x4& cs, const f32x4& cb) { return (a - cs * mu) * rs + cb; }
;     __device__ __forceinline__ void operator()(const f32x4 (&acc)[2][2][4][2], const Unit& u, int wr, int wc, int fr_in, int fq_in) const {
;     ...
;         for (int ai = 0; ai < 2; ++ai)
; #pragma unroll
;             for (int m = 0; m < 4; ++m) { bf16_t* rowp = H + ((size_t)kt * mrows + (row0 + ai * HALF + m * 16)) * 64 + cin;
;                 float h[8];
; #pragma unroll
;                 for (int n = 0; n < 2; ++n) { f32x4 g = acc[ai][0][m][n], uu = acc[ai][1][m][n];
;                     if constexpr (LN) { g = ln_fix(g, rst.mu[ai][m], rst.rs[ai][m], csv[0][n], cbv[0][n]); uu = ln_fix(uu, rst.mu[ai][m], rst.rs[ai][m], csv[1][n], cbv[1][n]); }
; #pragma unroll
;                     for (int j = 0; j < 4; ++j) h[4 * n + j] = g[j] * fast_sigmoid(g[j]) * uu[j]; }
;                 u32x4 w; w.x = cvt_pk_bf16(h[0], h[1]); w.y = cvt_pk_bf16(h[2], h[3]); w.z = cvt_pk_bf16(h[4], h[5]); w.w = cvt_pk_bf16(h[6], h[7]);
;                 *(u32x4*)rowp = w; }
	v_mul_f32_e32 v24, 0xbfb8aa3b, v35
	v_exp_f32_e32 v24, v24
	v_lshl_add_u64 v[32:33], s[44:45], 0, v[188:189]
	v_lshlrev_b64 v[32:33], 7, v[32:33]
	v_lshl_add_u64 v[32:33], s[6:7], 0, v[32:33]
	v_add_f32_e32 v24, 1.0, v24
	v_rcp_f32_e32 v24, v24
	s_nop 0
	v_mul_f32_e32 v24, v35, v24
	v_mul_f32_e32 v28, v34, v24
	v_mov_b32_e32 v24, v29
	v_pk_fma_f32 v[24:25], v[180:181], v[208:209], v[24:25] op_sel_hi:[0,1,1] neg_lo:[1,0,0] neg_hi:[1,0,0]
	v_pk_fma_f32 v[24:25], v[184:185], v[24:25], v[132:133] op_sel_hi:[0,1,1]
	v_mul_f32_e32 v29, 0xbfb8aa3b, v25
	v_exp_f32_e32 v29, v29
	s_nop 0
	v_add_f32_e32 v29, 1.0, v29
	v_rcp_f32_e32 v29, v29
	s_nop 0
	v_mul_f32_e32 v25, v25, v29
	v_mul_f32_e32 v29, v24, v25
	v_mov_b32_e32 v24, v30
	v_mov_b32_e32 v25, v26
	v_pk_fma_f32 v[24:25], v[180:181], v[156:157], v[24:25] op_sel_hi:[0,1,1] neg_lo:[1,0,0] neg_hi:[1,0,0]
	v_pk_fma_f32 v[24:25], v[184:185], v[24:25], v[140:141] op_sel_hi:[0,1,1]
	v_mul_f32_e32 v26, 0xbfb8aa3b, v25
	v_exp_f32_e32 v26, v26
	s_nop 0
	v_add_f32_e32 v26, 1.0, v26
	v_rcp_f32_e32 v26, v26
	s_nop 0
	v_mul_f32_e32 v25, v25, v26
	v_mov_b32_e32 v26, v31
	v_mul_f32_e32 v30, v24, v25
	v_pk_fma_f32 v[24:25], v[180:181], v[210:211], v[26:27] op_sel_hi:[0,1,1] neg_lo:[1,0,0] neg_hi:[1,0,0]
	v_pk_fma_f32 v[24:25], v[184:185], v[24:25], v[134:135] op_sel_hi:[0,1,1]
	v_mul_f32_e32 v26, 0xbfb8aa3b, v25
	v_exp_f32_e32 v26, v26
	s_nop 0
	v_add_f32_e32 v26, 1.0, v26
	v_rcp_f32_e32 v26, v26
	s_nop 0
	v_mul_f32_e32 v25, v25, v26
	v_mul_f32_e32 v26, v24, v25
	v_mov_b32_e32 v24, v20
	v_mov_b32_e32 v25, v16
	v_pk_fma_f32 v[24:25], v[180:181], v[142:143], v[24:25] op_sel_hi:[0,1,1] neg_lo:[1,0,0] neg_hi:[1,0,0]
	v_pk_fma_f32 v[24:25], v[184:185], v[24:25], v[144:145] op_sel_hi:[0,1,1]
	v_mul_f32_e32 v16, 0xbfb8aa3b, v25
	v_exp_f32_e32 v16, v16
	s_nop 0
	v_add_f32_e32 v16, 1.0, v16
	v_rcp_f32_e32 v16, v16
	s_nop 0
	v_mul_f32_e32 v16, v25, v16
	v_mul_f32_e32 v24, v24, v16
	v_mov_b32_e32 v16, v21
	v_pk_fma_f32 v[16:17], v[180:181], v[112:113], v[16:17] op_sel_hi:[0,1,1] neg_lo:[1,0,0] neg_hi:[1,0,0]
	v_pk_fma_f32 v[16:17], v[184:185], v[16:17], v[116:117] op_sel_hi:[0,1,1]
	v_mul_f32_e32 v20, 0xbfb8aa3b, v17
	v_exp_f32_e32 v20, v20
	s_nop 0
	v_add_f32_e32 v20, 1.0, v20
	v_rcp_f32_e32 v20, v20
	s_nop 0
	v_mul_f32_e32 v17, v17, v20
	v_mul_f32_e32 v25, v16, v17
	v_mov_b32_e32 v16, v22
	v_mov_b32_e32 v17, v18
	v_pk_fma_f32 v[16:17], v[180:181], v[120:121], v[16:17] op_sel_hi:[0,1,1] neg_lo:[1,0,0] neg_hi:[1,0,0]
	v_pk_fma_f32 v[16:17], v[184:185], v[16:17], v[124:125] op_sel_hi:[0,1,1]
	v_mul_f32_e32 v18, 0xbfb8aa3b, v17
	v_exp_f32_e32 v18, v18
	v_lshl_add_u64 v[20:21], v[32:33], 0, v[122:123]
	v_add_f32_e32 v18, 1.0, v18
	v_rcp_f32_e32 v18, v18
	s_nop 0
	v_mul_f32_e32 v17, v17, v18
	v_mov_b32_e32 v18, v23
	v_mul_f32_e32 v22, v16, v17
	v_pk_fma_f32 v[16:17], v[180:181], v[114:115], v[18:19] op_sel_hi:[0,1,1] neg_lo:[1,0,0] neg_hi:[1,0,0]
	v_pk_fma_f32 v[16:17], v[184:185], v[16:17], v[118:119] op_sel_hi:[0,1,1]
	v_mul_f32_e32 v18, 0xbfb8aa3b, v17
	v_exp_f32_e32 v18, v18
	v_mov_b32_e32 v23, v8
	v_add_f32_e32 v18, 1.0, v18
	v_rcp_f32_e32 v18, v18
	s_nop 0
	v_mul_f32_e32 v17, v17, v18
	v_mul_f32_e32 v19, v16, v17
	v_cvt_pk_bf16_f32 v18, v24, v25
	v_cvt_pk_bf16_f32 v19, v22, v19
	v_cvt_pk_bf16_f32 v16, v28, v29
	v_cvt_pk_bf16_f32 v17, v30, v26
	global_store_dwordx4 v[20:21], v[16:19], off
	v_mov_b32_e32 v20, v136
	v_mov_b32_e32 v21, v176
	v_mov_b32_e32 v18, v176
	v_mov_b32_e32 v19, v128
	v_mov_b32_e32 v22, v12
	v_pk_fma_f32 v[18:19], v[18:19], v[20:21], v[22:23] neg_lo:[1,0,0] neg_hi:[1,0,0]
	v_mov_b32_e32 v128, v176
; __device__ __forceinline__ unsigned cvt_pk_bf16(float lo, float hi) { unsigned r; asm("v_cvt_pk_bf16_f32 %0, %1, %2" : "=v"(r) : "v"(lo), "v"(hi)); return r; }
; __device__ __forceinline__ float fast_sigmoid(float v) { return __builtin_amdgcn_rcpf(1.0f + __builtin_amdgcn_exp2f(-1.4426950408889634f * v)); }
; __device__ __forceinline__ f32x4 ln_fix(const f32x4& a, float mu, float rs, const f32x4& cs, const f32x4& cb) { return (a - cs * mu) * rs + cb; }
; #define PG8_BAR __builtin_amdgcn_s_barrier()
;     __device__ __forceinline__ void operator()(const f32x4 (&acc)[2][2][4][2], const Unit& u, int wr, int wc, int fr_in, int fq_in) const {
;     ...
;         for (int ai = 0; ai < 2; ++ai)
; #pragma unroll
;             for (int m = 0; m < 4; ++m) { bf16_t* rowp = H + ((size_t)kt * mrows + (row0 + ai * HALF + m * 16)) * 64 + cin;
;                 float h[8];
; #pragma unroll
;                 for (int n = 0; n < 2; ++n) { f32x4 g = acc[ai][0][m][n], uu = acc[ai][1][m][n];
;                     if constexpr (LN) { g = ln_fix(g, rst.mu[ai][m], rst.rs[ai][m], csv[0][n], cbv[0][n]); uu = ln_fix(uu, rst.mu[ai][m], rst.rs[ai][m], csv[1][n], cbv[1][n]); }
; #pragma unroll
;                     for (int j = 0; j < 4; ++j) h[4 * n + j] = g[j] * fast_sigmoid(g[j]) * uu[j]; }
;                 u32x4 w; w.x = cvt_pk_bf16(h[0], h[1]); w.y = cvt_pk_bf16(h[2], h[3]); w.z = cvt_pk_bf16(h[4], h[5]); w.w = cvt_pk_bf16(h[6], h[7]);
;                 *(u32x4*)rowp = w; }
; template <class Epi, class Sched, bool ALIGN_EPI = false, bool SP2 = false>
; __device__ __forceinline__ void gemm_phase(PG8_LAS unsigned char* lds, const Gemm g, const Sched& S, const Epi& E) {
;     ...
;         if constexpr (ALIGN_EPI) { if (wr == 0) PG8_BAR; }
;         if constexpr (!Epi::AFTER_DRAIN) { E(acc, cur, wr, wc, fr, fq); S.done(cur); }
;         if (!has_next) break;
; #pragma unroll
;         for (int a = 0; a < 2; ++a)
; #pragma unroll
;             for (int b = 0; b < 2; ++b)
; #pragma unroll
;                 for (int m = 0; m < 4; ++m)
; #pragma unroll
;                     for (int n = 0; n < 2; ++n) acc[a][b][m][n] = (f32x4){0.f, 0.f, 0.f, 0.f};
;         cur = nxt; cA = nA; cB = nB; ++ui;
;         if constexpr (ALIGN_EPI) { if (wr == 1) PG8_BAR; }
	v_pk_fma_f32 v[18:19], v[18:19], v[178:179], v[192:193] op_sel_hi:[1,0,1]
	v_lshl_add_u64 v[16:17], s[44:45], 0, v[182:183]
	v_mul_f32_e32 v8, 0xbfb8aa3b, v19
	v_exp_f32_e32 v8, v8
	v_lshlrev_b64 v[16:17], 7, v[16:17]
	v_lshl_add_u64 v[16:17], s[6:7], 0, v[16:17]
	s_mov_b64 s[44:45], -1
	v_add_f32_e32 v8, 1.0, v8
	v_rcp_f32_e32 v8, v8
	s_nop 0
	v_mul_f32_e32 v8, v19, v8
	v_mul_f32_e32 v20, v18, v8
	v_pk_mov_b32 v[18:19], v[136:137], v[176:177] op_sel:[1,0]
	v_mov_b32_e32 v8, v13
	v_pk_fma_f32 v[8:9], v[128:129], v[18:19], v[8:9] neg_lo:[1,0,0] neg_hi:[1,0,0]
	v_mov_b32_e32 v13, v176
	v_pk_fma_f32 v[8:9], v[8:9], v[178:179], v[132:133] op_sel_hi:[1,0,1]
	v_mov_b32_e32 v18, v14
	v_mul_f32_e32 v12, 0xbfb8aa3b, v9
	v_exp_f32_e32 v12, v12
	v_mov_b32_e32 v19, v10
	v_add_f32_e32 v12, 1.0, v12
	v_rcp_f32_e32 v12, v12
	s_nop 0
	v_mul_f32_e32 v9, v9, v12
	v_mul_f32_e32 v21, v8, v9
	v_mov_b32_e32 v8, v176
	v_mov_b32_e32 v9, v130
	v_mov_b32_e32 v12, v138
	v_pk_fma_f32 v[8:9], v[8:9], v[12:13], v[18:19] neg_lo:[1,0,0] neg_hi:[1,0,0]
	v_mov_b32_e32 v130, v176
	v_pk_fma_f32 v[8:9], v[8:9], v[178:179], v[140:141] op_sel_hi:[1,0,1]
	s_nop 0
	v_mul_f32_e32 v10, 0xbfb8aa3b, v9
	v_exp_f32_e32 v10, v10
	s_nop 0
	v_add_f32_e32 v10, 1.0, v10
	v_rcp_f32_e32 v10, v10
	s_nop 0
	v_mul_f32_e32 v9, v9, v10
	v_mul_f32_e32 v12, v8, v9
	v_pk_mov_b32 v[8:9], v[138:139], v[176:177] op_sel:[1,0]
	v_mov_b32_e32 v10, v15
	v_pk_fma_f32 v[8:9], v[130:131], v[8:9], v[10:11] neg_lo:[1,0,0] neg_hi:[1,0,0]
	s_nop 0
	v_pk_fma_f32 v[8:9], v[8:9], v[178:179], v[134:135] op_sel_hi:[1,0,1]
	s_nop 0
	v_mul_f32_e32 v10, 0xbfb8aa3b, v9
	v_exp_f32_e32 v10, v10
	s_nop 0
	v_add_f32_e32 v10, 1.0, v10
	v_rcp_f32_e32 v10, v10
	s_nop 0
	v_mul_f32_e32 v9, v9, v10
	v_mul_f32_e32 v10, v8, v9
	v_mov_b32_e32 v8, v0
	v_mov_b32_e32 v9, v4
	v_pk_fma_f32 v[8:9], v[176:177], v[142:143], v[8:9] op_sel_hi:[0,1,1] neg_lo:[1,0,0] neg_hi:[1,0,0]
	v_pk_fma_f32 v[8:9], v[178:179], v[8:9], v[144:145] op_sel_hi:[0,1,1]
	v_mul_f32_e32 v0, 0xbfb8aa3b, v9
	v_exp_f32_e32 v0, v0
	v_mov_b32_e32 v4, v1
	v_add_f32_e32 v0, 1.0, v0
	v_rcp_f32_e32 v0, v0
	s_nop 0
	v_mul_f32_e32 v0, v9, v0
	v_mul_f32_e32 v8, v8, v0
	v_pk_fma_f32 v[0:1], v[176:177], v[112:113], v[4:5] op_sel_hi:[0,1,1] neg_lo:[1,0,0] neg_hi:[1,0,0]
	v_pk_fma_f32 v[0:1], v[178:179], v[0:1], v[116:117] op_sel_hi:[0,1,1]
	v_mul_f32_e32 v4, 0xbfb8aa3b, v1
	v_exp_f32_e32 v4, v4
	s_nop 0
	v_add_f32_e32 v4, 1.0, v4
	v_rcp_f32_e32 v4, v4
	s_nop 0
	v_mul_f32_e32 v1, v1, v4
	v_mul_f32_e32 v9, v0, v1
	v_mov_b32_e32 v0, v2
	v_mov_b32_e32 v1, v6
	v_pk_fma_f32 v[0:1], v[176:177], v[120:121], v[0:1] op_sel_hi:[0,1,1] neg_lo:[1,0,0] neg_hi:[1,0,0]
	v_pk_fma_f32 v[0:1], v[178:179], v[0:1], v[124:125] op_sel_hi:[0,1,1]
	v_mul_f32_e32 v2, 0xbfb8aa3b, v1
	v_exp_f32_e32 v2, v2
	v_mov_b32_e32 v6, v3
	v_lshl_add_u64 v[4:5], v[16:17], 0, v[122:123]
	v_add_f32_e32 v2, 1.0, v2
	v_rcp_f32_e32 v2, v2
	s_nop 0
	v_mul_f32_e32 v1, v1, v2
	v_mul_f32_e32 v11, v0, v1
	v_pk_fma_f32 v[0:1], v[176:177], v[114:115], v[6:7] op_sel_hi:[0,1,1] neg_lo:[1,0,0] neg_hi:[1,0,0]
	v_pk_fma_f32 v[0:1], v[178:179], v[0:1], v[118:119] op_sel_hi:[0,1,1]
	v_mul_f32_e32 v2, 0xbfb8aa3b, v1
	v_exp_f32_e32 v2, v2
	s_nop 0
	v_add_f32_e32 v2, 1.0, v2
	v_rcp_f32_e32 v2, v2
	s_nop 0
	v_mul_f32_e32 v1, v1, v2
	v_mul_f32_e32 v3, v0, v1
	v_cvt_pk_bf16_f32 v0, v20, v21
	v_cvt_pk_bf16_f32 v1, v12, v10
	v_cvt_pk_bf16_f32 v2, v8, v9
	v_cvt_pk_bf16_f32 v3, v11, v3
	global_store_dwordx4 v[4:5], v[0:3], off
	s_cbranch_vccnz .LBB0_1252
	s_andn2_b64 vcc, exec, s[4:5]
	s_cbranch_vccnz .LBB0_1251
	s_barrier
	s_branch .LBB0_1251

; __device__ __forceinline__ void load_row_stats(const float* sp, int row0, RowStats& r) {
; #pragma unroll
;     for (int ai = 0; ai < 2; ++ai) { asm volatile("" ::: "memory");
; #pragma unroll
;         for (int m = 0; m < 4; ++m) { const float* p = sp + (size_t)(row0 + ai * HALF + m * 16) * 8; const f32x4 a = *(const f32x4*)p, b = *(const f32x4*)(p + 4);
;             const float s1 = (a[0] + a[2]) + (b[0] + b[2]), s2 = (a[1] + a[3]) + (b[1] + b[3]); const float mu = s1 * (1.f / 1024.f); const float var = s2 * (1.f / 1024.f) - mu * mu;
;             r.mu[ai][m] = mu; r.rs[ai][m] = __builtin_amdgcn_rsqf(__builtin_fmaxf(var, 0.f) + 1e-5f); } }
;     __device__ __forceinline__ void operator()(const f32x4 (&acc)[2][2][4][2], const Unit& u, int wr, int wc, int fr_in, int fq_in) const {
;     ...
;         const int row0 = u.pm * BM + wr * 64 + fr, col0 = u.pn * BM + wc * 32 + 8 * fq;
;         RowStats rst; load_row_stats(sp, row0, rst);
; #pragma unroll
;         for (int bj = 0; bj < 2; ++bj) { f32x4 csv[2], cbv[2], gv[2], bv[2];
; #pragma unroll
;             for (int n = 0; n < 2; ++n) { csv[n] = *(const f32x4*)(cs + col0 + bj * HALF + 4 * n); cbv[n] = *(const f32x4*)(cb + col0 + bj * HALF + 4 * n); gv[n] = *(const f32x4*)(lg + col0 + bj * HALF + 4 * n); bv[n] = *(const f32x4*)(lb + col0 + bj * HALF + 4 * n); }
; #pragma unroll
;             for (int am = 0; am < (FINAL ? 8 : 4); ++am) { constexpr int GR = FINAL ? 1 : 2; const int ai = (am * GR) >> 2; u32x4 ppw[4], pzw[4];
; #pragma unroll
;                 for (int m = (am * GR) & 3; m < ((am * GR) & 3) + GR; ++m) { const size_t off = (size_t)(row0 + ai * HALF + m * 16) * 1024 + col0 + bj * HALF; ppw[m] = *(const u32x4*)(pexb + off); pzw[m] = *(const u32x4*)(zb + off); }
.LBB0_1458:
	s_lshl_b32 s10, s10, 8
	v_mov_b32_e32 v104, v187
	v_mov_b32_e32 v105, v191
	s_add_i32 s10, s10, s28
	s_andn2_b64 vcc, exec, s[38:39]
	v_add_u32_e32 v244, s10, v104
	s_lshl_b32 s10, s11, 8
	s_or_b32 s10, s10, s59
	v_ashrrev_i32_e32 v245, 31, v244
	v_lshl_add_u32 v216, v105, 3, s10
	v_and_b32_e32 v212, 0xffffff00, v244
	v_and_b32_e32 v185, 0xff, v244
	v_lshlrev_b32_e32 v185, 3, v185
	v_add_u32_e32 v185, 0x22400, v185
	v_add_u32_e32 v242, 16, v244
	v_ashrrev_i32_e32 v243, 31, v242
	v_add_u32_e32 v240, 32, v244
	v_ashrrev_i32_e32 v241, 31, v240
	v_add_u32_e32 v238, 48, v244
	v_ashrrev_i32_e32 v239, 31, v238
	v_add_u32_e32 v236, 0x80, v244
	v_ashrrev_i32_e32 v237, 31, v236
	v_add_u32_e32 v234, 0x90, v244
	v_ashrrev_i32_e32 v235, 31, v234
	v_add_u32_e32 v220, 0xa0, v244
	v_ashrrev_i32_e32 v221, 31, v220
	v_add_u32_e32 v218, 0xb0, v244
	v_ashrrev_i32_e32 v219, 31, v218
	v_ashrrev_i32_e32 v217, 31, v216
	v_lshlrev_b64 v[230:231], 10, v[244:245]
	v_lshl_add_u64 v[160:161], v[230:231], 0, v[216:217]
	v_lshlrev_b64 v[160:161], 1, v[160:161]
	v_lshl_add_u64 v[162:163], s[44:45], 0, v[160:161]
	v_lshl_add_u64 v[160:161], s[40:41], 0, v[160:161]
	v_lshlrev_b64 v[232:233], 10, v[242:243]
	s_mov_b64 s[10:11], -1
	s_nop 0
	s_nop 0
	s_nop 0
	s_nop 0
	s_nop 0
	s_nop 0
	s_nop 0
	s_nop 0
	v_lshlrev_b64 v[104:105], 2, v[216:217]
	v_lshl_add_u64 v[228:229], s[48:49], 0, v[104:105]
	v_lshl_add_u64 v[226:227], s[50:51], 0, v[104:105]
	v_lshl_add_u64 v[224:225], s[4:5], 0, v[104:105]
	v_lshl_add_u64 v[222:223], s[6:7], 0, v[104:105]
	global_load_dwordx4 v[108:111], v[228:229], off offset:16
	global_load_dwordx4 v[116:119], v[228:229], off
	global_load_dwordx4 v[104:107], v[226:227], off offset:16
	global_load_dwordx4 v[112:115], v[226:227], off
	global_load_dwordx4 v[120:123], v[224:225], off offset:16
	global_load_dwordx4 v[136:139], v[224:225], off
	global_load_dwordx4 v[124:127], v[222:223], off offset:16
	global_load_dwordx4 v[140:143], v[222:223], off
	global_load_dwordx4 v[168:171], v[162:163], off
	global_load_dwordx4 v[248:251], v[160:161], off
	v_lshl_add_u64 v[160:161], v[232:233], 0, v[216:217]
	v_lshlrev_b64 v[164:165], 1, v[160:161]
	v_lshl_add_u64 v[160:161], s[44:45], 0, v[164:165]
	v_lshl_add_u64 v[164:165], s[40:41], 0, v[164:165]
	global_load_dwordx4 v[160:163], v[160:161], off
	s_cselect_b32 s99, 1, 0
	v_readfirstlane_b32 s98, v254
	s_nop 0
	s_cmpk_lt_u32 s98, 0x100
	s_cbranch_scc0 .Lrs4_skip
	v_add_u32_e32 v212, v212, v254
	v_mov_b32_e32 v213, 0
	v_lshlrev_b64 v[212:213], 5, v[212:213]
	v_lshl_add_u64 v[212:213], s[46:47], 0, v[212:213]
	global_load_dwordx2 v[208:209], v[212:213], off offset:16
	global_load_dwordx2 v[204:205], v[212:213], off offset:24
	global_load_dwordx2 v[200:201], v[212:213], off
	global_load_dwordx2 v[196:197], v[212:213], off offset:8
	s_waitcnt vmcnt(0)
	v_pk_add_f32 v[208:209], v[208:209], v[204:205]
	v_pk_add_f32 v[200:201], v[200:201], v[196:197]
	s_nop 0
	v_pk_add_f32 v[208:209], v[200:201], v[208:209]
	s_nop 0
	v_pk_mul_f32 v[208:209], v[208:209], s[58:59] op_sel_hi:[1,0]
	v_lshlrev_b32_e32 v192, 3, v254
	v_add_u32_e32 v192, 0x22400, v192
	ds_write_b64 v192, v[208:209]
.Lrs4_skip:
	s_waitcnt vmcnt(0) lgkmcnt(0)
	s_barrier
	ds_read_b64 v[212:213], v185
	ds_read_b64 v[208:209], v185 offset:128
	ds_read_b64 v[204:205], v185 offset:256
	ds_read_b64 v[200:201], v185 offset:384
	ds_read_b64 v[196:197], v185 offset:1024
	ds_read_b64 v[192:193], v185 offset:1152
	ds_read_b64 v[188:189], v185 offset:1280
	ds_read_b64 v[184:185], v185 offset:1408
	s_cmp_lg_u32 s99, 0
	s_waitcnt lgkmcnt(0)
	v_fma_f32 v214, -v212, v212, v213
	v_max_f32_e32 v214, 0, v214
	v_add_f32_e32 v214, 0x3727c5ac, v214
	v_rsq_f32_e32 v214, v214
	v_fma_f32 v210, -v208, v208, v209
	v_max_f32_e32 v210, 0, v210
	v_add_f32_e32 v210, 0x3727c5ac, v210
	v_rsq_f32_e32 v210, v210
	v_fma_f32 v206, -v204, v204, v205
	v_max_f32_e32 v206, 0, v206
	v_add_f32_e32 v206, 0x3727c5ac, v206
	v_rsq_f32_e32 v206, v206
	v_fma_f32 v202, -v200, v200, v201
	v_max_f32_e32 v202, 0, v202
	v_add_f32_e32 v202, 0x3727c5ac, v202
	v_rsq_f32_e32 v202, v202
	v_fma_f32 v198, -v196, v196, v197
	v_max_f32_e32 v198, 0, v198
	v_add_f32_e32 v198, 0x3727c5ac, v198
	v_rsq_f32_e32 v198, v198
	v_fma_f32 v194, -v192, v192, v193
	v_max_f32_e32 v194, 0, v194
	v_add_f32_e32 v194, 0x3727c5ac, v194
	v_rsq_f32_e32 v194, v194
	v_fma_f32 v190, -v188, v188, v189
	v_max_f32_e32 v190, 0, v190
	v_add_f32_e32 v190, 0x3727c5ac, v190
	v_rsq_f32_e32 v190, v190
	v_fma_f32 v186, -v184, v184, v185
	v_max_f32_e32 v186, 0, v186
	v_add_f32_e32 v186, 0x3727c5ac, v186
	v_rsq_f32_e32 v186, v186
	s_waitcnt vmcnt(0)
; __device__ __forceinline__ unsigned cvt_pk_bf16(float lo, float hi) { unsigned r; asm("v_cvt_pk_bf16_f32 %0, %1, %2" : "=v"(r) : "v"(lo), "v"(hi)); return r; }
; __device__ __forceinline__ float fast_sigmoid(float v) { return __builtin_amdgcn_rcpf(1.0f + __builtin_amdgcn_exp2f(-1.4426950408889634f * v)); }
;     __device__ __forceinline__ void operator()(const f32x4 (&acc)[2][2][4][2], const Unit& u, int wr, int wc, int fr_in, int fq_in) const {
;     ...
;             for (int am = 0; am < (FINAL ? 8 : 4); ++am) { constexpr int GR = FINAL ? 1 : 2; const int ai = (am * GR) >> 2; u32x4 ppw[4], pzw[4];
; #pragma unroll
;                 for (int m = (am * GR) & 3; m < ((am * GR) & 3) + GR; ++m) { const size_t off = (size_t)(row0 + ai * HALF + m * 16) * 1024 + col0 + bj * HALF; ppw[m] = *(const u32x4*)(pexb + off); pzw[m] = *(const u32x4*)(zb + off); }
;                 asm volatile("" ::: "memory");
; #pragma unroll
;                 for (int m = (am * GR) & 3; m < ((am * GR) & 3) + GR; ++m) { const size_t off = (size_t)(row0 + ai * HALF + m * 16) * 1024 + col0 + bj * HALF; const float mu = rst.mu[ai][m], rs = rst.rs[ai][m];
;                     const u32x4 pw = ppw[m]; const u32x4 zw = pzw[m];
;                     const f32x4 x0 = ((f32x4){bf_lo(zw.x), bf_hi(zw.x), bf_lo(zw.y), bf_hi(zw.y)} - mu) * rs * gv[0] + bv[0], x1 = ((f32x4){bf_lo(zw.z), bf_hi(zw.z), bf_lo(zw.w), bf_hi(zw.w)} - mu) * rs * gv[1] + bv[1];
;                     const f32x4 a0 = ln_fix(acc[ai][bj][m][0], mu, rs, csv[0], cbv[0]), a1 = ln_fix(acc[ai][bj][m][1], mu, rs, csv[1], cbv[1]); f32x4 o0, o1;
;                     o0[0] = x0[0] + fast_sigmoid(a0[0]) * bf_lo(pw.x); o0[1] = x0[1] + fast_sigmoid(a0[1]) * bf_hi(pw.x);
;                     o0[2] = x0[2] + fast_sigmoid(a0[2]) * bf_lo(pw.y); o0[3] = x0[3] + fast_sigmoid(a0[3]) * bf_hi(pw.y);
;                     o1[0] = x1[0] + fast_sigmoid(a1[0]) * bf_lo(pw.z); o1[1] = x1[1] + fast_sigmoid(a1[1]) * bf_hi(pw.z);
;                     o1[2] = x1[2] + fast_sigmoid(a1[2]) * bf_lo(pw.w); o1[3] = x1[3] + fast_sigmoid(a1[3]) * bf_hi(pw.w);
;                     if constexpr (FINAL) { *(f32x4*)(outf + off) = o0; *(f32x4*)(outf + off + 4) = o1; }
;                     else { u32x4 w; w.x = cvt_pk_bf16(o0[0], o0[1]); w.y = cvt_pk_bf16(o0[2], o0[3]); w.z = cvt_pk_bf16(o1[0], o1[1]); w.w = cvt_pk_bf16(o1[2], o1[3]); *(u32x4*)(pexb + off) = w; } } } }
	v_pk_fma_f32 v[152:153], v[212:213], v[108:109], v[152:153] op_sel_hi:[0,1,1] neg_lo:[1,0,0] neg_hi:[1,0,0]
	global_load_dwordx4 v[164:167], v[164:165], off
	v_pk_fma_f32 v[156:157], v[212:213], v[116:117], v[156:157] op_sel_hi:[0,1,1] neg_lo:[1,0,0] neg_hi:[1,0,0]
	v_pk_fma_f32 v[158:159], v[212:213], v[118:119], v[158:159] op_sel_hi:[0,1,1] neg_lo:[1,0,0] neg_hi:[1,0,0]
	v_pk_fma_f32 v[154:155], v[212:213], v[110:111], v[154:155] op_sel_hi:[0,1,1] neg_lo:[1,0,0] neg_hi:[1,0,0]
	v_pk_fma_f32 v[148:149], v[208:209], v[116:117], v[148:149] op_sel_hi:[0,1,1] neg_lo:[1,0,0] neg_hi:[1,0,0]
	v_pk_fma_f32 v[150:151], v[208:209], v[118:119], v[150:151] op_sel_hi:[0,1,1] neg_lo:[1,0,0] neg_hi:[1,0,0]
	v_pk_fma_f32 v[132:133], v[204:205], v[116:117], v[132:133] op_sel_hi:[0,1,1] neg_lo:[1,0,0] neg_hi:[1,0,0]
	v_lshlrev_b32_e32 v211, 16, v248
	v_and_b32_e32 v215, 0xffff0000, v248
	v_lshlrev_b32_e32 v246, 16, v249
	v_and_b32_e32 v247, 0xffff0000, v249
	v_sub_f32_e32 v247, v247, v212
	v_sub_f32_e32 v246, v246, v212
	v_sub_f32_e32 v249, v215, v212
	v_sub_f32_e32 v248, v211, v212
	v_pk_mul_f32 v[248:249], v[214:215], v[248:249] op_sel_hi:[0,1]
	v_pk_mul_f32 v[246:247], v[214:215], v[246:247] op_sel_hi:[0,1]
	v_and_b32_e32 v215, 0xffff0000, v250
	v_pk_fma_f32 v[156:157], v[214:215], v[156:157], v[112:113] op_sel_hi:[0,1,1]
	v_mul_f32_e32 v157, 0xbfb8aa3b, v157
	v_exp_f32_e32 v157, v157
	v_lshlrev_b32_e32 v211, 16, v250
	v_pk_fma_f32 v[248:249], v[136:137], v[248:249], v[140:141]
	v_sub_f32_e32 v252, v211, v212
	v_add_f32_e32 v157, 1.0, v157
	v_rcp_f32_e32 v157, v157
	v_pk_fma_f32 v[158:159], v[214:215], v[158:159], v[114:115] op_sel_hi:[0,1,1]
	v_lshlrev_b32_e32 v211, 16, v168
	v_and_b32_e32 v168, 0xffff0000, v168
	v_fmac_f32_e32 v249, v157, v168
	v_mul_f32_e32 v157, 0xbfb8aa3b, v158
	v_exp_f32_e32 v157, v157
	v_pk_fma_f32 v[246:247], v[138:139], v[246:247], v[142:143]
	v_lshlrev_b32_e32 v158, 16, v169
	v_pk_fma_f32 v[152:153], v[214:215], v[152:153], v[104:105] op_sel_hi:[0,1,1]
	v_add_f32_e32 v157, 1.0, v157
	v_rcp_f32_e32 v157, v157
	v_mul_f32_e32 v152, 0xbfb8aa3b, v152
	v_exp_f32_e32 v152, v152
	v_sub_f32_e32 v253, v215, v212
	v_fma_f32 v157, v157, v158, v246
	v_mul_f32_e32 v158, 0xbfb8aa3b, v159
	v_exp_f32_e32 v158, v158
	v_add_f32_e32 v152, 1.0, v152
	v_rcp_f32_e32 v152, v152
	v_pk_mul_f32 v[252:253], v[214:215], v[252:253] op_sel_hi:[0,1]
	v_add_f32_e32 v158, 1.0, v158
	v_rcp_f32_e32 v158, v158
	v_and_b32_e32 v159, 0xffff0000, v169
	v_pk_fma_f32 v[252:253], v[120:121], v[252:253], v[124:125]
	v_pk_fma_f32 v[154:155], v[214:215], v[154:155], v[106:107] op_sel_hi:[0,1,1]
	v_fmac_f32_e32 v247, v158, v159
	v_lshlrev_b32_e32 v158, 16, v170
	v_fma_f32 v158, v152, v158, v252
	v_mul_f32_e32 v152, 0xbfb8aa3b, v153
	v_exp_f32_e32 v152, v152
	v_and_b32_e32 v153, 0xffff0000, v170
	v_lshlrev_b32_e32 v250, 16, v251
	v_and_b32_e32 v251, 0xffff0000, v251
	v_add_f32_e32 v152, 1.0, v152
	v_rcp_f32_e32 v152, v152
	v_sub_f32_e32 v251, v251, v212
	v_sub_f32_e32 v250, v250, v212
	v_pk_mul_f32 v[250:251], v[214:215], v[250:251] op_sel_hi:[0,1]
	v_fmac_f32_e32 v253, v152, v153
	v_mul_f32_e32 v152, 0xbfb8aa3b, v154
	v_exp_f32_e32 v152, v152
	v_pk_fma_f32 v[250:251], v[122:123], v[250:251], v[126:127]
	v_mul_f32_e32 v156, 0xbfb8aa3b, v156
	v_lshlrev_b32_e32 v153, 16, v171
	v_add_f32_e32 v152, 1.0, v152
	v_rcp_f32_e32 v152, v152
	v_exp_f32_e32 v156, v156
	v_pk_fma_f32 v[148:149], v[210:211], v[148:149], v[112:113] op_sel_hi:[0,1,1]
	v_mul_f32_e32 v148, 0xbfb8aa3b, v148
	v_fma_f32 v159, v152, v153, v250
	v_mul_f32_e32 v152, 0xbfb8aa3b, v155
	v_exp_f32_e32 v152, v152
	v_add_f32_e32 v156, 1.0, v156
	v_rcp_f32_e32 v156, v156
	v_exp_f32_e32 v148, v148
	v_add_f32_e32 v152, 1.0, v152
	v_rcp_f32_e32 v152, v152
	v_mul_f32_e32 v149, 0xbfb8aa3b, v149
	v_fma_f32 v156, v156, v211, v248
	v_and_b32_e32 v153, 0xffff0000, v171
	v_exp_f32_e32 v149, v149
	v_fmac_f32_e32 v251, v152, v153
	v_cvt_pk_bf16_f32 v152, v156, v249
	v_cvt_pk_bf16_f32 v153, v157, v247
	v_lshlrev_b64 v[156:157], 11, v[244:245]
	v_lshl_add_u64 v[156:157], s[44:45], 0, v[156:157]
	v_lshlrev_b64 v[168:169], 1, v[216:217]
	v_cvt_pk_bf16_f32 v154, v158, v253
	v_cvt_pk_bf16_f32 v155, v159, v251
	v_lshl_add_u64 v[156:157], v[156:157], 0, v[168:169]
	v_add_f32_e32 v148, 1.0, v148
	global_store_dwordx4 v[156:157], v[152:155], off
	v_rcp_f32_e32 v148, v148
	v_add_f32_e32 v149, 1.0, v149
	s_waitcnt vmcnt(0)
; __device__ __forceinline__ unsigned cvt_pk_bf16(float lo, float hi) { unsigned r; asm("v_cvt_pk_bf16_f32 %0, %1, %2" : "=v"(r) : "v"(lo), "v"(hi)); return r; }
; __device__ __forceinline__ float fast_sigmoid(float v) { return __builtin_amdgcn_rcpf(1.0f + __builtin_amdgcn_exp2f(-1.4426950408889634f * v)); }
;     __device__ __forceinline__ void operator()(const f32x4 (&acc)[2][2][4][2], const Unit& u, int wr, int wc, int fr_in, int fq_in) const {
;     ...
;             for (int am = 0; am < (FINAL ? 8 : 4); ++am) { constexpr int GR = FINAL ? 1 : 2; const int ai = (am * GR) >> 2; u32x4 ppw[4], pzw[4];
; #pragma unroll
;                 for (int m = (am * GR) & 3; m < ((am * GR) & 3) + GR; ++m) { const size_t off = (size_t)(row0 + ai * HALF + m * 16) * 1024 + col0 + bj * HALF; ppw[m] = *(const u32x4*)(pexb + off); pzw[m] = *(const u32x4*)(zb + off); }
;                 asm volatile("" ::: "memory");
; #pragma unroll
;                 for (int m = (am * GR) & 3; m < ((am * GR) & 3) + GR; ++m) { const size_t off = (size_t)(row0 + ai * HALF + m * 16) * 1024 + col0 + bj * HALF; const float mu = rst.mu[ai][m], rs = rst.rs[ai][m];
;                     const u32x4 pw = ppw[m]; const u32x4 zw = pzw[m];
;                     const f32x4 x0 = ((f32x4){bf_lo(zw.x), bf_hi(zw.x), bf_lo(zw.y), bf_hi(zw.y)} - mu) * rs * gv[0] + bv[0], x1 = ((f32x4){bf_lo(zw.z), bf_hi(zw.z), bf_lo(zw.w), bf_hi(zw.w)} - mu) * rs * gv[1] + bv[1];
;                     const f32x4 a0 = ln_fix(acc[ai][bj][m][0], mu, rs, csv[0], cbv[0]), a1 = ln_fix(acc[ai][bj][m][1], mu, rs, csv[1], cbv[1]); f32x4 o0, o1;
;                     o0[0] = x0[0] + fast_sigmoid(a0[0]) * bf_lo(pw.x); o0[1] = x0[1] + fast_sigmoid(a0[1]) * bf_hi(pw.x);
;                     o0[2] = x0[2] + fast_sigmoid(a0[2]) * bf_lo(pw.y); o0[3] = x0[3] + fast_sigmoid(a0[3]) * bf_hi(pw.y);
;                     o1[0] = x1[0] + fast_sigmoid(a1[0]) * bf_lo(pw.z); o1[1] = x1[1] + fast_sigmoid(a1[1]) * bf_hi(pw.z);
;                     o1[2] = x1[2] + fast_sigmoid(a1[2]) * bf_lo(pw.w); o1[3] = x1[3] + fast_sigmoid(a1[3]) * bf_hi(pw.w);
;                     if constexpr (FINAL) { *(f32x4*)(outf + off) = o0; *(f32x4*)(outf + off + 4) = o1; }
;                     else { u32x4 w; w.x = cvt_pk_bf16(o0[0], o0[1]); w.y = cvt_pk_bf16(o0[2], o0[3]); w.z = cvt_pk_bf16(o1[0], o1[1]); w.w = cvt_pk_bf16(o1[2], o1[3]); *(u32x4*)(pexb + off) = w; } } } }
	v_lshlrev_b32_e32 v154, 16, v164
	v_and_b32_e32 v155, 0xffff0000, v164
	v_sub_f32_e32 v155, v155, v208
	v_sub_f32_e32 v154, v154, v208
	v_rcp_f32_e32 v149, v149
	v_lshlrev_b32_e32 v152, 16, v165
	v_and_b32_e32 v153, 0xffff0000, v165
	v_pk_mul_f32 v[154:155], v[210:211], v[154:155] op_sel_hi:[0,1]
	v_lshlrev_b32_e32 v164, 16, v166
	v_and_b32_e32 v165, 0xffff0000, v166
	v_lshlrev_b32_e32 v158, 16, v167
	v_and_b32_e32 v159, 0xffff0000, v167
	v_pk_fma_f32 v[166:167], v[208:209], v[108:109], v[144:145] op_sel_hi:[0,1,1] neg_lo:[1,0,0] neg_hi:[1,0,0]
	v_pk_fma_f32 v[154:155], v[136:137], v[154:155], v[140:141]
	v_pk_fma_f32 v[144:145], v[208:209], v[110:111], v[146:147] op_sel_hi:[0,1,1] neg_lo:[1,0,0] neg_hi:[1,0,0]
	v_pk_fma_f32 v[146:147], v[210:211], v[166:167], v[104:105] op_sel_hi:[0,1,1]
	v_lshlrev_b32_e32 v166, 16, v160
	v_pk_fma_f32 v[150:151], v[210:211], v[150:151], v[114:115] op_sel_hi:[0,1,1]
	v_fma_f32 v148, v148, v166, v154
	v_and_b32_e32 v154, 0xffff0000, v160
	v_fmac_f32_e32 v155, v149, v154
	v_mul_f32_e32 v149, 0xbfb8aa3b, v150
	v_exp_f32_e32 v149, v149
	v_sub_f32_e32 v153, v153, v208
	v_sub_f32_e32 v152, v152, v208
	v_pk_mul_f32 v[152:153], v[210:211], v[152:153] op_sel_hi:[0,1]
	v_add_f32_e32 v149, 1.0, v149
	v_rcp_f32_e32 v149, v149
	v_pk_fma_f32 v[152:153], v[138:139], v[152:153], v[142:143]
	v_lshlrev_b32_e32 v150, 16, v161
	v_mul_f32_e32 v146, 0xbfb8aa3b, v146
	v_fma_f32 v149, v149, v150, v152
	v_mul_f32_e32 v150, 0xbfb8aa3b, v151
	v_exp_f32_e32 v150, v150
	v_pk_fma_f32 v[144:145], v[210:211], v[144:145], v[106:107] op_sel_hi:[0,1,1]
	v_exp_f32_e32 v146, v146
	v_mul_f32_e32 v147, 0xbfb8aa3b, v147
	v_exp_f32_e32 v147, v147
	v_mul_f32_e32 v144, 0xbfb8aa3b, v144
	v_exp_f32_e32 v144, v144
	v_add_f32_e32 v150, 1.0, v150
	v_rcp_f32_e32 v150, v150
	v_add_f32_e32 v146, 1.0, v146
	v_rcp_f32_e32 v146, v146
	v_add_f32_e32 v147, 1.0, v147
	v_sub_f32_e32 v165, v165, v208
	v_sub_f32_e32 v164, v164, v208
	v_rcp_f32_e32 v147, v147
	v_add_f32_e32 v144, 1.0, v144
	v_pk_mul_f32 v[164:165], v[210:211], v[164:165] op_sel_hi:[0,1]
	v_and_b32_e32 v151, 0xffff0000, v161
	v_rcp_f32_e32 v144, v144
	v_sub_f32_e32 v159, v159, v208
	v_sub_f32_e32 v158, v158, v208
	v_pk_fma_f32 v[164:165], v[120:121], v[164:165], v[124:125]
	v_fmac_f32_e32 v153, v150, v151
	v_lshlrev_b32_e32 v150, 16, v162
	v_pk_mul_f32 v[158:159], v[210:211], v[158:159] op_sel_hi:[0,1]
	v_fma_f32 v146, v146, v150, v164
	v_and_b32_e32 v150, 0xffff0000, v162
	v_pk_fma_f32 v[158:159], v[122:123], v[158:159], v[126:127]
	v_fmac_f32_e32 v165, v147, v150
	v_lshlrev_b32_e32 v147, 16, v163
	v_fma_f32 v147, v144, v147, v158
	v_mul_f32_e32 v144, 0xbfb8aa3b, v145
	v_exp_f32_e32 v144, v144
	v_and_b32_e32 v145, 0xffff0000, v163
	v_lshlrev_b64 v[160:161], 10, v[240:241]
	v_cvt_pk_bf16_f32 v146, v146, v165
	v_add_f32_e32 v144, 1.0, v144
	v_rcp_f32_e32 v144, v144
	v_lshlrev_b64 v[162:163], 10, v[238:239]
	v_pk_fma_f32 v[132:133], v[206:207], v[132:133], v[112:113] op_sel_hi:[0,1,1]
	v_mul_f32_e32 v133, 0xbfb8aa3b, v133
	v_fmac_f32_e32 v159, v144, v145
	v_cvt_pk_bf16_f32 v144, v148, v155
	v_cvt_pk_bf16_f32 v145, v149, v153
	v_lshlrev_b64 v[148:149], 11, v[242:243]
	v_lshl_add_u64 v[148:149], s[44:45], 0, v[148:149]
	v_cvt_pk_bf16_f32 v147, v147, v159
	v_lshl_add_u64 v[158:159], v[148:149], 0, v[168:169]
	global_store_dwordx4 v[158:159], v[144:147], off
	v_exp_f32_e32 v133, v133
	v_pk_fma_f32 v[134:135], v[204:205], v[118:119], v[134:135] op_sel_hi:[0,1,1] neg_lo:[1,0,0] neg_hi:[1,0,0]
	v_lshl_add_u64 v[144:145], v[160:161], 0, v[216:217]
	v_lshlrev_b64 v[144:145], 1, v[144:145]
	v_lshl_add_u64 v[146:147], s[44:45], 0, v[144:145]
	v_lshl_add_u64 v[144:145], s[40:41], 0, v[144:145]
	global_load_dwordx4 v[152:155], v[146:147], off
	global_load_dwordx4 v[242:245], v[144:145], off
	v_lshl_add_u64 v[144:145], v[162:163], 0, v[216:217]
	v_lshlrev_b64 v[148:149], 1, v[144:145]
	v_lshl_add_u64 v[144:145], s[44:45], 0, v[148:149]
	v_lshl_add_u64 v[148:149], s[40:41], 0, v[148:149]
	global_load_dwordx4 v[144:147], v[144:145], off
	v_add_f32_e32 v133, 1.0, v133
	global_load_dwordx4 v[148:151], v[148:149], off
	v_rcp_f32_e32 v133, v133
	v_pk_fma_f32 v[134:135], v[206:207], v[134:135], v[114:115] op_sel_hi:[0,1,1]
	v_pk_fma_f32 v[128:129], v[204:205], v[108:109], v[128:129] op_sel_hi:[0,1,1] neg_lo:[1,0,0] neg_hi:[1,0,0]
	v_pk_fma_f32 v[128:129], v[206:207], v[128:129], v[104:105] op_sel_hi:[0,1,1]
	v_mul_f32_e32 v128, 0xbfb8aa3b, v128
	v_exp_f32_e32 v128, v128
	v_pk_fma_f32 v[130:131], v[204:205], v[110:111], v[130:131] op_sel_hi:[0,1,1] neg_lo:[1,0,0] neg_hi:[1,0,0]
	v_pk_fma_f32 v[130:131], v[206:207], v[130:131], v[106:107] op_sel_hi:[0,1,1]
	v_mul_f32_e32 v132, 0xbfb8aa3b, v132
	v_add_f32_e32 v128, 1.0, v128
	v_rcp_f32_e32 v128, v128
	v_exp_f32_e32 v132, v132
	v_pk_fma_f32 v[100:101], v[200:201], v[116:117], v[100:101] op_sel_hi:[0,1,1] neg_lo:[1,0,0] neg_hi:[1,0,0]
	v_pk_fma_f32 v[100:101], v[202:203], v[100:101], v[112:113] op_sel_hi:[0,1,1]
	v_mul_f32_e32 v100, 0xbfb8aa3b, v100
	v_add_f32_e32 v132, 1.0, v132
	v_rcp_f32_e32 v132, v132
	v_exp_f32_e32 v100, v100
	v_mul_f32_e32 v101, 0xbfb8aa3b, v101
	v_exp_f32_e32 v101, v101
	v_add_f32_e32 v100, 1.0, v100
	v_rcp_f32_e32 v100, v100
	v_add_f32_e32 v101, 1.0, v101
	v_rcp_f32_e32 v101, v101
	v_pk_fma_f32 v[102:103], v[200:201], v[118:119], v[102:103] op_sel_hi:[0,1,1] neg_lo:[1,0,0] neg_hi:[1,0,0]
	v_pk_fma_f32 v[102:103], v[202:203], v[102:103], v[114:115] op_sel_hi:[0,1,1]
	v_pk_fma_f32 v[96:97], v[200:201], v[108:109], v[96:97] op_sel_hi:[0,1,1] neg_lo:[1,0,0] neg_hi:[1,0,0]
	v_pk_fma_f32 v[96:97], v[202:203], v[96:97], v[104:105] op_sel_hi:[0,1,1]
; __device__ __forceinline__ unsigned cvt_pk_bf16(float lo, float hi) { unsigned r; asm("v_cvt_pk_bf16_f32 %0, %1, %2" : "=v"(r) : "v"(lo), "v"(hi)); return r; }
; __device__ __forceinline__ float fast_sigmoid(float v) { return __builtin_amdgcn_rcpf(1.0f + __builtin_amdgcn_exp2f(-1.4426950408889634f * v)); }
;     __device__ __forceinline__ void operator()(const f32x4 (&acc)[2][2][4][2], const Unit& u, int wr, int wc, int fr_in, int fq_in) const {
;     ...
;             for (int am = 0; am < (FINAL ? 8 : 4); ++am) { constexpr int GR = FINAL ? 1 : 2; const int ai = (am * GR) >> 2; u32x4 ppw[4], pzw[4];
; #pragma unroll
;                 for (int m = (am * GR) & 3; m < ((am * GR) & 3) + GR; ++m) { const size_t off = (size_t)(row0 + ai * HALF + m * 16) * 1024 + col0 + bj * HALF; ppw[m] = *(const u32x4*)(pexb + off); pzw[m] = *(const u32x4*)(zb + off); }
;                 asm volatile("" ::: "memory");
; #pragma unroll
;                 for (int m = (am * GR) & 3; m < ((am * GR) & 3) + GR; ++m) { const size_t off = (size_t)(row0 + ai * HALF + m * 16) * 1024 + col0 + bj * HALF; const float mu = rst.mu[ai][m], rs = rst.rs[ai][m];
;                     const u32x4 pw = ppw[m]; const u32x4 zw = pzw[m];
;                     const f32x4 x0 = ((f32x4){bf_lo(zw.x), bf_hi(zw.x), bf_lo(zw.y), bf_hi(zw.y)} - mu) * rs * gv[0] + bv[0], x1 = ((f32x4){bf_lo(zw.z), bf_hi(zw.z), bf_lo(zw.w), bf_hi(zw.w)} - mu) * rs * gv[1] + bv[1];
;                     const f32x4 a0 = ln_fix(acc[ai][bj][m][0], mu, rs, csv[0], cbv[0]), a1 = ln_fix(acc[ai][bj][m][1], mu, rs, csv[1], cbv[1]); f32x4 o0, o1;
;                     o0[0] = x0[0] + fast_sigmoid(a0[0]) * bf_lo(pw.x); o0[1] = x0[1] + fast_sigmoid(a0[1]) * bf_hi(pw.x);
;                     o0[2] = x0[2] + fast_sigmoid(a0[2]) * bf_lo(pw.y); o0[3] = x0[3] + fast_sigmoid(a0[3]) * bf_hi(pw.y);
;                     o1[0] = x1[0] + fast_sigmoid(a1[0]) * bf_lo(pw.z); o1[1] = x1[1] + fast_sigmoid(a1[1]) * bf_hi(pw.z);
;                     o1[2] = x1[2] + fast_sigmoid(a1[2]) * bf_lo(pw.w); o1[3] = x1[3] + fast_sigmoid(a1[3]) * bf_hi(pw.w);
;                     if constexpr (FINAL) { *(f32x4*)(outf + off) = o0; *(f32x4*)(outf + off + 4) = o1; }
;                     else { u32x4 w; w.x = cvt_pk_bf16(o0[0], o0[1]); w.y = cvt_pk_bf16(o0[2], o0[3]); w.z = cvt_pk_bf16(o1[0], o1[1]); w.w = cvt_pk_bf16(o1[2], o1[3]); *(u32x4*)(pexb + off) = w; } } } }
	v_mul_f32_e32 v96, 0xbfb8aa3b, v96
	v_exp_f32_e32 v96, v96
	v_pk_fma_f32 v[98:99], v[200:201], v[110:111], v[98:99] op_sel_hi:[0,1,1] neg_lo:[1,0,0] neg_hi:[1,0,0]
	v_pk_fma_f32 v[98:99], v[202:203], v[98:99], v[106:107] op_sel_hi:[0,1,1]
	v_pk_fma_f32 v[92:93], v[196:197], v[116:117], v[92:93] op_sel_hi:[0,1,1] neg_lo:[1,0,0] neg_hi:[1,0,0]
	v_add_f32_e32 v96, 1.0, v96
	v_rcp_f32_e32 v96, v96
	v_pk_fma_f32 v[92:93], v[92:93], v[198:199], v[112:113] op_sel_hi:[1,0,1]
	v_pk_fma_f32 v[94:95], v[196:197], v[118:119], v[94:95] op_sel_hi:[0,1,1] neg_lo:[1,0,0] neg_hi:[1,0,0]
	v_mul_f32_e32 v93, 0xbfb8aa3b, v93
	v_exp_f32_e32 v93, v93
	v_pk_fma_f32 v[94:95], v[94:95], v[198:199], v[114:115] op_sel_hi:[1,0,1]
	v_pk_fma_f32 v[88:89], v[196:197], v[108:109], v[88:89] op_sel_hi:[0,1,1] neg_lo:[1,0,0] neg_hi:[1,0,0]
	v_pk_fma_f32 v[88:89], v[198:199], v[88:89], v[104:105] op_sel_hi:[0,1,1]
	v_add_f32_e32 v93, 1.0, v93
	v_rcp_f32_e32 v93, v93
	v_mul_f32_e32 v88, 0xbfb8aa3b, v88
	v_exp_f32_e32 v88, v88
	v_pk_fma_f32 v[90:91], v[196:197], v[110:111], v[90:91] op_sel_hi:[0,1,1] neg_lo:[1,0,0] neg_hi:[1,0,0]
	v_pk_fma_f32 v[90:91], v[198:199], v[90:91], v[106:107] op_sel_hi:[0,1,1]
	v_mul_f32_e32 v92, 0xbfb8aa3b, v92
	v_add_f32_e32 v88, 1.0, v88
	v_rcp_f32_e32 v88, v88
	v_exp_f32_e32 v92, v92
	v_pk_fma_f32 v[84:85], v[116:117], v[192:193], v[84:85] op_sel_hi:[1,0,1] neg_lo:[1,0,0] neg_hi:[1,0,0]
	v_pk_fma_f32 v[80:81], v[192:193], v[108:109], v[80:81] op_sel_hi:[0,1,1] neg_lo:[1,0,0] neg_hi:[1,0,0]
	v_pk_fma_f32 v[84:85], v[84:85], v[194:195], v[112:113] op_sel_hi:[1,0,1]
	v_add_f32_e32 v92, 1.0, v92
	v_rcp_f32_e32 v92, v92
	v_mul_f32_e32 v84, 0xbfb8aa3b, v84
	v_exp_f32_e32 v84, v84
	v_mul_f32_e32 v85, 0xbfb8aa3b, v85
	v_exp_f32_e32 v85, v85
	v_pk_fma_f32 v[80:81], v[194:195], v[80:81], v[104:105] op_sel_hi:[0,1,1]
	v_add_f32_e32 v84, 1.0, v84
	v_rcp_f32_e32 v84, v84
	v_add_f32_e32 v85, 1.0, v85
	v_rcp_f32_e32 v85, v85
	v_mul_f32_e32 v80, 0xbfb8aa3b, v80
	v_exp_f32_e32 v80, v80
	v_pk_fma_f32 v[82:83], v[192:193], v[110:111], v[82:83] op_sel_hi:[0,1,1] neg_lo:[1,0,0] neg_hi:[1,0,0]
	v_pk_fma_f32 v[82:83], v[194:195], v[82:83], v[106:107] op_sel_hi:[0,1,1]
	v_pk_fma_f32 v[76:77], v[116:117], v[188:189], v[76:77] op_sel_hi:[1,0,1] neg_lo:[1,0,0] neg_hi:[1,0,0]
	s_waitcnt vmcnt(0)
	v_lshlrev_b32_e32 v166, 16, v242
	v_and_b32_e32 v167, 0xffff0000, v242
	v_sub_f32_e32 v167, v167, v204
	v_sub_f32_e32 v166, v166, v204
	v_pk_mul_f32 v[166:167], v[206:207], v[166:167] op_sel_hi:[0,1]
	v_lshlrev_b32_e32 v211, 16, v244
	v_pk_fma_f32 v[166:167], v[136:137], v[166:167], v[140:141]
	v_sub_f32_e32 v242, v211, v204
	v_lshlrev_b32_e32 v211, 16, v152
	v_and_b32_e32 v152, 0xffff0000, v152
	v_fmac_f32_e32 v167, v133, v152
	v_mul_f32_e32 v133, 0xbfb8aa3b, v134
	v_exp_f32_e32 v133, v133
	v_lshlrev_b32_e32 v164, 16, v243
	v_and_b32_e32 v165, 0xffff0000, v243
	v_sub_f32_e32 v165, v165, v204
	v_add_f32_e32 v133, 1.0, v133
	v_rcp_f32_e32 v133, v133
	v_sub_f32_e32 v164, v164, v204
	v_pk_mul_f32 v[164:165], v[206:207], v[164:165] op_sel_hi:[0,1]
	v_pk_fma_f32 v[164:165], v[138:139], v[164:165], v[142:143]
	v_lshlrev_b32_e32 v134, 16, v153
	v_fma_f32 v133, v133, v134, v164
	v_mul_f32_e32 v134, 0xbfb8aa3b, v135
	v_exp_f32_e32 v134, v134
	v_and_b32_e32 v215, 0xffff0000, v244
	v_sub_f32_e32 v243, v215, v204
	v_pk_mul_f32 v[242:243], v[206:207], v[242:243] op_sel_hi:[0,1]
	v_add_f32_e32 v134, 1.0, v134
	v_rcp_f32_e32 v134, v134
	v_and_b32_e32 v135, 0xffff0000, v153
	v_pk_fma_f32 v[242:243], v[120:121], v[242:243], v[124:125]
	v_lshlrev_b32_e32 v170, 16, v245
	v_fmac_f32_e32 v165, v134, v135
	v_lshlrev_b32_e32 v134, 16, v154
	v_fma_f32 v134, v128, v134, v242
	v_mul_f32_e32 v128, 0xbfb8aa3b, v129
	v_exp_f32_e32 v128, v128
	v_and_b32_e32 v129, 0xffff0000, v154
	v_and_b32_e32 v171, 0xffff0000, v245
	v_sub_f32_e32 v171, v171, v204
	v_add_f32_e32 v128, 1.0, v128
	v_rcp_f32_e32 v128, v128
	v_sub_f32_e32 v170, v170, v204
	v_pk_mul_f32 v[170:171], v[206:207], v[170:171] op_sel_hi:[0,1]
	v_pk_fma_f32 v[170:171], v[122:123], v[170:171], v[126:127]
	v_fmac_f32_e32 v243, v128, v129
	v_mul_f32_e32 v128, 0xbfb8aa3b, v130
	v_exp_f32_e32 v128, v128
	v_lshlrev_b32_e32 v129, 16, v155
	v_fma_f32 v132, v132, v211, v166
	v_cvt_pk_bf16_f32 v130, v134, v243
	v_add_f32_e32 v128, 1.0, v128
	v_rcp_f32_e32 v128, v128
	v_lshlrev_b32_e32 v134, 16, v151
	v_sub_f32_e32 v134, v134, v200
	v_add_f32_e32 v80, 1.0, v80
	v_fma_f32 v135, v128, v129, v170
	v_mul_f32_e32 v128, 0xbfb8aa3b, v131
	v_exp_f32_e32 v128, v128
	v_and_b32_e32 v129, 0xffff0000, v155
	v_rcp_f32_e32 v80, v80
	v_pk_fma_f32 v[76:77], v[76:77], v[190:191], v[112:113] op_sel_hi:[1,0,1]
	v_add_f32_e32 v128, 1.0, v128
	v_rcp_f32_e32 v128, v128
	v_mul_f32_e32 v77, 0xbfb8aa3b, v77
	v_exp_f32_e32 v77, v77
	v_pk_fma_f32 v[72:73], v[188:189], v[108:109], v[72:73] op_sel_hi:[0,1,1] neg_lo:[1,0,0] neg_hi:[1,0,0]
	v_fmac_f32_e32 v171, v128, v129
	v_cvt_pk_bf16_f32 v128, v132, v167
	v_cvt_pk_bf16_f32 v129, v133, v165
	v_lshlrev_b64 v[132:133], 11, v[240:241]
	v_lshl_add_u64 v[132:133], s[44:45], 0, v[132:133]
	v_cvt_pk_bf16_f32 v131, v135, v171
	v_lshl_add_u64 v[132:133], v[132:133], 0, v[168:169]
	global_store_dwordx4 v[132:133], v[128:131], off
	v_and_b32_e32 v135, 0xffff0000, v151
	v_sub_f32_e32 v135, v135, v200
	v_lshlrev_b32_e32 v130, 16, v148
	v_and_b32_e32 v131, 0xffff0000, v148
	v_sub_f32_e32 v131, v131, v200
	v_sub_f32_e32 v130, v130, v200
	v_pk_mul_f32 v[130:131], v[202:203], v[130:131] op_sel_hi:[0,1]
	v_lshlrev_b32_e32 v128, 16, v149
	v_and_b32_e32 v129, 0xffff0000, v149
	v_pk_fma_f32 v[130:131], v[136:137], v[130:131], v[140:141]
	v_lshlrev_b32_e32 v148, 16, v150
; __device__ __forceinline__ unsigned cvt_pk_bf16(float lo, float hi) { unsigned r; asm("v_cvt_pk_bf16_f32 %0, %1, %2" : "=v"(r) : "v"(lo), "v"(hi)); return r; }
; __device__ __forceinline__ float fast_sigmoid(float v) { return __builtin_amdgcn_rcpf(1.0f + __builtin_amdgcn_exp2f(-1.4426950408889634f * v)); }
;     __device__ __forceinline__ void operator()(const f32x4 (&acc)[2][2][4][2], const Unit& u, int wr, int wc, int fr_in, int fq_in) const {
;     ...
;             for (int am = 0; am < (FINAL ? 8 : 4); ++am) { constexpr int GR = FINAL ? 1 : 2; const int ai = (am * GR) >> 2; u32x4 ppw[4], pzw[4];
; #pragma unroll
;                 for (int m = (am * GR) & 3; m < ((am * GR) & 3) + GR; ++m) { const size_t off = (size_t)(row0 + ai * HALF + m * 16) * 1024 + col0 + bj * HALF; ppw[m] = *(const u32x4*)(pexb + off); pzw[m] = *(const u32x4*)(zb + off); }
;                 asm volatile("" ::: "memory");
; #pragma unroll
;                 for (int m = (am * GR) & 3; m < ((am * GR) & 3) + GR; ++m) { const size_t off = (size_t)(row0 + ai * HALF + m * 16) * 1024 + col0 + bj * HALF; const float mu = rst.mu[ai][m], rs = rst.rs[ai][m];
;                     const u32x4 pw = ppw[m]; const u32x4 zw = pzw[m];
;                     const f32x4 x0 = ((f32x4){bf_lo(zw.x), bf_hi(zw.x), bf_lo(zw.y), bf_hi(zw.y)} - mu) * rs * gv[0] + bv[0], x1 = ((f32x4){bf_lo(zw.z), bf_hi(zw.z), bf_lo(zw.w), bf_hi(zw.w)} - mu) * rs * gv[1] + bv[1];
;                     const f32x4 a0 = ln_fix(acc[ai][bj][m][0], mu, rs, csv[0], cbv[0]), a1 = ln_fix(acc[ai][bj][m][1], mu, rs, csv[1], cbv[1]); f32x4 o0, o1;
;                     o0[0] = x0[0] + fast_sigmoid(a0[0]) * bf_lo(pw.x); o0[1] = x0[1] + fast_sigmoid(a0[1]) * bf_hi(pw.x);
;                     o0[2] = x0[2] + fast_sigmoid(a0[2]) * bf_lo(pw.y); o0[3] = x0[3] + fast_sigmoid(a0[3]) * bf_hi(pw.y);
;                     o1[0] = x1[0] + fast_sigmoid(a1[0]) * bf_lo(pw.z); o1[1] = x1[1] + fast_sigmoid(a1[1]) * bf_hi(pw.z);
;                     o1[2] = x1[2] + fast_sigmoid(a1[2]) * bf_lo(pw.w); o1[3] = x1[3] + fast_sigmoid(a1[3]) * bf_hi(pw.w);
;                     if constexpr (FINAL) { *(f32x4*)(outf + off) = o0; *(f32x4*)(outf + off + 4) = o1; }
;                     else { u32x4 w; w.x = cvt_pk_bf16(o0[0], o0[1]); w.y = cvt_pk_bf16(o0[2], o0[3]); w.z = cvt_pk_bf16(o1[0], o1[1]); w.w = cvt_pk_bf16(o1[2], o1[3]); *(u32x4*)(pexb + off) = w; } } } }
	v_and_b32_e32 v149, 0xffff0000, v150
	v_lshlrev_b32_e32 v150, 16, v144
	v_fma_f32 v100, v100, v150, v130
	v_and_b32_e32 v130, 0xffff0000, v144
	v_fmac_f32_e32 v131, v101, v130
	v_mul_f32_e32 v101, 0xbfb8aa3b, v102
	v_exp_f32_e32 v101, v101
	v_sub_f32_e32 v129, v129, v200
	v_sub_f32_e32 v128, v128, v200
	v_pk_mul_f32 v[128:129], v[202:203], v[128:129] op_sel_hi:[0,1]
	v_add_f32_e32 v101, 1.0, v101
	v_rcp_f32_e32 v101, v101
	v_pk_fma_f32 v[128:129], v[138:139], v[128:129], v[142:143]
	v_lshlrev_b32_e32 v102, 16, v145
	v_sub_f32_e32 v149, v149, v200
	v_fma_f32 v101, v101, v102, v128
	v_mul_f32_e32 v102, 0xbfb8aa3b, v103
	v_exp_f32_e32 v102, v102
	v_sub_f32_e32 v148, v148, v200
	v_pk_mul_f32 v[148:149], v[202:203], v[148:149] op_sel_hi:[0,1]
	v_and_b32_e32 v103, 0xffff0000, v145
	v_add_f32_e32 v102, 1.0, v102
	v_rcp_f32_e32 v102, v102
	v_pk_fma_f32 v[148:149], v[120:121], v[148:149], v[124:125]
	v_pk_mul_f32 v[134:135], v[202:203], v[134:135] op_sel_hi:[0,1]
	v_pk_fma_f32 v[134:135], v[122:123], v[134:135], v[126:127]
	v_fmac_f32_e32 v129, v102, v103
	v_lshlrev_b32_e32 v102, 16, v146
	v_fma_f32 v102, v96, v102, v148
	v_mul_f32_e32 v96, 0xbfb8aa3b, v97
	v_exp_f32_e32 v96, v96
	v_and_b32_e32 v97, 0xffff0000, v146
	v_lshlrev_b64 v[144:145], 10, v[236:237]
	v_add_f32_e32 v77, 1.0, v77
	v_add_f32_e32 v96, 1.0, v96
	v_rcp_f32_e32 v96, v96
	v_rcp_f32_e32 v77, v77
	v_pk_fma_f32 v[72:73], v[72:73], v[190:191], v[104:105] op_sel_hi:[1,0,1]
	v_pk_fma_f32 v[74:75], v[188:189], v[110:111], v[74:75] op_sel_hi:[0,1,1] neg_lo:[1,0,0] neg_hi:[1,0,0]
	v_fmac_f32_e32 v149, v96, v97
	v_mul_f32_e32 v96, 0xbfb8aa3b, v98
	v_exp_f32_e32 v96, v96
	v_lshlrev_b32_e32 v97, 16, v147
	v_cvt_pk_bf16_f32 v98, v102, v149
	v_mul_f32_e32 v72, 0xbfb8aa3b, v72
	v_add_f32_e32 v96, 1.0, v96
	v_rcp_f32_e32 v96, v96
	v_exp_f32_e32 v72, v72
	v_pk_fma_f32 v[74:75], v[74:75], v[190:191], v[106:107] op_sel_hi:[1,0,1]
	v_mul_f32_e32 v76, 0xbfb8aa3b, v76
	v_fma_f32 v103, v96, v97, v134
	v_mul_f32_e32 v96, 0xbfb8aa3b, v99
	v_exp_f32_e32 v96, v96
	v_and_b32_e32 v97, 0xffff0000, v147
	v_lshlrev_b64 v[146:147], 10, v[234:235]
	v_add_f32_e32 v72, 1.0, v72
	v_add_f32_e32 v96, 1.0, v96
	v_rcp_f32_e32 v96, v96
	v_rcp_f32_e32 v72, v72
	v_exp_f32_e32 v76, v76
	v_pk_fma_f32 v[68:69], v[116:117], v[184:185], v[68:69] op_sel_hi:[1,0,1] neg_lo:[1,0,0] neg_hi:[1,0,0]
	v_fmac_f32_e32 v135, v96, v97
	v_cvt_pk_bf16_f32 v96, v100, v131
	v_cvt_pk_bf16_f32 v97, v101, v129
	v_lshlrev_b64 v[100:101], 11, v[238:239]
	v_lshl_add_u64 v[100:101], s[44:45], 0, v[100:101]
	v_cvt_pk_bf16_f32 v99, v103, v135
	v_lshl_add_u64 v[134:135], v[100:101], 0, v[168:169]
	global_store_dwordx4 v[134:135], v[96:99], off
	v_add_f32_e32 v76, 1.0, v76
	v_rcp_f32_e32 v76, v76
	v_lshl_add_u64 v[96:97], v[144:145], 0, v[216:217]
	v_lshlrev_b64 v[96:97], 1, v[96:97]
	v_lshl_add_u64 v[98:99], s[44:45], 0, v[96:97]
	v_lshl_add_u64 v[96:97], s[40:41], 0, v[96:97]
	global_load_dwordx4 v[100:103], v[98:99], off
	global_load_dwordx4 v[148:151], v[96:97], off
	v_lshl_add_u64 v[96:97], v[146:147], 0, v[216:217]
	v_lshlrev_b64 v[128:129], 1, v[96:97]
	v_lshl_add_u64 v[96:97], s[44:45], 0, v[128:129]
	v_lshl_add_u64 v[128:129], s[40:41], 0, v[128:129]
	global_load_dwordx4 v[96:99], v[96:97], off
	v_pk_fma_f32 v[68:69], v[68:69], v[186:187], v[112:113] op_sel_hi:[1,0,1]
	global_load_dwordx4 v[128:131], v[128:129], off
	v_mul_f32_e32 v68, 0xbfb8aa3b, v68
	v_exp_f32_e32 v68, v68
	v_mul_f32_e32 v69, 0xbfb8aa3b, v69
	v_exp_f32_e32 v69, v69
	v_pk_fma_f32 v[64:65], v[108:109], v[184:185], v[64:65] op_sel_hi:[1,0,1] neg_lo:[1,0,0] neg_hi:[1,0,0]
	v_add_f32_e32 v68, 1.0, v68
	v_rcp_f32_e32 v68, v68
	v_add_f32_e32 v69, 1.0, v69
	v_rcp_f32_e32 v69, v69
	v_pk_fma_f32 v[64:65], v[64:65], v[186:187], v[104:105] op_sel_hi:[1,0,1]
	s_waitcnt vmcnt(0)
	v_lshlrev_b32_e32 v164, 16, v100
	v_lshlrev_b32_e32 v152, 16, v148
	v_and_b32_e32 v153, 0xffff0000, v148
	v_sub_f32_e32 v153, v153, v196
	v_sub_f32_e32 v152, v152, v196
	v_pk_mul_f32 v[152:153], v[198:199], v[152:153] op_sel_hi:[0,1]
	v_pk_fma_f32 v[152:153], v[136:137], v[152:153], v[140:141]
	v_and_b32_e32 v100, 0xffff0000, v100
	v_fmac_f32_e32 v153, v93, v100
	v_mul_f32_e32 v93, 0xbfb8aa3b, v94
	v_exp_f32_e32 v93, v93
	v_lshlrev_b32_e32 v148, 16, v149
	v_and_b32_e32 v149, 0xffff0000, v149
	v_sub_f32_e32 v149, v149, v196
	v_add_f32_e32 v93, 1.0, v93
	v_rcp_f32_e32 v93, v93
	v_sub_f32_e32 v148, v148, v196
	v_pk_mul_f32 v[148:149], v[198:199], v[148:149] op_sel_hi:[0,1]
	v_pk_fma_f32 v[148:149], v[138:139], v[148:149], v[142:143]
	v_lshlrev_b32_e32 v94, 16, v101
	v_fma_f32 v93, v93, v94, v148
	v_mul_f32_e32 v94, 0xbfb8aa3b, v95
	v_exp_f32_e32 v94, v94
	v_lshlrev_b32_e32 v154, 16, v150
	v_and_b32_e32 v155, 0xffff0000, v150
	v_sub_f32_e32 v155, v155, v196
	v_add_f32_e32 v94, 1.0, v94
	v_rcp_f32_e32 v94, v94
	v_sub_f32_e32 v154, v154, v196
	v_pk_mul_f32 v[154:155], v[198:199], v[154:155] op_sel_hi:[0,1]
	v_and_b32_e32 v95, 0xffff0000, v101
	v_pk_fma_f32 v[154:155], v[120:121], v[154:155], v[124:125]
	v_fmac_f32_e32 v149, v94, v95
	v_lshlrev_b32_e32 v94, 16, v102
	v_fma_f32 v94, v88, v94, v154
	v_mul_f32_e32 v88, 0xbfb8aa3b, v89
	v_exp_f32_e32 v88, v88
	v_and_b32_e32 v89, 0xffff0000, v102
	v_lshlrev_b32_e32 v150, 16, v151
	v_and_b32_e32 v151, 0xffff0000, v151
	v_add_f32_e32 v88, 1.0, v88
	v_rcp_f32_e32 v88, v88
	v_sub_f32_e32 v151, v151, v196
	v_sub_f32_e32 v150, v150, v196
	v_pk_mul_f32 v[150:151], v[198:199], v[150:151] op_sel_hi:[0,1]
	v_fmac_f32_e32 v155, v88, v89
	v_mul_f32_e32 v88, 0xbfb8aa3b, v90
	v_exp_f32_e32 v88, v88
	v_pk_fma_f32 v[150:151], v[122:123], v[150:151], v[126:127]
	v_lshlrev_b32_e32 v89, 16, v103
; __device__ __forceinline__ unsigned cvt_pk_bf16(float lo, float hi) { unsigned r; asm("v_cvt_pk_bf16_f32 %0, %1, %2" : "=v"(r) : "v"(lo), "v"(hi)); return r; }
; __device__ __forceinline__ float fast_sigmoid(float v) { return __builtin_amdgcn_rcpf(1.0f + __builtin_amdgcn_exp2f(-1.4426950408889634f * v)); }
;     __device__ __forceinline__ void operator()(const f32x4 (&acc)[2][2][4][2], const Unit& u, int wr, int wc, int fr_in, int fq_in) const {
;     ...
;             for (int am = 0; am < (FINAL ? 8 : 4); ++am) { constexpr int GR = FINAL ? 1 : 2; const int ai = (am * GR) >> 2; u32x4 ppw[4], pzw[4];
; #pragma unroll
;                 for (int m = (am * GR) & 3; m < ((am * GR) & 3) + GR; ++m) { const size_t off = (size_t)(row0 + ai * HALF + m * 16) * 1024 + col0 + bj * HALF; ppw[m] = *(const u32x4*)(pexb + off); pzw[m] = *(const u32x4*)(zb + off); }
;                 asm volatile("" ::: "memory");
; #pragma unroll
;                 for (int m = (am * GR) & 3; m < ((am * GR) & 3) + GR; ++m) { const size_t off = (size_t)(row0 + ai * HALF + m * 16) * 1024 + col0 + bj * HALF; const float mu = rst.mu[ai][m], rs = rst.rs[ai][m];
;                     const u32x4 pw = ppw[m]; const u32x4 zw = pzw[m];
;                     const f32x4 x0 = ((f32x4){bf_lo(zw.x), bf_hi(zw.x), bf_lo(zw.y), bf_hi(zw.y)} - mu) * rs * gv[0] + bv[0], x1 = ((f32x4){bf_lo(zw.z), bf_hi(zw.z), bf_lo(zw.w), bf_hi(zw.w)} - mu) * rs * gv[1] + bv[1];
;                     const f32x4 a0 = ln_fix(acc[ai][bj][m][0], mu, rs, csv[0], cbv[0]), a1 = ln_fix(acc[ai][bj][m][1], mu, rs, csv[1], cbv[1]); f32x4 o0, o1;
;                     o0[0] = x0[0] + fast_sigmoid(a0[0]) * bf_lo(pw.x); o0[1] = x0[1] + fast_sigmoid(a0[1]) * bf_hi(pw.x);
;                     o0[2] = x0[2] + fast_sigmoid(a0[2]) * bf_lo(pw.y); o0[3] = x0[3] + fast_sigmoid(a0[3]) * bf_hi(pw.y);
;                     o1[0] = x1[0] + fast_sigmoid(a1[0]) * bf_lo(pw.z); o1[1] = x1[1] + fast_sigmoid(a1[1]) * bf_hi(pw.z);
;                     o1[2] = x1[2] + fast_sigmoid(a1[2]) * bf_lo(pw.w); o1[3] = x1[3] + fast_sigmoid(a1[3]) * bf_hi(pw.w);
;                     if constexpr (FINAL) { *(f32x4*)(outf + off) = o0; *(f32x4*)(outf + off + 4) = o1; }
;                     else { u32x4 w; w.x = cvt_pk_bf16(o0[0], o0[1]); w.y = cvt_pk_bf16(o0[2], o0[3]); w.z = cvt_pk_bf16(o1[0], o1[1]); w.w = cvt_pk_bf16(o1[2], o1[3]); *(u32x4*)(pexb + off) = w; } } } }
	v_fma_f32 v92, v92, v164, v152
	v_add_f32_e32 v88, 1.0, v88
	v_rcp_f32_e32 v88, v88
	v_cvt_pk_bf16_f32 v90, v94, v155
	v_lshlrev_b32_e32 v102, 16, v96
	v_lshlrev_b32_e32 v94, 16, v130
	v_fma_f32 v95, v88, v89, v150
	v_mul_f32_e32 v88, 0xbfb8aa3b, v91
	v_exp_f32_e32 v88, v88
	v_and_b32_e32 v89, 0xffff0000, v103
	v_sub_f32_e32 v94, v94, v192
	v_mul_f32_e32 v64, 0xbfb8aa3b, v64
	v_add_f32_e32 v88, 1.0, v88
	v_rcp_f32_e32 v88, v88
	v_exp_f32_e32 v64, v64
	v_fmac_f32_e32 v151, v88, v89
	v_cvt_pk_bf16_f32 v88, v92, v153
	v_cvt_pk_bf16_f32 v89, v93, v149
	v_lshlrev_b64 v[92:93], 11, v[236:237]
	v_lshl_add_u64 v[92:93], s[44:45], 0, v[92:93]
	v_cvt_pk_bf16_f32 v91, v95, v151
	v_lshl_add_u64 v[148:149], v[92:93], 0, v[168:169]
	v_lshlrev_b32_e32 v92, 16, v131
	v_and_b32_e32 v93, 0xffff0000, v131
	global_store_dwordx4 v[148:149], v[88:91], off
	v_sub_f32_e32 v93, v93, v192
	v_sub_f32_e32 v92, v92, v192
	v_lshlrev_b32_e32 v90, 16, v128
	v_and_b32_e32 v91, 0xffff0000, v128
	v_sub_f32_e32 v91, v91, v192
	v_sub_f32_e32 v90, v90, v192
	v_pk_mul_f32 v[92:93], v[194:195], v[92:93] op_sel_hi:[0,1]
	v_pk_mul_f32 v[90:91], v[194:195], v[90:91] op_sel_hi:[0,1]
	v_pk_fma_f32 v[100:101], v[122:123], v[92:93], v[126:127]
	v_xor_b32_e32 v93, 0x80000000, v119
	v_xor_b32_e32 v92, 0x80000000, v118
	v_pk_fma_f32 v[90:91], v[136:137], v[90:91], v[140:141]
	v_pk_fma_f32 v[86:87], v[92:93], v[192:193], v[86:87] op_sel_hi:[1,0,1]
	v_fma_f32 v84, v84, v102, v90
	v_pk_fma_f32 v[86:87], v[86:87], v[194:195], v[114:115] op_sel_hi:[1,0,1]
	v_and_b32_e32 v90, 0xffff0000, v96
	v_fmac_f32_e32 v91, v85, v90
	v_mul_f32_e32 v85, 0xbfb8aa3b, v86
	v_exp_f32_e32 v85, v85
	v_lshlrev_b32_e32 v88, 16, v129
	v_and_b32_e32 v89, 0xffff0000, v129
	v_sub_f32_e32 v89, v89, v192
	v_add_f32_e32 v85, 1.0, v85
	v_rcp_f32_e32 v85, v85
	v_sub_f32_e32 v88, v88, v192
	v_pk_mul_f32 v[88:89], v[194:195], v[88:89] op_sel_hi:[0,1]
	v_pk_fma_f32 v[88:89], v[138:139], v[88:89], v[142:143]
	v_lshlrev_b32_e32 v86, 16, v97
	v_fma_f32 v85, v85, v86, v88
	v_mul_f32_e32 v86, 0xbfb8aa3b, v87
	v_exp_f32_e32 v86, v86
	v_and_b32_e32 v95, 0xffff0000, v130
	v_sub_f32_e32 v95, v95, v192
	v_pk_mul_f32 v[94:95], v[194:195], v[94:95] op_sel_hi:[0,1]
	v_add_f32_e32 v86, 1.0, v86
	v_rcp_f32_e32 v86, v86
	v_and_b32_e32 v87, 0xffff0000, v97
	v_pk_fma_f32 v[94:95], v[120:121], v[94:95], v[124:125]
	v_lshlrev_b64 v[128:129], 10, v[220:221]
	v_fmac_f32_e32 v89, v86, v87
	v_lshlrev_b32_e32 v86, 16, v98
	v_fma_f32 v86, v80, v86, v94
	v_mul_f32_e32 v80, 0xbfb8aa3b, v81
	v_exp_f32_e32 v80, v80
	v_and_b32_e32 v81, 0xffff0000, v98
	v_lshlrev_b64 v[130:131], 10, v[218:219]
	v_pk_fma_f32 v[78:79], v[92:93], v[188:189], v[78:79] op_sel_hi:[1,0,1]
	v_add_f32_e32 v80, 1.0, v80
	v_rcp_f32_e32 v80, v80
	v_pk_fma_f32 v[78:79], v[78:79], v[190:191], v[114:115] op_sel_hi:[1,0,1]
	v_pk_fma_f32 v[70:71], v[92:93], v[184:185], v[70:71] op_sel_hi:[1,0,1]
	v_add_f32_e32 v64, 1.0, v64
	v_fmac_f32_e32 v95, v80, v81
	v_mul_f32_e32 v80, 0xbfb8aa3b, v82
	v_exp_f32_e32 v80, v80
	v_lshlrev_b32_e32 v81, 16, v99
	v_cvt_pk_bf16_f32 v82, v86, v95
	v_pk_fma_f32 v[70:71], v[70:71], v[186:187], v[114:115] op_sel_hi:[1,0,1]
	v_add_f32_e32 v80, 1.0, v80
	v_rcp_f32_e32 v80, v80
	v_rcp_f32_e32 v64, v64
	v_fma_f32 v87, v80, v81, v100
	v_mul_f32_e32 v80, 0xbfb8aa3b, v83
	v_exp_f32_e32 v80, v80
	v_and_b32_e32 v81, 0xffff0000, v99
	v_add_f32_e32 v80, 1.0, v80
	v_rcp_f32_e32 v80, v80
	s_nop 0
	v_fmac_f32_e32 v101, v80, v81
	v_cvt_pk_bf16_f32 v80, v84, v91
	v_cvt_pk_bf16_f32 v81, v85, v89
	v_lshlrev_b64 v[84:85], 11, v[234:235]
	v_lshl_add_u64 v[84:85], s[44:45], 0, v[84:85]
	v_lshl_add_u64 v[118:119], v[84:85], 0, v[168:169]
	v_cvt_pk_bf16_f32 v83, v87, v101
	global_store_dwordx4 v[118:119], v[80:83], off
	s_nop 1
	v_lshl_add_u64 v[80:81], v[128:129], 0, v[216:217]
	v_lshlrev_b64 v[80:81], 1, v[80:81]
	v_lshl_add_u64 v[82:83], s[44:45], 0, v[80:81]
	v_lshl_add_u64 v[80:81], s[40:41], 0, v[80:81]
	global_load_dwordx4 v[84:87], v[82:83], off
	global_load_dwordx4 v[94:97], v[80:81], off
	v_lshl_add_u64 v[80:81], v[130:131], 0, v[216:217]
	v_lshlrev_b64 v[88:89], 1, v[80:81]
	v_lshl_add_u64 v[80:81], s[44:45], 0, v[88:89]
	v_lshl_add_u64 v[88:89], s[40:41], 0, v[88:89]
	global_load_dwordx4 v[80:83], v[80:81], off
	s_waitcnt vmcnt(0)
; __device__ __forceinline__ float bf_lo(unsigned w) { return __uint_as_float(w << 16); }
;     __device__ __forceinline__ void operator()(const f32x4 (&acc)[2][2][4][2], const Unit& u, int wr, int wc, int fr_in, int fq_in) const {
;     ...
;         for (int bj = 0; bj < 2; ++bj) { f32x4 csv[2], cbv[2], gv[2], bv[2];
; #pragma unroll
;             for (int n = 0; n < 2; ++n) { csv[n] = *(const f32x4*)(cs + col0 + bj * HALF + 4 * n); cbv[n] = *(const f32x4*)(cb + col0 + bj * HALF + 4 * n); gv[n] = *(const f32x4*)(lg + col0 + bj * HALF + 4 * n); bv[n] = *(const f32x4*)(lb + col0 + bj * HALF + 4 * n); }
; #pragma unroll
;             for (int am = 0; am < (FINAL ? 8 : 4); ++am) { constexpr int GR = FINAL ? 1 : 2; const int ai = (am * GR) >> 2; u32x4 ppw[4], pzw[4];
; #pragma unroll
;                 for (int m = (am * GR) & 3; m < ((am * GR) & 3) + GR; ++m) { const size_t off = (size_t)(row0 + ai * HALF + m * 16) * 1024 + col0 + bj * HALF; ppw[m] = *(const u32x4*)(pexb + off); pzw[m] = *(const u32x4*)(zb + off); }
;                 asm volatile("" ::: "memory");
; #pragma unroll
;                 for (int m = (am * GR) & 3; m < ((am * GR) & 3) + GR; ++m) { const size_t off = (size_t)(row0 + ai * HALF + m * 16) * 1024 + col0 + bj * HALF; const float mu = rst.mu[ai][m], rs = rst.rs[ai][m];
;                     const u32x4 pw = ppw[m]; const u32x4 zw = pzw[m];
;                     const f32x4 x0 = ((f32x4){bf_lo(zw.x), bf_hi(zw.x), bf_lo(zw.y), bf_hi(zw.y)} - mu) * rs * gv[0] + bv[0], x1 = ((f32x4){bf_lo(zw.z), bf_hi(zw.z), bf_lo(zw.w), bf_hi(zw.w)} - mu) * rs * gv[1] + bv[1];
;                     const f32x4 a0 = ln_fix(acc[ai][bj][m][0], mu, rs, csv[0], cbv[0]), a1 = ln_fix(acc[ai][bj][m][1], mu, rs, csv[1], cbv[1]); f32x4 o0, o1;
;                     o0[0] = x0[0] + fast_sigmoid(a0[0]) * bf_lo(pw.x); o0[1] = x0[1] + fast_sigmoid(a0[1]) * bf_hi(pw.x);
;                     o0[2] = x0[2] + fast_sigmoid(a0[2]) * bf_lo(pw.y); o0[3] = x0[3] + fast_sigmoid(a0[3]) * bf_hi(pw.y);
;                     o1[0] = x1[0] + fast_sigmoid(a1[0]) * bf_lo(pw.z); o1[1] = x1[1] + fast_sigmoid(a1[1]) * bf_hi(pw.z);
;                     o1[2] = x1[2] + fast_sigmoid(a1[2]) * bf_lo(pw.w); o1[3] = x1[3] + fast_sigmoid(a1[3]) * bf_hi(pw.w);
;                     if constexpr (FINAL) { *(f32x4*)(outf + off) = o0; *(f32x4*)(outf + off + 4) = o1; }
	v_lshlrev_b32_e32 v102, 16, v84
	global_load_dwordx4 v[88:91], v[88:89], off
	v_lshlrev_b32_e32 v98, 16, v94
	v_and_b32_e32 v99, 0xffff0000, v94
	v_sub_f32_e32 v99, v99, v188
	v_sub_f32_e32 v98, v98, v188
	v_pk_mul_f32 v[98:99], v[190:191], v[98:99] op_sel_hi:[0,1]
	v_pk_fma_f32 v[98:99], v[136:137], v[98:99], v[140:141]
	v_and_b32_e32 v84, 0xffff0000, v84
	v_fmac_f32_e32 v99, v77, v84
	v_mul_f32_e32 v77, 0xbfb8aa3b, v78
	v_exp_f32_e32 v77, v77
	v_lshlrev_b32_e32 v94, 16, v95
	v_and_b32_e32 v95, 0xffff0000, v95
	v_sub_f32_e32 v95, v95, v188
	v_add_f32_e32 v77, 1.0, v77
	v_rcp_f32_e32 v77, v77
	v_sub_f32_e32 v94, v94, v188
	v_pk_mul_f32 v[94:95], v[190:191], v[94:95] op_sel_hi:[0,1]
	v_pk_fma_f32 v[94:95], v[138:139], v[94:95], v[142:143]
	v_lshlrev_b32_e32 v78, 16, v85
	v_fma_f32 v77, v77, v78, v94
	v_mul_f32_e32 v78, 0xbfb8aa3b, v79
	v_exp_f32_e32 v78, v78
	v_lshlrev_b32_e32 v100, 16, v96
	v_and_b32_e32 v101, 0xffff0000, v96
	v_sub_f32_e32 v101, v101, v188
	v_add_f32_e32 v78, 1.0, v78
	v_rcp_f32_e32 v78, v78
	v_sub_f32_e32 v100, v100, v188
	v_pk_mul_f32 v[100:101], v[190:191], v[100:101] op_sel_hi:[0,1]
	v_and_b32_e32 v79, 0xffff0000, v85
	v_pk_fma_f32 v[100:101], v[120:121], v[100:101], v[124:125]
	v_fmac_f32_e32 v95, v78, v79
	v_lshlrev_b32_e32 v78, 16, v86
	v_fma_f32 v78, v72, v78, v100
	v_mul_f32_e32 v72, 0xbfb8aa3b, v73
	v_exp_f32_e32 v72, v72
	v_and_b32_e32 v73, 0xffff0000, v86
	v_lshlrev_b32_e32 v96, 16, v97
	v_and_b32_e32 v97, 0xffff0000, v97
	v_add_f32_e32 v72, 1.0, v72
	v_rcp_f32_e32 v72, v72
	v_sub_f32_e32 v97, v97, v188
	v_sub_f32_e32 v96, v96, v188
	v_pk_mul_f32 v[96:97], v[190:191], v[96:97] op_sel_hi:[0,1]
	v_fmac_f32_e32 v101, v72, v73
	v_mul_f32_e32 v72, 0xbfb8aa3b, v74
	v_exp_f32_e32 v72, v72
	v_pk_fma_f32 v[96:97], v[122:123], v[96:97], v[126:127]
	v_lshlrev_b32_e32 v73, 16, v87
	v_fma_f32 v76, v76, v102, v98
	v_add_f32_e32 v72, 1.0, v72
	v_rcp_f32_e32 v72, v72
	v_cvt_pk_bf16_f32 v74, v78, v101
	v_xor_b32_e32 v85, 0x80000000, v111
	v_fma_f32 v79, v72, v73, v96
	v_mul_f32_e32 v72, 0xbfb8aa3b, v75
	v_exp_f32_e32 v72, v72
	v_and_b32_e32 v73, 0xffff0000, v87
	v_xor_b32_e32 v84, 0x80000000, v110
	v_pk_fma_f32 v[66:67], v[84:85], v[184:185], v[66:67] op_sel_hi:[1,0,1]
	v_add_f32_e32 v72, 1.0, v72
	v_rcp_f32_e32 v72, v72
	v_lshlrev_b32_e32 v84, 16, v80
	v_pk_fma_f32 v[66:67], v[66:67], v[186:187], v[106:107] op_sel_hi:[1,0,1]
	v_lshl_add_u64 v[110:111], v[216:217], 0, s[52:53]
	v_fmac_f32_e32 v97, v72, v73
	v_cvt_pk_bf16_f32 v72, v76, v99
	v_cvt_pk_bf16_f32 v73, v77, v95
	v_lshlrev_b64 v[76:77], 11, v[220:221]
	v_lshl_add_u64 v[76:77], s[44:45], 0, v[76:77]
	v_cvt_pk_bf16_f32 v75, v79, v97
	v_lshl_add_u64 v[150:151], v[76:77], 0, v[168:169]
	global_store_dwordx4 v[150:151], v[72:75], off
	v_lshl_add_u64 v[96:97], v[110:111], 0, v[230:231]
	v_lshl_add_u64 v[96:97], v[96:97], 1, s[40:41]
	v_lshl_add_u64 v[104:105], v[110:111], 0, v[232:233]
	v_lshl_add_u64 v[104:105], v[104:105], 1, s[40:41]
	s_waitcnt vmcnt(0)
	v_lshlrev_b32_e32 v74, 16, v88
	v_and_b32_e32 v75, 0xffff0000, v88
	v_sub_f32_e32 v75, v75, v184
	v_sub_f32_e32 v74, v74, v184
	v_pk_mul_f32 v[74:75], v[186:187], v[74:75] op_sel_hi:[0,1]
	v_pk_fma_f32 v[74:75], v[136:137], v[74:75], v[140:141]
	v_lshlrev_b32_e32 v72, 16, v89
	v_fma_f32 v68, v68, v84, v74
	v_and_b32_e32 v74, 0xffff0000, v80
	v_fmac_f32_e32 v75, v69, v74
	v_mul_f32_e32 v69, 0xbfb8aa3b, v70
	v_exp_f32_e32 v69, v69
	v_and_b32_e32 v73, 0xffff0000, v89
	v_sub_f32_e32 v73, v73, v184
	v_sub_f32_e32 v72, v72, v184
	v_add_f32_e32 v69, 1.0, v69
	v_rcp_f32_e32 v69, v69
	v_pk_mul_f32 v[72:73], v[186:187], v[72:73] op_sel_hi:[0,1]
	v_pk_fma_f32 v[72:73], v[138:139], v[72:73], v[142:143]
	v_lshlrev_b32_e32 v70, 16, v81
	v_fma_f32 v69, v69, v70, v72
	v_mul_f32_e32 v70, 0xbfb8aa3b, v71
	v_exp_f32_e32 v70, v70
	v_lshlrev_b32_e32 v78, 16, v90
	v_and_b32_e32 v79, 0xffff0000, v90
	v_sub_f32_e32 v79, v79, v184
	v_add_f32_e32 v70, 1.0, v70
	v_rcp_f32_e32 v70, v70
	v_sub_f32_e32 v78, v78, v184
	v_pk_mul_f32 v[78:79], v[186:187], v[78:79] op_sel_hi:[0,1]
	v_and_b32_e32 v71, 0xffff0000, v81
	v_pk_fma_f32 v[78:79], v[120:121], v[78:79], v[124:125]
	v_fmac_f32_e32 v73, v70, v71
	v_lshlrev_b32_e32 v70, 16, v82
	v_fma_f32 v70, v64, v70, v78
	v_mul_f32_e32 v64, 0xbfb8aa3b, v65
	v_exp_f32_e32 v64, v64
	v_and_b32_e32 v65, 0xffff0000, v82
	v_lshlrev_b32_e32 v76, 16, v91
	v_and_b32_e32 v77, 0xffff0000, v91
	v_add_f32_e32 v64, 1.0, v64
	v_rcp_f32_e32 v64, v64
	v_sub_f32_e32 v77, v77, v184
	v_sub_f32_e32 v76, v76, v184
	v_pk_mul_f32 v[76:77], v[186:187], v[76:77] op_sel_hi:[0,1]
	v_fmac_f32_e32 v79, v64, v65
	v_mul_f32_e32 v64, 0xbfb8aa3b, v66
	v_exp_f32_e32 v64, v64
	v_pk_fma_f32 v[76:77], v[122:123], v[76:77], v[126:127]
	v_lshlrev_b32_e32 v65, 16, v83
	v_cvt_pk_bf16_f32 v66, v70, v79
	v_add_f32_e32 v64, 1.0, v64
	v_rcp_f32_e32 v64, v64
	s_nop 0
	v_fma_f32 v71, v64, v65, v76
	v_mul_f32_e32 v64, 0xbfb8aa3b, v67
	v_exp_f32_e32 v64, v64
	v_and_b32_e32 v65, 0xffff0000, v83
	v_add_f32_e32 v64, 1.0, v64
	v_rcp_f32_e32 v64, v64
	s_nop 0
	v_fmac_f32_e32 v77, v64, v65
	v_cvt_pk_bf16_f32 v64, v68, v75
	v_cvt_pk_bf16_f32 v65, v69, v73
	v_lshlrev_b64 v[68:69], 11, v[218:219]
	v_lshl_add_u64 v[68:69], s[44:45], 0, v[68:69]
	v_lshl_add_u64 v[108:109], v[68:69], 0, v[168:169]
	v_cvt_pk_bf16_f32 v67, v71, v77
	global_store_dwordx4 v[108:109], v[64:67], off
	global_load_dwordx4 v[64:67], v[228:229], off offset:528
	s_nop 0
	global_load_dwordx4 v[72:75], v[228:229], off offset:512
	global_load_dwordx4 v[68:71], v[226:227], off offset:528
	global_load_dwordx4 v[76:79], v[226:227], off offset:512
	global_load_dwordx4 v[80:83], v[224:225], off offset:528
	global_load_dwordx4 v[88:91], v[224:225], off offset:512
	global_load_dwordx4 v[84:87], v[222:223], off offset:528
	global_load_dwordx4 v[92:95], v[222:223], off offset:512
	global_load_dwordx4 v[112:115], v[96:97], off
	global_load_dwordx4 v[100:103], v[156:157], off offset:256
	s_waitcnt vmcnt(0)
; __device__ __forceinline__ unsigned cvt_pk_bf16(float lo, float hi) { unsigned r; asm("v_cvt_pk_bf16_f32 %0, %1, %2" : "=v"(r) : "v"(lo), "v"(hi)); return r; }
; __device__ __forceinline__ float fast_sigmoid(float v) { return __builtin_amdgcn_rcpf(1.0f + __builtin_amdgcn_exp2f(-1.4426950408889634f * v)); }
;     __device__ __forceinline__ void operator()(const f32x4 (&acc)[2][2][4][2], const Unit& u, int wr, int wc, int fr_in, int fq_in) const {
;     ...
;             for (int am = 0; am < (FINAL ? 8 : 4); ++am) { constexpr int GR = FINAL ? 1 : 2; const int ai = (am * GR) >> 2; u32x4 ppw[4], pzw[4];
; #pragma unroll
;                 for (int m = (am * GR) & 3; m < ((am * GR) & 3) + GR; ++m) { const size_t off = (size_t)(row0 + ai * HALF + m * 16) * 1024 + col0 + bj * HALF; ppw[m] = *(const u32x4*)(pexb + off); pzw[m] = *(const u32x4*)(zb + off); }
;                 asm volatile("" ::: "memory");
; #pragma unroll
;                 for (int m = (am * GR) & 3; m < ((am * GR) & 3) + GR; ++m) { const size_t off = (size_t)(row0 + ai * HALF + m * 16) * 1024 + col0 + bj * HALF; const float mu = rst.mu[ai][m], rs = rst.rs[ai][m];
;                     const u32x4 pw = ppw[m]; const u32x4 zw = pzw[m];
;                     const f32x4 x0 = ((f32x4){bf_lo(zw.x), bf_hi(zw.x), bf_lo(zw.y), bf_hi(zw.y)} - mu) * rs * gv[0] + bv[0], x1 = ((f32x4){bf_lo(zw.z), bf_hi(zw.z), bf_lo(zw.w), bf_hi(zw.w)} - mu) * rs * gv[1] + bv[1];
;                     const f32x4 a0 = ln_fix(acc[ai][bj][m][0], mu, rs, csv[0], cbv[0]), a1 = ln_fix(acc[ai][bj][m][1], mu, rs, csv[1], cbv[1]); f32x4 o0, o1;
;                     o0[0] = x0[0] + fast_sigmoid(a0[0]) * bf_lo(pw.x); o0[1] = x0[1] + fast_sigmoid(a0[1]) * bf_hi(pw.x);
;                     o0[2] = x0[2] + fast_sigmoid(a0[2]) * bf_lo(pw.y); o0[3] = x0[3] + fast_sigmoid(a0[3]) * bf_hi(pw.y);
;                     o1[0] = x1[0] + fast_sigmoid(a1[0]) * bf_lo(pw.z); o1[1] = x1[1] + fast_sigmoid(a1[1]) * bf_hi(pw.z);
;                     o1[2] = x1[2] + fast_sigmoid(a1[2]) * bf_lo(pw.w); o1[3] = x1[3] + fast_sigmoid(a1[3]) * bf_hi(pw.w);
;                     if constexpr (FINAL) { *(f32x4*)(outf + off) = o0; *(f32x4*)(outf + off + 4) = o1; }
;                     else { u32x4 w; w.x = cvt_pk_bf16(o0[0], o0[1]); w.y = cvt_pk_bf16(o0[2], o0[3]); w.z = cvt_pk_bf16(o1[0], o1[1]); w.w = cvt_pk_bf16(o1[2], o1[3]); *(u32x4*)(pexb + off) = w; } } } }
	v_pk_fma_f32 v[56:57], v[212:213], v[64:65], v[56:57] op_sel_hi:[0,1,1] neg_lo:[1,0,0] neg_hi:[1,0,0]
	global_load_dwordx4 v[104:107], v[104:105], off
	v_pk_fma_f32 v[60:61], v[212:213], v[72:73], v[60:61] op_sel_hi:[0,1,1] neg_lo:[1,0,0] neg_hi:[1,0,0]
	global_load_dwordx4 v[96:99], v[158:159], off offset:256
	v_pk_fma_f32 v[60:61], v[214:215], v[60:61], v[76:77] op_sel_hi:[0,1,1]
	v_mul_f32_e32 v61, 0xbfb8aa3b, v61
	v_exp_f32_e32 v61, v61
	v_pk_fma_f32 v[62:63], v[212:213], v[74:75], v[62:63] op_sel_hi:[0,1,1] neg_lo:[1,0,0] neg_hi:[1,0,0]
	v_lshlrev_b32_e32 v116, 16, v112
	v_and_b32_e32 v117, 0xffff0000, v112
	v_add_f32_e32 v61, 1.0, v61
	v_rcp_f32_e32 v61, v61
	v_sub_f32_e32 v117, v117, v212
	v_sub_f32_e32 v116, v116, v212
	v_pk_mul_f32 v[116:117], v[214:215], v[116:117] op_sel_hi:[0,1]
	v_pk_fma_f32 v[116:117], v[88:89], v[116:117], v[92:93]
	v_pk_fma_f32 v[62:63], v[214:215], v[62:63], v[78:79] op_sel_hi:[0,1,1]
	v_lshlrev_b32_e32 v122, 16, v100
	v_and_b32_e32 v100, 0xffff0000, v100
	v_fmac_f32_e32 v117, v61, v100
	v_mul_f32_e32 v61, 0xbfb8aa3b, v62
	v_exp_f32_e32 v61, v61
	v_lshlrev_b32_e32 v112, 16, v113
	v_and_b32_e32 v113, 0xffff0000, v113
	v_sub_f32_e32 v113, v113, v212
	v_add_f32_e32 v61, 1.0, v61
	v_rcp_f32_e32 v61, v61
	v_sub_f32_e32 v112, v112, v212
	v_pk_mul_f32 v[112:113], v[214:215], v[112:113] op_sel_hi:[0,1]
	v_pk_fma_f32 v[112:113], v[90:91], v[112:113], v[94:95]
	v_lshlrev_b32_e32 v62, 16, v101
	v_pk_fma_f32 v[56:57], v[214:215], v[56:57], v[68:69] op_sel_hi:[0,1,1]
	v_fma_f32 v61, v61, v62, v112
	v_mul_f32_e32 v62, 0xbfb8aa3b, v63
	v_exp_f32_e32 v62, v62
	v_mul_f32_e32 v56, 0xbfb8aa3b, v56
	v_exp_f32_e32 v56, v56
	v_lshlrev_b32_e32 v120, 16, v114
	v_add_f32_e32 v62, 1.0, v62
	v_rcp_f32_e32 v62, v62
	v_add_f32_e32 v56, 1.0, v56
	v_and_b32_e32 v121, 0xffff0000, v114
	v_rcp_f32_e32 v56, v56
	v_sub_f32_e32 v121, v121, v212
	v_sub_f32_e32 v120, v120, v212
	v_pk_mul_f32 v[120:121], v[214:215], v[120:121] op_sel_hi:[0,1]
	v_and_b32_e32 v63, 0xffff0000, v101
	v_pk_fma_f32 v[120:121], v[80:81], v[120:121], v[84:85]
	v_fmac_f32_e32 v113, v62, v63
	v_lshlrev_b32_e32 v62, 16, v102
	v_fma_f32 v62, v56, v62, v120
	v_mul_f32_e32 v56, 0xbfb8aa3b, v57
	v_exp_f32_e32 v56, v56
	v_pk_fma_f32 v[58:59], v[212:213], v[66:67], v[58:59] op_sel_hi:[0,1,1] neg_lo:[1,0,0] neg_hi:[1,0,0]
	v_pk_fma_f32 v[58:59], v[214:215], v[58:59], v[70:71] op_sel_hi:[0,1,1]
	v_and_b32_e32 v57, 0xffff0000, v102
	v_add_f32_e32 v56, 1.0, v56
	v_rcp_f32_e32 v56, v56
	v_lshlrev_b32_e32 v114, 16, v115
	v_and_b32_e32 v115, 0xffff0000, v115
	v_sub_f32_e32 v115, v115, v212
	v_fmac_f32_e32 v121, v56, v57
	v_mul_f32_e32 v56, 0xbfb8aa3b, v58
	v_exp_f32_e32 v56, v56
	v_sub_f32_e32 v114, v114, v212
	v_pk_mul_f32 v[114:115], v[214:215], v[114:115] op_sel_hi:[0,1]
	v_pk_fma_f32 v[114:115], v[82:83], v[114:115], v[86:87]
	v_add_f32_e32 v56, 1.0, v56
	v_rcp_f32_e32 v56, v56
	v_lshlrev_b32_e32 v57, 16, v103
	v_mul_f32_e32 v60, 0xbfb8aa3b, v60
	v_exp_f32_e32 v60, v60
	v_fma_f32 v63, v56, v57, v114
	v_mul_f32_e32 v56, 0xbfb8aa3b, v59
	v_exp_f32_e32 v56, v56
	v_pk_fma_f32 v[52:53], v[208:209], v[72:73], v[52:53] op_sel_hi:[0,1,1] neg_lo:[1,0,0] neg_hi:[1,0,0]
	v_pk_fma_f32 v[52:53], v[210:211], v[52:53], v[76:77] op_sel_hi:[0,1,1]
	v_mul_f32_e32 v52, 0xbfb8aa3b, v52
	v_add_f32_e32 v56, 1.0, v56
	v_add_f32_e32 v60, 1.0, v60
	v_rcp_f32_e32 v56, v56
	v_exp_f32_e32 v52, v52
	v_mul_f32_e32 v53, 0xbfb8aa3b, v53
	v_rcp_f32_e32 v60, v60
	v_exp_f32_e32 v53, v53
	v_and_b32_e32 v57, 0xffff0000, v103
	v_fmac_f32_e32 v115, v56, v57
	v_cvt_pk_bf16_f32 v58, v62, v121
	v_cvt_pk_bf16_f32 v59, v63, v115
	v_add_f32_e32 v52, 1.0, v52
	v_fma_f32 v60, v60, v122, v116
	v_cvt_pk_bf16_f32 v56, v60, v117
	v_cvt_pk_bf16_f32 v57, v61, v113
	global_store_dwordx4 v[156:157], v[56:59], off offset:256
	v_rcp_f32_e32 v52, v52
	v_add_f32_e32 v53, 1.0, v53
	s_waitcnt vmcnt(0)
	v_lshlrev_b32_e32 v58, 16, v104
	v_and_b32_e32 v59, 0xffff0000, v104
	v_sub_f32_e32 v59, v59, v208
	v_sub_f32_e32 v58, v58, v208
	v_rcp_f32_e32 v53, v53
	v_pk_mul_f32 v[58:59], v[210:211], v[58:59] op_sel_hi:[0,1]
	v_pk_fma_f32 v[58:59], v[88:89], v[58:59], v[92:93]
	v_pk_fma_f32 v[54:55], v[208:209], v[74:75], v[54:55] op_sel_hi:[0,1,1] neg_lo:[1,0,0] neg_hi:[1,0,0]
	v_lshlrev_b32_e32 v100, 16, v96
	v_pk_fma_f32 v[54:55], v[210:211], v[54:55], v[78:79] op_sel_hi:[0,1,1]
	v_fma_f32 v52, v52, v100, v58
	v_and_b32_e32 v58, 0xffff0000, v96
	v_fmac_f32_e32 v59, v53, v58
	v_mul_f32_e32 v53, 0xbfb8aa3b, v54
	v_exp_f32_e32 v53, v53
	v_lshlrev_b32_e32 v56, 16, v105
	v_and_b32_e32 v57, 0xffff0000, v105
	v_sub_f32_e32 v57, v57, v208
	v_add_f32_e32 v53, 1.0, v53
	v_rcp_f32_e32 v53, v53
	v_sub_f32_e32 v56, v56, v208
	v_pk_mul_f32 v[56:57], v[210:211], v[56:57] op_sel_hi:[0,1]
	v_pk_fma_f32 v[56:57], v[90:91], v[56:57], v[94:95]
	v_pk_fma_f32 v[48:49], v[208:209], v[64:65], v[48:49] op_sel_hi:[0,1,1] neg_lo:[1,0,0] neg_hi:[1,0,0]
	v_lshlrev_b32_e32 v54, 16, v97
	v_pk_fma_f32 v[48:49], v[210:211], v[48:49], v[68:69] op_sel_hi:[0,1,1]
	v_fma_f32 v53, v53, v54, v56
	v_mul_f32_e32 v54, 0xbfb8aa3b, v55
	v_exp_f32_e32 v54, v54
	v_mul_f32_e32 v48, 0xbfb8aa3b, v48
	v_exp_f32_e32 v48, v48
	v_lshlrev_b32_e32 v62, 16, v106
	v_add_f32_e32 v54, 1.0, v54
	v_rcp_f32_e32 v54, v54
	v_add_f32_e32 v48, 1.0, v48
	v_and_b32_e32 v63, 0xffff0000, v106
	v_rcp_f32_e32 v48, v48
	v_sub_f32_e32 v63, v63, v208
	v_sub_f32_e32 v62, v62, v208
	v_pk_mul_f32 v[62:63], v[210:211], v[62:63] op_sel_hi:[0,1]
	v_and_b32_e32 v55, 0xffff0000, v97
	v_pk_fma_f32 v[62:63], v[80:81], v[62:63], v[84:85]
	v_fmac_f32_e32 v57, v54, v55
	v_lshlrev_b32_e32 v54, 16, v98
	v_fma_f32 v54, v48, v54, v62
; __device__ __forceinline__ unsigned cvt_pk_bf16(float lo, float hi) { unsigned r; asm("v_cvt_pk_bf16_f32 %0, %1, %2" : "=v"(r) : "v"(lo), "v"(hi)); return r; }
; __device__ __forceinline__ float fast_sigmoid(float v) { return __builtin_amdgcn_rcpf(1.0f + __builtin_amdgcn_exp2f(-1.4426950408889634f * v)); }
;     __device__ __forceinline__ void operator()(const f32x4 (&acc)[2][2][4][2], const Unit& u, int wr, int wc, int fr_in, int fq_in) const {
;     ...
;             for (int am = 0; am < (FINAL ? 8 : 4); ++am) { constexpr int GR = FINAL ? 1 : 2; const int ai = (am * GR) >> 2; u32x4 ppw[4], pzw[4];
; #pragma unroll
;                 for (int m = (am * GR) & 3; m < ((am * GR) & 3) + GR; ++m) { const size_t off = (size_t)(row0 + ai * HALF + m * 16) * 1024 + col0 + bj * HALF; ppw[m] = *(const u32x4*)(pexb + off); pzw[m] = *(const u32x4*)(zb + off); }
;                 asm volatile("" ::: "memory");
; #pragma unroll
;                 for (int m = (am * GR) & 3; m < ((am * GR) & 3) + GR; ++m) { const size_t off = (size_t)(row0 + ai * HALF + m * 16) * 1024 + col0 + bj * HALF; const float mu = rst.mu[ai][m], rs = rst.rs[ai][m];
;                     const u32x4 pw = ppw[m]; const u32x4 zw = pzw[m];
;                     const f32x4 x0 = ((f32x4){bf_lo(zw.x), bf_hi(zw.x), bf_lo(zw.y), bf_hi(zw.y)} - mu) * rs * gv[0] + bv[0], x1 = ((f32x4){bf_lo(zw.z), bf_hi(zw.z), bf_lo(zw.w), bf_hi(zw.w)} - mu) * rs * gv[1] + bv[1];
;                     const f32x4 a0 = ln_fix(acc[ai][bj][m][0], mu, rs, csv[0], cbv[0]), a1 = ln_fix(acc[ai][bj][m][1], mu, rs, csv[1], cbv[1]); f32x4 o0, o1;
;                     o0[0] = x0[0] + fast_sigmoid(a0[0]) * bf_lo(pw.x); o0[1] = x0[1] + fast_sigmoid(a0[1]) * bf_hi(pw.x);
;                     o0[2] = x0[2] + fast_sigmoid(a0[2]) * bf_lo(pw.y); o0[3] = x0[3] + fast_sigmoid(a0[3]) * bf_hi(pw.y);
;                     o1[0] = x1[0] + fast_sigmoid(a1[0]) * bf_lo(pw.z); o1[1] = x1[1] + fast_sigmoid(a1[1]) * bf_hi(pw.z);
;                     o1[2] = x1[2] + fast_sigmoid(a1[2]) * bf_lo(pw.w); o1[3] = x1[3] + fast_sigmoid(a1[3]) * bf_hi(pw.w);
;                     if constexpr (FINAL) { *(f32x4*)(outf + off) = o0; *(f32x4*)(outf + off + 4) = o1; }
;                     else { u32x4 w; w.x = cvt_pk_bf16(o0[0], o0[1]); w.y = cvt_pk_bf16(o0[2], o0[3]); w.z = cvt_pk_bf16(o1[0], o1[1]); w.w = cvt_pk_bf16(o1[2], o1[3]); *(u32x4*)(pexb + off) = w; } } } }
	v_mul_f32_e32 v48, 0xbfb8aa3b, v49
	v_exp_f32_e32 v48, v48
	v_pk_fma_f32 v[50:51], v[208:209], v[66:67], v[50:51] op_sel_hi:[0,1,1] neg_lo:[1,0,0] neg_hi:[1,0,0]
	v_pk_fma_f32 v[50:51], v[210:211], v[50:51], v[70:71] op_sel_hi:[0,1,1]
	v_and_b32_e32 v49, 0xffff0000, v98
	v_add_f32_e32 v48, 1.0, v48
	v_rcp_f32_e32 v48, v48
	v_lshlrev_b32_e32 v60, 16, v107
	v_and_b32_e32 v61, 0xffff0000, v107
	v_sub_f32_e32 v61, v61, v208
	v_fmac_f32_e32 v63, v48, v49
	v_mul_f32_e32 v48, 0xbfb8aa3b, v50
	v_exp_f32_e32 v48, v48
	v_sub_f32_e32 v60, v60, v208
	v_pk_mul_f32 v[60:61], v[210:211], v[60:61] op_sel_hi:[0,1]
	v_pk_fma_f32 v[60:61], v[82:83], v[60:61], v[86:87]
	v_add_f32_e32 v48, 1.0, v48
	v_rcp_f32_e32 v48, v48
	v_lshlrev_b32_e32 v49, 16, v99
	v_cvt_pk_bf16_f32 v50, v54, v63
	v_pk_fma_f32 v[44:45], v[204:205], v[72:73], v[44:45] op_sel_hi:[0,1,1] neg_lo:[1,0,0] neg_hi:[1,0,0]
	v_fma_f32 v55, v48, v49, v60
	v_mul_f32_e32 v48, 0xbfb8aa3b, v51
	v_exp_f32_e32 v48, v48
	v_and_b32_e32 v49, 0xffff0000, v99
	v_pk_fma_f32 v[44:45], v[206:207], v[44:45], v[76:77] op_sel_hi:[0,1,1]
	v_mul_f32_e32 v45, 0xbfb8aa3b, v45
	v_add_f32_e32 v48, 1.0, v48
	v_rcp_f32_e32 v48, v48
	v_exp_f32_e32 v45, v45
	v_pk_fma_f32 v[46:47], v[204:205], v[74:75], v[46:47] op_sel_hi:[0,1,1] neg_lo:[1,0,0] neg_hi:[1,0,0]
	v_pk_fma_f32 v[46:47], v[206:207], v[46:47], v[78:79] op_sel_hi:[0,1,1]
	v_fmac_f32_e32 v61, v48, v49
	v_cvt_pk_bf16_f32 v48, v52, v59
	v_cvt_pk_bf16_f32 v49, v53, v57
	v_cvt_pk_bf16_f32 v51, v55, v61
	global_store_dwordx4 v[158:159], v[48:51], off offset:256
	global_load_dwordx4 v[56:59], v[132:133], off offset:256
	v_lshl_add_u64 v[52:53], v[110:111], 0, v[162:163]
	v_lshl_add_u64 v[48:49], v[110:111], 0, v[160:161]
	v_lshl_add_u64 v[48:49], v[48:49], 1, s[40:41]
	global_load_dwordx4 v[60:63], v[48:49], off
	v_lshl_add_u64 v[52:53], v[52:53], 1, s[40:41]
	global_load_dwordx4 v[52:55], v[52:53], off
	v_add_f32_e32 v45, 1.0, v45
	global_load_dwordx4 v[48:51], v[134:135], off offset:256
	v_rcp_f32_e32 v45, v45
	v_pk_fma_f32 v[40:41], v[204:205], v[64:65], v[40:41] op_sel_hi:[0,1,1] neg_lo:[1,0,0] neg_hi:[1,0,0]
	v_pk_fma_f32 v[40:41], v[206:207], v[40:41], v[68:69] op_sel_hi:[0,1,1]
	v_mul_f32_e32 v40, 0xbfb8aa3b, v40
	v_exp_f32_e32 v40, v40
	v_pk_fma_f32 v[42:43], v[204:205], v[66:67], v[42:43] op_sel_hi:[0,1,1] neg_lo:[1,0,0] neg_hi:[1,0,0]
	v_pk_fma_f32 v[42:43], v[206:207], v[42:43], v[70:71] op_sel_hi:[0,1,1]
	v_mul_f32_e32 v44, 0xbfb8aa3b, v44
	v_add_f32_e32 v40, 1.0, v40
	v_rcp_f32_e32 v40, v40
	v_exp_f32_e32 v44, v44
	v_pk_fma_f32 v[36:37], v[200:201], v[72:73], v[36:37] op_sel_hi:[0,1,1] neg_lo:[1,0,0] neg_hi:[1,0,0]
	v_pk_fma_f32 v[36:37], v[202:203], v[36:37], v[76:77] op_sel_hi:[0,1,1]
	v_mul_f32_e32 v36, 0xbfb8aa3b, v36
	v_add_f32_e32 v44, 1.0, v44
	v_exp_f32_e32 v36, v36
	v_mul_f32_e32 v37, 0xbfb8aa3b, v37
	v_rcp_f32_e32 v44, v44
	v_exp_f32_e32 v37, v37
	v_add_f32_e32 v36, 1.0, v36
	v_rcp_f32_e32 v36, v36
	v_add_f32_e32 v37, 1.0, v37
	v_rcp_f32_e32 v37, v37
	v_pk_fma_f32 v[38:39], v[200:201], v[74:75], v[38:39] op_sel_hi:[0,1,1] neg_lo:[1,0,0] neg_hi:[1,0,0]
	v_pk_fma_f32 v[38:39], v[202:203], v[38:39], v[78:79] op_sel_hi:[0,1,1]
	v_pk_fma_f32 v[32:33], v[200:201], v[64:65], v[32:33] op_sel_hi:[0,1,1] neg_lo:[1,0,0] neg_hi:[1,0,0]
	v_pk_fma_f32 v[32:33], v[202:203], v[32:33], v[68:69] op_sel_hi:[0,1,1]
	v_mul_f32_e32 v32, 0xbfb8aa3b, v32
	v_exp_f32_e32 v32, v32
	v_pk_fma_f32 v[34:35], v[200:201], v[66:67], v[34:35] op_sel_hi:[0,1,1] neg_lo:[1,0,0] neg_hi:[1,0,0]
	v_pk_fma_f32 v[34:35], v[202:203], v[34:35], v[70:71] op_sel_hi:[0,1,1]
	v_pk_fma_f32 v[28:29], v[196:197], v[72:73], v[28:29] op_sel_hi:[0,1,1] neg_lo:[1,0,0] neg_hi:[1,0,0]
	v_add_f32_e32 v32, 1.0, v32
	v_rcp_f32_e32 v32, v32
	v_pk_fma_f32 v[28:29], v[198:199], v[28:29], v[76:77] op_sel_hi:[0,1,1]
	v_mul_f32_e32 v29, 0xbfb8aa3b, v29
	v_exp_f32_e32 v29, v29
	v_pk_fma_f32 v[30:31], v[196:197], v[74:75], v[30:31] op_sel_hi:[0,1,1] neg_lo:[1,0,0] neg_hi:[1,0,0]
	v_pk_fma_f32 v[30:31], v[198:199], v[30:31], v[78:79] op_sel_hi:[0,1,1]
	v_pk_fma_f32 v[24:25], v[196:197], v[64:65], v[24:25] op_sel_hi:[0,1,1] neg_lo:[1,0,0] neg_hi:[1,0,0]
	v_add_f32_e32 v29, 1.0, v29
	v_rcp_f32_e32 v29, v29
	v_pk_fma_f32 v[24:25], v[198:199], v[24:25], v[68:69] op_sel_hi:[0,1,1]
	v_mul_f32_e32 v24, 0xbfb8aa3b, v24
	v_exp_f32_e32 v24, v24
	v_pk_fma_f32 v[26:27], v[196:197], v[66:67], v[26:27] op_sel_hi:[0,1,1] neg_lo:[1,0,0] neg_hi:[1,0,0]
	v_pk_fma_f32 v[26:27], v[198:199], v[26:27], v[70:71] op_sel_hi:[0,1,1]
	v_mul_f32_e32 v28, 0xbfb8aa3b, v28
	v_add_f32_e32 v24, 1.0, v24
	v_rcp_f32_e32 v24, v24
	v_exp_f32_e32 v28, v28
	v_pk_fma_f32 v[20:21], v[192:193], v[72:73], v[20:21] op_sel_hi:[0,1,1] neg_lo:[1,0,0] neg_hi:[1,0,0]
	v_pk_fma_f32 v[20:21], v[194:195], v[20:21], v[76:77] op_sel_hi:[0,1,1]
	v_mul_f32_e32 v20, 0xbfb8aa3b, v20
	v_add_f32_e32 v28, 1.0, v28
	v_exp_f32_e32 v20, v20
	v_mul_f32_e32 v21, 0xbfb8aa3b, v21
	v_rcp_f32_e32 v28, v28
	v_exp_f32_e32 v21, v21
	v_add_f32_e32 v20, 1.0, v20
	v_rcp_f32_e32 v20, v20
	v_pk_fma_f32 v[22:23], v[192:193], v[74:75], v[22:23] op_sel_hi:[0,1,1] neg_lo:[1,0,0] neg_hi:[1,0,0]
	v_add_f32_e32 v21, 1.0, v21
	v_rcp_f32_e32 v21, v21
	v_pk_fma_f32 v[22:23], v[194:195], v[22:23], v[78:79] op_sel_hi:[0,1,1]
	v_pk_fma_f32 v[16:17], v[192:193], v[64:65], v[16:17] op_sel_hi:[0,1,1] neg_lo:[1,0,0] neg_hi:[1,0,0]
	v_pk_fma_f32 v[16:17], v[194:195], v[16:17], v[68:69] op_sel_hi:[0,1,1]
	v_mul_f32_e32 v16, 0xbfb8aa3b, v16
	v_exp_f32_e32 v16, v16
	v_pk_fma_f32 v[18:19], v[192:193], v[66:67], v[18:19] op_sel_hi:[0,1,1] neg_lo:[1,0,0] neg_hi:[1,0,0]
	s_waitcnt vmcnt(0)
; __device__ __forceinline__ unsigned cvt_pk_bf16(float lo, float hi) { unsigned r; asm("v_cvt_pk_bf16_f32 %0, %1, %2" : "=v"(r) : "v"(lo), "v"(hi)); return r; }
; __device__ __forceinline__ float fast_sigmoid(float v) { return __builtin_amdgcn_rcpf(1.0f + __builtin_amdgcn_exp2f(-1.4426950408889634f * v)); }
;     __device__ __forceinline__ void operator()(const f32x4 (&acc)[2][2][4][2], const Unit& u, int wr, int wc, int fr_in, int fq_in) const {
;     ...
;             for (int am = 0; am < (FINAL ? 8 : 4); ++am) { constexpr int GR = FINAL ? 1 : 2; const int ai = (am * GR) >> 2; u32x4 ppw[4], pzw[4];
; #pragma unroll
;                 for (int m = (am * GR) & 3; m < ((am * GR) & 3) + GR; ++m) { const size_t off = (size_t)(row0 + ai * HALF + m * 16) * 1024 + col0 + bj * HALF; ppw[m] = *(const u32x4*)(pexb + off); pzw[m] = *(const u32x4*)(zb + off); }
;                 asm volatile("" ::: "memory");
; #pragma unroll
;                 for (int m = (am * GR) & 3; m < ((am * GR) & 3) + GR; ++m) { const size_t off = (size_t)(row0 + ai * HALF + m * 16) * 1024 + col0 + bj * HALF; const float mu = rst.mu[ai][m], rs = rst.rs[ai][m];
;                     const u32x4 pw = ppw[m]; const u32x4 zw = pzw[m];
;                     const f32x4 x0 = ((f32x4){bf_lo(zw.x), bf_hi(zw.x), bf_lo(zw.y), bf_hi(zw.y)} - mu) * rs * gv[0] + bv[0], x1 = ((f32x4){bf_lo(zw.z), bf_hi(zw.z), bf_lo(zw.w), bf_hi(zw.w)} - mu) * rs * gv[1] + bv[1];
;                     const f32x4 a0 = ln_fix(acc[ai][bj][m][0], mu, rs, csv[0], cbv[0]), a1 = ln_fix(acc[ai][bj][m][1], mu, rs, csv[1], cbv[1]); f32x4 o0, o1;
;                     o0[0] = x0[0] + fast_sigmoid(a0[0]) * bf_lo(pw.x); o0[1] = x0[1] + fast_sigmoid(a0[1]) * bf_hi(pw.x);
;                     o0[2] = x0[2] + fast_sigmoid(a0[2]) * bf_lo(pw.y); o0[3] = x0[3] + fast_sigmoid(a0[3]) * bf_hi(pw.y);
;                     o1[0] = x1[0] + fast_sigmoid(a1[0]) * bf_lo(pw.z); o1[1] = x1[1] + fast_sigmoid(a1[1]) * bf_hi(pw.z);
;                     o1[2] = x1[2] + fast_sigmoid(a1[2]) * bf_lo(pw.w); o1[3] = x1[3] + fast_sigmoid(a1[3]) * bf_hi(pw.w);
;                     if constexpr (FINAL) { *(f32x4*)(outf + off) = o0; *(f32x4*)(outf + off + 4) = o1; }
;                     else { u32x4 w; w.x = cvt_pk_bf16(o0[0], o0[1]); w.y = cvt_pk_bf16(o0[2], o0[3]); w.z = cvt_pk_bf16(o1[0], o1[1]); w.w = cvt_pk_bf16(o1[2], o1[3]); *(u32x4*)(pexb + off) = w; } } } }
	v_lshlrev_b32_e32 v100, 16, v56
	v_and_b32_e32 v56, 0xffff0000, v56
	v_add_f32_e32 v16, 1.0, v16
	v_rcp_f32_e32 v16, v16
	v_lshlrev_b32_e32 v96, 16, v60
	v_and_b32_e32 v97, 0xffff0000, v60
	v_sub_f32_e32 v97, v97, v204
	v_sub_f32_e32 v96, v96, v204
	v_pk_mul_f32 v[96:97], v[206:207], v[96:97] op_sel_hi:[0,1]
	v_pk_fma_f32 v[96:97], v[88:89], v[96:97], v[92:93]
	v_lshlrev_b32_e32 v60, 16, v61
	v_fmac_f32_e32 v97, v45, v56
	v_mul_f32_e32 v45, 0xbfb8aa3b, v46
	v_exp_f32_e32 v45, v45
	v_and_b32_e32 v61, 0xffff0000, v61
	v_sub_f32_e32 v61, v61, v204
	v_sub_f32_e32 v60, v60, v204
	v_add_f32_e32 v45, 1.0, v45
	v_rcp_f32_e32 v45, v45
	v_pk_mul_f32 v[60:61], v[206:207], v[60:61] op_sel_hi:[0,1]
	v_pk_fma_f32 v[60:61], v[90:91], v[60:61], v[94:95]
	v_lshlrev_b32_e32 v46, 16, v57
	v_fma_f32 v45, v45, v46, v60
	v_mul_f32_e32 v46, 0xbfb8aa3b, v47
	v_exp_f32_e32 v46, v46
	v_lshlrev_b32_e32 v98, 16, v62
	v_and_b32_e32 v99, 0xffff0000, v62
	v_sub_f32_e32 v99, v99, v204
	v_add_f32_e32 v46, 1.0, v46
	v_rcp_f32_e32 v46, v46
	v_sub_f32_e32 v98, v98, v204
	v_pk_mul_f32 v[98:99], v[206:207], v[98:99] op_sel_hi:[0,1]
	v_and_b32_e32 v47, 0xffff0000, v57
	v_pk_fma_f32 v[98:99], v[80:81], v[98:99], v[84:85]
	v_fmac_f32_e32 v61, v46, v47
	v_lshlrev_b32_e32 v46, 16, v58
	v_fma_f32 v46, v40, v46, v98
	v_mul_f32_e32 v40, 0xbfb8aa3b, v41
	v_exp_f32_e32 v40, v40
	v_and_b32_e32 v41, 0xffff0000, v58
	v_lshlrev_b32_e32 v62, 16, v63
	v_and_b32_e32 v63, 0xffff0000, v63
	v_add_f32_e32 v40, 1.0, v40
	v_rcp_f32_e32 v40, v40
	v_sub_f32_e32 v63, v63, v204
	v_sub_f32_e32 v62, v62, v204
	v_pk_mul_f32 v[62:63], v[206:207], v[62:63] op_sel_hi:[0,1]
	v_fmac_f32_e32 v99, v40, v41
	v_mul_f32_e32 v40, 0xbfb8aa3b, v42
	v_exp_f32_e32 v40, v40
	v_pk_fma_f32 v[62:63], v[82:83], v[62:63], v[86:87]
	v_lshlrev_b32_e32 v41, 16, v59
	v_cvt_pk_bf16_f32 v42, v46, v99
	v_add_f32_e32 v40, 1.0, v40
	v_rcp_f32_e32 v40, v40
	v_fma_f32 v44, v44, v100, v96
	v_lshlrev_b32_e32 v46, 16, v54
	v_sub_f32_e32 v46, v46, v200
	v_fma_f32 v47, v40, v41, v62
	v_mul_f32_e32 v40, 0xbfb8aa3b, v43
	v_exp_f32_e32 v40, v40
	v_and_b32_e32 v41, 0xffff0000, v59
	v_pk_fma_f32 v[18:19], v[194:195], v[18:19], v[70:71] op_sel_hi:[0,1,1]
	v_pk_fma_f32 v[12:13], v[188:189], v[72:73], v[12:13] op_sel_hi:[0,1,1] neg_lo:[1,0,0] neg_hi:[1,0,0]
	v_add_f32_e32 v40, 1.0, v40
	v_rcp_f32_e32 v40, v40
	v_pk_fma_f32 v[12:13], v[190:191], v[12:13], v[76:77] op_sel_hi:[0,1,1]
	v_mul_f32_e32 v13, 0xbfb8aa3b, v13
	v_exp_f32_e32 v13, v13
	v_fmac_f32_e32 v63, v40, v41
	v_cvt_pk_bf16_f32 v43, v47, v63
	v_cvt_pk_bf16_f32 v40, v44, v97
	v_cvt_pk_bf16_f32 v41, v45, v61
	global_store_dwordx4 v[132:133], v[40:43], off offset:256
	v_and_b32_e32 v47, 0xffff0000, v54
	v_sub_f32_e32 v47, v47, v200
	v_lshlrev_b32_e32 v42, 16, v52
	v_and_b32_e32 v43, 0xffff0000, v52
	v_sub_f32_e32 v43, v43, v200
	v_sub_f32_e32 v42, v42, v200
	v_pk_mul_f32 v[42:43], v[202:203], v[42:43] op_sel_hi:[0,1]
	v_pk_fma_f32 v[42:43], v[88:89], v[42:43], v[92:93]
	v_lshlrev_b32_e32 v52, 16, v48
	v_fma_f32 v36, v36, v52, v42
	v_and_b32_e32 v42, 0xffff0000, v48
	v_fmac_f32_e32 v43, v37, v42
	v_mul_f32_e32 v37, 0xbfb8aa3b, v38
	v_exp_f32_e32 v37, v37
	v_lshlrev_b32_e32 v40, 16, v53
	v_and_b32_e32 v41, 0xffff0000, v53
	v_sub_f32_e32 v41, v41, v200
	v_add_f32_e32 v37, 1.0, v37
	v_rcp_f32_e32 v37, v37
	v_sub_f32_e32 v40, v40, v200
	v_pk_mul_f32 v[40:41], v[202:203], v[40:41] op_sel_hi:[0,1]
	v_pk_fma_f32 v[40:41], v[90:91], v[40:41], v[94:95]
	v_lshlrev_b32_e32 v38, 16, v49
	v_fma_f32 v37, v37, v38, v40
	v_mul_f32_e32 v38, 0xbfb8aa3b, v39
	v_exp_f32_e32 v38, v38
	v_pk_mul_f32 v[46:47], v[202:203], v[46:47] op_sel_hi:[0,1]
	v_and_b32_e32 v39, 0xffff0000, v49
	v_pk_fma_f32 v[46:47], v[80:81], v[46:47], v[84:85]
	v_add_f32_e32 v38, 1.0, v38
	v_rcp_f32_e32 v38, v38
	v_lshlrev_b32_e32 v44, 16, v55
	v_and_b32_e32 v45, 0xffff0000, v55
	v_sub_f32_e32 v45, v45, v200
	v_fmac_f32_e32 v41, v38, v39
	v_lshlrev_b32_e32 v38, 16, v50
	v_fma_f32 v38, v32, v38, v46
	v_mul_f32_e32 v32, 0xbfb8aa3b, v33
	v_exp_f32_e32 v32, v32
	v_and_b32_e32 v33, 0xffff0000, v50
	v_sub_f32_e32 v44, v44, v200
	v_pk_mul_f32 v[44:45], v[202:203], v[44:45] op_sel_hi:[0,1]
	v_add_f32_e32 v32, 1.0, v32
	v_rcp_f32_e32 v32, v32
	v_pk_fma_f32 v[44:45], v[82:83], v[44:45], v[86:87]
	v_add_f32_e32 v13, 1.0, v13
	v_rcp_f32_e32 v13, v13
	v_fmac_f32_e32 v47, v32, v33
	v_mul_f32_e32 v32, 0xbfb8aa3b, v34
	v_exp_f32_e32 v32, v32
	v_lshlrev_b32_e32 v33, 16, v51
	v_cvt_pk_bf16_f32 v34, v38, v47
	v_pk_fma_f32 v[14:15], v[188:189], v[74:75], v[14:15] op_sel_hi:[0,1,1] neg_lo:[1,0,0] neg_hi:[1,0,0]
	v_add_f32_e32 v32, 1.0, v32
	v_rcp_f32_e32 v32, v32
	v_pk_fma_f32 v[14:15], v[190:191], v[14:15], v[78:79] op_sel_hi:[0,1,1]
	v_pk_fma_f32 v[8:9], v[188:189], v[64:65], v[8:9] op_sel_hi:[0,1,1] neg_lo:[1,0,0] neg_hi:[1,0,0]
	v_pk_fma_f32 v[8:9], v[190:191], v[8:9], v[68:69] op_sel_hi:[0,1,1]
	v_fma_f32 v39, v32, v33, v44
	v_mul_f32_e32 v32, 0xbfb8aa3b, v35
	v_exp_f32_e32 v32, v32
	v_and_b32_e32 v33, 0xffff0000, v51
	v_mul_f32_e32 v8, 0xbfb8aa3b, v8
	v_exp_f32_e32 v8, v8
	v_add_f32_e32 v32, 1.0, v32
	v_rcp_f32_e32 v32, v32
	v_pk_fma_f32 v[10:11], v[188:189], v[66:67], v[10:11] op_sel_hi:[0,1,1] neg_lo:[1,0,0] neg_hi:[1,0,0]
	v_add_f32_e32 v8, 1.0, v8
	v_rcp_f32_e32 v8, v8
	v_fmac_f32_e32 v45, v32, v33
	v_cvt_pk_bf16_f32 v32, v36, v43
	v_cvt_pk_bf16_f32 v33, v37, v41
	v_cvt_pk_bf16_f32 v35, v39, v45
	global_store_dwordx4 v[134:135], v[32:35], off offset:256
	global_load_dwordx4 v[40:43], v[148:149], off offset:256
	v_lshl_add_u64 v[36:37], v[110:111], 0, v[146:147]
	v_lshl_add_u64 v[32:33], v[110:111], 0, v[144:145]
	v_lshl_add_u64 v[32:33], v[32:33], 1, s[40:41]
	global_load_dwordx4 v[44:47], v[32:33], off
	v_lshl_add_u64 v[36:37], v[36:37], 1, s[40:41]
	global_load_dwordx4 v[36:39], v[36:37], off
	v_pk_fma_f32 v[10:11], v[190:191], v[10:11], v[70:71] op_sel_hi:[0,1,1]
	global_load_dwordx4 v[32:35], v[118:119], off offset:256
	v_mul_f32_e32 v12, 0xbfb8aa3b, v12
	v_exp_f32_e32 v12, v12
	v_pk_fma_f32 v[4:5], v[184:185], v[72:73], v[4:5] op_sel_hi:[0,1,1] neg_lo:[1,0,0] neg_hi:[1,0,0]
	v_pk_fma_f32 v[4:5], v[186:187], v[4:5], v[76:77] op_sel_hi:[0,1,1]
	v_mul_f32_e32 v4, 0xbfb8aa3b, v4
	v_add_f32_e32 v12, 1.0, v12
	v_exp_f32_e32 v4, v4
	v_mul_f32_e32 v5, 0xbfb8aa3b, v5
	v_rcp_f32_e32 v12, v12
	v_exp_f32_e32 v5, v5
	v_add_f32_e32 v4, 1.0, v4
	v_rcp_f32_e32 v4, v4
	v_pk_fma_f32 v[6:7], v[184:185], v[74:75], v[6:7] op_sel_hi:[0,1,1] neg_lo:[1,0,0] neg_hi:[1,0,0]
	v_add_f32_e32 v5, 1.0, v5
	v_rcp_f32_e32 v5, v5
	v_pk_fma_f32 v[6:7], v[186:187], v[6:7], v[78:79] op_sel_hi:[0,1,1]
	v_pk_fma_f32 v[0:1], v[184:185], v[64:65], v[0:1] op_sel_hi:[0,1,1] neg_lo:[1,0,0] neg_hi:[1,0,0]
	v_pk_fma_f32 v[0:1], v[186:187], v[0:1], v[68:69] op_sel_hi:[0,1,1]
	v_mul_f32_e32 v0, 0xbfb8aa3b, v0
	v_exp_f32_e32 v0, v0
	v_pk_fma_f32 v[2:3], v[184:185], v[66:67], v[2:3] op_sel_hi:[0,1,1] neg_lo:[1,0,0] neg_hi:[1,0,0]
	v_pk_fma_f32 v[2:3], v[186:187], v[2:3], v[70:71] op_sel_hi:[0,1,1]
	v_add_f32_e32 v0, 1.0, v0
	v_rcp_f32_e32 v0, v0
	s_waitcnt vmcnt(0)
; __device__ __forceinline__ unsigned cvt_pk_bf16(float lo, float hi) { unsigned r; asm("v_cvt_pk_bf16_f32 %0, %1, %2" : "=v"(r) : "v"(lo), "v"(hi)); return r; }
; __device__ __forceinline__ float fast_sigmoid(float v) { return __builtin_amdgcn_rcpf(1.0f + __builtin_amdgcn_exp2f(-1.4426950408889634f * v)); }
;     __device__ __forceinline__ void operator()(const f32x4 (&acc)[2][2][4][2], const Unit& u, int wr, int wc, int fr_in, int fq_in) const {
;     ...
;             for (int am = 0; am < (FINAL ? 8 : 4); ++am) { constexpr int GR = FINAL ? 1 : 2; const int ai = (am * GR) >> 2; u32x4 ppw[4], pzw[4];
; #pragma unroll
;                 for (int m = (am * GR) & 3; m < ((am * GR) & 3) + GR; ++m) { const size_t off = (size_t)(row0 + ai * HALF + m * 16) * 1024 + col0 + bj * HALF; ppw[m] = *(const u32x4*)(pexb + off); pzw[m] = *(const u32x4*)(zb + off); }
;                 asm volatile("" ::: "memory");
; #pragma unroll
;                 for (int m = (am * GR) & 3; m < ((am * GR) & 3) + GR; ++m) { const size_t off = (size_t)(row0 + ai * HALF + m * 16) * 1024 + col0 + bj * HALF; const float mu = rst.mu[ai][m], rs = rst.rs[ai][m];
;                     const u32x4 pw = ppw[m]; const u32x4 zw = pzw[m];
;                     const f32x4 x0 = ((f32x4){bf_lo(zw.x), bf_hi(zw.x), bf_lo(zw.y), bf_hi(zw.y)} - mu) * rs * gv[0] + bv[0], x1 = ((f32x4){bf_lo(zw.z), bf_hi(zw.z), bf_lo(zw.w), bf_hi(zw.w)} - mu) * rs * gv[1] + bv[1];
;                     const f32x4 a0 = ln_fix(acc[ai][bj][m][0], mu, rs, csv[0], cbv[0]), a1 = ln_fix(acc[ai][bj][m][1], mu, rs, csv[1], cbv[1]); f32x4 o0, o1;
;                     o0[0] = x0[0] + fast_sigmoid(a0[0]) * bf_lo(pw.x); o0[1] = x0[1] + fast_sigmoid(a0[1]) * bf_hi(pw.x);
;                     o0[2] = x0[2] + fast_sigmoid(a0[2]) * bf_lo(pw.y); o0[3] = x0[3] + fast_sigmoid(a0[3]) * bf_hi(pw.y);
;                     o1[0] = x1[0] + fast_sigmoid(a1[0]) * bf_lo(pw.z); o1[1] = x1[1] + fast_sigmoid(a1[1]) * bf_hi(pw.z);
;                     o1[2] = x1[2] + fast_sigmoid(a1[2]) * bf_lo(pw.w); o1[3] = x1[3] + fast_sigmoid(a1[3]) * bf_hi(pw.w);
;                     if constexpr (FINAL) { *(f32x4*)(outf + off) = o0; *(f32x4*)(outf + off + 4) = o1; }
;                     else { u32x4 w; w.x = cvt_pk_bf16(o0[0], o0[1]); w.y = cvt_pk_bf16(o0[2], o0[3]); w.z = cvt_pk_bf16(o1[0], o1[1]); w.w = cvt_pk_bf16(o1[2], o1[3]); *(u32x4*)(pexb + off) = w; } } } }
	v_lshlrev_b32_e32 v52, 16, v40
	v_and_b32_e32 v40, 0xffff0000, v40
	v_lshlrev_b32_e32 v48, 16, v44
	v_and_b32_e32 v49, 0xffff0000, v44
	v_sub_f32_e32 v49, v49, v196
	v_sub_f32_e32 v48, v48, v196
	v_pk_mul_f32 v[48:49], v[198:199], v[48:49] op_sel_hi:[0,1]
	v_pk_fma_f32 v[48:49], v[88:89], v[48:49], v[92:93]
	v_lshlrev_b32_e32 v44, 16, v45
	v_fmac_f32_e32 v49, v29, v40
	v_mul_f32_e32 v29, 0xbfb8aa3b, v30
	v_exp_f32_e32 v29, v29
	v_and_b32_e32 v45, 0xffff0000, v45
	v_sub_f32_e32 v45, v45, v196
	v_sub_f32_e32 v44, v44, v196
	v_add_f32_e32 v29, 1.0, v29
	v_rcp_f32_e32 v29, v29
	v_pk_mul_f32 v[44:45], v[198:199], v[44:45] op_sel_hi:[0,1]
	v_pk_fma_f32 v[44:45], v[90:91], v[44:45], v[94:95]
	v_lshlrev_b32_e32 v30, 16, v41
	v_fma_f32 v29, v29, v30, v44
	v_mul_f32_e32 v30, 0xbfb8aa3b, v31
	v_exp_f32_e32 v30, v30
	v_lshlrev_b32_e32 v50, 16, v46
	v_and_b32_e32 v51, 0xffff0000, v46
	v_sub_f32_e32 v51, v51, v196
	v_add_f32_e32 v30, 1.0, v30
	v_rcp_f32_e32 v30, v30
	v_sub_f32_e32 v50, v50, v196
	v_pk_mul_f32 v[50:51], v[198:199], v[50:51] op_sel_hi:[0,1]
	v_and_b32_e32 v31, 0xffff0000, v41
	v_pk_fma_f32 v[50:51], v[80:81], v[50:51], v[84:85]
	v_fmac_f32_e32 v45, v30, v31
	v_lshlrev_b32_e32 v30, 16, v42
	v_fma_f32 v30, v24, v30, v50
	v_mul_f32_e32 v24, 0xbfb8aa3b, v25
	v_exp_f32_e32 v24, v24
	v_and_b32_e32 v25, 0xffff0000, v42
	v_lshlrev_b32_e32 v46, 16, v47
	v_and_b32_e32 v47, 0xffff0000, v47
	v_add_f32_e32 v24, 1.0, v24
	v_rcp_f32_e32 v24, v24
	v_sub_f32_e32 v47, v47, v196
	v_sub_f32_e32 v46, v46, v196
	v_pk_mul_f32 v[46:47], v[198:199], v[46:47] op_sel_hi:[0,1]
	v_fmac_f32_e32 v51, v24, v25
	v_mul_f32_e32 v24, 0xbfb8aa3b, v26
	v_exp_f32_e32 v24, v24
	v_pk_fma_f32 v[46:47], v[82:83], v[46:47], v[86:87]
	v_lshlrev_b32_e32 v25, 16, v43
	v_cvt_pk_bf16_f32 v26, v30, v51
	v_add_f32_e32 v24, 1.0, v24
	v_rcp_f32_e32 v24, v24
	v_fma_f32 v28, v28, v52, v48
	v_lshlrev_b32_e32 v30, 16, v38
	v_sub_f32_e32 v30, v30, v192
	v_fma_f32 v31, v24, v25, v46
	v_mul_f32_e32 v24, 0xbfb8aa3b, v27
	v_exp_f32_e32 v24, v24
	v_and_b32_e32 v25, 0xffff0000, v43
	v_add_f32_e32 v24, 1.0, v24
	v_rcp_f32_e32 v24, v24
	s_nop 0
	v_fmac_f32_e32 v47, v24, v25
	v_cvt_pk_bf16_f32 v27, v31, v47
	v_cvt_pk_bf16_f32 v24, v28, v49
	v_cvt_pk_bf16_f32 v25, v29, v45
	global_store_dwordx4 v[148:149], v[24:27], off offset:256
	v_and_b32_e32 v31, 0xffff0000, v38
	v_sub_f32_e32 v31, v31, v192
	v_lshlrev_b32_e32 v26, 16, v36
	v_and_b32_e32 v27, 0xffff0000, v36
	v_sub_f32_e32 v27, v27, v192
	v_sub_f32_e32 v26, v26, v192
	v_pk_mul_f32 v[26:27], v[194:195], v[26:27] op_sel_hi:[0,1]
	v_pk_fma_f32 v[26:27], v[88:89], v[26:27], v[92:93]
	v_lshlrev_b32_e32 v36, 16, v32
	v_fma_f32 v20, v20, v36, v26
	v_and_b32_e32 v26, 0xffff0000, v32
	v_fmac_f32_e32 v27, v21, v26
	v_mul_f32_e32 v21, 0xbfb8aa3b, v22
	v_exp_f32_e32 v21, v21
	v_lshlrev_b32_e32 v24, 16, v37
	v_and_b32_e32 v25, 0xffff0000, v37
	v_sub_f32_e32 v25, v25, v192
	v_add_f32_e32 v21, 1.0, v21
	v_rcp_f32_e32 v21, v21
	v_sub_f32_e32 v24, v24, v192
	v_pk_mul_f32 v[24:25], v[194:195], v[24:25] op_sel_hi:[0,1]
	v_pk_fma_f32 v[24:25], v[90:91], v[24:25], v[94:95]
	v_lshlrev_b32_e32 v22, 16, v33
	v_fma_f32 v21, v21, v22, v24
	v_mul_f32_e32 v22, 0xbfb8aa3b, v23
	v_exp_f32_e32 v22, v22
	v_pk_mul_f32 v[30:31], v[194:195], v[30:31] op_sel_hi:[0,1]
	v_and_b32_e32 v23, 0xffff0000, v33
	v_pk_fma_f32 v[30:31], v[80:81], v[30:31], v[84:85]
	v_add_f32_e32 v22, 1.0, v22
	v_rcp_f32_e32 v22, v22
	v_lshlrev_b32_e32 v28, 16, v39
	v_and_b32_e32 v29, 0xffff0000, v39
	v_sub_f32_e32 v29, v29, v192
	v_fmac_f32_e32 v25, v22, v23
	v_lshlrev_b32_e32 v22, 16, v34
	v_fma_f32 v22, v16, v22, v30
	v_mul_f32_e32 v16, 0xbfb8aa3b, v17
	v_exp_f32_e32 v16, v16
	v_and_b32_e32 v17, 0xffff0000, v34
	v_sub_f32_e32 v28, v28, v192
	v_pk_mul_f32 v[28:29], v[194:195], v[28:29] op_sel_hi:[0,1]
	v_add_f32_e32 v16, 1.0, v16
	v_rcp_f32_e32 v16, v16
	v_pk_fma_f32 v[28:29], v[82:83], v[28:29], v[86:87]
	v_fmac_f32_e32 v31, v16, v17
	v_mul_f32_e32 v16, 0xbfb8aa3b, v18
	v_exp_f32_e32 v16, v16
	v_lshlrev_b32_e32 v17, 16, v35
	v_cvt_pk_bf16_f32 v18, v22, v31
	v_add_f32_e32 v16, 1.0, v16
	v_rcp_f32_e32 v16, v16
	s_nop 0
	v_fma_f32 v23, v16, v17, v28
	v_mul_f32_e32 v16, 0xbfb8aa3b, v19
	v_exp_f32_e32 v16, v16
	v_and_b32_e32 v17, 0xffff0000, v35
	v_add_f32_e32 v16, 1.0, v16
	v_rcp_f32_e32 v16, v16
	s_nop 0
	v_fmac_f32_e32 v29, v16, v17
	v_cvt_pk_bf16_f32 v16, v20, v27
	v_cvt_pk_bf16_f32 v17, v21, v25
	v_cvt_pk_bf16_f32 v19, v23, v29
	global_store_dwordx4 v[118:119], v[16:19], off offset:256
	global_load_dwordx4 v[24:27], v[150:151], off offset:256
	v_lshl_add_u64 v[20:21], v[110:111], 0, v[130:131]
	v_lshl_add_u64 v[16:17], v[110:111], 0, v[128:129]
	v_lshl_add_u64 v[16:17], v[16:17], 1, s[40:41]
	global_load_dwordx4 v[28:31], v[16:17], off
	v_lshl_add_u64 v[20:21], v[20:21], 1, s[40:41]
	global_load_dwordx4 v[20:23], v[20:21], off
	s_waitcnt vmcnt(0)
; #define PG8_BAR __builtin_amdgcn_s_barrier()
;     __device__ __forceinline__ void operator()(const f32x4 (&acc)[2][2][4][2], const Unit& u, int wr, int wc, int fr_in, int fq_in) const {
;     ...
;             for (int am = 0; am < (FINAL ? 8 : 4); ++am) { constexpr int GR = FINAL ? 1 : 2; const int ai = (am * GR) >> 2; u32x4 ppw[4], pzw[4];
; #pragma unroll
;                 for (int m = (am * GR) & 3; m < ((am * GR) & 3) + GR; ++m) { const size_t off = (size_t)(row0 + ai * HALF + m * 16) * 1024 + col0 + bj * HALF; ppw[m] = *(const u32x4*)(pexb + off); pzw[m] = *(const u32x4*)(zb + off); }
;                 asm volatile("" ::: "memory");
; #pragma unroll
;                 for (int m = (am * GR) & 3; m < ((am * GR) & 3) + GR; ++m) { const size_t off = (size_t)(row0 + ai * HALF + m * 16) * 1024 + col0 + bj * HALF; const float mu = rst.mu[ai][m], rs = rst.rs[ai][m];
;                     const u32x4 pw = ppw[m]; const u32x4 zw = pzw[m];
;                     const f32x4 x0 = ((f32x4){bf_lo(zw.x), bf_hi(zw.x), bf_lo(zw.y), bf_hi(zw.y)} - mu) * rs * gv[0] + bv[0], x1 = ((f32x4){bf_lo(zw.z), bf_hi(zw.z), bf_lo(zw.w), bf_hi(zw.w)} - mu) * rs * gv[1] + bv[1];
;                     const f32x4 a0 = ln_fix(acc[ai][bj][m][0], mu, rs, csv[0], cbv[0]), a1 = ln_fix(acc[ai][bj][m][1], mu, rs, csv[1], cbv[1]); f32x4 o0, o1;
;                     o0[0] = x0[0] + fast_sigmoid(a0[0]) * bf_lo(pw.x); o0[1] = x0[1] + fast_sigmoid(a0[1]) * bf_hi(pw.x);
;                     o0[2] = x0[2] + fast_sigmoid(a0[2]) * bf_lo(pw.y); o0[3] = x0[3] + fast_sigmoid(a0[3]) * bf_hi(pw.y);
;                     o1[0] = x1[0] + fast_sigmoid(a1[0]) * bf_lo(pw.z); o1[1] = x1[1] + fast_sigmoid(a1[1]) * bf_hi(pw.z);
;                     o1[2] = x1[2] + fast_sigmoid(a1[2]) * bf_lo(pw.w); o1[3] = x1[3] + fast_sigmoid(a1[3]) * bf_hi(pw.w);
;                     if constexpr (FINAL) { *(f32x4*)(outf + off) = o0; *(f32x4*)(outf + off + 4) = o1; }
;                     else { u32x4 w; w.x = cvt_pk_bf16(o0[0], o0[1]); w.y = cvt_pk_bf16(o0[2], o0[3]); w.z = cvt_pk_bf16(o1[0], o1[1]); w.w = cvt_pk_bf16(o1[2], o1[3]); *(u32x4*)(pexb + off) = w; } } } }
; template <class Epi, class Sched, bool ALIGN_EPI = false, bool SP2 = false>
; __device__ __forceinline__ void gemm_phase(PG8_LAS unsigned char* lds, const Gemm g, const Sched& S, const Epi& E) {
;     ...
;         if constexpr (ALIGN_EPI) { if (wr == 0) PG8_BAR; }
	v_lshlrev_b32_e32 v32, 16, v28
	global_load_dwordx4 v[16:19], v[108:109], off offset:256
	v_and_b32_e32 v33, 0xffff0000, v28
	v_sub_f32_e32 v33, v33, v188
	v_sub_f32_e32 v32, v32, v188
	v_pk_mul_f32 v[32:33], v[190:191], v[32:33] op_sel_hi:[0,1]
	v_pk_fma_f32 v[32:33], v[88:89], v[32:33], v[92:93]
	v_lshlrev_b32_e32 v36, 16, v24
	v_and_b32_e32 v24, 0xffff0000, v24
	v_fmac_f32_e32 v33, v13, v24
	v_mul_f32_e32 v13, 0xbfb8aa3b, v14
	v_exp_f32_e32 v13, v13
	v_lshlrev_b32_e32 v28, 16, v29
	v_and_b32_e32 v29, 0xffff0000, v29
	v_sub_f32_e32 v29, v29, v188
	v_add_f32_e32 v13, 1.0, v13
	v_rcp_f32_e32 v13, v13
	v_sub_f32_e32 v28, v28, v188
	v_pk_mul_f32 v[28:29], v[190:191], v[28:29] op_sel_hi:[0,1]
	v_pk_fma_f32 v[28:29], v[90:91], v[28:29], v[94:95]
	v_lshlrev_b32_e32 v14, 16, v25
	v_fma_f32 v13, v13, v14, v28
	v_mul_f32_e32 v14, 0xbfb8aa3b, v15
	v_exp_f32_e32 v14, v14
	v_lshlrev_b32_e32 v34, 16, v30
	v_and_b32_e32 v35, 0xffff0000, v30
	v_sub_f32_e32 v35, v35, v188
	v_add_f32_e32 v14, 1.0, v14
	v_rcp_f32_e32 v14, v14
	v_sub_f32_e32 v34, v34, v188
	v_pk_mul_f32 v[34:35], v[190:191], v[34:35] op_sel_hi:[0,1]
	v_and_b32_e32 v15, 0xffff0000, v25
	v_pk_fma_f32 v[34:35], v[80:81], v[34:35], v[84:85]
	v_fmac_f32_e32 v29, v14, v15
	v_lshlrev_b32_e32 v14, 16, v26
	v_fma_f32 v14, v8, v14, v34
	v_mul_f32_e32 v8, 0xbfb8aa3b, v9
	v_exp_f32_e32 v8, v8
	v_and_b32_e32 v9, 0xffff0000, v26
	v_lshlrev_b32_e32 v30, 16, v31
	v_and_b32_e32 v31, 0xffff0000, v31
	v_add_f32_e32 v8, 1.0, v8
	v_rcp_f32_e32 v8, v8
	v_sub_f32_e32 v31, v31, v188
	v_sub_f32_e32 v30, v30, v188
	v_pk_mul_f32 v[30:31], v[190:191], v[30:31] op_sel_hi:[0,1]
	v_fmac_f32_e32 v35, v8, v9
	v_mul_f32_e32 v8, 0xbfb8aa3b, v10
	v_exp_f32_e32 v8, v8
	v_pk_fma_f32 v[30:31], v[82:83], v[30:31], v[86:87]
	v_lshlrev_b32_e32 v9, 16, v27
	v_cvt_pk_bf16_f32 v10, v14, v35
	v_add_f32_e32 v8, 1.0, v8
	v_rcp_f32_e32 v8, v8
	v_fma_f32 v12, v12, v36, v32
	v_lshlrev_b32_e32 v14, 16, v22
	v_fma_f32 v15, v8, v9, v30
	v_mul_f32_e32 v8, 0xbfb8aa3b, v11
	v_exp_f32_e32 v8, v8
	v_and_b32_e32 v9, 0xffff0000, v27
	v_sub_f32_e32 v14, v14, v184
	v_add_f32_e32 v8, 1.0, v8
	v_rcp_f32_e32 v8, v8
	s_nop 0
	v_fmac_f32_e32 v31, v8, v9
	v_cvt_pk_bf16_f32 v11, v15, v31
	v_cvt_pk_bf16_f32 v8, v12, v33
	v_cvt_pk_bf16_f32 v9, v13, v29
	global_store_dwordx4 v[150:151], v[8:11], off offset:256
	v_and_b32_e32 v15, 0xffff0000, v22
	v_sub_f32_e32 v15, v15, v184
	v_lshlrev_b32_e32 v10, 16, v20
	v_and_b32_e32 v11, 0xffff0000, v20
	v_sub_f32_e32 v11, v11, v184
	v_sub_f32_e32 v10, v10, v184
	v_pk_mul_f32 v[10:11], v[186:187], v[10:11] op_sel_hi:[0,1]
	v_pk_fma_f32 v[10:11], v[88:89], v[10:11], v[92:93]
	s_waitcnt vmcnt(0)
	v_lshlrev_b32_e32 v20, 16, v16
	v_fma_f32 v4, v4, v20, v10
	v_and_b32_e32 v10, 0xffff0000, v16
	v_fmac_f32_e32 v11, v5, v10
	v_mul_f32_e32 v5, 0xbfb8aa3b, v6
	v_exp_f32_e32 v5, v5
	v_lshlrev_b32_e32 v8, 16, v21
	v_and_b32_e32 v9, 0xffff0000, v21
	v_sub_f32_e32 v9, v9, v184
	v_add_f32_e32 v5, 1.0, v5
	v_rcp_f32_e32 v5, v5
	v_sub_f32_e32 v8, v8, v184
	v_pk_mul_f32 v[8:9], v[186:187], v[8:9] op_sel_hi:[0,1]
	v_pk_fma_f32 v[8:9], v[90:91], v[8:9], v[94:95]
	v_lshlrev_b32_e32 v6, 16, v17
	v_fma_f32 v5, v5, v6, v8
	v_mul_f32_e32 v6, 0xbfb8aa3b, v7
	v_exp_f32_e32 v6, v6
	v_pk_mul_f32 v[14:15], v[186:187], v[14:15] op_sel_hi:[0,1]
	v_and_b32_e32 v7, 0xffff0000, v17
	v_pk_fma_f32 v[14:15], v[80:81], v[14:15], v[84:85]
	v_add_f32_e32 v6, 1.0, v6
	v_rcp_f32_e32 v6, v6
	v_lshlrev_b32_e32 v12, 16, v23
	v_and_b32_e32 v13, 0xffff0000, v23
	v_sub_f32_e32 v13, v13, v184
	v_fmac_f32_e32 v9, v6, v7
	v_lshlrev_b32_e32 v6, 16, v18
	v_fma_f32 v6, v0, v6, v14
	v_mul_f32_e32 v0, 0xbfb8aa3b, v1
	v_exp_f32_e32 v0, v0
	v_and_b32_e32 v1, 0xffff0000, v18
	v_sub_f32_e32 v12, v12, v184
	v_pk_mul_f32 v[12:13], v[186:187], v[12:13] op_sel_hi:[0,1]
	v_add_f32_e32 v0, 1.0, v0
	v_rcp_f32_e32 v0, v0
	v_pk_fma_f32 v[12:13], v[82:83], v[12:13], v[86:87]
	v_fmac_f32_e32 v15, v0, v1
	v_mul_f32_e32 v0, 0xbfb8aa3b, v2
	v_exp_f32_e32 v0, v0
	v_lshlrev_b32_e32 v1, 16, v19
	v_cvt_pk_bf16_f32 v2, v6, v15
	v_add_f32_e32 v0, 1.0, v0
	v_rcp_f32_e32 v0, v0
	s_nop 0
	v_fma_f32 v7, v0, v1, v12
	v_mul_f32_e32 v0, 0xbfb8aa3b, v3
	v_exp_f32_e32 v0, v0
	v_and_b32_e32 v1, 0xffff0000, v19
	v_add_f32_e32 v0, 1.0, v0
	v_rcp_f32_e32 v0, v0
	s_nop 0
	v_fmac_f32_e32 v13, v0, v1
	v_cvt_pk_bf16_f32 v0, v4, v11
	v_cvt_pk_bf16_f32 v1, v5, v9
	v_cvt_pk_bf16_f32 v3, v7, v13
	global_store_dwordx4 v[108:109], v[0:3], off offset:256
	s_cbranch_vccnz .LBB0_1446
	s_andn2_b64 vcc, exec, s[42:43]
	s_cbranch_vccnz .LBB0_1445
	s_barrier
	s_branch .LBB0_1445

; __device__ __forceinline__ void load_row_stats(const float* sp, int row0, RowStats& r) {
; #pragma unroll
;     for (int ai = 0; ai < 2; ++ai) { asm volatile("" ::: "memory");
; #pragma unroll
;         for (int m = 0; m < 4; ++m) { const float* p = sp + (size_t)(row0 + ai * HALF + m * 16) * 8; const f32x4 a = *(const f32x4*)p, b = *(const f32x4*)(p + 4);
;             const float s1 = (a[0] + a[2]) + (b[0] + b[2]), s2 = (a[1] + a[3]) + (b[1] + b[3]); const float mu = s1 * (1.f / 1024.f); const float var = s2 * (1.f / 1024.f) - mu * mu;
;             r.mu[ai][m] = mu; r.rs[ai][m] = __builtin_amdgcn_rsqf(__builtin_fmaxf(var, 0.f) + 1e-5f); } }
;     __device__ __forceinline__ void operator()(const f32x4 (&acc)[2][2][4][2], const Unit& u, int wr, int wc, int fr_in, int fq_in) const {
;     ...
;         const int row0 = u.pm * BM + wr * 64 + fr; const int t = u.pn >> 2; bf16_t* base = t ? V : U;
;         const int col0 = (u.pn & 3) * BM + wc * 32 + 8 * fq, n0 = u.pn * BM + wc * 32 + 8 * fq;
;         RowStats rst; load_row_stats(sp, row0, rst);
; #pragma unroll
;         for (int bj = 0; bj < 2; ++bj) { f32x4 csv[2], cbv[2];
; #pragma unroll
;             for (int n = 0; n < 2; ++n) { csv[n] = *(const f32x4*)(cs + n0 + bj * HALF + 4 * n); cbv[n] = *(const f32x4*)(cb + n0 + bj * HALF + 4 * n) + *(const f32x4*)(bias + n0 + bj * HALF + 4 * n); }
.LBB0_1698:
	s_lshl_b32 s10, s10, 8
	v_mov_b32_e32 v120, v171
	v_mov_b32_e32 v121, v175
	s_add_i32 s10, s10, s15
	s_cmp_lt_u32 s18, 4
	v_add_u32_e32 v222, s10, v120
	v_ashrrev_i32_e32 v223, 31, v222
	v_and_b32_e32 v196, 0xffffff00, v222
	v_and_b32_e32 v169, 0xff, v222
	v_lshlrev_b32_e32 v169, 3, v169
	v_add_u32_e32 v169, 0x22400, v169
	v_add_u32_e32 v220, 16, v222
	v_ashrrev_i32_e32 v221, 31, v220
	v_add_u32_e32 v218, 32, v222
	v_ashrrev_i32_e32 v219, 31, v218
	v_add_u32_e32 v216, 48, v222
	v_ashrrev_i32_e32 v217, 31, v216
	v_add_u32_e32 v214, 0x80, v222
	v_ashrrev_i32_e32 v215, 31, v214
	v_add_u32_e32 v212, 0x90, v222
	v_ashrrev_i32_e32 v213, 31, v212
	v_add_u32_e32 v210, 0xa0, v222
	v_ashrrev_i32_e32 v211, 31, v210
	v_add_u32_e32 v208, 0xb0, v222
	v_ashrrev_i32_e32 v209, 31, v208
	v_lshlrev_b32_e32 v120, 3, v121
	s_mov_b32 s10, 0xbc00000
	s_cselect_b32 s10, s10, 0xfc00000
	s_add_u32 s10, s4, s10
	s_addc_u32 s11, s5, 0
	s_lshl_b32 s12, s18, 8
	s_and_b32 s13, s12, 0x300
	s_or_b32 s13, s13, s16
	s_or_b32 s12, s12, s16
	v_add_u32_e32 v122, s13, v120
	v_add_u32_e32 v120, s12, v120
	v_ashrrev_i32_e32 v123, 31, v122
	v_lshl_add_u64 v[202:203], v[122:123], 1, s[10:11]
	s_mov_b64 s[10:11], -1
	s_andn2_b64 vcc, exec, s[38:39]
	s_nop 0
	v_ashrrev_i32_e32 v121, 31, v120
	v_lshlrev_b64 v[120:121], 2, v[120:121]
	v_lshl_add_u64 v[204:205], s[26:27], 0, v[120:121]
	v_lshl_add_u64 v[206:207], s[28:29], 0, v[120:121]
	s_waitcnt lgkmcnt(0)
	v_lshl_add_u64 v[200:201], s[6:7], 0, v[120:121]
	global_load_dwordx4 v[120:123], v[204:205], off offset:16
	global_load_dwordx4 v[124:127], v[204:205], off
	global_load_dwordx4 v[136:139], v[206:207], off offset:16
	global_load_dwordx4 v[144:147], v[206:207], off
	global_load_dwordx4 v[140:143], v[200:201], off offset:16
	global_load_dwordx4 v[148:151], v[200:201], off
	s_cselect_b32 s99, 1, 0
	v_readfirstlane_b32 s98, v254
	s_nop 0
	s_cmpk_lt_u32 s98, 0x100
	s_cbranch_scc0 .Lrs5_skip
	v_add_u32_e32 v196, v196, v254
	v_mov_b32_e32 v197, 0
	v_lshlrev_b64 v[196:197], 5, v[196:197]
	v_lshl_add_u64 v[196:197], s[24:25], 0, v[196:197]
	global_load_dwordx2 v[192:193], v[196:197], off offset:16
	global_load_dwordx2 v[188:189], v[196:197], off offset:24
	global_load_dwordx2 v[184:185], v[196:197], off
	global_load_dwordx2 v[180:181], v[196:197], off offset:8
	s_waitcnt vmcnt(0)
	v_pk_add_f32 v[192:193], v[192:193], v[188:189]
	v_pk_add_f32 v[184:185], v[184:185], v[180:181]
	s_nop 0
	v_pk_add_f32 v[192:193], v[184:185], v[192:193]
	s_nop 0
	v_pk_mul_f32 v[192:193], v[192:193], s[42:43] op_sel_hi:[1,0]
	v_lshlrev_b32_e32 v176, 3, v254
	v_add_u32_e32 v176, 0x22400, v176
	ds_write_b64 v176, v[192:193]
.Lrs5_skip:
	s_waitcnt vmcnt(0) lgkmcnt(0)
	s_barrier
	ds_read_b64 v[196:197], v169
	ds_read_b64 v[192:193], v169 offset:128
	ds_read_b64 v[188:189], v169 offset:256
	ds_read_b64 v[184:185], v169 offset:384
	ds_read_b64 v[180:181], v169 offset:1024
	ds_read_b64 v[176:177], v169 offset:1152
	ds_read_b64 v[172:173], v169 offset:1280
	ds_read_b64 v[168:169], v169 offset:1408
	s_cmp_lg_u32 s99, 0
	s_waitcnt lgkmcnt(0)
	v_fma_f32 v198, -v196, v196, v197
	v_max_f32_e32 v198, 0, v198
	v_add_f32_e32 v198, 0x3727c5ac, v198
	v_rsq_f32_e32 v198, v198
	v_fma_f32 v194, -v192, v192, v193
	v_max_f32_e32 v194, 0, v194
	v_add_f32_e32 v194, 0x3727c5ac, v194
	v_rsq_f32_e32 v194, v194
	v_fma_f32 v190, -v188, v188, v189
	v_max_f32_e32 v190, 0, v190
	v_add_f32_e32 v190, 0x3727c5ac, v190
	v_rsq_f32_e32 v190, v190
	v_fma_f32 v186, -v184, v184, v185
	v_max_f32_e32 v186, 0, v186
	v_add_f32_e32 v186, 0x3727c5ac, v186
	v_rsq_f32_e32 v186, v186
	v_fma_f32 v182, -v180, v180, v181
	v_max_f32_e32 v182, 0, v182
	v_add_f32_e32 v182, 0x3727c5ac, v182
	v_rsq_f32_e32 v182, v182
	v_fma_f32 v178, -v176, v176, v177
	v_max_f32_e32 v178, 0, v178
	v_add_f32_e32 v178, 0x3727c5ac, v178
	v_rsq_f32_e32 v178, v178
	v_fma_f32 v174, -v172, v172, v173
	v_max_f32_e32 v174, 0, v174
	v_add_f32_e32 v174, 0x3727c5ac, v174
	v_rsq_f32_e32 v174, v174
	v_fma_f32 v170, -v168, v168, v169
	v_max_f32_e32 v170, 0, v170
	v_add_f32_e32 v170, 0x3727c5ac, v170
	v_rsq_f32_e32 v170, v170
	s_waitcnt vmcnt(5)
	v_pk_fma_f32 v[128:129], v[196:197], v[120:121], v[128:129] op_sel_hi:[0,1,1] neg_lo:[1,0,0] neg_hi:[1,0,0]
	s_waitcnt vmcnt(4)
	v_pk_fma_f32 v[132:133], v[196:197], v[124:125], v[132:133] op_sel_hi:[0,1,1] neg_lo:[1,0,0] neg_hi:[1,0,0]
	v_pk_fma_f32 v[134:135], v[196:197], v[126:127], v[134:135] op_sel_hi:[0,1,1] neg_lo:[1,0,0] neg_hi:[1,0,0]
	v_pk_fma_f32 v[130:131], v[196:197], v[122:123], v[130:131] op_sel_hi:[0,1,1] neg_lo:[1,0,0] neg_hi:[1,0,0]
	s_waitcnt vmcnt(1)
	v_pk_add_f32 v[138:139], v[138:139], v[142:143]
	s_waitcnt vmcnt(0)
; __device__ __forceinline__ unsigned cvt_pk_bf16(float lo, float hi) { unsigned r; asm("v_cvt_pk_bf16_f32 %0, %1, %2" : "=v"(r) : "v"(lo), "v"(hi)); return r; }
; __device__ __forceinline__ float gelu_tanh(float v) { const float u = 0.7978845608028654f * (v + 0.044715f * v * v * v); return v * fast_sigmoid(2.0f * u); }
; __device__ __forceinline__ f32x4 ln_fix(const f32x4& a, float mu, float rs, const f32x4& cs, const f32x4& cb) { return (a - cs * mu) * rs + cb; }
; __device__ __forceinline__ float fast_sigmoid(float v) { return __builtin_amdgcn_rcpf(1.0f + __builtin_amdgcn_exp2f(-1.4426950408889634f * v)); }
;     __device__ __forceinline__ void operator()(const f32x4 (&acc)[2][2][4][2], const Unit& u, int wr, int wc, int fr_in, int fq_in) const {
;     ...
;             for (int n = 0; n < 2; ++n) { csv[n] = *(const f32x4*)(cs + n0 + bj * HALF + 4 * n); cbv[n] = *(const f32x4*)(cb + n0 + bj * HALF + 4 * n) + *(const f32x4*)(bias + n0 + bj * HALF + 4 * n); }
; #pragma unroll
;             for (int ai = 0; ai < 2; ++ai)
; #pragma unroll
;                 for (int m = 0; m < 4; ++m) { bf16_t* rowp = base + (size_t)(row0 + ai * HALF + m * 16) * 1024 + col0 + bj * HALF;
;                     f32x4 v0 = ln_fix(acc[ai][bj][m][0], rst.mu[ai][m], rst.rs[ai][m], csv[0], cbv[0]), v1 = ln_fix(acc[ai][bj][m][1], rst.mu[ai][m], rst.rs[ai][m], csv[1], cbv[1]);
; #pragma unroll
;                     for (int j = 0; j < 4; ++j) { v0[j] = gelu_tanh(v0[j]); v1[j] = gelu_tanh(v1[j]); }
;                     u32x4 w; w.x = cvt_pk_bf16(v0[0], v0[1]); w.y = cvt_pk_bf16(v0[2], v0[3]); w.z = cvt_pk_bf16(v1[0], v1[1]); w.w = cvt_pk_bf16(v1[2], v1[3]);
;                     *(u32x4*)rowp = w; } }
	v_pk_add_f32 v[144:145], v[144:145], v[148:149]
	v_pk_add_f32 v[136:137], v[136:137], v[140:141]
	v_pk_fma_f32 v[132:133], v[198:199], v[132:133], v[144:145] op_sel_hi:[0,1,1]
	v_mul_f32_e32 v142, 0x3d372713, v132
	v_mul_f32_e32 v142, v132, v142
	v_fma_f32 v142, v132, v142, v132
	v_mul_f32_e32 v142, 0x3f4c422a, v142
	v_add_f32_e32 v142, v142, v142
	v_mul_f32_e32 v142, 0xbfb8aa3b, v142
	v_exp_f32_e32 v142, v142
	v_pk_fma_f32 v[128:129], v[198:199], v[128:129], v[136:137] op_sel_hi:[0,1,1]
	v_pk_add_f32 v[146:147], v[146:147], v[150:151]
	v_pk_fma_f32 v[130:131], v[198:199], v[130:131], v[138:139] op_sel_hi:[0,1,1]
	v_add_f32_e32 v142, 1.0, v142
	v_rcp_f32_e32 v142, v142
	v_pk_fma_f32 v[134:135], v[198:199], v[134:135], v[146:147] op_sel_hi:[0,1,1]
	v_lshlrev_b64 v[140:141], 11, v[222:223]
	v_pk_fma_f32 v[116:117], v[192:193], v[124:125], v[116:117] op_sel_hi:[0,1,1] neg_lo:[1,0,0] neg_hi:[1,0,0]
	v_mul_f32_e32 v132, v132, v142
	v_mul_f32_e32 v142, 0x3d372713, v128
	v_mul_f32_e32 v142, v128, v142
	v_fma_f32 v142, v128, v142, v128
	v_mul_f32_e32 v142, 0x3f4c422a, v142
	v_add_f32_e32 v142, v142, v142
	v_mul_f32_e32 v142, 0xbfb8aa3b, v142
	v_exp_f32_e32 v142, v142
	v_pk_fma_f32 v[116:117], v[194:195], v[116:117], v[144:145] op_sel_hi:[0,1,1]
	v_pk_fma_f32 v[112:113], v[192:193], v[120:121], v[112:113] op_sel_hi:[0,1,1] neg_lo:[1,0,0] neg_hi:[1,0,0]
	v_pk_fma_f32 v[112:113], v[194:195], v[112:113], v[136:137] op_sel_hi:[0,1,1]
	v_add_f32_e32 v142, 1.0, v142
	v_rcp_f32_e32 v142, v142
	v_pk_fma_f32 v[118:119], v[192:193], v[126:127], v[118:119] op_sel_hi:[0,1,1] neg_lo:[1,0,0] neg_hi:[1,0,0]
	v_pk_fma_f32 v[118:119], v[194:195], v[118:119], v[146:147] op_sel_hi:[0,1,1]
	v_pk_fma_f32 v[114:115], v[192:193], v[122:123], v[114:115] op_sel_hi:[0,1,1] neg_lo:[1,0,0] neg_hi:[1,0,0]
	v_mul_f32_e32 v142, v128, v142
	v_mul_f32_e32 v128, 0x3d372713, v133
	v_mul_f32_e32 v128, v133, v128
	v_fma_f32 v128, v133, v128, v133
	v_mul_f32_e32 v128, 0x3f4c422a, v128
	v_add_f32_e32 v128, v128, v128
	v_mul_f32_e32 v128, 0xbfb8aa3b, v128
	v_exp_f32_e32 v128, v128
	v_pk_fma_f32 v[114:115], v[194:195], v[114:115], v[138:139] op_sel_hi:[0,1,1]
	v_pk_fma_f32 v[108:109], v[188:189], v[124:125], v[108:109] op_sel_hi:[0,1,1] neg_lo:[1,0,0] neg_hi:[1,0,0]
	v_pk_fma_f32 v[108:109], v[190:191], v[108:109], v[144:145] op_sel_hi:[0,1,1]
	v_add_f32_e32 v128, 1.0, v128
	v_rcp_f32_e32 v128, v128
	v_pk_fma_f32 v[104:105], v[188:189], v[120:121], v[104:105] op_sel_hi:[0,1,1] neg_lo:[1,0,0] neg_hi:[1,0,0]
	v_pk_fma_f32 v[104:105], v[190:191], v[104:105], v[136:137] op_sel_hi:[0,1,1]
	v_pk_fma_f32 v[110:111], v[188:189], v[126:127], v[110:111] op_sel_hi:[0,1,1] neg_lo:[1,0,0] neg_hi:[1,0,0]
	v_mul_f32_e32 v133, v133, v128
	v_mul_f32_e32 v128, 0x3d372713, v129
	v_mul_f32_e32 v128, v129, v128
	v_fma_f32 v128, v129, v128, v129
	v_mul_f32_e32 v128, 0x3f4c422a, v128
	v_add_f32_e32 v128, v128, v128
	v_mul_f32_e32 v128, 0xbfb8aa3b, v128
	v_exp_f32_e32 v128, v128
	v_pk_fma_f32 v[110:111], v[190:191], v[110:111], v[146:147] op_sel_hi:[0,1,1]
	v_pk_fma_f32 v[106:107], v[188:189], v[122:123], v[106:107] op_sel_hi:[0,1,1] neg_lo:[1,0,0] neg_hi:[1,0,0]
	v_pk_fma_f32 v[106:107], v[190:191], v[106:107], v[138:139] op_sel_hi:[0,1,1]
	v_add_f32_e32 v128, 1.0, v128
	v_rcp_f32_e32 v128, v128
	v_pk_fma_f32 v[100:101], v[184:185], v[124:125], v[100:101] op_sel_hi:[0,1,1] neg_lo:[1,0,0] neg_hi:[1,0,0]
	v_pk_fma_f32 v[100:101], v[186:187], v[100:101], v[144:145] op_sel_hi:[0,1,1]
	v_pk_fma_f32 v[96:97], v[184:185], v[120:121], v[96:97] op_sel_hi:[0,1,1] neg_lo:[1,0,0] neg_hi:[1,0,0]
	v_mul_f32_e32 v143, v129, v128
	v_mul_f32_e32 v128, 0x3d372713, v134
	v_mul_f32_e32 v128, v134, v128
	v_fma_f32 v128, v134, v128, v134
	v_mul_f32_e32 v128, 0x3f4c422a, v128
	v_add_f32_e32 v128, v128, v128
	v_mul_f32_e32 v128, 0xbfb8aa3b, v128
	v_exp_f32_e32 v128, v128
	v_pk_fma_f32 v[96:97], v[186:187], v[96:97], v[136:137] op_sel_hi:[0,1,1]
	v_pk_fma_f32 v[102:103], v[184:185], v[126:127], v[102:103] op_sel_hi:[0,1,1] neg_lo:[1,0,0] neg_hi:[1,0,0]
	v_pk_fma_f32 v[102:103], v[186:187], v[102:103], v[146:147] op_sel_hi:[0,1,1]
	v_add_f32_e32 v128, 1.0, v128
	v_rcp_f32_e32 v128, v128
	v_pk_fma_f32 v[98:99], v[184:185], v[122:123], v[98:99] op_sel_hi:[0,1,1] neg_lo:[1,0,0] neg_hi:[1,0,0]
	v_pk_fma_f32 v[98:99], v[186:187], v[98:99], v[138:139] op_sel_hi:[0,1,1]
	v_pk_fma_f32 v[92:93], v[180:181], v[124:125], v[92:93] op_sel_hi:[0,1,1] neg_lo:[1,0,0] neg_hi:[1,0,0]
	v_mul_f32_e32 v134, v134, v128
	v_mul_f32_e32 v128, 0x3d372713, v130
	v_mul_f32_e32 v128, v130, v128
	v_fma_f32 v128, v130, v128, v130
	v_mul_f32_e32 v128, 0x3f4c422a, v128
	v_add_f32_e32 v128, v128, v128
	v_mul_f32_e32 v128, 0xbfb8aa3b, v128
	v_exp_f32_e32 v128, v128
	v_pk_fma_f32 v[92:93], v[92:93], v[182:183], v[144:145] op_sel_hi:[1,0,1]
	v_pk_fma_f32 v[88:89], v[180:181], v[120:121], v[88:89] op_sel_hi:[0,1,1] neg_lo:[1,0,0] neg_hi:[1,0,0]
	v_pk_fma_f32 v[88:89], v[182:183], v[88:89], v[136:137] op_sel_hi:[0,1,1]
	v_add_f32_e32 v128, 1.0, v128
	v_rcp_f32_e32 v128, v128
	v_pk_fma_f32 v[94:95], v[180:181], v[126:127], v[94:95] op_sel_hi:[0,1,1] neg_lo:[1,0,0] neg_hi:[1,0,0]
	v_pk_fma_f32 v[94:95], v[94:95], v[182:183], v[146:147] op_sel_hi:[1,0,1]
	v_pk_fma_f32 v[90:91], v[180:181], v[122:123], v[90:91] op_sel_hi:[0,1,1] neg_lo:[1,0,0] neg_hi:[1,0,0]
	v_mul_f32_e32 v148, v130, v128
	v_mul_f32_e32 v128, 0x3d372713, v135
	v_mul_f32_e32 v128, v135, v128
	v_fma_f32 v128, v135, v128, v135
	v_mul_f32_e32 v128, 0x3f4c422a, v128
	v_add_f32_e32 v128, v128, v128
	v_mul_f32_e32 v128, 0xbfb8aa3b, v128
	v_exp_f32_e32 v128, v128
	v_cvt_pk_bf16_f32 v130, v132, v133
; __device__ __forceinline__ unsigned cvt_pk_bf16(float lo, float hi) { unsigned r; asm("v_cvt_pk_bf16_f32 %0, %1, %2" : "=v"(r) : "v"(lo), "v"(hi)); return r; }
; __device__ __forceinline__ float gelu_tanh(float v) { const float u = 0.7978845608028654f * (v + 0.044715f * v * v * v); return v * fast_sigmoid(2.0f * u); }
; __device__ __forceinline__ f32x4 ln_fix(const f32x4& a, float mu, float rs, const f32x4& cs, const f32x4& cb) { return (a - cs * mu) * rs + cb; }
; __device__ __forceinline__ float fast_sigmoid(float v) { return __builtin_amdgcn_rcpf(1.0f + __builtin_amdgcn_exp2f(-1.4426950408889634f * v)); }
;     __device__ __forceinline__ void operator()(const f32x4 (&acc)[2][2][4][2], const Unit& u, int wr, int wc, int fr_in, int fq_in) const {
;     ...
;             for (int n = 0; n < 2; ++n) { csv[n] = *(const f32x4*)(cs + n0 + bj * HALF + 4 * n); cbv[n] = *(const f32x4*)(cb + n0 + bj * HALF + 4 * n) + *(const f32x4*)(bias + n0 + bj * HALF + 4 * n); }
; #pragma unroll
;             for (int ai = 0; ai < 2; ++ai)
; #pragma unroll
;                 for (int m = 0; m < 4; ++m) { bf16_t* rowp = base + (size_t)(row0 + ai * HALF + m * 16) * 1024 + col0 + bj * HALF;
;                     f32x4 v0 = ln_fix(acc[ai][bj][m][0], rst.mu[ai][m], rst.rs[ai][m], csv[0], cbv[0]), v1 = ln_fix(acc[ai][bj][m][1], rst.mu[ai][m], rst.rs[ai][m], csv[1], cbv[1]);
; #pragma unroll
;                     for (int j = 0; j < 4; ++j) { v0[j] = gelu_tanh(v0[j]); v1[j] = gelu_tanh(v1[j]); }
;                     u32x4 w; w.x = cvt_pk_bf16(v0[0], v0[1]); w.y = cvt_pk_bf16(v0[2], v0[3]); w.z = cvt_pk_bf16(v1[0], v1[1]); w.w = cvt_pk_bf16(v1[2], v1[3]);
;                     *(u32x4*)rowp = w; } }
	v_cvt_pk_bf16_f32 v132, v142, v143
	v_pk_fma_f32 v[90:91], v[182:183], v[90:91], v[138:139] op_sel_hi:[0,1,1]
	v_add_f32_e32 v128, 1.0, v128
	v_rcp_f32_e32 v128, v128
	v_pk_fma_f32 v[80:81], v[176:177], v[120:121], v[80:81] op_sel_hi:[0,1,1] neg_lo:[1,0,0] neg_hi:[1,0,0]
	v_pk_fma_f32 v[80:81], v[80:81], v[178:179], v[136:137] op_sel_hi:[1,0,1]
	v_pk_fma_f32 v[82:83], v[176:177], v[122:123], v[82:83] op_sel_hi:[0,1,1] neg_lo:[1,0,0] neg_hi:[1,0,0]
	v_mul_f32_e32 v135, v135, v128
	v_mul_f32_e32 v128, 0x3d372713, v131
	v_mul_f32_e32 v128, v131, v128
	v_fma_f32 v128, v131, v128, v131
	v_mul_f32_e32 v128, 0x3f4c422a, v128
	v_add_f32_e32 v128, v128, v128
	v_mul_f32_e32 v128, 0xbfb8aa3b, v128
	v_exp_f32_e32 v128, v128
	v_pk_fma_f32 v[82:83], v[82:83], v[178:179], v[138:139] op_sel_hi:[1,0,1]
	v_pk_fma_f32 v[76:77], v[124:125], v[172:173], v[76:77] op_sel_hi:[1,0,1] neg_lo:[1,0,0] neg_hi:[1,0,0]
	v_pk_fma_f32 v[72:73], v[172:173], v[120:121], v[72:73] op_sel_hi:[0,1,1] neg_lo:[1,0,0] neg_hi:[1,0,0]
	v_add_f32_e32 v128, 1.0, v128
	v_rcp_f32_e32 v128, v128
	v_pk_fma_f32 v[76:77], v[76:77], v[174:175], v[144:145] op_sel_hi:[1,0,1]
	v_pk_fma_f32 v[72:73], v[72:73], v[174:175], v[136:137] op_sel_hi:[1,0,1]
	v_pk_fma_f32 v[74:75], v[172:173], v[122:123], v[74:75] op_sel_hi:[0,1,1] neg_lo:[1,0,0] neg_hi:[1,0,0]
	v_mul_f32_e32 v149, v131, v128
	v_lshl_add_u64 v[128:129], v[202:203], 0, v[140:141]
	v_cvt_pk_bf16_f32 v131, v134, v135
	v_cvt_pk_bf16_f32 v133, v148, v149
	global_store_dwordx4 v[128:129], v[130:133], off
	v_pk_fma_f32 v[74:75], v[74:75], v[174:175], v[138:139] op_sel_hi:[1,0,1]
	v_pk_fma_f32 v[68:69], v[124:125], v[168:169], v[68:69] op_sel_hi:[1,0,1] neg_lo:[1,0,0] neg_hi:[1,0,0]
	v_mul_f32_e32 v132, 0x3d372713, v116
	v_mul_f32_e32 v132, v116, v132
	v_fma_f32 v132, v116, v132, v116
	v_mul_f32_e32 v132, 0x3f4c422a, v132
	v_add_f32_e32 v132, v132, v132
	v_mul_f32_e32 v132, 0xbfb8aa3b, v132
	v_exp_f32_e32 v132, v132
	v_lshlrev_b64 v[130:131], 11, v[220:221]
	v_pk_fma_f32 v[68:69], v[68:69], v[170:171], v[144:145] op_sel_hi:[1,0,1]
	v_pk_fma_f32 v[64:65], v[120:121], v[168:169], v[64:65] op_sel_hi:[1,0,1] neg_lo:[1,0,0] neg_hi:[1,0,0]
	v_add_f32_e32 v132, 1.0, v132
	v_rcp_f32_e32 v132, v132
	v_pk_fma_f32 v[64:65], v[64:65], v[170:171], v[136:137] op_sel_hi:[1,0,1]
	v_mul_f32_e32 v116, v116, v132
	v_mul_f32_e32 v132, 0x3d372713, v112
	v_mul_f32_e32 v132, v112, v132
	v_fma_f32 v132, v112, v132, v112
	v_mul_f32_e32 v132, 0x3f4c422a, v132
	v_add_f32_e32 v132, v132, v132
	v_mul_f32_e32 v132, 0xbfb8aa3b, v132
	v_exp_f32_e32 v132, v132
	s_nop 0
	v_add_f32_e32 v132, 1.0, v132
	v_rcp_f32_e32 v132, v132
	s_nop 0
	v_mul_f32_e32 v132, v112, v132
	v_mul_f32_e32 v112, 0x3d372713, v117
	v_mul_f32_e32 v112, v117, v112
	v_fma_f32 v112, v117, v112, v117
	v_mul_f32_e32 v112, 0x3f4c422a, v112
	v_add_f32_e32 v112, v112, v112
	v_mul_f32_e32 v112, 0xbfb8aa3b, v112
	v_exp_f32_e32 v112, v112
	s_nop 0
	v_add_f32_e32 v112, 1.0, v112
	v_rcp_f32_e32 v112, v112
	s_nop 0
	v_mul_f32_e32 v117, v117, v112
	v_mul_f32_e32 v112, 0x3d372713, v113
	v_mul_f32_e32 v112, v113, v112
	v_fma_f32 v112, v113, v112, v113
	v_mul_f32_e32 v112, 0x3f4c422a, v112
	v_add_f32_e32 v112, v112, v112
	v_mul_f32_e32 v112, 0xbfb8aa3b, v112
	v_exp_f32_e32 v112, v112
	s_nop 0
	v_add_f32_e32 v112, 1.0, v112
	v_rcp_f32_e32 v112, v112
	s_nop 0
	v_mul_f32_e32 v133, v113, v112
	v_mul_f32_e32 v112, 0x3d372713, v118
	v_mul_f32_e32 v112, v118, v112
	v_fma_f32 v112, v118, v112, v118
	v_mul_f32_e32 v112, 0x3f4c422a, v112
	v_add_f32_e32 v112, v112, v112
	v_mul_f32_e32 v112, 0xbfb8aa3b, v112
	v_exp_f32_e32 v112, v112
	s_nop 0
	v_add_f32_e32 v112, 1.0, v112
	v_rcp_f32_e32 v112, v112
	s_nop 0
	v_mul_f32_e32 v118, v118, v112
	v_mul_f32_e32 v112, 0x3d372713, v114
	v_mul_f32_e32 v112, v114, v112
	v_fma_f32 v112, v114, v112, v114
	v_mul_f32_e32 v112, 0x3f4c422a, v112
	v_add_f32_e32 v112, v112, v112
	v_mul_f32_e32 v112, 0xbfb8aa3b, v112
	v_exp_f32_e32 v112, v112
	s_nop 0
	v_add_f32_e32 v112, 1.0, v112
	v_rcp_f32_e32 v112, v112
	s_nop 0
	v_mul_f32_e32 v134, v114, v112
	v_mul_f32_e32 v112, 0x3d372713, v119
	v_mul_f32_e32 v112, v119, v112
	v_fma_f32 v112, v119, v112, v119
	v_mul_f32_e32 v112, 0x3f4c422a, v112
	v_add_f32_e32 v112, v112, v112
	v_mul_f32_e32 v112, 0xbfb8aa3b, v112
	v_exp_f32_e32 v112, v112
	v_cvt_pk_bf16_f32 v114, v116, v117
	v_cvt_pk_bf16_f32 v116, v132, v133
	s_nop 0
	v_add_f32_e32 v112, 1.0, v112
	v_rcp_f32_e32 v112, v112
	s_nop 0
	v_mul_f32_e32 v119, v119, v112
	v_mul_f32_e32 v112, 0x3d372713, v115
	v_mul_f32_e32 v112, v115, v112
	v_fma_f32 v112, v115, v112, v115
	v_mul_f32_e32 v112, 0x3f4c422a, v112
	v_add_f32_e32 v112, v112, v112
	v_mul_f32_e32 v112, 0xbfb8aa3b, v112
	v_exp_f32_e32 v112, v112
	s_nop 0
	v_add_f32_e32 v112, 1.0, v112
	v_rcp_f32_e32 v112, v112
	s_nop 0
	v_mul_f32_e32 v135, v115, v112
	v_lshl_add_u64 v[112:113], v[202:203], 0, v[130:131]
	v_cvt_pk_bf16_f32 v115, v118, v119
	v_cvt_pk_bf16_f32 v117, v134, v135
	global_store_dwordx4 v[112:113], v[114:117], off
	s_nop 1
	v_mul_f32_e32 v116, 0x3d372713, v108
	v_mul_f32_e32 v116, v108, v116
	v_fma_f32 v116, v108, v116, v108
	v_mul_f32_e32 v116, 0x3f4c422a, v116
	v_add_f32_e32 v116, v116, v116
	v_mul_f32_e32 v116, 0xbfb8aa3b, v116
	v_exp_f32_e32 v116, v116
	v_lshlrev_b64 v[114:115], 11, v[218:219]
	v_add_f32_e32 v116, 1.0, v116
	v_rcp_f32_e32 v116, v116
	s_nop 0
	v_mul_f32_e32 v108, v108, v116
	v_mul_f32_e32 v116, 0x3d372713, v104
	v_mul_f32_e32 v116, v104, v116
	v_fma_f32 v116, v104, v116, v104
	v_mul_f32_e32 v116, 0x3f4c422a, v116
	v_add_f32_e32 v116, v116, v116
	v_mul_f32_e32 v116, 0xbfb8aa3b, v116
	v_exp_f32_e32 v116, v116
	s_nop 0
; __device__ __forceinline__ unsigned cvt_pk_bf16(float lo, float hi) { unsigned r; asm("v_cvt_pk_bf16_f32 %0, %1, %2" : "=v"(r) : "v"(lo), "v"(hi)); return r; }
; __device__ __forceinline__ float gelu_tanh(float v) { const float u = 0.7978845608028654f * (v + 0.044715f * v * v * v); return v * fast_sigmoid(2.0f * u); }
; __device__ __forceinline__ f32x4 ln_fix(const f32x4& a, float mu, float rs, const f32x4& cs, const f32x4& cb) { return (a - cs * mu) * rs + cb; }
; __device__ __forceinline__ float fast_sigmoid(float v) { return __builtin_amdgcn_rcpf(1.0f + __builtin_amdgcn_exp2f(-1.4426950408889634f * v)); }
;     __device__ __forceinline__ void operator()(const f32x4 (&acc)[2][2][4][2], const Unit& u, int wr, int wc, int fr_in, int fq_in) const {
;     ...
;             for (int n = 0; n < 2; ++n) { csv[n] = *(const f32x4*)(cs + n0 + bj * HALF + 4 * n); cbv[n] = *(const f32x4*)(cb + n0 + bj * HALF + 4 * n) + *(const f32x4*)(bias + n0 + bj * HALF + 4 * n); }
; #pragma unroll
;             for (int ai = 0; ai < 2; ++ai)
; #pragma unroll
;                 for (int m = 0; m < 4; ++m) { bf16_t* rowp = base + (size_t)(row0 + ai * HALF + m * 16) * 1024 + col0 + bj * HALF;
;                     f32x4 v0 = ln_fix(acc[ai][bj][m][0], rst.mu[ai][m], rst.rs[ai][m], csv[0], cbv[0]), v1 = ln_fix(acc[ai][bj][m][1], rst.mu[ai][m], rst.rs[ai][m], csv[1], cbv[1]);
; #pragma unroll
;                     for (int j = 0; j < 4; ++j) { v0[j] = gelu_tanh(v0[j]); v1[j] = gelu_tanh(v1[j]); }
;                     u32x4 w; w.x = cvt_pk_bf16(v0[0], v0[1]); w.y = cvt_pk_bf16(v0[2], v0[3]); w.z = cvt_pk_bf16(v1[0], v1[1]); w.w = cvt_pk_bf16(v1[2], v1[3]);
;                     *(u32x4*)rowp = w; } }
	v_add_f32_e32 v116, 1.0, v116
	v_rcp_f32_e32 v116, v116
	s_nop 0
	v_mul_f32_e32 v116, v104, v116
	v_mul_f32_e32 v104, 0x3d372713, v109
	v_mul_f32_e32 v104, v109, v104
	v_fma_f32 v104, v109, v104, v109
	v_mul_f32_e32 v104, 0x3f4c422a, v104
	v_add_f32_e32 v104, v104, v104
	v_mul_f32_e32 v104, 0xbfb8aa3b, v104
	v_exp_f32_e32 v104, v104
	s_nop 0
	v_add_f32_e32 v104, 1.0, v104
	v_rcp_f32_e32 v104, v104
	s_nop 0
	v_mul_f32_e32 v109, v109, v104
	v_mul_f32_e32 v104, 0x3d372713, v105
	v_mul_f32_e32 v104, v105, v104
	v_fma_f32 v104, v105, v104, v105
	v_mul_f32_e32 v104, 0x3f4c422a, v104
	v_add_f32_e32 v104, v104, v104
	v_mul_f32_e32 v104, 0xbfb8aa3b, v104
	v_exp_f32_e32 v104, v104
	s_nop 0
	v_add_f32_e32 v104, 1.0, v104
	v_rcp_f32_e32 v104, v104
	s_nop 0
	v_mul_f32_e32 v117, v105, v104
	v_mul_f32_e32 v104, 0x3d372713, v110
	v_mul_f32_e32 v104, v110, v104
	v_fma_f32 v104, v110, v104, v110
	v_mul_f32_e32 v104, 0x3f4c422a, v104
	v_add_f32_e32 v104, v104, v104
	v_mul_f32_e32 v104, 0xbfb8aa3b, v104
	v_exp_f32_e32 v104, v104
	s_nop 0
	v_add_f32_e32 v104, 1.0, v104
	v_rcp_f32_e32 v104, v104
	s_nop 0
	v_mul_f32_e32 v110, v110, v104
	v_mul_f32_e32 v104, 0x3d372713, v106
	v_mul_f32_e32 v104, v106, v104
	v_fma_f32 v104, v106, v104, v106
	v_mul_f32_e32 v104, 0x3f4c422a, v104
	v_add_f32_e32 v104, v104, v104
	v_mul_f32_e32 v104, 0xbfb8aa3b, v104
	v_exp_f32_e32 v104, v104
	s_nop 0
	v_add_f32_e32 v104, 1.0, v104
	v_rcp_f32_e32 v104, v104
	s_nop 0
	v_mul_f32_e32 v118, v106, v104
	v_mul_f32_e32 v104, 0x3d372713, v111
	v_mul_f32_e32 v104, v111, v104
	v_fma_f32 v104, v111, v104, v111
	v_mul_f32_e32 v104, 0x3f4c422a, v104
	v_add_f32_e32 v104, v104, v104
	v_mul_f32_e32 v104, 0xbfb8aa3b, v104
	v_exp_f32_e32 v104, v104
	v_cvt_pk_bf16_f32 v106, v108, v109
	v_cvt_pk_bf16_f32 v108, v116, v117
	s_nop 0
	v_add_f32_e32 v104, 1.0, v104
	v_rcp_f32_e32 v104, v104
	s_nop 0
	v_mul_f32_e32 v111, v111, v104
	v_mul_f32_e32 v104, 0x3d372713, v107
	v_mul_f32_e32 v104, v107, v104
	v_fma_f32 v104, v107, v104, v107
	v_mul_f32_e32 v104, 0x3f4c422a, v104
	v_add_f32_e32 v104, v104, v104
	v_mul_f32_e32 v104, 0xbfb8aa3b, v104
	v_exp_f32_e32 v104, v104
	s_nop 0
	v_add_f32_e32 v104, 1.0, v104
	v_rcp_f32_e32 v104, v104
	s_nop 0
	v_mul_f32_e32 v119, v107, v104
	v_lshl_add_u64 v[104:105], v[202:203], 0, v[114:115]
	v_cvt_pk_bf16_f32 v107, v110, v111
	v_cvt_pk_bf16_f32 v109, v118, v119
	global_store_dwordx4 v[104:105], v[106:109], off
	s_nop 1
	v_mul_f32_e32 v108, 0x3d372713, v100
	v_mul_f32_e32 v108, v100, v108
	v_fma_f32 v108, v100, v108, v100
	v_mul_f32_e32 v108, 0x3f4c422a, v108
	v_add_f32_e32 v108, v108, v108
	v_mul_f32_e32 v108, 0xbfb8aa3b, v108
	v_exp_f32_e32 v108, v108
	v_lshlrev_b64 v[106:107], 11, v[216:217]
	v_add_f32_e32 v108, 1.0, v108
	v_rcp_f32_e32 v108, v108
	s_nop 0
	v_mul_f32_e32 v100, v100, v108
	v_mul_f32_e32 v108, 0x3d372713, v96
	v_mul_f32_e32 v108, v96, v108
	v_fma_f32 v108, v96, v108, v96
	v_mul_f32_e32 v108, 0x3f4c422a, v108
	v_add_f32_e32 v108, v108, v108
	v_mul_f32_e32 v108, 0xbfb8aa3b, v108
	v_exp_f32_e32 v108, v108
	s_nop 0
	v_add_f32_e32 v108, 1.0, v108
	v_rcp_f32_e32 v108, v108
	s_nop 0
	v_mul_f32_e32 v108, v96, v108
	v_mul_f32_e32 v96, 0x3d372713, v101
	v_mul_f32_e32 v96, v101, v96
	v_fma_f32 v96, v101, v96, v101
	v_mul_f32_e32 v96, 0x3f4c422a, v96
	v_add_f32_e32 v96, v96, v96
	v_mul_f32_e32 v96, 0xbfb8aa3b, v96
	v_exp_f32_e32 v96, v96
	s_nop 0
	v_add_f32_e32 v96, 1.0, v96
	v_rcp_f32_e32 v96, v96
	s_nop 0
	v_mul_f32_e32 v101, v101, v96
	v_mul_f32_e32 v96, 0x3d372713, v97
	v_mul_f32_e32 v96, v97, v96
	v_fma_f32 v96, v97, v96, v97
	v_mul_f32_e32 v96, 0x3f4c422a, v96
	v_add_f32_e32 v96, v96, v96
	v_mul_f32_e32 v96, 0xbfb8aa3b, v96
	v_exp_f32_e32 v96, v96
	s_nop 0
	v_add_f32_e32 v96, 1.0, v96
	v_rcp_f32_e32 v96, v96
	s_nop 0
	v_mul_f32_e32 v109, v97, v96
	v_mul_f32_e32 v96, 0x3d372713, v102
	v_mul_f32_e32 v96, v102, v96
	v_fma_f32 v96, v102, v96, v102
	v_mul_f32_e32 v96, 0x3f4c422a, v96
	v_add_f32_e32 v96, v96, v96
	v_mul_f32_e32 v96, 0xbfb8aa3b, v96
	v_exp_f32_e32 v96, v96
	s_nop 0
	v_add_f32_e32 v96, 1.0, v96
	v_rcp_f32_e32 v96, v96
	s_nop 0
	v_mul_f32_e32 v102, v102, v96
	v_mul_f32_e32 v96, 0x3d372713, v98
	v_mul_f32_e32 v96, v98, v96
	v_fma_f32 v96, v98, v96, v98
	v_mul_f32_e32 v96, 0x3f4c422a, v96
	v_add_f32_e32 v96, v96, v96
	v_mul_f32_e32 v96, 0xbfb8aa3b, v96
	v_exp_f32_e32 v96, v96
	s_nop 0
	v_add_f32_e32 v96, 1.0, v96
	v_rcp_f32_e32 v96, v96
	s_nop 0
	v_mul_f32_e32 v110, v98, v96
	v_mul_f32_e32 v96, 0x3d372713, v103
	v_mul_f32_e32 v96, v103, v96
	v_fma_f32 v96, v103, v96, v103
	v_mul_f32_e32 v96, 0x3f4c422a, v96
	v_add_f32_e32 v96, v96, v96
	v_mul_f32_e32 v96, 0xbfb8aa3b, v96
	v_exp_f32_e32 v96, v96
	v_cvt_pk_bf16_f32 v98, v100, v101
	v_cvt_pk_bf16_f32 v100, v108, v109
	s_nop 0
	v_add_f32_e32 v96, 1.0, v96
	v_rcp_f32_e32 v96, v96
	s_nop 0
	v_mul_f32_e32 v103, v103, v96
	v_mul_f32_e32 v96, 0x3d372713, v99
	v_mul_f32_e32 v96, v99, v96
	v_fma_f32 v96, v99, v96, v99
	v_mul_f32_e32 v96, 0x3f4c422a, v96
	v_add_f32_e32 v96, v96, v96
	v_mul_f32_e32 v96, 0xbfb8aa3b, v96
	v_exp_f32_e32 v96, v96
	s_nop 0
	v_add_f32_e32 v96, 1.0, v96
	v_rcp_f32_e32 v96, v96
	s_nop 0
	v_mul_f32_e32 v111, v99, v96
	v_lshl_add_u64 v[96:97], v[202:203], 0, v[106:107]
	v_cvt_pk_bf16_f32 v99, v102, v103
	v_cvt_pk_bf16_f32 v101, v110, v111
	global_store_dwordx4 v[96:97], v[98:101], off
	s_nop 1
	v_mul_f32_e32 v100, 0x3d372713, v92
	v_mul_f32_e32 v100, v92, v100
	v_fma_f32 v100, v92, v100, v92
	v_mul_f32_e32 v100, 0x3f4c422a, v100
	v_add_f32_e32 v100, v100, v100
	v_mul_f32_e32 v100, 0xbfb8aa3b, v100
	v_exp_f32_e32 v100, v100
	v_lshlrev_b64 v[98:99], 11, v[214:215]
	v_add_f32_e32 v100, 1.0, v100
; __device__ __forceinline__ unsigned cvt_pk_bf16(float lo, float hi) { unsigned r; asm("v_cvt_pk_bf16_f32 %0, %1, %2" : "=v"(r) : "v"(lo), "v"(hi)); return r; }
; __device__ __forceinline__ float gelu_tanh(float v) { const float u = 0.7978845608028654f * (v + 0.044715f * v * v * v); return v * fast_sigmoid(2.0f * u); }
; __device__ __forceinline__ f32x4 ln_fix(const f32x4& a, float mu, float rs, const f32x4& cs, const f32x4& cb) { return (a - cs * mu) * rs + cb; }
; __device__ __forceinline__ float fast_sigmoid(float v) { return __builtin_amdgcn_rcpf(1.0f + __builtin_amdgcn_exp2f(-1.4426950408889634f * v)); }
;     __device__ __forceinline__ void operator()(const f32x4 (&acc)[2][2][4][2], const Unit& u, int wr, int wc, int fr_in, int fq_in) const {
;     ...
;             for (int n = 0; n < 2; ++n) { csv[n] = *(const f32x4*)(cs + n0 + bj * HALF + 4 * n); cbv[n] = *(const f32x4*)(cb + n0 + bj * HALF + 4 * n) + *(const f32x4*)(bias + n0 + bj * HALF + 4 * n); }
; #pragma unroll
;             for (int ai = 0; ai < 2; ++ai)
; #pragma unroll
;                 for (int m = 0; m < 4; ++m) { bf16_t* rowp = base + (size_t)(row0 + ai * HALF + m * 16) * 1024 + col0 + bj * HALF;
;                     f32x4 v0 = ln_fix(acc[ai][bj][m][0], rst.mu[ai][m], rst.rs[ai][m], csv[0], cbv[0]), v1 = ln_fix(acc[ai][bj][m][1], rst.mu[ai][m], rst.rs[ai][m], csv[1], cbv[1]);
; #pragma unroll
;                     for (int j = 0; j < 4; ++j) { v0[j] = gelu_tanh(v0[j]); v1[j] = gelu_tanh(v1[j]); }
;                     u32x4 w; w.x = cvt_pk_bf16(v0[0], v0[1]); w.y = cvt_pk_bf16(v0[2], v0[3]); w.z = cvt_pk_bf16(v1[0], v1[1]); w.w = cvt_pk_bf16(v1[2], v1[3]);
;                     *(u32x4*)rowp = w; } }
	v_rcp_f32_e32 v100, v100
	s_nop 0
	v_mul_f32_e32 v92, v92, v100
	v_mul_f32_e32 v100, 0x3d372713, v88
	v_mul_f32_e32 v100, v88, v100
	v_fma_f32 v100, v88, v100, v88
	v_mul_f32_e32 v100, 0x3f4c422a, v100
	v_add_f32_e32 v100, v100, v100
	v_mul_f32_e32 v100, 0xbfb8aa3b, v100
	v_exp_f32_e32 v100, v100
	s_nop 0
	v_add_f32_e32 v100, 1.0, v100
	v_rcp_f32_e32 v100, v100
	s_nop 0
	v_mul_f32_e32 v100, v88, v100
	v_mul_f32_e32 v88, 0x3d372713, v93
	v_mul_f32_e32 v88, v93, v88
	v_fma_f32 v88, v93, v88, v93
	v_mul_f32_e32 v88, 0x3f4c422a, v88
	v_add_f32_e32 v88, v88, v88
	v_mul_f32_e32 v88, 0xbfb8aa3b, v88
	v_exp_f32_e32 v88, v88
	s_nop 0
	v_add_f32_e32 v88, 1.0, v88
	v_rcp_f32_e32 v88, v88
	s_nop 0
	v_mul_f32_e32 v93, v93, v88
	v_mul_f32_e32 v88, 0x3d372713, v89
	v_mul_f32_e32 v88, v89, v88
	v_fma_f32 v88, v89, v88, v89
	v_mul_f32_e32 v88, 0x3f4c422a, v88
	v_add_f32_e32 v88, v88, v88
	v_mul_f32_e32 v88, 0xbfb8aa3b, v88
	v_exp_f32_e32 v88, v88
	s_nop 0
	v_add_f32_e32 v88, 1.0, v88
	v_rcp_f32_e32 v88, v88
	s_nop 0
	v_mul_f32_e32 v101, v89, v88
	v_mul_f32_e32 v88, 0x3d372713, v94
	v_mul_f32_e32 v88, v94, v88
	v_fma_f32 v88, v94, v88, v94
	v_mul_f32_e32 v88, 0x3f4c422a, v88
	v_add_f32_e32 v88, v88, v88
	v_mul_f32_e32 v88, 0xbfb8aa3b, v88
	v_exp_f32_e32 v88, v88
	s_nop 0
	v_add_f32_e32 v88, 1.0, v88
	v_rcp_f32_e32 v88, v88
	s_nop 0
	v_mul_f32_e32 v94, v94, v88
	v_mul_f32_e32 v88, 0x3d372713, v90
	v_mul_f32_e32 v88, v90, v88
	v_fma_f32 v88, v90, v88, v90
	v_mul_f32_e32 v88, 0x3f4c422a, v88
	v_add_f32_e32 v88, v88, v88
	v_mul_f32_e32 v88, 0xbfb8aa3b, v88
	v_exp_f32_e32 v88, v88
	s_nop 0
	v_add_f32_e32 v88, 1.0, v88
	v_rcp_f32_e32 v88, v88
	s_nop 0
	v_mul_f32_e32 v102, v90, v88
	v_mul_f32_e32 v88, 0x3d372713, v95
	v_mul_f32_e32 v88, v95, v88
	v_fma_f32 v88, v95, v88, v95
	v_mul_f32_e32 v88, 0x3f4c422a, v88
	v_add_f32_e32 v88, v88, v88
	v_mul_f32_e32 v88, 0xbfb8aa3b, v88
	v_exp_f32_e32 v88, v88
	v_cvt_pk_bf16_f32 v90, v92, v93
	v_cvt_pk_bf16_f32 v92, v100, v101
	s_nop 0
	v_add_f32_e32 v88, 1.0, v88
	v_rcp_f32_e32 v88, v88
	s_nop 0
	v_mul_f32_e32 v95, v95, v88
	v_mul_f32_e32 v88, 0x3d372713, v91
	v_mul_f32_e32 v88, v91, v88
	v_fma_f32 v88, v91, v88, v91
	v_mul_f32_e32 v88, 0x3f4c422a, v88
	v_add_f32_e32 v88, v88, v88
	v_mul_f32_e32 v88, 0xbfb8aa3b, v88
	v_exp_f32_e32 v88, v88
	s_nop 0
	v_add_f32_e32 v88, 1.0, v88
	v_rcp_f32_e32 v88, v88
	s_nop 0
	v_mul_f32_e32 v103, v91, v88
	v_lshl_add_u64 v[88:89], v[202:203], 0, v[98:99]
	v_cvt_pk_bf16_f32 v93, v102, v103
	v_cvt_pk_bf16_f32 v91, v94, v95
	global_store_dwordx4 v[88:89], v[90:93], off
	s_nop 1
	v_pk_fma_f32 v[92:93], v[124:125], v[176:177], v[84:85] op_sel_hi:[1,0,1] neg_lo:[1,0,0] neg_hi:[1,0,0]
	v_xor_b32_e32 v85, 0x80000000, v127
	v_pk_fma_f32 v[92:93], v[92:93], v[178:179], v[144:145] op_sel_hi:[1,0,1]
	v_xor_b32_e32 v84, 0x80000000, v126
	v_mul_f32_e32 v94, 0x3d372713, v92
	v_mul_f32_e32 v94, v92, v94
	v_fma_f32 v94, v92, v94, v92
	v_mul_f32_e32 v94, 0x3f4c422a, v94
	v_add_f32_e32 v94, v94, v94
	v_mul_f32_e32 v94, 0xbfb8aa3b, v94
	v_exp_f32_e32 v94, v94
	v_pk_fma_f32 v[86:87], v[84:85], v[176:177], v[86:87] op_sel_hi:[1,0,1]
	v_lshlrev_b64 v[90:91], 11, v[212:213]
	v_pk_fma_f32 v[86:87], v[86:87], v[178:179], v[146:147] op_sel_hi:[1,0,1]
	v_add_f32_e32 v94, 1.0, v94
	v_rcp_f32_e32 v94, v94
	v_pk_fma_f32 v[78:79], v[84:85], v[172:173], v[78:79] op_sel_hi:[1,0,1]
	v_pk_fma_f32 v[70:71], v[84:85], v[168:169], v[70:71] op_sel_hi:[1,0,1]
	v_pk_fma_f32 v[78:79], v[78:79], v[174:175], v[146:147] op_sel_hi:[1,0,1]
	v_mul_f32_e32 v92, v92, v94
	v_mul_f32_e32 v94, 0x3d372713, v80
	v_mul_f32_e32 v94, v80, v94
	v_fma_f32 v94, v80, v94, v80
	v_mul_f32_e32 v94, 0x3f4c422a, v94
	v_add_f32_e32 v94, v94, v94
	v_mul_f32_e32 v94, 0xbfb8aa3b, v94
	v_exp_f32_e32 v94, v94
	v_pk_fma_f32 v[70:71], v[70:71], v[170:171], v[146:147] op_sel_hi:[1,0,1]
	v_add_f32_e32 v94, 1.0, v94
	v_rcp_f32_e32 v94, v94
	s_nop 0
	v_mul_f32_e32 v94, v80, v94
	v_mul_f32_e32 v80, 0x3d372713, v93
	v_mul_f32_e32 v80, v93, v80
	v_fma_f32 v80, v93, v80, v93
	v_mul_f32_e32 v80, 0x3f4c422a, v80
	v_add_f32_e32 v80, v80, v80
	v_mul_f32_e32 v80, 0xbfb8aa3b, v80
	v_exp_f32_e32 v80, v80
	s_nop 0
	v_add_f32_e32 v80, 1.0, v80
	v_rcp_f32_e32 v80, v80
	s_nop 0
	v_mul_f32_e32 v93, v93, v80
	v_mul_f32_e32 v80, 0x3d372713, v81
	v_mul_f32_e32 v80, v81, v80
	v_fma_f32 v80, v81, v80, v81
	v_mul_f32_e32 v80, 0x3f4c422a, v80
	v_add_f32_e32 v80, v80, v80
	v_mul_f32_e32 v80, 0xbfb8aa3b, v80
	v_exp_f32_e32 v80, v80
	s_nop 0
	v_add_f32_e32 v80, 1.0, v80
	v_rcp_f32_e32 v80, v80
	s_nop 0
	v_mul_f32_e32 v95, v81, v80
	v_mul_f32_e32 v80, 0x3d372713, v86
	v_mul_f32_e32 v80, v86, v80
	v_fma_f32 v80, v86, v80, v86
	v_mul_f32_e32 v80, 0x3f4c422a, v80
	v_add_f32_e32 v80, v80, v80
	v_mul_f32_e32 v80, 0xbfb8aa3b, v80
	v_exp_f32_e32 v80, v80
	s_nop 0
	v_add_f32_e32 v80, 1.0, v80
	v_rcp_f32_e32 v80, v80
	s_nop 0
	v_mul_f32_e32 v86, v86, v80
	v_mul_f32_e32 v80, 0x3d372713, v82
	v_mul_f32_e32 v80, v82, v80
	v_fma_f32 v80, v82, v80, v82
	v_mul_f32_e32 v80, 0x3f4c422a, v80
	v_add_f32_e32 v80, v80, v80
	v_mul_f32_e32 v80, 0xbfb8aa3b, v80
	v_exp_f32_e32 v80, v80
	s_nop 0
	v_add_f32_e32 v80, 1.0, v80
	v_rcp_f32_e32 v80, v80
	s_nop 0
	v_mul_f32_e32 v82, v82, v80
	v_mul_f32_e32 v80, 0x3d372713, v87
	v_mul_f32_e32 v80, v87, v80
	v_fma_f32 v80, v87, v80, v87
	v_mul_f32_e32 v80, 0x3f4c422a, v80
	v_add_f32_e32 v80, v80, v80
	v_mul_f32_e32 v80, 0xbfb8aa3b, v80
	v_exp_f32_e32 v80, v80
	s_nop 0
	v_add_f32_e32 v80, 1.0, v80
	v_rcp_f32_e32 v80, v80
	s_nop 0
	v_mul_f32_e32 v87, v87, v80
	v_mul_f32_e32 v80, 0x3d372713, v83
	v_mul_f32_e32 v80, v83, v80
	v_fma_f32 v80, v83, v80, v83
	v_mul_f32_e32 v80, 0x3f4c422a, v80
; __device__ __forceinline__ unsigned cvt_pk_bf16(float lo, float hi) { unsigned r; asm("v_cvt_pk_bf16_f32 %0, %1, %2" : "=v"(r) : "v"(lo), "v"(hi)); return r; }
; __device__ __forceinline__ float gelu_tanh(float v) { const float u = 0.7978845608028654f * (v + 0.044715f * v * v * v); return v * fast_sigmoid(2.0f * u); }
; __device__ __forceinline__ f32x4 ln_fix(const f32x4& a, float mu, float rs, const f32x4& cs, const f32x4& cb) { return (a - cs * mu) * rs + cb; }
; __device__ __forceinline__ float fast_sigmoid(float v) { return __builtin_amdgcn_rcpf(1.0f + __builtin_amdgcn_exp2f(-1.4426950408889634f * v)); }
;     __device__ __forceinline__ void operator()(const f32x4 (&acc)[2][2][4][2], const Unit& u, int wr, int wc, int fr_in, int fq_in) const {
;     ...
;             for (int n = 0; n < 2; ++n) { csv[n] = *(const f32x4*)(cs + n0 + bj * HALF + 4 * n); cbv[n] = *(const f32x4*)(cb + n0 + bj * HALF + 4 * n) + *(const f32x4*)(bias + n0 + bj * HALF + 4 * n); }
; #pragma unroll
;             for (int ai = 0; ai < 2; ++ai)
; #pragma unroll
;                 for (int m = 0; m < 4; ++m) { bf16_t* rowp = base + (size_t)(row0 + ai * HALF + m * 16) * 1024 + col0 + bj * HALF;
;                     f32x4 v0 = ln_fix(acc[ai][bj][m][0], rst.mu[ai][m], rst.rs[ai][m], csv[0], cbv[0]), v1 = ln_fix(acc[ai][bj][m][1], rst.mu[ai][m], rst.rs[ai][m], csv[1], cbv[1]);
; #pragma unroll
;                     for (int j = 0; j < 4; ++j) { v0[j] = gelu_tanh(v0[j]); v1[j] = gelu_tanh(v1[j]); }
;                     u32x4 w; w.x = cvt_pk_bf16(v0[0], v0[1]); w.y = cvt_pk_bf16(v0[2], v0[3]); w.z = cvt_pk_bf16(v1[0], v1[1]); w.w = cvt_pk_bf16(v1[2], v1[3]);
;                     *(u32x4*)rowp = w; } }
	v_add_f32_e32 v80, v80, v80
	v_mul_f32_e32 v80, 0xbfb8aa3b, v80
	v_exp_f32_e32 v80, v80
	s_nop 0
	v_add_f32_e32 v80, 1.0, v80
	v_rcp_f32_e32 v80, v80
	s_nop 0
	v_mul_f32_e32 v83, v83, v80
	v_lshl_add_u64 v[80:81], v[202:203], 0, v[90:91]
	v_cvt_pk_bf16_f32 v91, v86, v87
	v_mul_f32_e32 v86, 0x3d372713, v76
	v_mul_f32_e32 v86, v76, v86
	v_fma_f32 v86, v76, v86, v76
	v_mul_f32_e32 v86, 0x3f4c422a, v86
	v_add_f32_e32 v86, v86, v86
	v_mul_f32_e32 v86, 0xbfb8aa3b, v86
	v_exp_f32_e32 v86, v86
	v_cvt_pk_bf16_f32 v90, v92, v93
	v_cvt_pk_bf16_f32 v92, v94, v95
	v_cvt_pk_bf16_f32 v93, v82, v83
	global_store_dwordx4 v[80:81], v[90:93], off
	v_add_f32_e32 v86, 1.0, v86
	v_rcp_f32_e32 v86, v86
	v_lshlrev_b64 v[82:83], 11, v[210:211]
	v_mul_f32_e32 v76, v76, v86
	v_mul_f32_e32 v86, 0x3d372713, v72
	v_mul_f32_e32 v86, v72, v86
	v_fma_f32 v86, v72, v86, v72
	v_mul_f32_e32 v86, 0x3f4c422a, v86
	v_add_f32_e32 v86, v86, v86
	v_mul_f32_e32 v86, 0xbfb8aa3b, v86
	v_exp_f32_e32 v86, v86
	s_nop 0
	v_add_f32_e32 v86, 1.0, v86
	v_rcp_f32_e32 v86, v86
	s_nop 0
	v_mul_f32_e32 v86, v72, v86
	v_mul_f32_e32 v72, 0x3d372713, v77
	v_mul_f32_e32 v72, v77, v72
	v_fma_f32 v72, v77, v72, v77
	v_mul_f32_e32 v72, 0x3f4c422a, v72
	v_add_f32_e32 v72, v72, v72
	v_mul_f32_e32 v72, 0xbfb8aa3b, v72
	v_exp_f32_e32 v72, v72
	s_nop 0
	v_add_f32_e32 v72, 1.0, v72
	v_rcp_f32_e32 v72, v72
	s_nop 0
	v_mul_f32_e32 v77, v77, v72
	v_mul_f32_e32 v72, 0x3d372713, v73
	v_mul_f32_e32 v72, v73, v72
	v_fma_f32 v72, v73, v72, v73
	v_mul_f32_e32 v72, 0x3f4c422a, v72
	v_add_f32_e32 v72, v72, v72
	v_mul_f32_e32 v72, 0xbfb8aa3b, v72
	v_exp_f32_e32 v72, v72
	s_nop 0
	v_add_f32_e32 v72, 1.0, v72
	v_rcp_f32_e32 v72, v72
	s_nop 0
	v_mul_f32_e32 v87, v73, v72
	v_mul_f32_e32 v72, 0x3d372713, v78
	v_mul_f32_e32 v72, v78, v72
	v_fma_f32 v72, v78, v72, v78
	v_mul_f32_e32 v72, 0x3f4c422a, v72
	v_add_f32_e32 v72, v72, v72
	v_mul_f32_e32 v72, 0xbfb8aa3b, v72
	v_exp_f32_e32 v72, v72
	s_nop 0
	v_add_f32_e32 v72, 1.0, v72
	v_rcp_f32_e32 v72, v72
	s_nop 0
	v_mul_f32_e32 v78, v78, v72
	v_mul_f32_e32 v72, 0x3d372713, v74
	v_mul_f32_e32 v72, v74, v72
	v_fma_f32 v72, v74, v72, v74
	v_mul_f32_e32 v72, 0x3f4c422a, v72
	v_add_f32_e32 v72, v72, v72
	v_mul_f32_e32 v72, 0xbfb8aa3b, v72
	v_exp_f32_e32 v72, v72
	s_nop 0
	v_add_f32_e32 v72, 1.0, v72
	v_rcp_f32_e32 v72, v72
	s_nop 0
	v_mul_f32_e32 v90, v74, v72
	v_mul_f32_e32 v72, 0x3d372713, v79
	v_mul_f32_e32 v72, v79, v72
	v_fma_f32 v72, v79, v72, v79
	v_mul_f32_e32 v72, 0x3f4c422a, v72
	v_add_f32_e32 v72, v72, v72
	v_mul_f32_e32 v72, 0xbfb8aa3b, v72
	v_exp_f32_e32 v72, v72
	v_cvt_pk_bf16_f32 v74, v76, v77
	v_cvt_pk_bf16_f32 v76, v86, v87
	s_nop 0
	v_add_f32_e32 v72, 1.0, v72
	v_rcp_f32_e32 v72, v72
	s_nop 0
	v_mul_f32_e32 v79, v79, v72
	v_mul_f32_e32 v72, 0x3d372713, v75
	v_mul_f32_e32 v72, v75, v72
	v_fma_f32 v72, v75, v72, v75
	v_mul_f32_e32 v72, 0x3f4c422a, v72
	v_add_f32_e32 v72, v72, v72
	v_mul_f32_e32 v72, 0xbfb8aa3b, v72
	v_exp_f32_e32 v72, v72
	s_nop 0
	v_add_f32_e32 v72, 1.0, v72
	v_rcp_f32_e32 v72, v72
	s_nop 0
	v_mul_f32_e32 v91, v75, v72
	v_lshl_add_u64 v[72:73], v[202:203], 0, v[82:83]
	v_cvt_pk_bf16_f32 v77, v90, v91
	v_cvt_pk_bf16_f32 v75, v78, v79
	global_store_dwordx4 v[72:73], v[74:77], off
	s_nop 1
	v_xor_b32_e32 v77, 0x80000000, v123
	v_xor_b32_e32 v76, 0x80000000, v122
	v_pk_fma_f32 v[66:67], v[76:77], v[168:169], v[66:67] op_sel_hi:[1,0,1]
	v_mul_f32_e32 v76, 0x3d372713, v68
	v_mul_f32_e32 v76, v68, v76
	v_fma_f32 v76, v68, v76, v68
	v_mul_f32_e32 v76, 0x3f4c422a, v76
	v_add_f32_e32 v76, v76, v76
	v_mul_f32_e32 v76, 0xbfb8aa3b, v76
	v_exp_f32_e32 v76, v76
	v_pk_fma_f32 v[66:67], v[66:67], v[170:171], v[138:139] op_sel_hi:[1,0,1]
	v_lshlrev_b64 v[74:75], 11, v[208:209]
	v_lshl_add_u64 v[74:75], v[202:203], 0, v[74:75]
	v_add_f32_e32 v76, 1.0, v76
	v_rcp_f32_e32 v76, v76
	s_nop 0
	v_mul_f32_e32 v68, v68, v76
	v_mul_f32_e32 v76, 0x3d372713, v64
	v_mul_f32_e32 v76, v64, v76
	v_fma_f32 v76, v64, v76, v64
	v_mul_f32_e32 v76, 0x3f4c422a, v76
	v_add_f32_e32 v76, v76, v76
	v_mul_f32_e32 v76, 0xbfb8aa3b, v76
	v_exp_f32_e32 v76, v76
	s_nop 0
	v_add_f32_e32 v76, 1.0, v76
	v_rcp_f32_e32 v76, v76
	s_nop 0
	v_mul_f32_e32 v76, v64, v76
	v_mul_f32_e32 v64, 0x3d372713, v69
	v_mul_f32_e32 v64, v69, v64
	v_fma_f32 v64, v69, v64, v69
	v_mul_f32_e32 v64, 0x3f4c422a, v64
	v_add_f32_e32 v64, v64, v64
	v_mul_f32_e32 v64, 0xbfb8aa3b, v64
	v_exp_f32_e32 v64, v64
	s_nop 0
	v_add_f32_e32 v64, 1.0, v64
	v_rcp_f32_e32 v64, v64
	s_nop 0
	v_mul_f32_e32 v64, v69, v64
	v_mul_f32_e32 v69, 0x3d372713, v65
	v_mul_f32_e32 v69, v65, v69
	v_fma_f32 v69, v65, v69, v65
	v_mul_f32_e32 v69, 0x3f4c422a, v69
	v_add_f32_e32 v69, v69, v69
	v_mul_f32_e32 v69, 0xbfb8aa3b, v69
	v_exp_f32_e32 v69, v69
	v_cvt_pk_bf16_f32 v64, v68, v64
	s_nop 0
	v_add_f32_e32 v69, 1.0, v69
	v_rcp_f32_e32 v69, v69
	s_nop 0
	v_mul_f32_e32 v69, v65, v69
	v_mul_f32_e32 v65, 0x3d372713, v70
	v_mul_f32_e32 v65, v70, v65
	v_fma_f32 v65, v70, v65, v70
	v_mul_f32_e32 v65, 0x3f4c422a, v65
	v_add_f32_e32 v65, v65, v65
	v_mul_f32_e32 v65, 0xbfb8aa3b, v65
	v_exp_f32_e32 v65, v65
	s_nop 0
	v_add_f32_e32 v65, 1.0, v65
	v_rcp_f32_e32 v65, v65
	s_nop 0
	v_mul_f32_e32 v65, v70, v65
	v_mul_f32_e32 v70, 0x3d372713, v66
	v_mul_f32_e32 v70, v66, v70
	v_fma_f32 v70, v66, v70, v66
	v_mul_f32_e32 v70, 0x3f4c422a, v70
	v_add_f32_e32 v70, v70, v70
	v_mul_f32_e32 v70, 0xbfb8aa3b, v70
	v_exp_f32_e32 v70, v70
	s_nop 0
	v_add_f32_e32 v70, 1.0, v70
	v_rcp_f32_e32 v70, v70
	s_nop 0
	v_mul_f32_e32 v70, v66, v70
	v_mul_f32_e32 v66, 0x3d372713, v71
	v_mul_f32_e32 v66, v71, v66
	v_fma_f32 v66, v71, v66, v71
	v_mul_f32_e32 v66, 0x3f4c422a, v66
	v_add_f32_e32 v66, v66, v66
	v_mul_f32_e32 v66, 0xbfb8aa3b, v66
	v_exp_f32_e32 v66, v66
	s_nop 0
	v_add_f32_e32 v66, 1.0, v66
	v_rcp_f32_e32 v66, v66
	s_nop 0
	v_mul_f32_e32 v66, v71, v66
	v_mul_f32_e32 v71, 0x3d372713, v67
	v_mul_f32_e32 v71, v67, v71
	v_fma_f32 v71, v67, v71, v67
	v_mul_f32_e32 v71, 0x3f4c422a, v71
	v_add_f32_e32 v71, v71, v71
	v_mul_f32_e32 v71, 0xbfb8aa3b, v71
	v_exp_f32_e32 v71, v71
	v_cvt_pk_bf16_f32 v65, v65, v66
	v_cvt_pk_bf16_f32 v66, v76, v69
	s_nop 0
	v_add_f32_e32 v71, 1.0, v71
	v_rcp_f32_e32 v71, v71
	s_nop 0
	v_mul_f32_e32 v67, v67, v71
	v_cvt_pk_bf16_f32 v67, v70, v67
	global_store_dwordx4 v[74:75], v[64:67], off
	global_load_dwordx4 v[64:67], v[204:205], off offset:528
	s_nop 0
	global_load_dwordx4 v[68:71], v[204:205], off offset:512
	global_load_dwordx4 v[84:87], v[206:207], off offset:528
	global_load_dwordx4 v[90:93], v[206:207], off offset:512
	global_load_dwordx4 v[98:101], v[200:201], off offset:528
	global_load_dwordx4 v[106:109], v[200:201], off offset:512
	s_waitcnt vmcnt(5)
; __device__ __forceinline__ float gelu_tanh(float v) { const float u = 0.7978845608028654f * (v + 0.044715f * v * v * v); return v * fast_sigmoid(2.0f * u); }
; __device__ __forceinline__ f32x4 ln_fix(const f32x4& a, float mu, float rs, const f32x4& cs, const f32x4& cb) { return (a - cs * mu) * rs + cb; }
;     __device__ __forceinline__ void operator()(const f32x4 (&acc)[2][2][4][2], const Unit& u, int wr, int wc, int fr_in, int fq_in) const {
;     ...
;             for (int n = 0; n < 2; ++n) { csv[n] = *(const f32x4*)(cs + n0 + bj * HALF + 4 * n); cbv[n] = *(const f32x4*)(cb + n0 + bj * HALF + 4 * n) + *(const f32x4*)(bias + n0 + bj * HALF + 4 * n); }
; #pragma unroll
;             for (int ai = 0; ai < 2; ++ai)
; #pragma unroll
;                 for (int m = 0; m < 4; ++m) { bf16_t* rowp = base + (size_t)(row0 + ai * HALF + m * 16) * 1024 + col0 + bj * HALF;
;                     f32x4 v0 = ln_fix(acc[ai][bj][m][0], rst.mu[ai][m], rst.rs[ai][m], csv[0], cbv[0]), v1 = ln_fix(acc[ai][bj][m][1], rst.mu[ai][m], rst.rs[ai][m], csv[1], cbv[1]);
; #pragma unroll
;                     for (int j = 0; j < 4; ++j) { v0[j] = gelu_tanh(v0[j]); v1[j] = gelu_tanh(v1[j]); }
	v_pk_fma_f32 v[56:57], v[196:197], v[64:65], v[56:57] op_sel_hi:[0,1,1] neg_lo:[1,0,0] neg_hi:[1,0,0]
	s_waitcnt vmcnt(4)
	v_pk_fma_f32 v[60:61], v[196:197], v[68:69], v[60:61] op_sel_hi:[0,1,1] neg_lo:[1,0,0] neg_hi:[1,0,0]
	v_pk_fma_f32 v[62:63], v[196:197], v[70:71], v[62:63] op_sel_hi:[0,1,1] neg_lo:[1,0,0] neg_hi:[1,0,0]
	v_pk_fma_f32 v[58:59], v[196:197], v[66:67], v[58:59] op_sel_hi:[0,1,1] neg_lo:[1,0,0] neg_hi:[1,0,0]
	s_waitcnt vmcnt(1)
	v_pk_add_f32 v[82:83], v[86:87], v[100:101]
	s_waitcnt vmcnt(0)
	v_pk_add_f32 v[78:79], v[90:91], v[106:107]
	v_pk_add_f32 v[84:85], v[84:85], v[98:99]
	v_pk_fma_f32 v[60:61], v[198:199], v[60:61], v[78:79] op_sel_hi:[0,1,1]
	v_mul_f32_e32 v86, 0x3d372713, v60
	v_mul_f32_e32 v86, v60, v86
	v_fma_f32 v86, v60, v86, v60
	v_mul_f32_e32 v86, 0x3f4c422a, v86
	v_add_f32_e32 v86, v86, v86
	v_mul_f32_e32 v86, 0xbfb8aa3b, v86
	v_exp_f32_e32 v86, v86
	v_pk_fma_f32 v[56:57], v[198:199], v[56:57], v[84:85] op_sel_hi:[0,1,1]
	v_pk_add_f32 v[76:77], v[92:93], v[108:109]
	v_pk_fma_f32 v[58:59], v[198:199], v[58:59], v[82:83] op_sel_hi:[0,1,1]
	v_add_f32_e32 v86, 1.0, v86
	v_rcp_f32_e32 v86, v86
	v_pk_fma_f32 v[62:63], v[198:199], v[62:63], v[76:77] op_sel_hi:[0,1,1]
	v_pk_fma_f32 v[52:53], v[192:193], v[68:69], v[52:53] op_sel_hi:[0,1,1] neg_lo:[1,0,0] neg_hi:[1,0,0]
	v_pk_fma_f32 v[52:53], v[194:195], v[52:53], v[78:79] op_sel_hi:[0,1,1]
	v_mul_f32_e32 v60, v60, v86
	v_mul_f32_e32 v86, 0x3d372713, v56
	v_mul_f32_e32 v86, v56, v86
	v_fma_f32 v86, v56, v86, v56
	v_mul_f32_e32 v86, 0x3f4c422a, v86
	v_add_f32_e32 v86, v86, v86
	v_mul_f32_e32 v86, 0xbfb8aa3b, v86
	v_exp_f32_e32 v86, v86
	v_pk_fma_f32 v[48:49], v[192:193], v[64:65], v[48:49] op_sel_hi:[0,1,1] neg_lo:[1,0,0] neg_hi:[1,0,0]
	v_pk_fma_f32 v[48:49], v[194:195], v[48:49], v[84:85] op_sel_hi:[0,1,1]
	v_pk_fma_f32 v[54:55], v[192:193], v[70:71], v[54:55] op_sel_hi:[0,1,1] neg_lo:[1,0,0] neg_hi:[1,0,0]
	v_add_f32_e32 v86, 1.0, v86
	v_rcp_f32_e32 v86, v86
	v_pk_fma_f32 v[54:55], v[194:195], v[54:55], v[76:77] op_sel_hi:[0,1,1]
	v_pk_fma_f32 v[50:51], v[192:193], v[66:67], v[50:51] op_sel_hi:[0,1,1] neg_lo:[1,0,0] neg_hi:[1,0,0]
	v_pk_fma_f32 v[50:51], v[194:195], v[50:51], v[82:83] op_sel_hi:[0,1,1]
	v_mul_f32_e32 v86, v56, v86
	v_mul_f32_e32 v56, 0x3d372713, v61
	v_mul_f32_e32 v56, v61, v56
	v_fma_f32 v56, v61, v56, v61
	v_mul_f32_e32 v56, 0x3f4c422a, v56
	v_add_f32_e32 v56, v56, v56
	v_mul_f32_e32 v56, 0xbfb8aa3b, v56
	v_exp_f32_e32 v56, v56
	v_pk_fma_f32 v[44:45], v[188:189], v[68:69], v[44:45] op_sel_hi:[0,1,1] neg_lo:[1,0,0] neg_hi:[1,0,0]
	v_pk_fma_f32 v[44:45], v[190:191], v[44:45], v[78:79] op_sel_hi:[0,1,1]
	v_pk_fma_f32 v[40:41], v[188:189], v[64:65], v[40:41] op_sel_hi:[0,1,1] neg_lo:[1,0,0] neg_hi:[1,0,0]
	v_add_f32_e32 v56, 1.0, v56
	v_rcp_f32_e32 v56, v56
	v_pk_fma_f32 v[40:41], v[190:191], v[40:41], v[84:85] op_sel_hi:[0,1,1]
	v_pk_fma_f32 v[46:47], v[188:189], v[70:71], v[46:47] op_sel_hi:[0,1,1] neg_lo:[1,0,0] neg_hi:[1,0,0]
	v_pk_fma_f32 v[46:47], v[190:191], v[46:47], v[76:77] op_sel_hi:[0,1,1]
	v_mul_f32_e32 v56, v61, v56
	v_mul_f32_e32 v61, 0x3d372713, v57
	v_mul_f32_e32 v61, v57, v61
	v_fma_f32 v61, v57, v61, v57
	v_mul_f32_e32 v61, 0x3f4c422a, v61
	v_add_f32_e32 v61, v61, v61
	v_mul_f32_e32 v61, 0xbfb8aa3b, v61
	v_exp_f32_e32 v61, v61
	v_cvt_pk_bf16_f32 v56, v60, v56
	v_pk_fma_f32 v[42:43], v[188:189], v[66:67], v[42:43] op_sel_hi:[0,1,1] neg_lo:[1,0,0] neg_hi:[1,0,0]
	v_pk_fma_f32 v[42:43], v[190:191], v[42:43], v[82:83] op_sel_hi:[0,1,1]
	v_add_f32_e32 v61, 1.0, v61
	v_rcp_f32_e32 v61, v61
	v_pk_fma_f32 v[36:37], v[184:185], v[68:69], v[36:37] op_sel_hi:[0,1,1] neg_lo:[1,0,0] neg_hi:[1,0,0]
	v_pk_fma_f32 v[36:37], v[186:187], v[36:37], v[78:79] op_sel_hi:[0,1,1]
	v_pk_fma_f32 v[32:33], v[184:185], v[64:65], v[32:33] op_sel_hi:[0,1,1] neg_lo:[1,0,0] neg_hi:[1,0,0]
	v_mul_f32_e32 v61, v57, v61
	v_mul_f32_e32 v57, 0x3d372713, v62
	v_mul_f32_e32 v57, v62, v57
	v_fma_f32 v57, v62, v57, v62
	v_mul_f32_e32 v57, 0x3f4c422a, v57
	v_add_f32_e32 v57, v57, v57
	v_mul_f32_e32 v57, 0xbfb8aa3b, v57
	v_exp_f32_e32 v57, v57
	v_pk_fma_f32 v[32:33], v[186:187], v[32:33], v[84:85] op_sel_hi:[0,1,1]
	v_pk_fma_f32 v[38:39], v[184:185], v[70:71], v[38:39] op_sel_hi:[0,1,1] neg_lo:[1,0,0] neg_hi:[1,0,0]
	v_pk_fma_f32 v[38:39], v[186:187], v[38:39], v[76:77] op_sel_hi:[0,1,1]
	v_add_f32_e32 v57, 1.0, v57
	v_rcp_f32_e32 v57, v57
	v_pk_fma_f32 v[34:35], v[184:185], v[66:67], v[34:35] op_sel_hi:[0,1,1] neg_lo:[1,0,0] neg_hi:[1,0,0]
	v_pk_fma_f32 v[34:35], v[186:187], v[34:35], v[82:83] op_sel_hi:[0,1,1]
	v_pk_fma_f32 v[28:29], v[180:181], v[68:69], v[28:29] op_sel_hi:[0,1,1] neg_lo:[1,0,0] neg_hi:[1,0,0]
	v_mul_f32_e32 v57, v62, v57
	v_mul_f32_e32 v62, 0x3d372713, v58
	v_mul_f32_e32 v62, v58, v62
	v_fma_f32 v62, v58, v62, v58
	v_mul_f32_e32 v62, 0x3f4c422a, v62
	v_add_f32_e32 v62, v62, v62
	v_mul_f32_e32 v62, 0xbfb8aa3b, v62
	v_exp_f32_e32 v62, v62
	v_pk_fma_f32 v[28:29], v[182:183], v[28:29], v[78:79] op_sel_hi:[0,1,1]
	v_pk_fma_f32 v[24:25], v[180:181], v[64:65], v[24:25] op_sel_hi:[0,1,1] neg_lo:[1,0,0] neg_hi:[1,0,0]
	v_pk_fma_f32 v[24:25], v[182:183], v[24:25], v[84:85] op_sel_hi:[0,1,1]
	v_add_f32_e32 v62, 1.0, v62
	v_rcp_f32_e32 v62, v62
	v_pk_fma_f32 v[30:31], v[180:181], v[70:71], v[30:31] op_sel_hi:[0,1,1] neg_lo:[1,0,0] neg_hi:[1,0,0]
	v_pk_fma_f32 v[30:31], v[182:183], v[30:31], v[76:77] op_sel_hi:[0,1,1]
	v_pk_fma_f32 v[26:27], v[180:181], v[66:67], v[26:27] op_sel_hi:[0,1,1] neg_lo:[1,0,0] neg_hi:[1,0,0]
	v_mul_f32_e32 v62, v58, v62
	v_mul_f32_e32 v58, 0x3d372713, v63
	v_mul_f32_e32 v58, v63, v58
	v_fma_f32 v58, v63, v58, v63
; __device__ __forceinline__ unsigned cvt_pk_bf16(float lo, float hi) { unsigned r; asm("v_cvt_pk_bf16_f32 %0, %1, %2" : "=v"(r) : "v"(lo), "v"(hi)); return r; }
; __device__ __forceinline__ float gelu_tanh(float v) { const float u = 0.7978845608028654f * (v + 0.044715f * v * v * v); return v * fast_sigmoid(2.0f * u); }
; __device__ __forceinline__ f32x4 ln_fix(const f32x4& a, float mu, float rs, const f32x4& cs, const f32x4& cb) { return (a - cs * mu) * rs + cb; }
; __device__ __forceinline__ float fast_sigmoid(float v) { return __builtin_amdgcn_rcpf(1.0f + __builtin_amdgcn_exp2f(-1.4426950408889634f * v)); }
;     __device__ __forceinline__ void operator()(const f32x4 (&acc)[2][2][4][2], const Unit& u, int wr, int wc, int fr_in, int fq_in) const {
;     ...
;                     f32x4 v0 = ln_fix(acc[ai][bj][m][0], rst.mu[ai][m], rst.rs[ai][m], csv[0], cbv[0]), v1 = ln_fix(acc[ai][bj][m][1], rst.mu[ai][m], rst.rs[ai][m], csv[1], cbv[1]);
; #pragma unroll
;                     for (int j = 0; j < 4; ++j) { v0[j] = gelu_tanh(v0[j]); v1[j] = gelu_tanh(v1[j]); }
;                     u32x4 w; w.x = cvt_pk_bf16(v0[0], v0[1]); w.y = cvt_pk_bf16(v0[2], v0[3]); w.z = cvt_pk_bf16(v1[0], v1[1]); w.w = cvt_pk_bf16(v1[2], v1[3]);
;                     *(u32x4*)rowp = w; } }
	v_mul_f32_e32 v58, 0x3f4c422a, v58
	v_add_f32_e32 v58, v58, v58
	v_mul_f32_e32 v58, 0xbfb8aa3b, v58
	v_exp_f32_e32 v58, v58
	v_pk_fma_f32 v[26:27], v[182:183], v[26:27], v[82:83] op_sel_hi:[0,1,1]
	v_pk_fma_f32 v[20:21], v[176:177], v[68:69], v[20:21] op_sel_hi:[0,1,1] neg_lo:[1,0,0] neg_hi:[1,0,0]
	v_pk_fma_f32 v[20:21], v[178:179], v[20:21], v[78:79] op_sel_hi:[0,1,1]
	v_add_f32_e32 v58, 1.0, v58
	v_rcp_f32_e32 v58, v58
	v_pk_fma_f32 v[16:17], v[176:177], v[64:65], v[16:17] op_sel_hi:[0,1,1] neg_lo:[1,0,0] neg_hi:[1,0,0]
	v_pk_fma_f32 v[16:17], v[178:179], v[16:17], v[84:85] op_sel_hi:[0,1,1]
	v_pk_fma_f32 v[22:23], v[176:177], v[70:71], v[22:23] op_sel_hi:[0,1,1] neg_lo:[1,0,0] neg_hi:[1,0,0]
	v_mul_f32_e32 v58, v63, v58
	v_mul_f32_e32 v63, 0x3d372713, v59
	v_mul_f32_e32 v63, v59, v63
	v_fma_f32 v63, v59, v63, v59
	v_mul_f32_e32 v63, 0x3f4c422a, v63
	v_add_f32_e32 v63, v63, v63
	v_mul_f32_e32 v63, 0xbfb8aa3b, v63
	v_exp_f32_e32 v63, v63
	v_cvt_pk_bf16_f32 v57, v57, v58
	v_cvt_pk_bf16_f32 v58, v86, v61
	v_pk_fma_f32 v[22:23], v[178:179], v[22:23], v[76:77] op_sel_hi:[0,1,1]
	v_add_f32_e32 v63, 1.0, v63
	v_rcp_f32_e32 v63, v63
	v_pk_fma_f32 v[18:19], v[176:177], v[66:67], v[18:19] op_sel_hi:[0,1,1] neg_lo:[1,0,0] neg_hi:[1,0,0]
	v_pk_fma_f32 v[18:19], v[178:179], v[18:19], v[82:83] op_sel_hi:[0,1,1]
	v_pk_fma_f32 v[12:13], v[172:173], v[68:69], v[12:13] op_sel_hi:[0,1,1] neg_lo:[1,0,0] neg_hi:[1,0,0]
	v_mul_f32_e32 v59, v59, v63
	v_cvt_pk_bf16_f32 v59, v62, v59
	global_store_dwordx4 v[128:129], v[56:59], off offset:256
	v_pk_fma_f32 v[12:13], v[174:175], v[12:13], v[78:79] op_sel_hi:[0,1,1]
	v_pk_fma_f32 v[8:9], v[172:173], v[64:65], v[8:9] op_sel_hi:[0,1,1] neg_lo:[1,0,0] neg_hi:[1,0,0]
	v_mul_f32_e32 v56, 0x3d372713, v52
	v_mul_f32_e32 v56, v52, v56
	v_fma_f32 v56, v52, v56, v52
	v_mul_f32_e32 v56, 0x3f4c422a, v56
	v_add_f32_e32 v56, v56, v56
	v_mul_f32_e32 v56, 0xbfb8aa3b, v56
	v_exp_f32_e32 v56, v56
	v_pk_fma_f32 v[8:9], v[174:175], v[8:9], v[84:85] op_sel_hi:[0,1,1]
	v_pk_fma_f32 v[14:15], v[172:173], v[70:71], v[14:15] op_sel_hi:[0,1,1] neg_lo:[1,0,0] neg_hi:[1,0,0]
	v_pk_fma_f32 v[14:15], v[174:175], v[14:15], v[76:77] op_sel_hi:[0,1,1]
	v_add_f32_e32 v56, 1.0, v56
	v_rcp_f32_e32 v56, v56
	v_pk_fma_f32 v[10:11], v[172:173], v[66:67], v[10:11] op_sel_hi:[0,1,1] neg_lo:[1,0,0] neg_hi:[1,0,0]
	v_pk_fma_f32 v[10:11], v[174:175], v[10:11], v[82:83] op_sel_hi:[0,1,1]
	v_pk_fma_f32 v[4:5], v[168:169], v[68:69], v[4:5] op_sel_hi:[0,1,1] neg_lo:[1,0,0] neg_hi:[1,0,0]
	v_mul_f32_e32 v52, v52, v56
	v_mul_f32_e32 v56, 0x3d372713, v48
	v_mul_f32_e32 v56, v48, v56
	v_fma_f32 v56, v48, v56, v48
	v_mul_f32_e32 v56, 0x3f4c422a, v56
	v_add_f32_e32 v56, v56, v56
	v_mul_f32_e32 v56, 0xbfb8aa3b, v56
	v_exp_f32_e32 v56, v56
	v_pk_fma_f32 v[4:5], v[170:171], v[4:5], v[78:79] op_sel_hi:[0,1,1]
	v_pk_fma_f32 v[0:1], v[168:169], v[64:65], v[0:1] op_sel_hi:[0,1,1] neg_lo:[1,0,0] neg_hi:[1,0,0]
	v_pk_fma_f32 v[0:1], v[170:171], v[0:1], v[84:85] op_sel_hi:[0,1,1]
	v_add_f32_e32 v56, 1.0, v56
	v_rcp_f32_e32 v56, v56
	v_pk_fma_f32 v[6:7], v[168:169], v[70:71], v[6:7] op_sel_hi:[0,1,1] neg_lo:[1,0,0] neg_hi:[1,0,0]
	v_pk_fma_f32 v[6:7], v[170:171], v[6:7], v[76:77] op_sel_hi:[0,1,1]
	v_pk_fma_f32 v[2:3], v[168:169], v[66:67], v[2:3] op_sel_hi:[0,1,1] neg_lo:[1,0,0] neg_hi:[1,0,0]
	v_mul_f32_e32 v56, v48, v56
	v_mul_f32_e32 v48, 0x3d372713, v53
	v_mul_f32_e32 v48, v53, v48
	v_fma_f32 v48, v53, v48, v53
	v_mul_f32_e32 v48, 0x3f4c422a, v48
	v_add_f32_e32 v48, v48, v48
	v_mul_f32_e32 v48, 0xbfb8aa3b, v48
	v_exp_f32_e32 v48, v48
	v_pk_fma_f32 v[2:3], v[170:171], v[2:3], v[82:83] op_sel_hi:[0,1,1]
	v_add_f32_e32 v48, 1.0, v48
	v_rcp_f32_e32 v48, v48
	s_nop 0
	v_mul_f32_e32 v48, v53, v48
	v_mul_f32_e32 v53, 0x3d372713, v49
	v_mul_f32_e32 v53, v49, v53
	v_fma_f32 v53, v49, v53, v49
	v_mul_f32_e32 v53, 0x3f4c422a, v53
	v_add_f32_e32 v53, v53, v53
	v_mul_f32_e32 v53, 0xbfb8aa3b, v53
	v_exp_f32_e32 v53, v53
	v_cvt_pk_bf16_f32 v48, v52, v48
	s_nop 0
	v_add_f32_e32 v53, 1.0, v53
	v_rcp_f32_e32 v53, v53
	s_nop 0
	v_mul_f32_e32 v53, v49, v53
	v_mul_f32_e32 v49, 0x3d372713, v54
	v_mul_f32_e32 v49, v54, v49
	v_fma_f32 v49, v54, v49, v54
	v_mul_f32_e32 v49, 0x3f4c422a, v49
	v_add_f32_e32 v49, v49, v49
	v_mul_f32_e32 v49, 0xbfb8aa3b, v49
	v_exp_f32_e32 v49, v49
	s_nop 0
	v_add_f32_e32 v49, 1.0, v49
	v_rcp_f32_e32 v49, v49
	s_nop 0
	v_mul_f32_e32 v49, v54, v49
	v_mul_f32_e32 v54, 0x3d372713, v50
	v_mul_f32_e32 v54, v50, v54
	v_fma_f32 v54, v50, v54, v50
	v_mul_f32_e32 v54, 0x3f4c422a, v54
	v_add_f32_e32 v54, v54, v54
	v_mul_f32_e32 v54, 0xbfb8aa3b, v54
	v_exp_f32_e32 v54, v54
	s_nop 0
	v_add_f32_e32 v54, 1.0, v54
	v_rcp_f32_e32 v54, v54
	s_nop 0
	v_mul_f32_e32 v54, v50, v54
	v_mul_f32_e32 v50, 0x3d372713, v55
	v_mul_f32_e32 v50, v55, v50
	v_fma_f32 v50, v55, v50, v55
	v_mul_f32_e32 v50, 0x3f4c422a, v50
	v_add_f32_e32 v50, v50, v50
	v_mul_f32_e32 v50, 0xbfb8aa3b, v50
	v_exp_f32_e32 v50, v50
	s_nop 0
	v_add_f32_e32 v50, 1.0, v50
	v_rcp_f32_e32 v50, v50
	s_nop 0
	v_mul_f32_e32 v50, v55, v50
	v_mul_f32_e32 v55, 0x3d372713, v51
	v_mul_f32_e32 v55, v51, v55
	v_fma_f32 v55, v51, v55, v51
	v_mul_f32_e32 v55, 0x3f4c422a, v55
	v_add_f32_e32 v55, v55, v55
	v_mul_f32_e32 v55, 0xbfb8aa3b, v55
	v_exp_f32_e32 v55, v55
	v_cvt_pk_bf16_f32 v49, v49, v50
	v_cvt_pk_bf16_f32 v50, v56, v53
	s_nop 0
	v_add_f32_e32 v55, 1.0, v55
	v_rcp_f32_e32 v55, v55
	s_nop 0
	v_mul_f32_e32 v51, v51, v55
	v_cvt_pk_bf16_f32 v51, v54, v51
	global_store_dwordx4 v[112:113], v[48:51], off offset:256
	s_nop 1
	v_mul_f32_e32 v48, 0x3d372713, v44
	v_mul_f32_e32 v48, v44, v48
	v_fma_f32 v48, v44, v48, v44
; __device__ __forceinline__ unsigned cvt_pk_bf16(float lo, float hi) { unsigned r; asm("v_cvt_pk_bf16_f32 %0, %1, %2" : "=v"(r) : "v"(lo), "v"(hi)); return r; }
; __device__ __forceinline__ float gelu_tanh(float v) { const float u = 0.7978845608028654f * (v + 0.044715f * v * v * v); return v * fast_sigmoid(2.0f * u); }
; __device__ __forceinline__ f32x4 ln_fix(const f32x4& a, float mu, float rs, const f32x4& cs, const f32x4& cb) { return (a - cs * mu) * rs + cb; }
; __device__ __forceinline__ float fast_sigmoid(float v) { return __builtin_amdgcn_rcpf(1.0f + __builtin_amdgcn_exp2f(-1.4426950408889634f * v)); }
;     __device__ __forceinline__ void operator()(const f32x4 (&acc)[2][2][4][2], const Unit& u, int wr, int wc, int fr_in, int fq_in) const {
;     ...
;                     f32x4 v0 = ln_fix(acc[ai][bj][m][0], rst.mu[ai][m], rst.rs[ai][m], csv[0], cbv[0]), v1 = ln_fix(acc[ai][bj][m][1], rst.mu[ai][m], rst.rs[ai][m], csv[1], cbv[1]);
; #pragma unroll
;                     for (int j = 0; j < 4; ++j) { v0[j] = gelu_tanh(v0[j]); v1[j] = gelu_tanh(v1[j]); }
;                     u32x4 w; w.x = cvt_pk_bf16(v0[0], v0[1]); w.y = cvt_pk_bf16(v0[2], v0[3]); w.z = cvt_pk_bf16(v1[0], v1[1]); w.w = cvt_pk_bf16(v1[2], v1[3]);
;                     *(u32x4*)rowp = w; } }
	v_mul_f32_e32 v48, 0x3f4c422a, v48
	v_add_f32_e32 v48, v48, v48
	v_mul_f32_e32 v48, 0xbfb8aa3b, v48
	v_exp_f32_e32 v48, v48
	s_nop 0
	v_add_f32_e32 v48, 1.0, v48
	v_rcp_f32_e32 v48, v48
	s_nop 0
	v_mul_f32_e32 v44, v44, v48
	v_mul_f32_e32 v48, 0x3d372713, v40
	v_mul_f32_e32 v48, v40, v48
	v_fma_f32 v48, v40, v48, v40
	v_mul_f32_e32 v48, 0x3f4c422a, v48
	v_add_f32_e32 v48, v48, v48
	v_mul_f32_e32 v48, 0xbfb8aa3b, v48
	v_exp_f32_e32 v48, v48
	s_nop 0
	v_add_f32_e32 v48, 1.0, v48
	v_rcp_f32_e32 v48, v48
	s_nop 0
	v_mul_f32_e32 v48, v40, v48
	v_mul_f32_e32 v40, 0x3d372713, v45
	v_mul_f32_e32 v40, v45, v40
	v_fma_f32 v40, v45, v40, v45
	v_mul_f32_e32 v40, 0x3f4c422a, v40
	v_add_f32_e32 v40, v40, v40
	v_mul_f32_e32 v40, 0xbfb8aa3b, v40
	v_exp_f32_e32 v40, v40
	s_nop 0
	v_add_f32_e32 v40, 1.0, v40
	v_rcp_f32_e32 v40, v40
	s_nop 0
	v_mul_f32_e32 v40, v45, v40
	v_mul_f32_e32 v45, 0x3d372713, v41
	v_mul_f32_e32 v45, v41, v45
	v_fma_f32 v45, v41, v45, v41
	v_mul_f32_e32 v45, 0x3f4c422a, v45
	v_add_f32_e32 v45, v45, v45
	v_mul_f32_e32 v45, 0xbfb8aa3b, v45
	v_exp_f32_e32 v45, v45
	v_cvt_pk_bf16_f32 v40, v44, v40
	s_nop 0
	v_add_f32_e32 v45, 1.0, v45
	v_rcp_f32_e32 v45, v45
	s_nop 0
	v_mul_f32_e32 v45, v41, v45
	v_mul_f32_e32 v41, 0x3d372713, v46
	v_mul_f32_e32 v41, v46, v41
	v_fma_f32 v41, v46, v41, v46
	v_mul_f32_e32 v41, 0x3f4c422a, v41
	v_add_f32_e32 v41, v41, v41
	v_mul_f32_e32 v41, 0xbfb8aa3b, v41
	v_exp_f32_e32 v41, v41
	s_nop 0
	v_add_f32_e32 v41, 1.0, v41
	v_rcp_f32_e32 v41, v41
	s_nop 0
	v_mul_f32_e32 v41, v46, v41
	v_mul_f32_e32 v46, 0x3d372713, v42
	v_mul_f32_e32 v46, v42, v46
	v_fma_f32 v46, v42, v46, v42
	v_mul_f32_e32 v46, 0x3f4c422a, v46
	v_add_f32_e32 v46, v46, v46
	v_mul_f32_e32 v46, 0xbfb8aa3b, v46
	v_exp_f32_e32 v46, v46
	s_nop 0
	v_add_f32_e32 v46, 1.0, v46
	v_rcp_f32_e32 v46, v46
	s_nop 0
	v_mul_f32_e32 v46, v42, v46
	v_mul_f32_e32 v42, 0x3d372713, v47
	v_mul_f32_e32 v42, v47, v42
	v_fma_f32 v42, v47, v42, v47
	v_mul_f32_e32 v42, 0x3f4c422a, v42
	v_add_f32_e32 v42, v42, v42
	v_mul_f32_e32 v42, 0xbfb8aa3b, v42
	v_exp_f32_e32 v42, v42
	s_nop 0
	v_add_f32_e32 v42, 1.0, v42
	v_rcp_f32_e32 v42, v42
	s_nop 0
	v_mul_f32_e32 v42, v47, v42
	v_mul_f32_e32 v47, 0x3d372713, v43
	v_mul_f32_e32 v47, v43, v47
	v_fma_f32 v47, v43, v47, v43
	v_mul_f32_e32 v47, 0x3f4c422a, v47
	v_add_f32_e32 v47, v47, v47
	v_mul_f32_e32 v47, 0xbfb8aa3b, v47
	v_exp_f32_e32 v47, v47
	v_cvt_pk_bf16_f32 v41, v41, v42
	v_cvt_pk_bf16_f32 v42, v48, v45
	s_nop 0
	v_add_f32_e32 v47, 1.0, v47
	v_rcp_f32_e32 v47, v47
	s_nop 0
	v_mul_f32_e32 v43, v43, v47
	v_cvt_pk_bf16_f32 v43, v46, v43
	global_store_dwordx4 v[104:105], v[40:43], off offset:256
	s_nop 1
	v_mul_f32_e32 v40, 0x3d372713, v36
	v_mul_f32_e32 v40, v36, v40
	v_fma_f32 v40, v36, v40, v36
	v_mul_f32_e32 v40, 0x3f4c422a, v40
	v_add_f32_e32 v40, v40, v40
	v_mul_f32_e32 v40, 0xbfb8aa3b, v40
	v_exp_f32_e32 v40, v40
	s_nop 0
	v_add_f32_e32 v40, 1.0, v40
	v_rcp_f32_e32 v40, v40
	s_nop 0
	v_mul_f32_e32 v36, v36, v40
	v_mul_f32_e32 v40, 0x3d372713, v32
	v_mul_f32_e32 v40, v32, v40
	v_fma_f32 v40, v32, v40, v32
	v_mul_f32_e32 v40, 0x3f4c422a, v40
	v_add_f32_e32 v40, v40, v40
	v_mul_f32_e32 v40, 0xbfb8aa3b, v40
	v_exp_f32_e32 v40, v40
	s_nop 0
	v_add_f32_e32 v40, 1.0, v40
	v_rcp_f32_e32 v40, v40
	s_nop 0
	v_mul_f32_e32 v40, v32, v40
	v_mul_f32_e32 v32, 0x3d372713, v37
	v_mul_f32_e32 v32, v37, v32
	v_fma_f32 v32, v37, v32, v37
	v_mul_f32_e32 v32, 0x3f4c422a, v32
	v_add_f32_e32 v32, v32, v32
	v_mul_f32_e32 v32, 0xbfb8aa3b, v32
	v_exp_f32_e32 v32, v32
	s_nop 0
	v_add_f32_e32 v32, 1.0, v32
	v_rcp_f32_e32 v32, v32
	s_nop 0
	v_mul_f32_e32 v32, v37, v32
	v_mul_f32_e32 v37, 0x3d372713, v33
	v_mul_f32_e32 v37, v33, v37
	v_fma_f32 v37, v33, v37, v33
	v_mul_f32_e32 v37, 0x3f4c422a, v37
	v_add_f32_e32 v37, v37, v37
	v_mul_f32_e32 v37, 0xbfb8aa3b, v37
	v_exp_f32_e32 v37, v37
	v_cvt_pk_bf16_f32 v32, v36, v32
	s_nop 0
	v_add_f32_e32 v37, 1.0, v37
	v_rcp_f32_e32 v37, v37
	s_nop 0
	v_mul_f32_e32 v37, v33, v37
	v_mul_f32_e32 v33, 0x3d372713, v38
	v_mul_f32_e32 v33, v38, v33
	v_fma_f32 v33, v38, v33, v38
	v_mul_f32_e32 v33, 0x3f4c422a, v33
	v_add_f32_e32 v33, v33, v33
	v_mul_f32_e32 v33, 0xbfb8aa3b, v33
	v_exp_f32_e32 v33, v33
	s_nop 0
	v_add_f32_e32 v33, 1.0, v33
	v_rcp_f32_e32 v33, v33
	s_nop 0
	v_mul_f32_e32 v33, v38, v33
	v_mul_f32_e32 v38, 0x3d372713, v34
	v_mul_f32_e32 v38, v34, v38
	v_fma_f32 v38, v34, v38, v34
	v_mul_f32_e32 v38, 0x3f4c422a, v38
	v_add_f32_e32 v38, v38, v38
	v_mul_f32_e32 v38, 0xbfb8aa3b, v38
	v_exp_f32_e32 v38, v38
	s_nop 0
	v_add_f32_e32 v38, 1.0, v38
	v_rcp_f32_e32 v38, v38
	s_nop 0
	v_mul_f32_e32 v38, v34, v38
	v_mul_f32_e32 v34, 0x3d372713, v39
	v_mul_f32_e32 v34, v39, v34
	v_fma_f32 v34, v39, v34, v39
	v_mul_f32_e32 v34, 0x3f4c422a, v34
	v_add_f32_e32 v34, v34, v34
	v_mul_f32_e32 v34, 0xbfb8aa3b, v34
	v_exp_f32_e32 v34, v34
	s_nop 0
	v_add_f32_e32 v34, 1.0, v34
	v_rcp_f32_e32 v34, v34
	s_nop 0
	v_mul_f32_e32 v34, v39, v34
	v_mul_f32_e32 v39, 0x3d372713, v35
	v_mul_f32_e32 v39, v35, v39
	v_fma_f32 v39, v35, v39, v35
	v_mul_f32_e32 v39, 0x3f4c422a, v39
	v_add_f32_e32 v39, v39, v39
	v_mul_f32_e32 v39, 0xbfb8aa3b, v39
	v_exp_f32_e32 v39, v39
	v_cvt_pk_bf16_f32 v33, v33, v34
	v_cvt_pk_bf16_f32 v34, v40, v37
	s_nop 0
	v_add_f32_e32 v39, 1.0, v39
	v_rcp_f32_e32 v39, v39
	s_nop 0
	v_mul_f32_e32 v35, v35, v39
	v_cvt_pk_bf16_f32 v35, v38, v35
	global_store_dwordx4 v[96:97], v[32:35], off offset:256
	s_nop 1
	v_mul_f32_e32 v32, 0x3d372713, v28
	v_mul_f32_e32 v32, v28, v32
	v_fma_f32 v32, v28, v32, v28
	v_mul_f32_e32 v32, 0x3f4c422a, v32
	v_add_f32_e32 v32, v32, v32
	v_mul_f32_e32 v32, 0xbfb8aa3b, v32
	v_exp_f32_e32 v32, v32
; __device__ __forceinline__ unsigned cvt_pk_bf16(float lo, float hi) { unsigned r; asm("v_cvt_pk_bf16_f32 %0, %1, %2" : "=v"(r) : "v"(lo), "v"(hi)); return r; }
; __device__ __forceinline__ float gelu_tanh(float v) { const float u = 0.7978845608028654f * (v + 0.044715f * v * v * v); return v * fast_sigmoid(2.0f * u); }
; __device__ __forceinline__ f32x4 ln_fix(const f32x4& a, float mu, float rs, const f32x4& cs, const f32x4& cb) { return (a - cs * mu) * rs + cb; }
; __device__ __forceinline__ float fast_sigmoid(float v) { return __builtin_amdgcn_rcpf(1.0f + __builtin_amdgcn_exp2f(-1.4426950408889634f * v)); }
;     __device__ __forceinline__ void operator()(const f32x4 (&acc)[2][2][4][2], const Unit& u, int wr, int wc, int fr_in, int fq_in) const {
;     ...
;                     f32x4 v0 = ln_fix(acc[ai][bj][m][0], rst.mu[ai][m], rst.rs[ai][m], csv[0], cbv[0]), v1 = ln_fix(acc[ai][bj][m][1], rst.mu[ai][m], rst.rs[ai][m], csv[1], cbv[1]);
; #pragma unroll
;                     for (int j = 0; j < 4; ++j) { v0[j] = gelu_tanh(v0[j]); v1[j] = gelu_tanh(v1[j]); }
;                     u32x4 w; w.x = cvt_pk_bf16(v0[0], v0[1]); w.y = cvt_pk_bf16(v0[2], v0[3]); w.z = cvt_pk_bf16(v1[0], v1[1]); w.w = cvt_pk_bf16(v1[2], v1[3]);
;                     *(u32x4*)rowp = w; } }
	s_nop 0
	v_add_f32_e32 v32, 1.0, v32
	v_rcp_f32_e32 v32, v32
	s_nop 0
	v_mul_f32_e32 v28, v28, v32
	v_mul_f32_e32 v32, 0x3d372713, v24
	v_mul_f32_e32 v32, v24, v32
	v_fma_f32 v32, v24, v32, v24
	v_mul_f32_e32 v32, 0x3f4c422a, v32
	v_add_f32_e32 v32, v32, v32
	v_mul_f32_e32 v32, 0xbfb8aa3b, v32
	v_exp_f32_e32 v32, v32
	s_nop 0
	v_add_f32_e32 v32, 1.0, v32
	v_rcp_f32_e32 v32, v32
	s_nop 0
	v_mul_f32_e32 v32, v24, v32
	v_mul_f32_e32 v24, 0x3d372713, v29
	v_mul_f32_e32 v24, v29, v24
	v_fma_f32 v24, v29, v24, v29
	v_mul_f32_e32 v24, 0x3f4c422a, v24
	v_add_f32_e32 v24, v24, v24
	v_mul_f32_e32 v24, 0xbfb8aa3b, v24
	v_exp_f32_e32 v24, v24
	s_nop 0
	v_add_f32_e32 v24, 1.0, v24
	v_rcp_f32_e32 v24, v24
	s_nop 0
	v_mul_f32_e32 v24, v29, v24
	v_mul_f32_e32 v29, 0x3d372713, v25
	v_mul_f32_e32 v29, v25, v29
	v_fma_f32 v29, v25, v29, v25
	v_mul_f32_e32 v29, 0x3f4c422a, v29
	v_add_f32_e32 v29, v29, v29
	v_mul_f32_e32 v29, 0xbfb8aa3b, v29
	v_exp_f32_e32 v29, v29
	v_cvt_pk_bf16_f32 v24, v28, v24
	s_nop 0
	v_add_f32_e32 v29, 1.0, v29
	v_rcp_f32_e32 v29, v29
	s_nop 0
	v_mul_f32_e32 v29, v25, v29
	v_mul_f32_e32 v25, 0x3d372713, v30
	v_mul_f32_e32 v25, v30, v25
	v_fma_f32 v25, v30, v25, v30
	v_mul_f32_e32 v25, 0x3f4c422a, v25
	v_add_f32_e32 v25, v25, v25
	v_mul_f32_e32 v25, 0xbfb8aa3b, v25
	v_exp_f32_e32 v25, v25
	s_nop 0
	v_add_f32_e32 v25, 1.0, v25
	v_rcp_f32_e32 v25, v25
	s_nop 0
	v_mul_f32_e32 v25, v30, v25
	v_mul_f32_e32 v30, 0x3d372713, v26
	v_mul_f32_e32 v30, v26, v30
	v_fma_f32 v30, v26, v30, v26
	v_mul_f32_e32 v30, 0x3f4c422a, v30
	v_add_f32_e32 v30, v30, v30
	v_mul_f32_e32 v30, 0xbfb8aa3b, v30
	v_exp_f32_e32 v30, v30
	s_nop 0
	v_add_f32_e32 v30, 1.0, v30
	v_rcp_f32_e32 v30, v30
	s_nop 0
	v_mul_f32_e32 v30, v26, v30
	v_mul_f32_e32 v26, 0x3d372713, v31
	v_mul_f32_e32 v26, v31, v26
	v_fma_f32 v26, v31, v26, v31
	v_mul_f32_e32 v26, 0x3f4c422a, v26
	v_add_f32_e32 v26, v26, v26
	v_mul_f32_e32 v26, 0xbfb8aa3b, v26
	v_exp_f32_e32 v26, v26
	s_nop 0
	v_add_f32_e32 v26, 1.0, v26
	v_rcp_f32_e32 v26, v26
	s_nop 0
	v_mul_f32_e32 v26, v31, v26
	v_mul_f32_e32 v31, 0x3d372713, v27
	v_mul_f32_e32 v31, v27, v31
	v_fma_f32 v31, v27, v31, v27
	v_mul_f32_e32 v31, 0x3f4c422a, v31
	v_add_f32_e32 v31, v31, v31
	v_mul_f32_e32 v31, 0xbfb8aa3b, v31
	v_exp_f32_e32 v31, v31
	v_cvt_pk_bf16_f32 v25, v25, v26
	v_cvt_pk_bf16_f32 v26, v32, v29
	s_nop 0
	v_add_f32_e32 v31, 1.0, v31
	v_rcp_f32_e32 v31, v31
	s_nop 0
	v_mul_f32_e32 v27, v27, v31
	v_cvt_pk_bf16_f32 v27, v30, v27
	global_store_dwordx4 v[88:89], v[24:27], off offset:256
	s_nop 1
	v_mul_f32_e32 v24, 0x3d372713, v20
	v_mul_f32_e32 v24, v20, v24
	v_fma_f32 v24, v20, v24, v20
	v_mul_f32_e32 v24, 0x3f4c422a, v24
	v_add_f32_e32 v24, v24, v24
	v_mul_f32_e32 v24, 0xbfb8aa3b, v24
	v_exp_f32_e32 v24, v24
	s_nop 0
	v_add_f32_e32 v24, 1.0, v24
	v_rcp_f32_e32 v24, v24
	s_nop 0
	v_mul_f32_e32 v20, v20, v24
	v_mul_f32_e32 v24, 0x3d372713, v16
	v_mul_f32_e32 v24, v16, v24
	v_fma_f32 v24, v16, v24, v16
	v_mul_f32_e32 v24, 0x3f4c422a, v24
	v_add_f32_e32 v24, v24, v24
	v_mul_f32_e32 v24, 0xbfb8aa3b, v24
	v_exp_f32_e32 v24, v24
	s_nop 0
	v_add_f32_e32 v24, 1.0, v24
	v_rcp_f32_e32 v24, v24
	s_nop 0
	v_mul_f32_e32 v24, v16, v24
	v_mul_f32_e32 v16, 0x3d372713, v21
	v_mul_f32_e32 v16, v21, v16
	v_fma_f32 v16, v21, v16, v21
	v_mul_f32_e32 v16, 0x3f4c422a, v16
	v_add_f32_e32 v16, v16, v16
	v_mul_f32_e32 v16, 0xbfb8aa3b, v16
	v_exp_f32_e32 v16, v16
	s_nop 0
	v_add_f32_e32 v16, 1.0, v16
	v_rcp_f32_e32 v16, v16
	s_nop 0
	v_mul_f32_e32 v16, v21, v16
	v_mul_f32_e32 v21, 0x3d372713, v17
	v_mul_f32_e32 v21, v17, v21
	v_fma_f32 v21, v17, v21, v17
	v_mul_f32_e32 v21, 0x3f4c422a, v21
	v_add_f32_e32 v21, v21, v21
	v_mul_f32_e32 v21, 0xbfb8aa3b, v21
	v_exp_f32_e32 v21, v21
	v_cvt_pk_bf16_f32 v16, v20, v16
	s_nop 0
	v_add_f32_e32 v21, 1.0, v21
	v_rcp_f32_e32 v21, v21
	s_nop 0
	v_mul_f32_e32 v21, v17, v21
	v_mul_f32_e32 v17, 0x3d372713, v22
	v_mul_f32_e32 v17, v22, v17
	v_fma_f32 v17, v22, v17, v22
	v_mul_f32_e32 v17, 0x3f4c422a, v17
	v_add_f32_e32 v17, v17, v17
	v_mul_f32_e32 v17, 0xbfb8aa3b, v17
	v_exp_f32_e32 v17, v17
	s_nop 0
	v_add_f32_e32 v17, 1.0, v17
	v_rcp_f32_e32 v17, v17
	s_nop 0
	v_mul_f32_e32 v17, v22, v17
	v_mul_f32_e32 v22, 0x3d372713, v18
	v_mul_f32_e32 v22, v18, v22
	v_fma_f32 v22, v18, v22, v18
	v_mul_f32_e32 v22, 0x3f4c422a, v22
	v_add_f32_e32 v22, v22, v22
	v_mul_f32_e32 v22, 0xbfb8aa3b, v22
	v_exp_f32_e32 v22, v22
	s_nop 0
	v_add_f32_e32 v22, 1.0, v22
	v_rcp_f32_e32 v22, v22
	s_nop 0
	v_mul_f32_e32 v22, v18, v22
	v_mul_f32_e32 v18, 0x3d372713, v23
	v_mul_f32_e32 v18, v23, v18
	v_fma_f32 v18, v23, v18, v23
	v_mul_f32_e32 v18, 0x3f4c422a, v18
	v_add_f32_e32 v18, v18, v18
	v_mul_f32_e32 v18, 0xbfb8aa3b, v18
	v_exp_f32_e32 v18, v18
	s_nop 0
	v_add_f32_e32 v18, 1.0, v18
	v_rcp_f32_e32 v18, v18
	s_nop 0
	v_mul_f32_e32 v18, v23, v18
	v_mul_f32_e32 v23, 0x3d372713, v19
	v_mul_f32_e32 v23, v19, v23
	v_fma_f32 v23, v19, v23, v19
	v_mul_f32_e32 v23, 0x3f4c422a, v23
	v_add_f32_e32 v23, v23, v23
	v_mul_f32_e32 v23, 0xbfb8aa3b, v23
	v_exp_f32_e32 v23, v23
	v_cvt_pk_bf16_f32 v17, v17, v18
	v_cvt_pk_bf16_f32 v18, v24, v21
	s_nop 0
	v_add_f32_e32 v23, 1.0, v23
	v_rcp_f32_e32 v23, v23
	s_nop 0
	v_mul_f32_e32 v19, v19, v23
	v_cvt_pk_bf16_f32 v19, v22, v19
	global_store_dwordx4 v[80:81], v[16:19], off offset:256
	s_nop 1
	v_mul_f32_e32 v16, 0x3d372713, v12
; __device__ __forceinline__ unsigned cvt_pk_bf16(float lo, float hi) { unsigned r; asm("v_cvt_pk_bf16_f32 %0, %1, %2" : "=v"(r) : "v"(lo), "v"(hi)); return r; }
; __device__ __forceinline__ float gelu_tanh(float v) { const float u = 0.7978845608028654f * (v + 0.044715f * v * v * v); return v * fast_sigmoid(2.0f * u); }
; __device__ __forceinline__ f32x4 ln_fix(const f32x4& a, float mu, float rs, const f32x4& cs, const f32x4& cb) { return (a - cs * mu) * rs + cb; }
; __device__ __forceinline__ float fast_sigmoid(float v) { return __builtin_amdgcn_rcpf(1.0f + __builtin_amdgcn_exp2f(-1.4426950408889634f * v)); }
;     __device__ __forceinline__ void operator()(const f32x4 (&acc)[2][2][4][2], const Unit& u, int wr, int wc, int fr_in, int fq_in) const {
;     ...
;                     f32x4 v0 = ln_fix(acc[ai][bj][m][0], rst.mu[ai][m], rst.rs[ai][m], csv[0], cbv[0]), v1 = ln_fix(acc[ai][bj][m][1], rst.mu[ai][m], rst.rs[ai][m], csv[1], cbv[1]);
; #pragma unroll
;                     for (int j = 0; j < 4; ++j) { v0[j] = gelu_tanh(v0[j]); v1[j] = gelu_tanh(v1[j]); }
;                     u32x4 w; w.x = cvt_pk_bf16(v0[0], v0[1]); w.y = cvt_pk_bf16(v0[2], v0[3]); w.z = cvt_pk_bf16(v1[0], v1[1]); w.w = cvt_pk_bf16(v1[2], v1[3]);
;                     *(u32x4*)rowp = w; } }
	v_mul_f32_e32 v16, v12, v16
	v_fma_f32 v16, v12, v16, v12
	v_mul_f32_e32 v16, 0x3f4c422a, v16
	v_add_f32_e32 v16, v16, v16
	v_mul_f32_e32 v16, 0xbfb8aa3b, v16
	v_exp_f32_e32 v16, v16
	s_nop 0
	v_add_f32_e32 v16, 1.0, v16
	v_rcp_f32_e32 v16, v16
	s_nop 0
	v_mul_f32_e32 v12, v12, v16
	v_mul_f32_e32 v16, 0x3d372713, v8
	v_mul_f32_e32 v16, v8, v16
	v_fma_f32 v16, v8, v16, v8
	v_mul_f32_e32 v16, 0x3f4c422a, v16
	v_add_f32_e32 v16, v16, v16
	v_mul_f32_e32 v16, 0xbfb8aa3b, v16
	v_exp_f32_e32 v16, v16
	s_nop 0
	v_add_f32_e32 v16, 1.0, v16
	v_rcp_f32_e32 v16, v16
	s_nop 0
	v_mul_f32_e32 v16, v8, v16
	v_mul_f32_e32 v8, 0x3d372713, v13
	v_mul_f32_e32 v8, v13, v8
	v_fma_f32 v8, v13, v8, v13
	v_mul_f32_e32 v8, 0x3f4c422a, v8
	v_add_f32_e32 v8, v8, v8
	v_mul_f32_e32 v8, 0xbfb8aa3b, v8
	v_exp_f32_e32 v8, v8
	s_nop 0
	v_add_f32_e32 v8, 1.0, v8
	v_rcp_f32_e32 v8, v8
	s_nop 0
	v_mul_f32_e32 v8, v13, v8
	v_mul_f32_e32 v13, 0x3d372713, v9
	v_mul_f32_e32 v13, v9, v13
	v_fma_f32 v13, v9, v13, v9
	v_mul_f32_e32 v13, 0x3f4c422a, v13
	v_add_f32_e32 v13, v13, v13
	v_mul_f32_e32 v13, 0xbfb8aa3b, v13
	v_exp_f32_e32 v13, v13
	v_cvt_pk_bf16_f32 v8, v12, v8
	s_nop 0
	v_add_f32_e32 v13, 1.0, v13
	v_rcp_f32_e32 v13, v13
	s_nop 0
	v_mul_f32_e32 v13, v9, v13
	v_mul_f32_e32 v9, 0x3d372713, v14
	v_mul_f32_e32 v9, v14, v9
	v_fma_f32 v9, v14, v9, v14
	v_mul_f32_e32 v9, 0x3f4c422a, v9
	v_add_f32_e32 v9, v9, v9
	v_mul_f32_e32 v9, 0xbfb8aa3b, v9
	v_exp_f32_e32 v9, v9
	s_nop 0
	v_add_f32_e32 v9, 1.0, v9
	v_rcp_f32_e32 v9, v9
	s_nop 0
	v_mul_f32_e32 v9, v14, v9
	v_mul_f32_e32 v14, 0x3d372713, v10
	v_mul_f32_e32 v14, v10, v14
	v_fma_f32 v14, v10, v14, v10
	v_mul_f32_e32 v14, 0x3f4c422a, v14
	v_add_f32_e32 v14, v14, v14
	v_mul_f32_e32 v14, 0xbfb8aa3b, v14
	v_exp_f32_e32 v14, v14
	s_nop 0
	v_add_f32_e32 v14, 1.0, v14
	v_rcp_f32_e32 v14, v14
	s_nop 0
	v_mul_f32_e32 v14, v10, v14
	v_mul_f32_e32 v10, 0x3d372713, v15
	v_mul_f32_e32 v10, v15, v10
	v_fma_f32 v10, v15, v10, v15
	v_mul_f32_e32 v10, 0x3f4c422a, v10
	v_add_f32_e32 v10, v10, v10
	v_mul_f32_e32 v10, 0xbfb8aa3b, v10
	v_exp_f32_e32 v10, v10
	s_nop 0
	v_add_f32_e32 v10, 1.0, v10
	v_rcp_f32_e32 v10, v10
	s_nop 0
	v_mul_f32_e32 v10, v15, v10
	v_mul_f32_e32 v15, 0x3d372713, v11
	v_mul_f32_e32 v15, v11, v15
	v_fma_f32 v15, v11, v15, v11
	v_mul_f32_e32 v15, 0x3f4c422a, v15
	v_add_f32_e32 v15, v15, v15
	v_mul_f32_e32 v15, 0xbfb8aa3b, v15
	v_exp_f32_e32 v15, v15
	v_cvt_pk_bf16_f32 v9, v9, v10
	v_cvt_pk_bf16_f32 v10, v16, v13
	s_nop 0
	v_add_f32_e32 v15, 1.0, v15
	v_rcp_f32_e32 v15, v15
	s_nop 0
	v_mul_f32_e32 v11, v11, v15
	v_cvt_pk_bf16_f32 v11, v14, v11
	global_store_dwordx4 v[72:73], v[8:11], off offset:256
	s_nop 1
	v_mul_f32_e32 v8, 0x3d372713, v4
	v_mul_f32_e32 v8, v4, v8
	v_fma_f32 v8, v4, v8, v4
	v_mul_f32_e32 v8, 0x3f4c422a, v8
	v_add_f32_e32 v8, v8, v8
	v_mul_f32_e32 v8, 0xbfb8aa3b, v8
	v_exp_f32_e32 v8, v8
	s_nop 0
	v_add_f32_e32 v8, 1.0, v8
	v_rcp_f32_e32 v8, v8
	s_nop 0
	v_mul_f32_e32 v4, v4, v8
	v_mul_f32_e32 v8, 0x3d372713, v0
	v_mul_f32_e32 v8, v0, v8
	v_fma_f32 v8, v0, v8, v0
	v_mul_f32_e32 v8, 0x3f4c422a, v8
	v_add_f32_e32 v8, v8, v8
	v_mul_f32_e32 v8, 0xbfb8aa3b, v8
	v_exp_f32_e32 v8, v8
	s_nop 0
	v_add_f32_e32 v8, 1.0, v8
	v_rcp_f32_e32 v8, v8
	s_nop 0
	v_mul_f32_e32 v8, v0, v8
	v_mul_f32_e32 v0, 0x3d372713, v5
	v_mul_f32_e32 v0, v5, v0
	v_fma_f32 v0, v5, v0, v5
	v_mul_f32_e32 v0, 0x3f4c422a, v0
	v_add_f32_e32 v0, v0, v0
	v_mul_f32_e32 v0, 0xbfb8aa3b, v0
	v_exp_f32_e32 v0, v0
	s_nop 0
	v_add_f32_e32 v0, 1.0, v0
	v_rcp_f32_e32 v0, v0
	s_nop 0
	v_mul_f32_e32 v0, v5, v0
	v_mul_f32_e32 v5, 0x3d372713, v1
	v_mul_f32_e32 v5, v1, v5
	v_fma_f32 v5, v1, v5, v1
	v_mul_f32_e32 v5, 0x3f4c422a, v5
	v_add_f32_e32 v5, v5, v5
	v_mul_f32_e32 v5, 0xbfb8aa3b, v5
	v_exp_f32_e32 v5, v5
	v_cvt_pk_bf16_f32 v0, v4, v0
	s_nop 0
	v_add_f32_e32 v5, 1.0, v5
	v_rcp_f32_e32 v5, v5
	s_nop 0
	v_mul_f32_e32 v5, v1, v5
	v_mul_f32_e32 v1, 0x3d372713, v6
	v_mul_f32_e32 v1, v6, v1
	v_fma_f32 v1, v6, v1, v6
	v_mul_f32_e32 v1, 0x3f4c422a, v1
	v_add_f32_e32 v1, v1, v1
	v_mul_f32_e32 v1, 0xbfb8aa3b, v1
	v_exp_f32_e32 v1, v1
	s_nop 0
	v_add_f32_e32 v1, 1.0, v1
	v_rcp_f32_e32 v1, v1
	s_nop 0
	v_mul_f32_e32 v1, v6, v1
	v_mul_f32_e32 v6, 0x3d372713, v2
	v_mul_f32_e32 v6, v2, v6
	v_fma_f32 v6, v2, v6, v2
	v_mul_f32_e32 v6, 0x3f4c422a, v6
	v_add_f32_e32 v6, v6, v6
	v_mul_f32_e32 v6, 0xbfb8aa3b, v6
	v_exp_f32_e32 v6, v6
	s_nop 0
	v_add_f32_e32 v6, 1.0, v6
	v_rcp_f32_e32 v6, v6
	s_nop 0
	v_mul_f32_e32 v6, v2, v6
	v_mul_f32_e32 v2, 0x3d372713, v7
	v_mul_f32_e32 v2, v7, v2
	v_fma_f32 v2, v7, v2, v7
	v_mul_f32_e32 v2, 0x3f4c422a, v2
	v_add_f32_e32 v2, v2, v2
	v_mul_f32_e32 v2, 0xbfb8aa3b, v2
	v_exp_f32_e32 v2, v2
	s_nop 0
	v_add_f32_e32 v2, 1.0, v2
	v_rcp_f32_e32 v2, v2
	s_nop 0
	v_mul_f32_e32 v2, v7, v2
	v_mul_f32_e32 v7, 0x3d372713, v3
	v_mul_f32_e32 v7, v3, v7
	v_fma_f32 v7, v3, v7, v3
	v_mul_f32_e32 v7, 0x3f4c422a, v7
	v_add_f32_e32 v7, v7, v7
	v_mul_f32_e32 v7, 0xbfb8aa3b, v7
	v_exp_f32_e32 v7, v7
	v_cvt_pk_bf16_f32 v1, v1, v2
	v_cvt_pk_bf16_f32 v2, v8, v5
	s_nop 0
	v_add_f32_e32 v7, 1.0, v7
	v_rcp_f32_e32 v7, v7
	s_nop 0
	v_mul_f32_e32 v3, v3, v7
	v_cvt_pk_bf16_f32 v3, v6, v3
	global_store_dwordx4 v[74:75], v[0:3], off offset:256
	s_cbranch_vccnz .LBB0_1686
	s_andn2_b64 vcc, exec, s[22:23]
	s_cbranch_vccnz .LBB0_1685
	s_barrier
	s_branch .LBB0_1685

; __device__ __forceinline__ void load_row_stats(const float* sp, int row0, RowStats& r) {
;     ...
;         for (int m = 0; m < 4; ++m) { const float* p = sp + (size_t)(row0 + ai * HALF + m * 16) * 8; const f32x4 a = *(const f32x4*)p, b = *(const f32x4*)(p + 4);
;             const float s1 = (a[0] + a[2]) + (b[0] + b[2]), s2 = (a[1] + a[3]) + (b[1] + b[3]); const float mu = s1 * (1.f / 1024.f); const float var = s2 * (1.f / 1024.f) - mu * mu;
;             r.mu[ai][m] = mu; r.rs[ai][m] = __builtin_amdgcn_rsqf(__builtin_fmaxf(var, 0.f) + 1e-5f); } }
;     __device__ __forceinline__ void operator()(const f32x4 (&acc)[2][2][4][2], const Unit& u, int wr, int wc, int fr_in, int fq_in) const {
;     ...
;         const int row0 = u.pm * BM + wr * 64 + fr, n0 = u.pn * BM + wc * 32 + 8 * fq; const int kt = u.pn * 2 + (wc >> 1), cin = (wc & 1) * 32 + 8 * fq;
;         RowStats rst; f32x4 csv[2][2], cbv[2][2];
;         if constexpr (LN) { load_row_stats(sp, row0, rst);
; #pragma unroll
;             for (int bj = 0; bj < 2; ++bj)
; #pragma unroll
;                 for (int n = 0; n < 2; ++n) { csv[bj][n] = *(const f32x4*)(cs + n0 + bj * HALF + 4 * n); cbv[bj][n] = *(const f32x4*)(cb + n0 + bj * HALF + 4 * n); } }
.LBB0_1995:
	s_lshl_b32 s35, s44, 8
	v_mov_b32_e32 v112, v179
	v_mov_b32_e32 v113, v185
	s_add_i32 s35, s35, s54
	s_andn2_b64 vcc, exec, s[38:39]
	v_add_u32_e32 v192, s35, v112
	v_ashrrev_i32_e32 v193, 31, v192
	v_and_b32_e32 v226, 0xffffff00, v192
	v_and_b32_e32 v177, 0xff, v192
	v_lshlrev_b32_e32 v177, 3, v177
	v_add_u32_e32 v177, 0x22400, v177
	v_add_u32_e32 v224, 16, v192
	v_ashrrev_i32_e32 v225, 31, v224
	v_add_u32_e32 v218, 32, v192
	v_ashrrev_i32_e32 v219, 31, v218
	v_add_u32_e32 v212, 48, v192
	v_ashrrev_i32_e32 v213, 31, v212
	v_add_u32_e32 v204, 0x80, v192
	v_ashrrev_i32_e32 v205, 31, v204
	v_add_u32_e32 v196, 0x90, v192
	v_ashrrev_i32_e32 v197, 31, v196
	v_add_u32_e32 v188, 0xa0, v192
	v_ashrrev_i32_e32 v189, 31, v188
	v_add_u32_e32 v182, 0xb0, v192
	v_ashrrev_i32_e32 v183, 31, v182
	v_lshlrev_b32_e32 v206, 3, v113
	s_lshl_b32 s35, s45, 8
	s_or_b32 s35, s35, s55
	v_add_u32_e32 v112, s35, v206
	s_lshl_b32 s35, s45, 1
	s_or_b32 s44, s35, s59
	s_ashr_i32 s45, s44, 31
	s_lshl_b64 s[44:45], s[44:45], 15
	v_lshl_add_u64 v[192:193], s[44:45], 0, v[192:193]
	v_lshlrev_b64 v[192:193], 7, v[192:193]
	v_add_u32_e32 v230, s60, v206
	v_lshl_add_u64 v[232:233], s[6:7], 0, v[192:193]
	v_mov_b32_e32 v192, v144
	v_mov_b32_e32 v193, v140
	v_mov_b32_e32 v140, v145
	v_ashrrev_i32_e32 v231, 31, v230
	s_nop 0
	v_ashrrev_i32_e32 v113, 31, v112
	v_lshlrev_b64 v[112:113], 2, v[112:113]
	v_lshl_add_u64 v[136:137], s[12:13], 0, v[112:113]
	v_lshl_add_u64 v[156:157], s[22:23], 0, v[112:113]
	global_load_dwordx4 v[112:115], v[136:137], off offset:16
	global_load_dwordx4 v[128:131], v[136:137], off
	global_load_dwordx4 v[116:119], v[156:157], off offset:16
	global_load_dwordx4 v[132:135], v[156:157], off
	global_load_dwordx4 v[148:151], v[136:137], off offset:528
	s_nop 0
	global_load_dwordx4 v[136:139], v[136:137], off offset:512
	s_nop 0
	global_load_dwordx4 v[152:155], v[156:157], off offset:528
	s_nop 0
	global_load_dwordx4 v[156:159], v[156:157], off offset:512
	s_cselect_b32 s99, 1, 0
	v_readfirstlane_b32 s98, v254
	s_nop 0
	s_cmpk_lt_u32 s98, 0x100
	s_cbranch_scc0 .Lrs9_skip
	v_add_u32_e32 v226, v226, v254
	v_mov_b32_e32 v227, 0
	v_lshlrev_b64 v[226:227], 5, v[226:227]
	v_lshl_add_u64 v[226:227], s[10:11], 0, v[226:227]
	global_load_dwordx2 v[220:221], v[226:227], off offset:16
	global_load_dwordx2 v[214:215], v[226:227], off offset:24
	global_load_dwordx2 v[200:201], v[226:227], off
	global_load_dwordx2 v[194:195], v[226:227], off offset:8
	s_waitcnt vmcnt(0)
	v_pk_add_f32 v[220:221], v[220:221], v[214:215]
	v_pk_add_f32 v[200:201], v[200:201], v[194:195]
	s_nop 0
	v_pk_add_f32 v[220:221], v[200:201], v[220:221]
	s_nop 0
	v_pk_mul_f32 v[220:221], v[220:221], s[30:31] op_sel_hi:[1,0]
	v_lshlrev_b32_e32 v186, 3, v254
	v_add_u32_e32 v186, 0x22400, v186
	ds_write_b64 v186, v[220:221]

; __device__ __forceinline__ void load_row_stats(const float* sp, int row0, RowStats& r) {
;     ...
;         for (int m = 0; m < 4; ++m) { const float* p = sp + (size_t)(row0 + ai * HALF + m * 16) * 8; const f32x4 a = *(const f32x4*)p, b = *(const f32x4*)(p + 4);
;             const float s1 = (a[0] + a[2]) + (b[0] + b[2]), s2 = (a[1] + a[3]) + (b[1] + b[3]); const float mu = s1 * (1.f / 1024.f); const float var = s2 * (1.f / 1024.f) - mu * mu;
;             r.mu[ai][m] = mu; r.rs[ai][m] = __builtin_amdgcn_rsqf(__builtin_fmaxf(var, 0.f) + 1e-5f); } }
;     __device__ __forceinline__ void operator()(const f32x4 (&acc)[2][2][4][2], const Unit& u, int wr, int wc, int fr_in, int fq_in) const {
;     ...
;         const int row0 = u.pm * BM + wr * 64 + fr, col0 = u.pn * BM + wc * 32 + 8 * fq;
;         RowStats rst; load_row_stats(sp, row0, rst);
; #pragma unroll
;         for (int bj = 0; bj < 2; ++bj) { f32x4 csv[2], cbv[2], gv[2], bv[2];
; #pragma unroll
;             for (int n = 0; n < 2; ++n) { csv[n] = *(const f32x4*)(cs + col0 + bj * HALF + 4 * n); cbv[n] = *(const f32x4*)(cb + col0 + bj * HALF + 4 * n); gv[n] = *(const f32x4*)(lg + col0 + bj * HALF + 4 * n); bv[n] = *(const f32x4*)(lb + col0 + bj * HALF + 4 * n); }
.LBB0_2193:
	s_lshl_b32 s10, s10, 8
	v_mov_b32_e32 v112, v183
	v_mov_b32_e32 v113, v187
	s_add_i32 s10, s10, s59
	s_andn2_b64 vcc, exec, s[0:1]
	v_add_u32_e32 v160, s10, v112
	s_lshl_b32 s10, s11, 8
	s_or_b32 s10, s10, s60
	v_ashrrev_i32_e32 v161, 31, v160
	v_lshl_add_u32 v212, v113, 3, s10
	v_and_b32_e32 v208, 0xffffff00, v160
	v_and_b32_e32 v181, 0xff, v160
	v_lshlrev_b32_e32 v181, 3, v181
	v_add_u32_e32 v181, 0x22400, v181
	v_add_u32_e32 v236, 16, v160
	v_ashrrev_i32_e32 v237, 31, v236
	v_add_u32_e32 v234, 32, v160
	v_ashrrev_i32_e32 v235, 31, v234
	v_add_u32_e32 v232, 48, v160
	v_ashrrev_i32_e32 v233, 31, v232
	v_add_u32_e32 v230, 0x80, v160
	v_ashrrev_i32_e32 v231, 31, v230
	v_add_u32_e32 v228, 0x90, v160
	v_ashrrev_i32_e32 v229, 31, v228
	v_add_u32_e32 v226, 0xa0, v160
	v_ashrrev_i32_e32 v227, 31, v226
	v_add_u32_e32 v224, 0xb0, v160
	v_ashrrev_i32_e32 v225, 31, v224
	v_ashrrev_i32_e32 v213, 31, v212
	v_lshlrev_b64 v[222:223], 10, v[160:161]
	v_lshl_add_u64 v[238:239], v[222:223], 0, v[212:213]
	v_lshlrev_b64 v[240:241], 1, v[238:239]
	v_lshl_add_u64 v[160:161], s[26:27], 0, v[240:241]
	v_lshl_add_u64 v[240:241], s[22:23], 0, v[240:241]
	s_mov_b64 s[10:11], -1
	s_nop 0
	s_nop 0
	s_nop 0
	s_nop 0
	s_nop 0
	s_nop 0
	s_nop 0
	s_nop 0
	v_lshlrev_b64 v[112:113], 2, v[212:213]
	v_lshl_add_u64 v[220:221], s[30:31], 0, v[112:113]
	v_lshl_add_u64 v[218:219], s[6:7], 0, v[112:113]
	v_lshl_add_u64 v[216:217], s[34:35], 0, v[112:113]
	v_lshl_add_u64 v[214:215], s[38:39], 0, v[112:113]
	global_load_dwordx4 v[116:119], v[220:221], off offset:16
	global_load_dwordx4 v[124:127], v[220:221], off
	global_load_dwordx4 v[112:115], v[218:219], off offset:16
	global_load_dwordx4 v[120:123], v[218:219], off
	global_load_dwordx4 v[128:131], v[216:217], off offset:16
	global_load_dwordx4 v[136:139], v[216:217], off
	global_load_dwordx4 v[132:135], v[214:215], off offset:16
	global_load_dwordx4 v[140:143], v[214:215], off
	s_cselect_b32 s99, 1, 0
	v_readfirstlane_b32 s98, v254
	s_nop 0
	s_cmpk_lt_u32 s98, 0x100
	s_cbranch_scc0 .Lrs11_skip
	v_add_u32_e32 v208, v208, v254
	v_mov_b32_e32 v209, 0
	v_lshlrev_b64 v[208:209], 5, v[208:209]
	v_lshl_add_u64 v[208:209], s[28:29], 0, v[208:209]
	global_load_dwordx2 v[204:205], v[208:209], off offset:16
	global_load_dwordx2 v[200:201], v[208:209], off offset:24
	global_load_dwordx2 v[196:197], v[208:209], off
	global_load_dwordx2 v[192:193], v[208:209], off offset:8
	s_waitcnt vmcnt(0)
	v_pk_add_f32 v[204:205], v[204:205], v[200:201]
	v_pk_add_f32 v[196:197], v[196:197], v[192:193]
	s_nop 0
	v_pk_add_f32 v[204:205], v[196:197], v[204:205]
	s_nop 0
	v_pk_mul_f32 v[204:205], v[204:205], s[46:47] op_sel_hi:[1,0]
	v_lshlrev_b32_e32 v188, 3, v254
	v_add_u32_e32 v188, 0x22400, v188
	ds_write_b64 v188, v[204:205]
.Lrs11_skip:
	s_waitcnt vmcnt(0) lgkmcnt(0)
	s_barrier
	ds_read_b64 v[208:209], v181
	ds_read_b64 v[204:205], v181 offset:128
	ds_read_b64 v[200:201], v181 offset:256
	ds_read_b64 v[196:197], v181 offset:384
	ds_read_b64 v[192:193], v181 offset:1024
	ds_read_b64 v[188:189], v181 offset:1152
	ds_read_b64 v[184:185], v181 offset:1280
	ds_read_b64 v[180:181], v181 offset:1408
	s_cmp_lg_u32 s99, 0
	s_waitcnt lgkmcnt(0)
	v_fma_f32 v210, -v208, v208, v209
	v_max_f32_e32 v210, 0, v210
	v_add_f32_e32 v210, 0x3727c5ac, v210
	v_rsq_f32_e32 v210, v210
	v_fma_f32 v206, -v204, v204, v205
	v_max_f32_e32 v206, 0, v206
	v_add_f32_e32 v206, 0x3727c5ac, v206
	v_rsq_f32_e32 v206, v206
	v_fma_f32 v202, -v200, v200, v201
	v_max_f32_e32 v202, 0, v202
	v_add_f32_e32 v202, 0x3727c5ac, v202
	v_rsq_f32_e32 v202, v202
	v_fma_f32 v198, -v196, v196, v197
	v_max_f32_e32 v198, 0, v198
	v_add_f32_e32 v198, 0x3727c5ac, v198
	v_rsq_f32_e32 v198, v198
	v_fma_f32 v194, -v192, v192, v193
	v_max_f32_e32 v194, 0, v194
	v_add_f32_e32 v194, 0x3727c5ac, v194
	v_rsq_f32_e32 v194, v194
	v_fma_f32 v190, -v188, v188, v189
	v_max_f32_e32 v190, 0, v190
	v_add_f32_e32 v190, 0x3727c5ac, v190
	v_rsq_f32_e32 v190, v190
	v_fma_f32 v186, -v184, v184, v185
	v_max_f32_e32 v186, 0, v186
	v_add_f32_e32 v186, 0x3727c5ac, v186
	v_rsq_f32_e32 v186, v186
	v_fma_f32 v182, -v180, v180, v181
	v_max_f32_e32 v182, 0, v182
	v_add_f32_e32 v182, 0x3727c5ac, v182
	v_rsq_f32_e32 v182, v182
	s_waitcnt vmcnt(0)
; __device__ __forceinline__ f32x4 ln_fix(const f32x4& a, float mu, float rs, const f32x4& cs, const f32x4& cb) { return (a - cs * mu) * rs + cb; }
; __device__ __forceinline__ float bf_lo(unsigned w) { return __uint_as_float(w << 16); }
; __device__ __forceinline__ float bf_hi(unsigned w) { return __uint_as_float(w & 0xffff0000u); }
; __device__ __forceinline__ float fast_sigmoid(float v) { return __builtin_amdgcn_rcpf(1.0f + __builtin_amdgcn_exp2f(-1.4426950408889634f * v)); }
;     __device__ __forceinline__ void operator()(const f32x4 (&acc)[2][2][4][2], const Unit& u, int wr, int wc, int fr_in, int fq_in) const {
;     ...
;             for (int am = 0; am < (FINAL ? 8 : 4); ++am) { constexpr int GR = FINAL ? 1 : 2; const int ai = (am * GR) >> 2; u32x4 ppw[4], pzw[4];
; #pragma unroll
;                 for (int m = (am * GR) & 3; m < ((am * GR) & 3) + GR; ++m) { const size_t off = (size_t)(row0 + ai * HALF + m * 16) * 1024 + col0 + bj * HALF; ppw[m] = *(const u32x4*)(pexb + off); pzw[m] = *(const u32x4*)(zb + off); }
;                 asm volatile("" ::: "memory");
; #pragma unroll
;                 for (int m = (am * GR) & 3; m < ((am * GR) & 3) + GR; ++m) { const size_t off = (size_t)(row0 + ai * HALF + m * 16) * 1024 + col0 + bj * HALF; const float mu = rst.mu[ai][m], rs = rst.rs[ai][m];
;                     const u32x4 pw = ppw[m]; const u32x4 zw = pzw[m];
;                     const f32x4 x0 = ((f32x4){bf_lo(zw.x), bf_hi(zw.x), bf_lo(zw.y), bf_hi(zw.y)} - mu) * rs * gv[0] + bv[0], x1 = ((f32x4){bf_lo(zw.z), bf_hi(zw.z), bf_lo(zw.w), bf_hi(zw.w)} - mu) * rs * gv[1] + bv[1];
;                     const f32x4 a0 = ln_fix(acc[ai][bj][m][0], mu, rs, csv[0], cbv[0]), a1 = ln_fix(acc[ai][bj][m][1], mu, rs, csv[1], cbv[1]); f32x4 o0, o1;
;                     o0[0] = x0[0] + fast_sigmoid(a0[0]) * bf_lo(pw.x); o0[1] = x0[1] + fast_sigmoid(a0[1]) * bf_hi(pw.x);
;                     o0[2] = x0[2] + fast_sigmoid(a0[2]) * bf_lo(pw.y); o0[3] = x0[3] + fast_sigmoid(a0[3]) * bf_hi(pw.y);
;                     o1[0] = x1[0] + fast_sigmoid(a1[0]) * bf_lo(pw.z); o1[1] = x1[1] + fast_sigmoid(a1[1]) * bf_hi(pw.z);
;                     o1[2] = x1[2] + fast_sigmoid(a1[2]) * bf_lo(pw.w); o1[3] = x1[3] + fast_sigmoid(a1[3]) * bf_hi(pw.w);
	v_pk_fma_f32 v[152:153], v[208:209], v[116:117], v[152:153] op_sel_hi:[0,1,1] neg_lo:[1,0,0] neg_hi:[1,0,0]
	global_load_dwordx4 v[160:163], v[160:161], off
	v_pk_fma_f32 v[156:157], v[208:209], v[124:125], v[156:157] op_sel_hi:[0,1,1] neg_lo:[1,0,0] neg_hi:[1,0,0]
	global_load_dwordx4 v[240:243], v[240:241], off
	v_pk_fma_f32 v[158:159], v[208:209], v[126:127], v[158:159] op_sel_hi:[0,1,1] neg_lo:[1,0,0] neg_hi:[1,0,0]
	v_pk_fma_f32 v[154:155], v[208:209], v[118:119], v[154:155] op_sel_hi:[0,1,1] neg_lo:[1,0,0] neg_hi:[1,0,0]
	v_pk_fma_f32 v[148:149], v[204:205], v[124:125], v[148:149] op_sel_hi:[0,1,1] neg_lo:[1,0,0] neg_hi:[1,0,0]
	v_pk_fma_f32 v[146:147], v[204:205], v[118:119], v[146:147] op_sel_hi:[0,1,1] neg_lo:[1,0,0] neg_hi:[1,0,0]
	v_pk_fma_f32 v[150:151], v[204:205], v[126:127], v[150:151] op_sel_hi:[0,1,1] neg_lo:[1,0,0] neg_hi:[1,0,0]
	v_pk_fma_f32 v[144:145], v[204:205], v[116:117], v[144:145] op_sel_hi:[0,1,1] neg_lo:[1,0,0] neg_hi:[1,0,0]
	v_pk_fma_f32 v[108:109], v[200:201], v[124:125], v[108:109] op_sel_hi:[0,1,1] neg_lo:[1,0,0] neg_hi:[1,0,0]
	v_pk_fma_f32 v[108:109], v[202:203], v[108:109], v[120:121] op_sel_hi:[0,1,1]
	v_pk_fma_f32 v[106:107], v[200:201], v[118:119], v[106:107] op_sel_hi:[0,1,1] neg_lo:[1,0,0] neg_hi:[1,0,0]
	v_pk_fma_f32 v[110:111], v[200:201], v[126:127], v[110:111] op_sel_hi:[0,1,1] neg_lo:[1,0,0] neg_hi:[1,0,0]
	v_pk_fma_f32 v[110:111], v[202:203], v[110:111], v[122:123] op_sel_hi:[0,1,1]
	v_pk_fma_f32 v[104:105], v[200:201], v[116:117], v[104:105] op_sel_hi:[0,1,1] neg_lo:[1,0,0] neg_hi:[1,0,0]
	v_pk_fma_f32 v[104:105], v[202:203], v[104:105], v[112:113] op_sel_hi:[0,1,1]
	v_mul_f32_e32 v104, 0xbfb8aa3b, v104
	v_mul_f32_e32 v105, 0xbfb8aa3b, v105
	v_exp_f32_e32 v104, v104
	v_exp_f32_e32 v105, v105
	v_pk_fma_f32 v[100:101], v[196:197], v[124:125], v[100:101] op_sel_hi:[0,1,1] neg_lo:[1,0,0] neg_hi:[1,0,0]
	v_pk_fma_f32 v[100:101], v[198:199], v[100:101], v[120:121] op_sel_hi:[0,1,1]
	v_add_f32_e32 v104, 1.0, v104
	v_add_f32_e32 v105, 1.0, v105
	v_rcp_f32_e32 v104, v104
	v_rcp_f32_e32 v105, v105
	v_pk_fma_f32 v[98:99], v[196:197], v[118:119], v[98:99] op_sel_hi:[0,1,1] neg_lo:[1,0,0] neg_hi:[1,0,0]
	v_pk_fma_f32 v[102:103], v[196:197], v[126:127], v[102:103] op_sel_hi:[0,1,1] neg_lo:[1,0,0] neg_hi:[1,0,0]
	v_pk_fma_f32 v[102:103], v[198:199], v[102:103], v[122:123] op_sel_hi:[0,1,1]
	v_pk_fma_f32 v[96:97], v[196:197], v[116:117], v[96:97] op_sel_hi:[0,1,1] neg_lo:[1,0,0] neg_hi:[1,0,0]
	v_pk_fma_f32 v[96:97], v[198:199], v[96:97], v[112:113] op_sel_hi:[0,1,1]
	v_mul_f32_e32 v96, 0xbfb8aa3b, v96
	v_mul_f32_e32 v97, 0xbfb8aa3b, v97
	v_exp_f32_e32 v96, v96
	v_exp_f32_e32 v97, v97
	v_pk_fma_f32 v[92:93], v[192:193], v[124:125], v[92:93] op_sel_hi:[0,1,1] neg_lo:[1,0,0] neg_hi:[1,0,0]
	v_pk_fma_f32 v[92:93], v[92:93], v[194:195], v[120:121] op_sel_hi:[1,0,1]
	v_add_f32_e32 v96, 1.0, v96
	v_add_f32_e32 v97, 1.0, v97
	v_rcp_f32_e32 v96, v96
	v_rcp_f32_e32 v97, v97
	v_pk_fma_f32 v[88:89], v[192:193], v[116:117], v[88:89] op_sel_hi:[0,1,1] neg_lo:[1,0,0] neg_hi:[1,0,0]
	v_pk_fma_f32 v[94:95], v[192:193], v[126:127], v[94:95] op_sel_hi:[0,1,1] neg_lo:[1,0,0] neg_hi:[1,0,0]
	v_pk_fma_f32 v[90:91], v[192:193], v[118:119], v[90:91] op_sel_hi:[0,1,1] neg_lo:[1,0,0] neg_hi:[1,0,0]
	v_pk_fma_f32 v[94:95], v[94:95], v[194:195], v[122:123] op_sel_hi:[1,0,1]
	v_pk_fma_f32 v[80:81], v[188:189], v[116:117], v[80:81] op_sel_hi:[0,1,1] neg_lo:[1,0,0] neg_hi:[1,0,0]
	v_pk_fma_f32 v[82:83], v[188:189], v[118:119], v[82:83] op_sel_hi:[0,1,1] neg_lo:[1,0,0] neg_hi:[1,0,0]
	v_pk_fma_f32 v[76:77], v[124:125], v[184:185], v[76:77] op_sel_hi:[1,0,1] neg_lo:[1,0,0] neg_hi:[1,0,0]
	v_pk_fma_f32 v[72:73], v[184:185], v[116:117], v[72:73] op_sel_hi:[0,1,1] neg_lo:[1,0,0] neg_hi:[1,0,0]
	v_pk_fma_f32 v[76:77], v[76:77], v[186:187], v[120:121] op_sel_hi:[1,0,1]
	v_pk_fma_f32 v[74:75], v[184:185], v[118:119], v[74:75] op_sel_hi:[0,1,1] neg_lo:[1,0,0] neg_hi:[1,0,0]
	v_pk_fma_f32 v[68:69], v[124:125], v[180:181], v[68:69] op_sel_hi:[1,0,1] neg_lo:[1,0,0] neg_hi:[1,0,0]
	v_pk_fma_f32 v[64:65], v[116:117], v[180:181], v[64:65] op_sel_hi:[1,0,1] neg_lo:[1,0,0] neg_hi:[1,0,0]
	v_pk_fma_f32 v[68:69], v[68:69], v[182:183], v[120:121] op_sel_hi:[1,0,1]
	s_waitcnt vmcnt(0)
; __device__ __forceinline__ f32x4 ln_fix(const f32x4& a, float mu, float rs, const f32x4& cs, const f32x4& cb) { return (a - cs * mu) * rs + cb; }
; __device__ __forceinline__ float bf_lo(unsigned w) { return __uint_as_float(w << 16); }
; __device__ __forceinline__ float bf_hi(unsigned w) { return __uint_as_float(w & 0xffff0000u); }
; __device__ __forceinline__ float fast_sigmoid(float v) { return __builtin_amdgcn_rcpf(1.0f + __builtin_amdgcn_exp2f(-1.4426950408889634f * v)); }
;     __device__ __forceinline__ void operator()(const f32x4 (&acc)[2][2][4][2], const Unit& u, int wr, int wc, int fr_in, int fq_in) const {
;     ...
;                 for (int m = (am * GR) & 3; m < ((am * GR) & 3) + GR; ++m) { const size_t off = (size_t)(row0 + ai * HALF + m * 16) * 1024 + col0 + bj * HALF; ppw[m] = *(const u32x4*)(pexb + off); pzw[m] = *(const u32x4*)(zb + off); }
;                 asm volatile("" ::: "memory");
; #pragma unroll
;                 for (int m = (am * GR) & 3; m < ((am * GR) & 3) + GR; ++m) { const size_t off = (size_t)(row0 + ai * HALF + m * 16) * 1024 + col0 + bj * HALF; const float mu = rst.mu[ai][m], rs = rst.rs[ai][m];
;                     const u32x4 pw = ppw[m]; const u32x4 zw = pzw[m];
;                     const f32x4 x0 = ((f32x4){bf_lo(zw.x), bf_hi(zw.x), bf_lo(zw.y), bf_hi(zw.y)} - mu) * rs * gv[0] + bv[0], x1 = ((f32x4){bf_lo(zw.z), bf_hi(zw.z), bf_lo(zw.w), bf_hi(zw.w)} - mu) * rs * gv[1] + bv[1];
;                     const f32x4 a0 = ln_fix(acc[ai][bj][m][0], mu, rs, csv[0], cbv[0]), a1 = ln_fix(acc[ai][bj][m][1], mu, rs, csv[1], cbv[1]); f32x4 o0, o1;
;                     o0[0] = x0[0] + fast_sigmoid(a0[0]) * bf_lo(pw.x); o0[1] = x0[1] + fast_sigmoid(a0[1]) * bf_hi(pw.x);
;                     o0[2] = x0[2] + fast_sigmoid(a0[2]) * bf_lo(pw.y); o0[3] = x0[3] + fast_sigmoid(a0[3]) * bf_hi(pw.y);
;                     o1[0] = x1[0] + fast_sigmoid(a1[0]) * bf_lo(pw.z); o1[1] = x1[1] + fast_sigmoid(a1[1]) * bf_hi(pw.z);
;                     o1[2] = x1[2] + fast_sigmoid(a1[2]) * bf_lo(pw.w); o1[3] = x1[3] + fast_sigmoid(a1[3]) * bf_hi(pw.w);
;                     if constexpr (FINAL) { *(f32x4*)(outf + off) = o0; *(f32x4*)(outf + off + 4) = o1; }
	v_lshlrev_b32_e32 v207, 16, v240
	v_and_b32_e32 v211, 0xffff0000, v240
	v_lshlrev_b32_e32 v240, 16, v241
	v_and_b32_e32 v241, 0xffff0000, v241
	v_sub_f32_e32 v241, v241, v208
	v_sub_f32_e32 v240, v240, v208
	v_sub_f32_e32 v245, v211, v208
	v_sub_f32_e32 v244, v207, v208
	v_pk_mul_f32 v[244:245], v[210:211], v[244:245] op_sel_hi:[0,1]
	v_pk_mul_f32 v[240:241], v[210:211], v[240:241] op_sel_hi:[0,1]
	v_and_b32_e32 v211, 0xffff0000, v242
	v_pk_fma_f32 v[156:157], v[210:211], v[156:157], v[120:121] op_sel_hi:[0,1,1]
	v_pk_fma_f32 v[250:251], v[210:211], v[152:153], v[112:113] op_sel_hi:[0,1,1]
	v_mul_f32_e32 v152, 0xbfb8aa3b, v156
	v_mul_f32_e32 v153, 0xbfb8aa3b, v157
	v_exp_f32_e32 v152, v152
	v_exp_f32_e32 v153, v153
	v_pk_fma_f32 v[244:245], v[136:137], v[244:245], v[140:141]
	v_pk_fma_f32 v[158:159], v[210:211], v[158:159], v[122:123] op_sel_hi:[0,1,1]
	v_add_f32_e32 v152, 1.0, v152
	v_add_f32_e32 v153, 1.0, v153
	v_rcp_f32_e32 v152, v152
	v_rcp_f32_e32 v153, v153
	v_pk_fma_f32 v[248:249], v[210:211], v[154:155], v[114:115] op_sel_hi:[0,1,1]
	v_lshlrev_b32_e32 v154, 16, v160
	v_and_b32_e32 v155, 0xffff0000, v160
	v_pk_fma_f32 v[152:153], v[152:153], v[154:155], v[244:245]
	v_mul_f32_e32 v154, 0xbfb8aa3b, v158
	v_mul_f32_e32 v155, 0xbfb8aa3b, v159
	v_exp_f32_e32 v154, v154
	v_exp_f32_e32 v155, v155
	v_pk_fma_f32 v[246:247], v[138:139], v[240:241], v[142:143]
	v_lshlrev_b32_e32 v156, 16, v161
	v_add_f32_e32 v154, 1.0, v154
	v_add_f32_e32 v155, 1.0, v155
	v_rcp_f32_e32 v154, v154
	v_rcp_f32_e32 v155, v155
	v_and_b32_e32 v157, 0xffff0000, v161
	v_lshlrev_b32_e32 v207, 16, v242
	v_lshlrev_b32_e32 v240, 16, v243
	v_pk_fma_f32 v[154:155], v[154:155], v[156:157], v[246:247]
	v_mul_f32_e32 v156, 0xbfb8aa3b, v250
	v_mul_f32_e32 v157, 0xbfb8aa3b, v251
	v_exp_f32_e32 v156, v156
	v_exp_f32_e32 v157, v157
	v_and_b32_e32 v241, 0xffff0000, v243
	v_sub_f32_e32 v243, v211, v208
	v_add_f32_e32 v156, 1.0, v156
	v_add_f32_e32 v157, 1.0, v157
	v_rcp_f32_e32 v156, v156
	v_rcp_f32_e32 v157, v157
	v_sub_f32_e32 v242, v207, v208
	v_pk_mul_f32 v[242:243], v[210:211], v[242:243] op_sel_hi:[0,1]
	v_pk_fma_f32 v[242:243], v[128:129], v[242:243], v[132:133]
	v_lshlrev_b32_e32 v158, 16, v162
	v_and_b32_e32 v159, 0xffff0000, v162
	v_pk_fma_f32 v[158:159], v[156:157], v[158:159], v[242:243]
	v_mul_f32_e32 v156, 0xbfb8aa3b, v248
	v_mul_f32_e32 v157, 0xbfb8aa3b, v249
	v_exp_f32_e32 v156, v156
	v_exp_f32_e32 v157, v157
	v_sub_f32_e32 v241, v241, v208
	v_sub_f32_e32 v240, v240, v208
	v_add_f32_e32 v156, 1.0, v156
	v_add_f32_e32 v157, 1.0, v157
	v_rcp_f32_e32 v156, v156
	v_rcp_f32_e32 v157, v157
	v_pk_mul_f32 v[240:241], v[210:211], v[240:241] op_sel_hi:[0,1]
	v_pk_fma_f32 v[240:241], v[130:131], v[240:241], v[134:135]
	v_lshlrev_b32_e32 v160, 16, v163
	v_and_b32_e32 v161, 0xffff0000, v163
	v_pk_fma_f32 v[160:161], v[156:157], v[160:161], v[240:241]
	v_lshl_add_u64 v[156:157], v[238:239], 2, s[4:5]
	global_store_dwordx4 v[156:157], v[152:155], off
	global_store_dwordx4 v[156:157], v[158:161], off offset:16
	s_nop 1
	v_lshlrev_b64 v[158:159], 10, v[236:237]
	v_lshl_add_u64 v[160:161], v[158:159], 0, v[212:213]
	v_lshlrev_b64 v[162:163], 1, v[160:161]
	v_lshl_add_u64 v[152:153], s[26:27], 0, v[162:163]
	v_lshl_add_u64 v[162:163], s[22:23], 0, v[162:163]
	global_load_dwordx4 v[152:155], v[152:153], off
	s_nop 0
	global_load_dwordx4 v[238:241], v[162:163], off
	s_waitcnt vmcnt(0)
	v_lshlrev_b32_e32 v207, 16, v238
	v_and_b32_e32 v211, 0xffff0000, v238
	v_lshlrev_b32_e32 v162, 16, v239
	v_and_b32_e32 v163, 0xffff0000, v239
	v_sub_f32_e32 v163, v163, v204
	v_sub_f32_e32 v162, v162, v204
	v_sub_f32_e32 v237, v211, v204
	v_sub_f32_e32 v236, v207, v204
	v_pk_mul_f32 v[236:237], v[206:207], v[236:237] op_sel_hi:[0,1]
	v_pk_mul_f32 v[162:163], v[206:207], v[162:163] op_sel_hi:[0,1]
	v_lshlrev_b32_e32 v207, 16, v240
	v_pk_fma_f32 v[148:149], v[206:207], v[148:149], v[120:121] op_sel_hi:[0,1,1]
	v_pk_fma_f32 v[238:239], v[138:139], v[162:163], v[142:143]
	v_and_b32_e32 v211, 0xffff0000, v240
	v_lshlrev_b32_e32 v162, 16, v241
	v_and_b32_e32 v163, 0xffff0000, v241
	v_pk_fma_f32 v[240:241], v[206:207], v[146:147], v[114:115] op_sel_hi:[0,1,1]
	v_mul_f32_e32 v146, 0xbfb8aa3b, v148
	v_mul_f32_e32 v147, 0xbfb8aa3b, v149
	v_exp_f32_e32 v146, v146
	v_exp_f32_e32 v147, v147
	v_pk_fma_f32 v[242:243], v[136:137], v[236:237], v[140:141]
	v_pk_fma_f32 v[150:151], v[206:207], v[150:151], v[122:123] op_sel_hi:[0,1,1]
	v_add_f32_e32 v146, 1.0, v146
	v_add_f32_e32 v147, 1.0, v147
	v_rcp_f32_e32 v146, v146
	v_rcp_f32_e32 v147, v147
	v_lshlrev_b32_e32 v148, 16, v152
	v_and_b32_e32 v149, 0xffff0000, v152
	v_pk_fma_f32 v[144:145], v[206:207], v[144:145], v[112:113] op_sel_hi:[0,1,1]
	v_pk_fma_f32 v[146:147], v[146:147], v[148:149], v[242:243]
	v_mul_f32_e32 v148, 0xbfb8aa3b, v150
	v_mul_f32_e32 v149, 0xbfb8aa3b, v151
	v_exp_f32_e32 v148, v148
	v_exp_f32_e32 v149, v149
	v_mul_f32_e32 v144, 0xbfb8aa3b, v144
	v_mul_f32_e32 v145, 0xbfb8aa3b, v145
	v_exp_f32_e32 v144, v144
	v_exp_f32_e32 v145, v145
	v_add_f32_e32 v148, 1.0, v148
	v_add_f32_e32 v149, 1.0, v149
	v_rcp_f32_e32 v148, v148
	v_rcp_f32_e32 v149, v149
	v_add_f32_e32 v144, 1.0, v144
	v_add_f32_e32 v145, 1.0, v145
	v_rcp_f32_e32 v144, v144
	v_rcp_f32_e32 v145, v145
	v_sub_f32_e32 v237, v211, v204
	v_sub_f32_e32 v236, v207, v204
	v_pk_mul_f32 v[236:237], v[206:207], v[236:237] op_sel_hi:[0,1]
	v_lshlrev_b32_e32 v150, 16, v153
	v_and_b32_e32 v151, 0xffff0000, v153
	v_pk_fma_f32 v[236:237], v[128:129], v[236:237], v[132:133]
	v_pk_fma_f32 v[148:149], v[148:149], v[150:151], v[238:239]
	v_lshlrev_b32_e32 v150, 16, v154
	v_and_b32_e32 v151, 0xffff0000, v154
; __device__ __forceinline__ f32x4 ln_fix(const f32x4& a, float mu, float rs, const f32x4& cs, const f32x4& cb) { return (a - cs * mu) * rs + cb; }
; __device__ __forceinline__ float bf_lo(unsigned w) { return __uint_as_float(w << 16); }
; __device__ __forceinline__ float bf_hi(unsigned w) { return __uint_as_float(w & 0xffff0000u); }
; __device__ __forceinline__ float fast_sigmoid(float v) { return __builtin_amdgcn_rcpf(1.0f + __builtin_amdgcn_exp2f(-1.4426950408889634f * v)); }
;     __device__ __forceinline__ void operator()(const f32x4 (&acc)[2][2][4][2], const Unit& u, int wr, int wc, int fr_in, int fq_in) const {
;     ...
;                 for (int m = (am * GR) & 3; m < ((am * GR) & 3) + GR; ++m) { const size_t off = (size_t)(row0 + ai * HALF + m * 16) * 1024 + col0 + bj * HALF; ppw[m] = *(const u32x4*)(pexb + off); pzw[m] = *(const u32x4*)(zb + off); }
;                 asm volatile("" ::: "memory");
; #pragma unroll
;                 for (int m = (am * GR) & 3; m < ((am * GR) & 3) + GR; ++m) { const size_t off = (size_t)(row0 + ai * HALF + m * 16) * 1024 + col0 + bj * HALF; const float mu = rst.mu[ai][m], rs = rst.rs[ai][m];
;                     const u32x4 pw = ppw[m]; const u32x4 zw = pzw[m];
;                     const f32x4 x0 = ((f32x4){bf_lo(zw.x), bf_hi(zw.x), bf_lo(zw.y), bf_hi(zw.y)} - mu) * rs * gv[0] + bv[0], x1 = ((f32x4){bf_lo(zw.z), bf_hi(zw.z), bf_lo(zw.w), bf_hi(zw.w)} - mu) * rs * gv[1] + bv[1];
;                     const f32x4 a0 = ln_fix(acc[ai][bj][m][0], mu, rs, csv[0], cbv[0]), a1 = ln_fix(acc[ai][bj][m][1], mu, rs, csv[1], cbv[1]); f32x4 o0, o1;
;                     o0[0] = x0[0] + fast_sigmoid(a0[0]) * bf_lo(pw.x); o0[1] = x0[1] + fast_sigmoid(a0[1]) * bf_hi(pw.x);
;                     o0[2] = x0[2] + fast_sigmoid(a0[2]) * bf_lo(pw.y); o0[3] = x0[3] + fast_sigmoid(a0[3]) * bf_hi(pw.y);
;                     o1[0] = x1[0] + fast_sigmoid(a1[0]) * bf_lo(pw.z); o1[1] = x1[1] + fast_sigmoid(a1[1]) * bf_hi(pw.z);
;                     o1[2] = x1[2] + fast_sigmoid(a1[2]) * bf_lo(pw.w); o1[3] = x1[3] + fast_sigmoid(a1[3]) * bf_hi(pw.w);
;                     if constexpr (FINAL) { *(f32x4*)(outf + off) = o0; *(f32x4*)(outf + off + 4) = o1; }
	v_pk_fma_f32 v[150:151], v[144:145], v[150:151], v[236:237]
	v_mul_f32_e32 v144, 0xbfb8aa3b, v240
	v_mul_f32_e32 v145, 0xbfb8aa3b, v241
	v_exp_f32_e32 v144, v144
	v_exp_f32_e32 v145, v145
	v_sub_f32_e32 v163, v163, v204
	v_sub_f32_e32 v162, v162, v204
	v_add_f32_e32 v144, 1.0, v144
	v_add_f32_e32 v145, 1.0, v145
	v_rcp_f32_e32 v144, v144
	v_rcp_f32_e32 v145, v145
	v_pk_mul_f32 v[162:163], v[206:207], v[162:163] op_sel_hi:[0,1]
	v_pk_fma_f32 v[162:163], v[130:131], v[162:163], v[134:135]
	v_lshlrev_b32_e32 v152, 16, v155
	v_and_b32_e32 v153, 0xffff0000, v155
	v_pk_fma_f32 v[152:153], v[144:145], v[152:153], v[162:163]
	v_lshl_add_u64 v[144:145], v[160:161], 2, s[4:5]
	global_store_dwordx4 v[144:145], v[146:149], off
	global_store_dwordx4 v[144:145], v[150:153], off offset:16
	v_pk_fma_f32 v[236:237], v[202:203], v[106:107], v[114:115] op_sel_hi:[0,1,1]
	v_lshlrev_b64 v[146:147], 10, v[234:235]
	v_lshl_add_u64 v[160:161], v[146:147], 0, v[212:213]
	v_lshlrev_b64 v[152:153], 1, v[160:161]
	v_lshl_add_u64 v[148:149], s[26:27], 0, v[152:153]
	v_lshl_add_u64 v[152:153], s[22:23], 0, v[152:153]
	global_load_dwordx4 v[148:151], v[148:149], off
	v_mul_f32_e32 v106, 0xbfb8aa3b, v108
	global_load_dwordx4 v[152:155], v[152:153], off
	v_mul_f32_e32 v107, 0xbfb8aa3b, v109
	v_exp_f32_e32 v106, v106
	v_exp_f32_e32 v107, v107
	v_add_f32_e32 v106, 1.0, v106
	v_add_f32_e32 v107, 1.0, v107
	v_rcp_f32_e32 v106, v106
	v_rcp_f32_e32 v107, v107
	s_waitcnt vmcnt(0)
	v_lshlrev_b32_e32 v108, 16, v148
	v_and_b32_e32 v109, 0xffff0000, v148
	v_lshlrev_b32_e32 v162, 16, v152
	v_and_b32_e32 v163, 0xffff0000, v152
	v_sub_f32_e32 v163, v163, v200
	v_sub_f32_e32 v162, v162, v200
	v_pk_mul_f32 v[162:163], v[202:203], v[162:163] op_sel_hi:[0,1]
	v_pk_fma_f32 v[162:163], v[136:137], v[162:163], v[140:141]
	v_lshlrev_b32_e32 v152, 16, v153
	v_pk_fma_f32 v[106:107], v[106:107], v[108:109], v[162:163]
	v_mul_f32_e32 v108, 0xbfb8aa3b, v110
	v_mul_f32_e32 v109, 0xbfb8aa3b, v111
	v_exp_f32_e32 v108, v108
	v_exp_f32_e32 v109, v109
	v_and_b32_e32 v153, 0xffff0000, v153
	v_sub_f32_e32 v153, v153, v200
	v_add_f32_e32 v108, 1.0, v108
	v_add_f32_e32 v109, 1.0, v109
	v_rcp_f32_e32 v108, v108
	v_rcp_f32_e32 v109, v109
	v_sub_f32_e32 v152, v152, v200
	v_lshlrev_b32_e32 v207, 16, v154
	v_and_b32_e32 v211, 0xffff0000, v154
	v_pk_mul_f32 v[152:153], v[202:203], v[152:153] op_sel_hi:[0,1]
	v_sub_f32_e32 v235, v211, v200
	v_sub_f32_e32 v234, v207, v200
	v_pk_fma_f32 v[152:153], v[138:139], v[152:153], v[142:143]
	v_pk_mul_f32 v[234:235], v[202:203], v[234:235] op_sel_hi:[0,1]
	v_lshlrev_b32_e32 v110, 16, v149
	v_and_b32_e32 v111, 0xffff0000, v149
	v_pk_fma_f32 v[234:235], v[128:129], v[234:235], v[132:133]
	v_pk_fma_f32 v[108:109], v[108:109], v[110:111], v[152:153]
	v_lshlrev_b32_e32 v110, 16, v150
	v_and_b32_e32 v111, 0xffff0000, v150
	v_pk_fma_f32 v[148:149], v[104:105], v[110:111], v[234:235]
	v_mul_f32_e32 v104, 0xbfb8aa3b, v236
	v_mul_f32_e32 v105, 0xbfb8aa3b, v237
	v_exp_f32_e32 v104, v104
	v_exp_f32_e32 v105, v105
	v_lshlrev_b32_e32 v154, 16, v155
	v_and_b32_e32 v155, 0xffff0000, v155
	v_add_f32_e32 v104, 1.0, v104
	v_add_f32_e32 v105, 1.0, v105
	v_rcp_f32_e32 v104, v104
	v_rcp_f32_e32 v105, v105
	v_sub_f32_e32 v155, v155, v200
	v_sub_f32_e32 v154, v154, v200
	v_pk_mul_f32 v[154:155], v[202:203], v[154:155] op_sel_hi:[0,1]
	v_pk_fma_f32 v[154:155], v[130:131], v[154:155], v[134:135]
	v_lshlrev_b32_e32 v110, 16, v151
	v_and_b32_e32 v111, 0xffff0000, v151
	v_pk_fma_f32 v[150:151], v[104:105], v[110:111], v[154:155]
	v_lshl_add_u64 v[104:105], v[160:161], 2, s[4:5]
	global_store_dwordx4 v[104:105], v[106:109], off
	global_store_dwordx4 v[104:105], v[148:151], off offset:16
	v_pk_fma_f32 v[162:163], v[198:199], v[98:99], v[114:115] op_sel_hi:[0,1,1]
	v_lshlrev_b64 v[106:107], 10, v[232:233]
	v_lshl_add_u64 v[152:153], v[106:107], 0, v[212:213]
	v_lshlrev_b64 v[148:149], 1, v[152:153]
	v_lshl_add_u64 v[108:109], s[26:27], 0, v[148:149]
	v_lshl_add_u64 v[148:149], s[22:23], 0, v[148:149]
	global_load_dwordx4 v[108:111], v[108:109], off
	v_mul_f32_e32 v98, 0xbfb8aa3b, v100
	global_load_dwordx4 v[148:151], v[148:149], off
	v_mul_f32_e32 v99, 0xbfb8aa3b, v101
	v_exp_f32_e32 v98, v98
	v_exp_f32_e32 v99, v99
	v_add_f32_e32 v98, 1.0, v98
	v_add_f32_e32 v99, 1.0, v99
	v_rcp_f32_e32 v98, v98
	v_rcp_f32_e32 v99, v99
	s_waitcnt vmcnt(0)
; __device__ __forceinline__ f32x4 ln_fix(const f32x4& a, float mu, float rs, const f32x4& cs, const f32x4& cb) { return (a - cs * mu) * rs + cb; }
; __device__ __forceinline__ float bf_lo(unsigned w) { return __uint_as_float(w << 16); }
; __device__ __forceinline__ float bf_hi(unsigned w) { return __uint_as_float(w & 0xffff0000u); }
; __device__ __forceinline__ float fast_sigmoid(float v) { return __builtin_amdgcn_rcpf(1.0f + __builtin_amdgcn_exp2f(-1.4426950408889634f * v)); }
;     __device__ __forceinline__ void operator()(const f32x4 (&acc)[2][2][4][2], const Unit& u, int wr, int wc, int fr_in, int fq_in) const {
;     ...
;                 for (int m = (am * GR) & 3; m < ((am * GR) & 3) + GR; ++m) { const size_t off = (size_t)(row0 + ai * HALF + m * 16) * 1024 + col0 + bj * HALF; ppw[m] = *(const u32x4*)(pexb + off); pzw[m] = *(const u32x4*)(zb + off); }
;                 asm volatile("" ::: "memory");
; #pragma unroll
;                 for (int m = (am * GR) & 3; m < ((am * GR) & 3) + GR; ++m) { const size_t off = (size_t)(row0 + ai * HALF + m * 16) * 1024 + col0 + bj * HALF; const float mu = rst.mu[ai][m], rs = rst.rs[ai][m];
;                     const u32x4 pw = ppw[m]; const u32x4 zw = pzw[m];
;                     const f32x4 x0 = ((f32x4){bf_lo(zw.x), bf_hi(zw.x), bf_lo(zw.y), bf_hi(zw.y)} - mu) * rs * gv[0] + bv[0], x1 = ((f32x4){bf_lo(zw.z), bf_hi(zw.z), bf_lo(zw.w), bf_hi(zw.w)} - mu) * rs * gv[1] + bv[1];
;                     const f32x4 a0 = ln_fix(acc[ai][bj][m][0], mu, rs, csv[0], cbv[0]), a1 = ln_fix(acc[ai][bj][m][1], mu, rs, csv[1], cbv[1]); f32x4 o0, o1;
;                     o0[0] = x0[0] + fast_sigmoid(a0[0]) * bf_lo(pw.x); o0[1] = x0[1] + fast_sigmoid(a0[1]) * bf_hi(pw.x);
;                     o0[2] = x0[2] + fast_sigmoid(a0[2]) * bf_lo(pw.y); o0[3] = x0[3] + fast_sigmoid(a0[3]) * bf_hi(pw.y);
;                     o1[0] = x1[0] + fast_sigmoid(a1[0]) * bf_lo(pw.z); o1[1] = x1[1] + fast_sigmoid(a1[1]) * bf_hi(pw.z);
;                     o1[2] = x1[2] + fast_sigmoid(a1[2]) * bf_lo(pw.w); o1[3] = x1[3] + fast_sigmoid(a1[3]) * bf_hi(pw.w);
;                     if constexpr (FINAL) { *(f32x4*)(outf + off) = o0; *(f32x4*)(outf + off + 4) = o1; }
	v_lshlrev_b32_e32 v100, 16, v108
	v_and_b32_e32 v101, 0xffff0000, v108
	v_lshlrev_b32_e32 v154, 16, v148
	v_and_b32_e32 v155, 0xffff0000, v148
	v_sub_f32_e32 v155, v155, v196
	v_sub_f32_e32 v154, v154, v196
	v_pk_mul_f32 v[154:155], v[198:199], v[154:155] op_sel_hi:[0,1]
	v_pk_fma_f32 v[154:155], v[136:137], v[154:155], v[140:141]
	v_lshlrev_b32_e32 v148, 16, v149
	v_pk_fma_f32 v[98:99], v[98:99], v[100:101], v[154:155]
	v_mul_f32_e32 v100, 0xbfb8aa3b, v102
	v_mul_f32_e32 v101, 0xbfb8aa3b, v103
	v_exp_f32_e32 v100, v100
	v_exp_f32_e32 v101, v101
	v_and_b32_e32 v149, 0xffff0000, v149
	v_sub_f32_e32 v149, v149, v196
	v_add_f32_e32 v100, 1.0, v100
	v_add_f32_e32 v101, 1.0, v101
	v_rcp_f32_e32 v100, v100
	v_rcp_f32_e32 v101, v101
	v_sub_f32_e32 v148, v148, v196
	v_lshlrev_b32_e32 v160, 16, v150
	v_and_b32_e32 v161, 0xffff0000, v150
	v_pk_mul_f32 v[148:149], v[198:199], v[148:149] op_sel_hi:[0,1]
	v_sub_f32_e32 v161, v161, v196
	v_sub_f32_e32 v160, v160, v196
	v_pk_fma_f32 v[148:149], v[138:139], v[148:149], v[142:143]
	v_pk_mul_f32 v[160:161], v[198:199], v[160:161] op_sel_hi:[0,1]
	v_lshlrev_b32_e32 v102, 16, v109
	v_and_b32_e32 v103, 0xffff0000, v109
	v_pk_fma_f32 v[160:161], v[128:129], v[160:161], v[132:133]
	v_pk_fma_f32 v[100:101], v[100:101], v[102:103], v[148:149]
	v_lshlrev_b32_e32 v102, 16, v110
	v_and_b32_e32 v103, 0xffff0000, v110
	v_pk_fma_f32 v[108:109], v[96:97], v[102:103], v[160:161]
	v_mul_f32_e32 v96, 0xbfb8aa3b, v162
	v_mul_f32_e32 v97, 0xbfb8aa3b, v163
	v_exp_f32_e32 v96, v96
	v_exp_f32_e32 v97, v97
	v_lshlrev_b32_e32 v150, 16, v151
	v_and_b32_e32 v151, 0xffff0000, v151
	v_add_f32_e32 v96, 1.0, v96
	v_add_f32_e32 v97, 1.0, v97
	v_rcp_f32_e32 v96, v96
	v_rcp_f32_e32 v97, v97
	v_sub_f32_e32 v151, v151, v196
	v_sub_f32_e32 v150, v150, v196
	v_pk_mul_f32 v[150:151], v[198:199], v[150:151] op_sel_hi:[0,1]
	v_pk_fma_f32 v[150:151], v[130:131], v[150:151], v[134:135]
	v_lshlrev_b32_e32 v102, 16, v111
	v_and_b32_e32 v103, 0xffff0000, v111
	v_pk_fma_f32 v[110:111], v[96:97], v[102:103], v[150:151]
	v_lshl_add_u64 v[96:97], v[152:153], 2, s[4:5]
	global_store_dwordx4 v[96:97], v[98:101], off
	global_store_dwordx4 v[96:97], v[108:111], off offset:16
	v_pk_fma_f32 v[160:161], v[194:195], v[88:89], v[112:113] op_sel_hi:[0,1,1]
	v_lshlrev_b64 v[98:99], 10, v[230:231]
	v_lshl_add_u64 v[148:149], v[98:99], 0, v[212:213]
	v_lshlrev_b64 v[108:109], 1, v[148:149]
	v_lshl_add_u64 v[100:101], s[26:27], 0, v[108:109]
	v_lshl_add_u64 v[108:109], s[22:23], 0, v[108:109]
	global_load_dwordx4 v[100:103], v[100:101], off
	v_mul_f32_e32 v88, 0xbfb8aa3b, v92
	global_load_dwordx4 v[108:111], v[108:109], off
	v_mul_f32_e32 v89, 0xbfb8aa3b, v93
	v_exp_f32_e32 v88, v88
	v_exp_f32_e32 v89, v89
	v_pk_fma_f32 v[154:155], v[194:195], v[90:91], v[114:115] op_sel_hi:[0,1,1]
	v_add_f32_e32 v88, 1.0, v88
	v_add_f32_e32 v89, 1.0, v89
	v_rcp_f32_e32 v88, v88
	v_rcp_f32_e32 v89, v89
	s_waitcnt vmcnt(0)
	v_lshlrev_b32_e32 v90, 16, v100
	v_and_b32_e32 v91, 0xffff0000, v100
	v_lshlrev_b32_e32 v150, 16, v108
	v_and_b32_e32 v151, 0xffff0000, v108
	v_sub_f32_e32 v151, v151, v192
	v_sub_f32_e32 v150, v150, v192
	v_pk_mul_f32 v[150:151], v[194:195], v[150:151] op_sel_hi:[0,1]
	v_pk_fma_f32 v[150:151], v[136:137], v[150:151], v[140:141]
	v_lshlrev_b32_e32 v108, 16, v109
	v_pk_fma_f32 v[88:89], v[88:89], v[90:91], v[150:151]
	v_mul_f32_e32 v90, 0xbfb8aa3b, v94
	v_mul_f32_e32 v91, 0xbfb8aa3b, v95
	v_exp_f32_e32 v90, v90
	v_exp_f32_e32 v91, v91
	v_and_b32_e32 v109, 0xffff0000, v109
	v_sub_f32_e32 v109, v109, v192
	v_add_f32_e32 v90, 1.0, v90
	v_add_f32_e32 v91, 1.0, v91
	v_rcp_f32_e32 v90, v90
	v_rcp_f32_e32 v91, v91
	v_sub_f32_e32 v108, v108, v192
	v_pk_mul_f32 v[108:109], v[194:195], v[108:109] op_sel_hi:[0,1]
	v_pk_fma_f32 v[108:109], v[138:139], v[108:109], v[142:143]
	v_lshlrev_b32_e32 v92, 16, v101
	v_and_b32_e32 v93, 0xffff0000, v101
	v_pk_fma_f32 v[90:91], v[90:91], v[92:93], v[108:109]
	v_mul_f32_e32 v92, 0xbfb8aa3b, v160
	v_mul_f32_e32 v93, 0xbfb8aa3b, v161
	v_exp_f32_e32 v92, v92
	v_exp_f32_e32 v93, v93
	v_lshlrev_b32_e32 v152, 16, v110
	v_and_b32_e32 v153, 0xffff0000, v110
	v_add_f32_e32 v92, 1.0, v92
	v_add_f32_e32 v93, 1.0, v93
	v_rcp_f32_e32 v92, v92
	v_rcp_f32_e32 v93, v93
	v_sub_f32_e32 v153, v153, v192
	v_sub_f32_e32 v152, v152, v192
	v_pk_mul_f32 v[152:153], v[194:195], v[152:153] op_sel_hi:[0,1]
	v_pk_fma_f32 v[152:153], v[128:129], v[152:153], v[132:133]
	v_lshlrev_b32_e32 v94, 16, v102
	v_and_b32_e32 v95, 0xffff0000, v102
	v_pk_fma_f32 v[92:93], v[92:93], v[94:95], v[152:153]
	v_mul_f32_e32 v94, 0xbfb8aa3b, v154
	v_mul_f32_e32 v95, 0xbfb8aa3b, v155
	v_exp_f32_e32 v94, v94
	v_exp_f32_e32 v95, v95
	v_lshlrev_b32_e32 v110, 16, v111
	v_and_b32_e32 v111, 0xffff0000, v111
	v_add_f32_e32 v94, 1.0, v94
	v_add_f32_e32 v95, 1.0, v95
	v_rcp_f32_e32 v94, v94
	v_rcp_f32_e32 v95, v95
	v_sub_f32_e32 v111, v111, v192
	v_sub_f32_e32 v110, v110, v192
	v_pk_mul_f32 v[110:111], v[194:195], v[110:111] op_sel_hi:[0,1]
	v_pk_fma_f32 v[110:111], v[130:131], v[110:111], v[134:135]
	v_lshlrev_b32_e32 v100, 16, v103
	v_and_b32_e32 v101, 0xffff0000, v103
	v_lshlrev_b64 v[102:103], 10, v[228:229]
	v_pk_fma_f32 v[94:95], v[94:95], v[100:101], v[110:111]
	v_lshl_add_u64 v[100:101], v[148:149], 2, s[4:5]
	v_lshl_add_u64 v[108:109], v[102:103], 0, v[212:213]
	global_store_dwordx4 v[100:101], v[88:91], off
	global_store_dwordx4 v[100:101], v[92:95], off offset:16
	v_pk_fma_f32 v[150:151], v[124:125], v[188:189], v[84:85] op_sel_hi:[1,0,1] neg_lo:[1,0,0] neg_hi:[1,0,0]
	v_xor_b32_e32 v85, 0x80000000, v127
	v_lshlrev_b64 v[92:93], 1, v[108:109]
	v_lshl_add_u64 v[88:89], s[26:27], 0, v[92:93]
; __device__ __forceinline__ f32x4 ln_fix(const f32x4& a, float mu, float rs, const f32x4& cs, const f32x4& cb) { return (a - cs * mu) * rs + cb; }
; __device__ __forceinline__ float bf_lo(unsigned w) { return __uint_as_float(w << 16); }
; __device__ __forceinline__ float bf_hi(unsigned w) { return __uint_as_float(w & 0xffff0000u); }
; __device__ __forceinline__ float fast_sigmoid(float v) { return __builtin_amdgcn_rcpf(1.0f + __builtin_amdgcn_exp2f(-1.4426950408889634f * v)); }
;     __device__ __forceinline__ void operator()(const f32x4 (&acc)[2][2][4][2], const Unit& u, int wr, int wc, int fr_in, int fq_in) const {
;     ...
;                 for (int m = (am * GR) & 3; m < ((am * GR) & 3) + GR; ++m) { const size_t off = (size_t)(row0 + ai * HALF + m * 16) * 1024 + col0 + bj * HALF; ppw[m] = *(const u32x4*)(pexb + off); pzw[m] = *(const u32x4*)(zb + off); }
;                 asm volatile("" ::: "memory");
; #pragma unroll
;                 for (int m = (am * GR) & 3; m < ((am * GR) & 3) + GR; ++m) { const size_t off = (size_t)(row0 + ai * HALF + m * 16) * 1024 + col0 + bj * HALF; const float mu = rst.mu[ai][m], rs = rst.rs[ai][m];
;                     const u32x4 pw = ppw[m]; const u32x4 zw = pzw[m];
;                     const f32x4 x0 = ((f32x4){bf_lo(zw.x), bf_hi(zw.x), bf_lo(zw.y), bf_hi(zw.y)} - mu) * rs * gv[0] + bv[0], x1 = ((f32x4){bf_lo(zw.z), bf_hi(zw.z), bf_lo(zw.w), bf_hi(zw.w)} - mu) * rs * gv[1] + bv[1];
;                     const f32x4 a0 = ln_fix(acc[ai][bj][m][0], mu, rs, csv[0], cbv[0]), a1 = ln_fix(acc[ai][bj][m][1], mu, rs, csv[1], cbv[1]); f32x4 o0, o1;
;                     o0[0] = x0[0] + fast_sigmoid(a0[0]) * bf_lo(pw.x); o0[1] = x0[1] + fast_sigmoid(a0[1]) * bf_hi(pw.x);
;                     o0[2] = x0[2] + fast_sigmoid(a0[2]) * bf_lo(pw.y); o0[3] = x0[3] + fast_sigmoid(a0[3]) * bf_hi(pw.y);
;                     o1[0] = x1[0] + fast_sigmoid(a1[0]) * bf_lo(pw.z); o1[1] = x1[1] + fast_sigmoid(a1[1]) * bf_hi(pw.z);
;                     o1[2] = x1[2] + fast_sigmoid(a1[2]) * bf_lo(pw.w); o1[3] = x1[3] + fast_sigmoid(a1[3]) * bf_hi(pw.w);
;                     if constexpr (FINAL) { *(f32x4*)(outf + off) = o0; *(f32x4*)(outf + off + 4) = o1; }
	v_lshl_add_u64 v[92:93], s[22:23], 0, v[92:93]
	global_load_dwordx4 v[88:91], v[88:89], off
	v_xor_b32_e32 v84, 0x80000000, v126
	global_load_dwordx4 v[92:95], v[92:93], off
	v_pk_fma_f32 v[126:127], v[150:151], v[190:191], v[120:121] op_sel_hi:[1,0,1]
	v_pk_fma_f32 v[152:153], v[190:191], v[80:81], v[112:113] op_sel_hi:[0,1,1]
	v_mul_f32_e32 v80, 0xbfb8aa3b, v126
	v_mul_f32_e32 v81, 0xbfb8aa3b, v127
	v_exp_f32_e32 v80, v80
	v_exp_f32_e32 v81, v81
	v_pk_fma_f32 v[86:87], v[84:85], v[188:189], v[86:87] op_sel_hi:[1,0,1]
	v_pk_fma_f32 v[150:151], v[190:191], v[82:83], v[114:115] op_sel_hi:[0,1,1]
	v_add_f32_e32 v80, 1.0, v80
	v_add_f32_e32 v81, 1.0, v81
	v_rcp_f32_e32 v80, v80
	v_rcp_f32_e32 v81, v81
	v_pk_fma_f32 v[86:87], v[86:87], v[190:191], v[122:123] op_sel_hi:[1,0,1]
	v_lshl_add_u64 v[108:109], v[108:109], 2, s[4:5]
	v_pk_fma_f32 v[78:79], v[84:85], v[184:185], v[78:79] op_sel_hi:[1,0,1]
	v_pk_fma_f32 v[126:127], v[74:75], v[186:187], v[114:115] op_sel_hi:[1,0,1]
	v_pk_fma_f32 v[78:79], v[78:79], v[186:187], v[122:123] op_sel_hi:[1,0,1]
	v_pk_fma_f32 v[70:71], v[84:85], v[180:181], v[70:71] op_sel_hi:[1,0,1]
	v_xor_b32_e32 v85, 0x80000000, v119
	v_xor_b32_e32 v84, 0x80000000, v118
	v_pk_fma_f32 v[66:67], v[84:85], v[180:181], v[66:67] op_sel_hi:[1,0,1]
	v_pk_fma_f32 v[70:71], v[70:71], v[182:183], v[122:123] op_sel_hi:[1,0,1]
	v_pk_fma_f32 v[84:85], v[66:67], v[182:183], v[114:115] op_sel_hi:[1,0,1]
	v_lshl_add_u64 v[114:115], v[212:213], 0, s[40:41]
	v_lshl_add_u64 v[116:117], v[114:115], 0, v[222:223]
	v_lshlrev_b64 v[120:121], 1, v[116:117]
	v_lshl_add_u64 v[116:117], s[26:27], 0, v[120:121]
	v_lshl_add_u64 v[120:121], s[22:23], 0, v[120:121]
	s_waitcnt vmcnt(0)
	v_lshlrev_b32_e32 v82, 16, v88
	v_and_b32_e32 v83, 0xffff0000, v88
	v_lshlrev_b32_e32 v110, 16, v92
	v_and_b32_e32 v111, 0xffff0000, v92
	v_sub_f32_e32 v111, v111, v188
	v_sub_f32_e32 v110, v110, v188
	v_pk_mul_f32 v[110:111], v[190:191], v[110:111] op_sel_hi:[0,1]
	v_pk_fma_f32 v[110:111], v[136:137], v[110:111], v[140:141]
	v_lshlrev_b32_e32 v92, 16, v93
	v_pk_fma_f32 v[80:81], v[80:81], v[82:83], v[110:111]
	v_mul_f32_e32 v82, 0xbfb8aa3b, v86
	v_mul_f32_e32 v83, 0xbfb8aa3b, v87
	v_exp_f32_e32 v82, v82
	v_exp_f32_e32 v83, v83
	v_and_b32_e32 v93, 0xffff0000, v93
	v_sub_f32_e32 v93, v93, v188
	v_add_f32_e32 v82, 1.0, v82
	v_add_f32_e32 v83, 1.0, v83
	v_rcp_f32_e32 v82, v82
	v_rcp_f32_e32 v83, v83
	v_sub_f32_e32 v92, v92, v188
	v_pk_mul_f32 v[92:93], v[190:191], v[92:93] op_sel_hi:[0,1]
	v_pk_fma_f32 v[92:93], v[138:139], v[92:93], v[142:143]
	v_lshlrev_b32_e32 v86, 16, v89
	v_and_b32_e32 v87, 0xffff0000, v89
	v_pk_fma_f32 v[82:83], v[82:83], v[86:87], v[92:93]
	v_mul_f32_e32 v86, 0xbfb8aa3b, v152
	v_mul_f32_e32 v87, 0xbfb8aa3b, v153
	v_exp_f32_e32 v86, v86
	v_exp_f32_e32 v87, v87
	v_lshlrev_b32_e32 v148, 16, v94
	v_and_b32_e32 v149, 0xffff0000, v94
	v_add_f32_e32 v86, 1.0, v86
	v_add_f32_e32 v87, 1.0, v87
	v_rcp_f32_e32 v86, v86
	v_rcp_f32_e32 v87, v87
	v_sub_f32_e32 v149, v149, v188
	v_sub_f32_e32 v148, v148, v188
	v_pk_mul_f32 v[148:149], v[190:191], v[148:149] op_sel_hi:[0,1]
	v_pk_fma_f32 v[148:149], v[128:129], v[148:149], v[132:133]
	v_lshlrev_b32_e32 v88, 16, v90
	v_and_b32_e32 v89, 0xffff0000, v90
	v_pk_fma_f32 v[86:87], v[86:87], v[88:89], v[148:149]
	v_mul_f32_e32 v88, 0xbfb8aa3b, v150
	v_mul_f32_e32 v89, 0xbfb8aa3b, v151
	v_exp_f32_e32 v88, v88
	v_exp_f32_e32 v89, v89
	v_lshlrev_b32_e32 v94, 16, v95
	v_and_b32_e32 v95, 0xffff0000, v95
	v_add_f32_e32 v88, 1.0, v88
	v_add_f32_e32 v89, 1.0, v89
	v_rcp_f32_e32 v88, v88
	v_rcp_f32_e32 v89, v89
	v_sub_f32_e32 v95, v95, v188
	v_sub_f32_e32 v94, v94, v188
	v_pk_mul_f32 v[94:95], v[190:191], v[94:95] op_sel_hi:[0,1]
	v_pk_fma_f32 v[94:95], v[130:131], v[94:95], v[134:135]
	v_lshlrev_b32_e32 v90, 16, v91
	v_and_b32_e32 v91, 0xffff0000, v91
	v_lshlrev_b64 v[110:111], 10, v[226:227]
	v_pk_fma_f32 v[88:89], v[88:89], v[90:91], v[94:95]
	v_lshl_add_u64 v[90:91], v[110:111], 0, v[212:213]
	global_store_dwordx4 v[108:109], v[80:83], off
	global_store_dwordx4 v[108:109], v[86:89], off offset:16
	v_pk_fma_f32 v[148:149], v[72:73], v[186:187], v[112:113] op_sel_hi:[1,0,1]
	v_mul_f32_e32 v72, 0xbfb8aa3b, v76
	v_lshlrev_b64 v[86:87], 1, v[90:91]
	v_lshl_add_u64 v[80:81], s[26:27], 0, v[86:87]
	v_lshl_add_u64 v[86:87], s[22:23], 0, v[86:87]
	global_load_dwordx4 v[80:83], v[80:81], off
	v_mul_f32_e32 v73, 0xbfb8aa3b, v77
	global_load_dwordx4 v[86:89], v[86:87], off
	v_exp_f32_e32 v72, v72
	v_exp_f32_e32 v73, v73
	v_add_f32_e32 v72, 1.0, v72
	v_add_f32_e32 v73, 1.0, v73
	v_rcp_f32_e32 v72, v72
	v_rcp_f32_e32 v73, v73
	s_waitcnt vmcnt(0)
; __device__ __forceinline__ f32x4 ln_fix(const f32x4& a, float mu, float rs, const f32x4& cs, const f32x4& cb) { return (a - cs * mu) * rs + cb; }
; __device__ __forceinline__ float bf_lo(unsigned w) { return __uint_as_float(w << 16); }
; __device__ __forceinline__ float bf_hi(unsigned w) { return __uint_as_float(w & 0xffff0000u); }
; __device__ __forceinline__ float fast_sigmoid(float v) { return __builtin_amdgcn_rcpf(1.0f + __builtin_amdgcn_exp2f(-1.4426950408889634f * v)); }
;     __device__ __forceinline__ void operator()(const f32x4 (&acc)[2][2][4][2], const Unit& u, int wr, int wc, int fr_in, int fq_in) const {
;     ...
;                 for (int m = (am * GR) & 3; m < ((am * GR) & 3) + GR; ++m) { const size_t off = (size_t)(row0 + ai * HALF + m * 16) * 1024 + col0 + bj * HALF; ppw[m] = *(const u32x4*)(pexb + off); pzw[m] = *(const u32x4*)(zb + off); }
;                 asm volatile("" ::: "memory");
; #pragma unroll
;                 for (int m = (am * GR) & 3; m < ((am * GR) & 3) + GR; ++m) { const size_t off = (size_t)(row0 + ai * HALF + m * 16) * 1024 + col0 + bj * HALF; const float mu = rst.mu[ai][m], rs = rst.rs[ai][m];
;                     const u32x4 pw = ppw[m]; const u32x4 zw = pzw[m];
;                     const f32x4 x0 = ((f32x4){bf_lo(zw.x), bf_hi(zw.x), bf_lo(zw.y), bf_hi(zw.y)} - mu) * rs * gv[0] + bv[0], x1 = ((f32x4){bf_lo(zw.z), bf_hi(zw.z), bf_lo(zw.w), bf_hi(zw.w)} - mu) * rs * gv[1] + bv[1];
;                     const f32x4 a0 = ln_fix(acc[ai][bj][m][0], mu, rs, csv[0], cbv[0]), a1 = ln_fix(acc[ai][bj][m][1], mu, rs, csv[1], cbv[1]); f32x4 o0, o1;
;                     o0[0] = x0[0] + fast_sigmoid(a0[0]) * bf_lo(pw.x); o0[1] = x0[1] + fast_sigmoid(a0[1]) * bf_hi(pw.x);
;                     o0[2] = x0[2] + fast_sigmoid(a0[2]) * bf_lo(pw.y); o0[3] = x0[3] + fast_sigmoid(a0[3]) * bf_hi(pw.y);
;                     o1[0] = x1[0] + fast_sigmoid(a1[0]) * bf_lo(pw.z); o1[1] = x1[1] + fast_sigmoid(a1[1]) * bf_hi(pw.z);
;                     o1[2] = x1[2] + fast_sigmoid(a1[2]) * bf_lo(pw.w); o1[3] = x1[3] + fast_sigmoid(a1[3]) * bf_hi(pw.w);
;                     if constexpr (FINAL) { *(f32x4*)(outf + off) = o0; *(f32x4*)(outf + off + 4) = o1; }
	v_lshlrev_b32_e32 v74, 16, v80
	v_and_b32_e32 v75, 0xffff0000, v80
	v_lshlrev_b32_e32 v92, 16, v86
	v_and_b32_e32 v93, 0xffff0000, v86
	v_sub_f32_e32 v93, v93, v184
	v_sub_f32_e32 v92, v92, v184
	v_pk_mul_f32 v[92:93], v[186:187], v[92:93] op_sel_hi:[0,1]
	v_pk_fma_f32 v[92:93], v[136:137], v[92:93], v[140:141]
	v_lshlrev_b32_e32 v86, 16, v87
	v_pk_fma_f32 v[72:73], v[72:73], v[74:75], v[92:93]
	v_mul_f32_e32 v74, 0xbfb8aa3b, v78
	v_mul_f32_e32 v75, 0xbfb8aa3b, v79
	v_exp_f32_e32 v74, v74
	v_exp_f32_e32 v75, v75
	v_and_b32_e32 v87, 0xffff0000, v87
	v_sub_f32_e32 v87, v87, v184
	v_add_f32_e32 v74, 1.0, v74
	v_add_f32_e32 v75, 1.0, v75
	v_rcp_f32_e32 v74, v74
	v_rcp_f32_e32 v75, v75
	v_sub_f32_e32 v86, v86, v184
	v_pk_mul_f32 v[86:87], v[186:187], v[86:87] op_sel_hi:[0,1]
	v_pk_fma_f32 v[86:87], v[138:139], v[86:87], v[142:143]
	v_lshlrev_b32_e32 v76, 16, v81
	v_and_b32_e32 v77, 0xffff0000, v81
	v_pk_fma_f32 v[74:75], v[74:75], v[76:77], v[86:87]
	v_mul_f32_e32 v76, 0xbfb8aa3b, v148
	v_mul_f32_e32 v77, 0xbfb8aa3b, v149
	v_exp_f32_e32 v76, v76
	v_exp_f32_e32 v77, v77
	v_lshlrev_b32_e32 v94, 16, v88
	v_and_b32_e32 v95, 0xffff0000, v88
	v_add_f32_e32 v76, 1.0, v76
	v_add_f32_e32 v77, 1.0, v77
	v_rcp_f32_e32 v76, v76
	v_rcp_f32_e32 v77, v77
	v_sub_f32_e32 v95, v95, v184
	v_sub_f32_e32 v94, v94, v184
	v_pk_mul_f32 v[94:95], v[186:187], v[94:95] op_sel_hi:[0,1]
	v_pk_fma_f32 v[94:95], v[128:129], v[94:95], v[132:133]
	v_lshlrev_b32_e32 v78, 16, v82
	v_and_b32_e32 v79, 0xffff0000, v82
	v_pk_fma_f32 v[76:77], v[76:77], v[78:79], v[94:95]
	v_mul_f32_e32 v78, 0xbfb8aa3b, v126
	v_mul_f32_e32 v79, 0xbfb8aa3b, v127
	v_exp_f32_e32 v78, v78
	v_exp_f32_e32 v79, v79
	v_lshlrev_b32_e32 v88, 16, v89
	v_and_b32_e32 v89, 0xffff0000, v89
	v_add_f32_e32 v78, 1.0, v78
	v_add_f32_e32 v79, 1.0, v79
	v_rcp_f32_e32 v78, v78
	v_rcp_f32_e32 v79, v79
	v_sub_f32_e32 v89, v89, v184
	v_sub_f32_e32 v88, v88, v184
	v_pk_mul_f32 v[88:89], v[186:187], v[88:89] op_sel_hi:[0,1]
	v_pk_fma_f32 v[88:89], v[130:131], v[88:89], v[134:135]
	v_lshlrev_b32_e32 v80, 16, v83
	v_and_b32_e32 v81, 0xffff0000, v83
	v_lshlrev_b64 v[148:149], 10, v[224:225]
	v_pk_fma_f32 v[78:79], v[78:79], v[80:81], v[88:89]
	v_lshl_add_u64 v[126:127], v[90:91], 2, s[4:5]
	v_lshl_add_u64 v[80:81], v[148:149], 0, v[212:213]
	global_store_dwordx4 v[126:127], v[72:75], off
	global_store_dwordx4 v[126:127], v[76:79], off offset:16
	v_pk_fma_f32 v[88:89], v[64:65], v[182:183], v[112:113] op_sel_hi:[1,0,1]
	v_mul_f32_e32 v64, 0xbfb8aa3b, v68
	v_lshlrev_b64 v[76:77], 1, v[80:81]
	v_lshl_add_u64 v[72:73], s[26:27], 0, v[76:77]
	v_lshl_add_u64 v[76:77], s[22:23], 0, v[76:77]
	global_load_dwordx4 v[72:75], v[72:73], off
	v_mul_f32_e32 v65, 0xbfb8aa3b, v69
	global_load_dwordx4 v[76:79], v[76:77], off
	v_exp_f32_e32 v64, v64
	v_exp_f32_e32 v65, v65
	v_lshl_add_u64 v[112:113], v[80:81], 2, s[4:5]
	v_add_f32_e32 v64, 1.0, v64
	v_add_f32_e32 v65, 1.0, v65
	v_rcp_f32_e32 v64, v64
	v_rcp_f32_e32 v65, v65
	s_waitcnt vmcnt(0)
	v_lshlrev_b32_e32 v66, 16, v72
	v_and_b32_e32 v67, 0xffff0000, v72
	v_lshlrev_b32_e32 v82, 16, v76
	v_and_b32_e32 v83, 0xffff0000, v76
	v_sub_f32_e32 v83, v83, v180
	v_sub_f32_e32 v82, v82, v180
	v_pk_mul_f32 v[82:83], v[182:183], v[82:83] op_sel_hi:[0,1]
	v_pk_fma_f32 v[82:83], v[136:137], v[82:83], v[140:141]
	v_lshlrev_b32_e32 v76, 16, v77
	v_pk_fma_f32 v[64:65], v[64:65], v[66:67], v[82:83]
	v_mul_f32_e32 v66, 0xbfb8aa3b, v70
	v_mul_f32_e32 v67, 0xbfb8aa3b, v71
	v_exp_f32_e32 v66, v66
	v_exp_f32_e32 v67, v67
	v_and_b32_e32 v77, 0xffff0000, v77
	v_sub_f32_e32 v77, v77, v180
	v_add_f32_e32 v66, 1.0, v66
	v_add_f32_e32 v67, 1.0, v67
	v_rcp_f32_e32 v66, v66
	v_rcp_f32_e32 v67, v67
	v_sub_f32_e32 v76, v76, v180
	v_pk_mul_f32 v[76:77], v[182:183], v[76:77] op_sel_hi:[0,1]
	v_pk_fma_f32 v[76:77], v[138:139], v[76:77], v[142:143]
	v_lshlrev_b32_e32 v68, 16, v73
	v_and_b32_e32 v69, 0xffff0000, v73
	v_pk_fma_f32 v[66:67], v[66:67], v[68:69], v[76:77]
	v_mul_f32_e32 v68, 0xbfb8aa3b, v88
	v_mul_f32_e32 v69, 0xbfb8aa3b, v89
	v_exp_f32_e32 v68, v68
	v_exp_f32_e32 v69, v69
	v_lshlrev_b32_e32 v86, 16, v78
	v_and_b32_e32 v87, 0xffff0000, v78
	v_add_f32_e32 v68, 1.0, v68
	v_add_f32_e32 v69, 1.0, v69
	v_rcp_f32_e32 v68, v68
	v_rcp_f32_e32 v69, v69
	v_sub_f32_e32 v87, v87, v180
	v_sub_f32_e32 v86, v86, v180
	v_pk_mul_f32 v[86:87], v[182:183], v[86:87] op_sel_hi:[0,1]
	v_pk_fma_f32 v[86:87], v[128:129], v[86:87], v[132:133]
	v_lshlrev_b32_e32 v70, 16, v74
	v_and_b32_e32 v71, 0xffff0000, v74
	v_pk_fma_f32 v[68:69], v[68:69], v[70:71], v[86:87]
	v_mul_f32_e32 v70, 0xbfb8aa3b, v84
	v_mul_f32_e32 v71, 0xbfb8aa3b, v85
	v_exp_f32_e32 v70, v70
	v_exp_f32_e32 v71, v71
	v_lshlrev_b32_e32 v78, 16, v79
	v_and_b32_e32 v79, 0xffff0000, v79
	v_add_f32_e32 v70, 1.0, v70
	v_add_f32_e32 v71, 1.0, v71
	v_rcp_f32_e32 v70, v70
	v_rcp_f32_e32 v71, v71
	v_sub_f32_e32 v79, v79, v180
	v_sub_f32_e32 v78, v78, v180
	v_pk_mul_f32 v[78:79], v[182:183], v[78:79] op_sel_hi:[0,1]
	v_pk_fma_f32 v[78:79], v[130:131], v[78:79], v[134:135]
	v_lshlrev_b32_e32 v72, 16, v75
	v_and_b32_e32 v73, 0xffff0000, v75
	v_pk_fma_f32 v[70:71], v[70:71], v[72:73], v[78:79]
	global_store_dwordx4 v[112:113], v[64:67], off
	global_store_dwordx4 v[112:113], v[68:71], off offset:16
	global_load_dwordx4 v[64:67], v[220:221], off offset:528
	s_nop 0
	global_load_dwordx4 v[72:75], v[220:221], off offset:512
	global_load_dwordx4 v[68:71], v[218:219], off offset:528
	global_load_dwordx4 v[76:79], v[218:219], off offset:512
	global_load_dwordx4 v[80:83], v[216:217], off offset:528
	global_load_dwordx4 v[88:91], v[216:217], off offset:512
	global_load_dwordx4 v[84:87], v[214:215], off offset:528
	global_load_dwordx4 v[92:95], v[214:215], off offset:512
	s_waitcnt vmcnt(0)
; __device__ __forceinline__ float fast_sigmoid(float v) { return __builtin_amdgcn_rcpf(1.0f + __builtin_amdgcn_exp2f(-1.4426950408889634f * v)); }
; __device__ __forceinline__ float bf_lo(unsigned w) { return __uint_as_float(w << 16); }
; __device__ __forceinline__ float bf_hi(unsigned w) { return __uint_as_float(w & 0xffff0000u); }
; __device__ __forceinline__ f32x4 ln_fix(const f32x4& a, float mu, float rs, const f32x4& cs, const f32x4& cb) { return (a - cs * mu) * rs + cb; }
;     __device__ __forceinline__ void operator()(const f32x4 (&acc)[2][2][4][2], const Unit& u, int wr, int wc, int fr_in, int fq_in) const {
;     ...
;                 for (int m = (am * GR) & 3; m < ((am * GR) & 3) + GR; ++m) { const size_t off = (size_t)(row0 + ai * HALF + m * 16) * 1024 + col0 + bj * HALF; const float mu = rst.mu[ai][m], rs = rst.rs[ai][m];
;                     const u32x4 pw = ppw[m]; const u32x4 zw = pzw[m];
;                     const f32x4 x0 = ((f32x4){bf_lo(zw.x), bf_hi(zw.x), bf_lo(zw.y), bf_hi(zw.y)} - mu) * rs * gv[0] + bv[0], x1 = ((f32x4){bf_lo(zw.z), bf_hi(zw.z), bf_lo(zw.w), bf_hi(zw.w)} - mu) * rs * gv[1] + bv[1];
;                     const f32x4 a0 = ln_fix(acc[ai][bj][m][0], mu, rs, csv[0], cbv[0]), a1 = ln_fix(acc[ai][bj][m][1], mu, rs, csv[1], cbv[1]); f32x4 o0, o1;
;                     o0[0] = x0[0] + fast_sigmoid(a0[0]) * bf_lo(pw.x); o0[1] = x0[1] + fast_sigmoid(a0[1]) * bf_hi(pw.x);
;                     o0[2] = x0[2] + fast_sigmoid(a0[2]) * bf_lo(pw.y); o0[3] = x0[3] + fast_sigmoid(a0[3]) * bf_hi(pw.y);
;                     o1[0] = x1[0] + fast_sigmoid(a1[0]) * bf_lo(pw.z); o1[1] = x1[1] + fast_sigmoid(a1[1]) * bf_hi(pw.z);
;                     o1[2] = x1[2] + fast_sigmoid(a1[2]) * bf_lo(pw.w); o1[3] = x1[3] + fast_sigmoid(a1[3]) * bf_hi(pw.w);
	v_pk_fma_f32 v[56:57], v[208:209], v[64:65], v[56:57] op_sel_hi:[0,1,1] neg_lo:[1,0,0] neg_hi:[1,0,0]
	global_load_dwordx4 v[116:119], v[116:117], off
	v_pk_fma_f32 v[60:61], v[208:209], v[72:73], v[60:61] op_sel_hi:[0,1,1] neg_lo:[1,0,0] neg_hi:[1,0,0]
	global_load_dwordx4 v[120:123], v[120:121], off
	v_pk_fma_f32 v[60:61], v[210:211], v[60:61], v[76:77] op_sel_hi:[0,1,1]
	v_pk_fma_f32 v[132:133], v[210:211], v[56:57], v[68:69] op_sel_hi:[0,1,1]
	v_mul_f32_e32 v56, 0xbfb8aa3b, v60
	v_mul_f32_e32 v57, 0xbfb8aa3b, v61
	v_exp_f32_e32 v56, v56
	v_exp_f32_e32 v57, v57
	v_pk_fma_f32 v[62:63], v[208:209], v[74:75], v[62:63] op_sel_hi:[0,1,1] neg_lo:[1,0,0] neg_hi:[1,0,0]
	v_pk_fma_f32 v[58:59], v[208:209], v[66:67], v[58:59] op_sel_hi:[0,1,1] neg_lo:[1,0,0] neg_hi:[1,0,0]
	v_add_f32_e32 v56, 1.0, v56
	v_add_f32_e32 v57, 1.0, v57
	v_rcp_f32_e32 v56, v56
	v_rcp_f32_e32 v57, v57
	v_pk_fma_f32 v[62:63], v[210:211], v[62:63], v[78:79] op_sel_hi:[0,1,1]
	v_pk_fma_f32 v[130:131], v[210:211], v[58:59], v[70:71] op_sel_hi:[0,1,1]
	v_pk_fma_f32 v[52:53], v[204:205], v[72:73], v[52:53] op_sel_hi:[0,1,1] neg_lo:[1,0,0] neg_hi:[1,0,0]
	v_pk_fma_f32 v[52:53], v[206:207], v[52:53], v[76:77] op_sel_hi:[0,1,1]
	v_pk_fma_f32 v[48:49], v[204:205], v[64:65], v[48:49] op_sel_hi:[0,1,1] neg_lo:[1,0,0] neg_hi:[1,0,0]
	v_pk_fma_f32 v[54:55], v[204:205], v[74:75], v[54:55] op_sel_hi:[0,1,1] neg_lo:[1,0,0] neg_hi:[1,0,0]
	v_pk_fma_f32 v[50:51], v[204:205], v[66:67], v[50:51] op_sel_hi:[0,1,1] neg_lo:[1,0,0] neg_hi:[1,0,0]
	v_pk_fma_f32 v[54:55], v[206:207], v[54:55], v[78:79] op_sel_hi:[0,1,1]
	v_pk_fma_f32 v[44:45], v[200:201], v[72:73], v[44:45] op_sel_hi:[0,1,1] neg_lo:[1,0,0] neg_hi:[1,0,0]
	v_pk_fma_f32 v[44:45], v[202:203], v[44:45], v[76:77] op_sel_hi:[0,1,1]
	v_pk_fma_f32 v[40:41], v[200:201], v[64:65], v[40:41] op_sel_hi:[0,1,1] neg_lo:[1,0,0] neg_hi:[1,0,0]
	v_pk_fma_f32 v[46:47], v[200:201], v[74:75], v[46:47] op_sel_hi:[0,1,1] neg_lo:[1,0,0] neg_hi:[1,0,0]
	v_pk_fma_f32 v[42:43], v[200:201], v[66:67], v[42:43] op_sel_hi:[0,1,1] neg_lo:[1,0,0] neg_hi:[1,0,0]
	v_pk_fma_f32 v[46:47], v[202:203], v[46:47], v[78:79] op_sel_hi:[0,1,1]
	v_pk_fma_f32 v[36:37], v[196:197], v[72:73], v[36:37] op_sel_hi:[0,1,1] neg_lo:[1,0,0] neg_hi:[1,0,0]
	v_pk_fma_f32 v[36:37], v[198:199], v[36:37], v[76:77] op_sel_hi:[0,1,1]
	v_pk_fma_f32 v[32:33], v[196:197], v[64:65], v[32:33] op_sel_hi:[0,1,1] neg_lo:[1,0,0] neg_hi:[1,0,0]
	v_pk_fma_f32 v[38:39], v[196:197], v[74:75], v[38:39] op_sel_hi:[0,1,1] neg_lo:[1,0,0] neg_hi:[1,0,0]
	v_pk_fma_f32 v[34:35], v[196:197], v[66:67], v[34:35] op_sel_hi:[0,1,1] neg_lo:[1,0,0] neg_hi:[1,0,0]
	v_pk_fma_f32 v[38:39], v[198:199], v[38:39], v[78:79] op_sel_hi:[0,1,1]
	v_pk_fma_f32 v[28:29], v[192:193], v[72:73], v[28:29] op_sel_hi:[0,1,1] neg_lo:[1,0,0] neg_hi:[1,0,0]
	v_pk_fma_f32 v[28:29], v[194:195], v[28:29], v[76:77] op_sel_hi:[0,1,1]
	v_pk_fma_f32 v[24:25], v[192:193], v[64:65], v[24:25] op_sel_hi:[0,1,1] neg_lo:[1,0,0] neg_hi:[1,0,0]
	v_pk_fma_f32 v[30:31], v[192:193], v[74:75], v[30:31] op_sel_hi:[0,1,1] neg_lo:[1,0,0] neg_hi:[1,0,0]
	v_pk_fma_f32 v[26:27], v[192:193], v[66:67], v[26:27] op_sel_hi:[0,1,1] neg_lo:[1,0,0] neg_hi:[1,0,0]
	v_pk_fma_f32 v[30:31], v[194:195], v[30:31], v[78:79] op_sel_hi:[0,1,1]
	v_pk_fma_f32 v[20:21], v[188:189], v[72:73], v[20:21] op_sel_hi:[0,1,1] neg_lo:[1,0,0] neg_hi:[1,0,0]
	v_pk_fma_f32 v[20:21], v[190:191], v[20:21], v[76:77] op_sel_hi:[0,1,1]
	v_pk_fma_f32 v[16:17], v[188:189], v[64:65], v[16:17] op_sel_hi:[0,1,1] neg_lo:[1,0,0] neg_hi:[1,0,0]
	v_pk_fma_f32 v[22:23], v[188:189], v[74:75], v[22:23] op_sel_hi:[0,1,1] neg_lo:[1,0,0] neg_hi:[1,0,0]
	v_pk_fma_f32 v[18:19], v[188:189], v[66:67], v[18:19] op_sel_hi:[0,1,1] neg_lo:[1,0,0] neg_hi:[1,0,0]
	v_pk_fma_f32 v[22:23], v[190:191], v[22:23], v[78:79] op_sel_hi:[0,1,1]
	v_pk_fma_f32 v[12:13], v[184:185], v[72:73], v[12:13] op_sel_hi:[0,1,1] neg_lo:[1,0,0] neg_hi:[1,0,0]
	v_pk_fma_f32 v[12:13], v[186:187], v[12:13], v[76:77] op_sel_hi:[0,1,1]
	v_pk_fma_f32 v[8:9], v[184:185], v[64:65], v[8:9] op_sel_hi:[0,1,1] neg_lo:[1,0,0] neg_hi:[1,0,0]
	v_pk_fma_f32 v[14:15], v[184:185], v[74:75], v[14:15] op_sel_hi:[0,1,1] neg_lo:[1,0,0] neg_hi:[1,0,0]
	v_pk_fma_f32 v[10:11], v[184:185], v[66:67], v[10:11] op_sel_hi:[0,1,1] neg_lo:[1,0,0] neg_hi:[1,0,0]
	v_pk_fma_f32 v[14:15], v[186:187], v[14:15], v[78:79] op_sel_hi:[0,1,1]
	v_pk_fma_f32 v[4:5], v[180:181], v[72:73], v[4:5] op_sel_hi:[0,1,1] neg_lo:[1,0,0] neg_hi:[1,0,0]
	v_pk_fma_f32 v[4:5], v[182:183], v[4:5], v[76:77] op_sel_hi:[0,1,1]
	v_pk_fma_f32 v[0:1], v[180:181], v[64:65], v[0:1] op_sel_hi:[0,1,1] neg_lo:[1,0,0] neg_hi:[1,0,0]
	v_pk_fma_f32 v[6:7], v[180:181], v[74:75], v[6:7] op_sel_hi:[0,1,1] neg_lo:[1,0,0] neg_hi:[1,0,0]
	v_pk_fma_f32 v[2:3], v[180:181], v[66:67], v[2:3] op_sel_hi:[0,1,1] neg_lo:[1,0,0] neg_hi:[1,0,0]
	v_pk_fma_f32 v[6:7], v[182:183], v[6:7], v[78:79] op_sel_hi:[0,1,1]
	s_waitcnt vmcnt(0)
; __device__ __forceinline__ f32x4 ln_fix(const f32x4& a, float mu, float rs, const f32x4& cs, const f32x4& cb) { return (a - cs * mu) * rs + cb; }
; __device__ __forceinline__ float bf_lo(unsigned w) { return __uint_as_float(w << 16); }
; __device__ __forceinline__ float bf_hi(unsigned w) { return __uint_as_float(w & 0xffff0000u); }
; __device__ __forceinline__ float fast_sigmoid(float v) { return __builtin_amdgcn_rcpf(1.0f + __builtin_amdgcn_exp2f(-1.4426950408889634f * v)); }
;     __device__ __forceinline__ void operator()(const f32x4 (&acc)[2][2][4][2], const Unit& u, int wr, int wc, int fr_in, int fq_in) const {
;     ...
;                 for (int m = (am * GR) & 3; m < ((am * GR) & 3) + GR; ++m) { const size_t off = (size_t)(row0 + ai * HALF + m * 16) * 1024 + col0 + bj * HALF; ppw[m] = *(const u32x4*)(pexb + off); pzw[m] = *(const u32x4*)(zb + off); }
;                 asm volatile("" ::: "memory");
; #pragma unroll
;                 for (int m = (am * GR) & 3; m < ((am * GR) & 3) + GR; ++m) { const size_t off = (size_t)(row0 + ai * HALF + m * 16) * 1024 + col0 + bj * HALF; const float mu = rst.mu[ai][m], rs = rst.rs[ai][m];
;                     const u32x4 pw = ppw[m]; const u32x4 zw = pzw[m];
;                     const f32x4 x0 = ((f32x4){bf_lo(zw.x), bf_hi(zw.x), bf_lo(zw.y), bf_hi(zw.y)} - mu) * rs * gv[0] + bv[0], x1 = ((f32x4){bf_lo(zw.z), bf_hi(zw.z), bf_lo(zw.w), bf_hi(zw.w)} - mu) * rs * gv[1] + bv[1];
;                     const f32x4 a0 = ln_fix(acc[ai][bj][m][0], mu, rs, csv[0], cbv[0]), a1 = ln_fix(acc[ai][bj][m][1], mu, rs, csv[1], cbv[1]); f32x4 o0, o1;
;                     o0[0] = x0[0] + fast_sigmoid(a0[0]) * bf_lo(pw.x); o0[1] = x0[1] + fast_sigmoid(a0[1]) * bf_hi(pw.x);
;                     o0[2] = x0[2] + fast_sigmoid(a0[2]) * bf_lo(pw.y); o0[3] = x0[3] + fast_sigmoid(a0[3]) * bf_hi(pw.y);
;                     o1[0] = x1[0] + fast_sigmoid(a1[0]) * bf_lo(pw.z); o1[1] = x1[1] + fast_sigmoid(a1[1]) * bf_hi(pw.z);
;                     o1[2] = x1[2] + fast_sigmoid(a1[2]) * bf_lo(pw.w); o1[3] = x1[3] + fast_sigmoid(a1[3]) * bf_hi(pw.w);
;                     if constexpr (FINAL) { *(f32x4*)(outf + off) = o0; *(f32x4*)(outf + off + 4) = o1; }
	v_lshlrev_b32_e32 v58, 16, v116
	v_and_b32_e32 v59, 0xffff0000, v116
	v_lshlrev_b32_e32 v124, 16, v120
	v_and_b32_e32 v125, 0xffff0000, v120
	v_sub_f32_e32 v125, v125, v208
	v_sub_f32_e32 v124, v124, v208
	v_pk_mul_f32 v[124:125], v[210:211], v[124:125] op_sel_hi:[0,1]
	v_pk_fma_f32 v[124:125], v[88:89], v[124:125], v[92:93]
	v_lshlrev_b32_e32 v120, 16, v121
	v_pk_fma_f32 v[56:57], v[56:57], v[58:59], v[124:125]
	v_mul_f32_e32 v58, 0xbfb8aa3b, v62
	v_mul_f32_e32 v59, 0xbfb8aa3b, v63
	v_exp_f32_e32 v58, v58
	v_exp_f32_e32 v59, v59
	v_and_b32_e32 v121, 0xffff0000, v121
	v_sub_f32_e32 v121, v121, v208
	v_add_f32_e32 v58, 1.0, v58
	v_add_f32_e32 v59, 1.0, v59
	v_rcp_f32_e32 v58, v58
	v_rcp_f32_e32 v59, v59
	v_sub_f32_e32 v120, v120, v208
	v_pk_mul_f32 v[120:121], v[210:211], v[120:121] op_sel_hi:[0,1]
	v_pk_fma_f32 v[120:121], v[90:91], v[120:121], v[94:95]
	v_lshlrev_b32_e32 v60, 16, v117
	v_and_b32_e32 v61, 0xffff0000, v117
	v_pk_fma_f32 v[58:59], v[58:59], v[60:61], v[120:121]
	v_mul_f32_e32 v60, 0xbfb8aa3b, v132
	v_mul_f32_e32 v61, 0xbfb8aa3b, v133
	v_exp_f32_e32 v60, v60
	v_exp_f32_e32 v61, v61
	v_lshlrev_b32_e32 v128, 16, v122
	v_and_b32_e32 v129, 0xffff0000, v122
	v_add_f32_e32 v60, 1.0, v60
	v_add_f32_e32 v61, 1.0, v61
	v_rcp_f32_e32 v60, v60
	v_rcp_f32_e32 v61, v61
	v_sub_f32_e32 v129, v129, v208
	v_sub_f32_e32 v128, v128, v208
	v_pk_mul_f32 v[128:129], v[210:211], v[128:129] op_sel_hi:[0,1]
	v_pk_fma_f32 v[128:129], v[80:81], v[128:129], v[84:85]
	v_lshlrev_b32_e32 v62, 16, v118
	v_and_b32_e32 v63, 0xffff0000, v118
	v_pk_fma_f32 v[60:61], v[60:61], v[62:63], v[128:129]
	v_mul_f32_e32 v62, 0xbfb8aa3b, v130
	v_mul_f32_e32 v63, 0xbfb8aa3b, v131
	v_exp_f32_e32 v62, v62
	v_exp_f32_e32 v63, v63
	v_lshlrev_b32_e32 v122, 16, v123
	v_and_b32_e32 v123, 0xffff0000, v123
	v_add_f32_e32 v62, 1.0, v62
	v_add_f32_e32 v63, 1.0, v63
	v_rcp_f32_e32 v62, v62
	v_rcp_f32_e32 v63, v63
	v_sub_f32_e32 v123, v123, v208
	v_sub_f32_e32 v122, v122, v208
	v_pk_mul_f32 v[122:123], v[210:211], v[122:123] op_sel_hi:[0,1]
	v_pk_fma_f32 v[122:123], v[82:83], v[122:123], v[86:87]
	v_lshlrev_b32_e32 v116, 16, v119
	v_and_b32_e32 v117, 0xffff0000, v119
	v_pk_fma_f32 v[62:63], v[62:63], v[116:117], v[122:123]
	global_store_dwordx4 v[156:157], v[56:59], off offset:512
	global_store_dwordx4 v[156:157], v[60:63], off offset:528
	v_pk_fma_f32 v[122:123], v[206:207], v[48:49], v[68:69] op_sel_hi:[0,1,1]
	v_lshl_add_u64 v[56:57], v[114:115], 0, v[158:159]
	v_lshlrev_b64 v[60:61], 1, v[56:57]
	v_lshl_add_u64 v[56:57], s[26:27], 0, v[60:61]
	v_lshl_add_u64 v[60:61], s[22:23], 0, v[60:61]
	global_load_dwordx4 v[56:59], v[56:57], off
	v_mul_f32_e32 v48, 0xbfb8aa3b, v52
	global_load_dwordx4 v[60:63], v[60:61], off
	v_mul_f32_e32 v49, 0xbfb8aa3b, v53
	v_exp_f32_e32 v48, v48
	v_exp_f32_e32 v49, v49
	v_pk_fma_f32 v[120:121], v[206:207], v[50:51], v[70:71] op_sel_hi:[0,1,1]
	v_add_f32_e32 v48, 1.0, v48
	v_add_f32_e32 v49, 1.0, v49
	v_rcp_f32_e32 v48, v48
	v_rcp_f32_e32 v49, v49
	s_waitcnt vmcnt(0)
	v_lshlrev_b32_e32 v50, 16, v56
	v_and_b32_e32 v51, 0xffff0000, v56
	v_lshlrev_b32_e32 v116, 16, v60
	v_and_b32_e32 v117, 0xffff0000, v60
	v_sub_f32_e32 v117, v117, v204
	v_sub_f32_e32 v116, v116, v204
	v_pk_mul_f32 v[116:117], v[206:207], v[116:117] op_sel_hi:[0,1]
	v_pk_fma_f32 v[116:117], v[88:89], v[116:117], v[92:93]
	v_lshlrev_b32_e32 v60, 16, v61
	v_pk_fma_f32 v[48:49], v[48:49], v[50:51], v[116:117]
	v_mul_f32_e32 v50, 0xbfb8aa3b, v54
	v_mul_f32_e32 v51, 0xbfb8aa3b, v55
	v_exp_f32_e32 v50, v50
	v_exp_f32_e32 v51, v51
	v_and_b32_e32 v61, 0xffff0000, v61
	v_sub_f32_e32 v61, v61, v204
	v_add_f32_e32 v50, 1.0, v50
	v_add_f32_e32 v51, 1.0, v51
	v_rcp_f32_e32 v50, v50
	v_rcp_f32_e32 v51, v51
	v_sub_f32_e32 v60, v60, v204
	v_pk_mul_f32 v[60:61], v[206:207], v[60:61] op_sel_hi:[0,1]
	v_pk_fma_f32 v[60:61], v[90:91], v[60:61], v[94:95]
	v_lshlrev_b32_e32 v52, 16, v57
	v_and_b32_e32 v53, 0xffff0000, v57
	v_pk_fma_f32 v[50:51], v[50:51], v[52:53], v[60:61]
	v_mul_f32_e32 v52, 0xbfb8aa3b, v122
	v_mul_f32_e32 v53, 0xbfb8aa3b, v123
	v_exp_f32_e32 v52, v52
	v_exp_f32_e32 v53, v53
	v_lshlrev_b32_e32 v118, 16, v62
	v_and_b32_e32 v119, 0xffff0000, v62
	v_add_f32_e32 v52, 1.0, v52
	v_add_f32_e32 v53, 1.0, v53
	v_rcp_f32_e32 v52, v52
	v_rcp_f32_e32 v53, v53
	v_sub_f32_e32 v119, v119, v204
	v_sub_f32_e32 v118, v118, v204
	v_pk_mul_f32 v[118:119], v[206:207], v[118:119] op_sel_hi:[0,1]
	v_pk_fma_f32 v[118:119], v[80:81], v[118:119], v[84:85]
	v_lshlrev_b32_e32 v54, 16, v58
	v_and_b32_e32 v55, 0xffff0000, v58
	v_pk_fma_f32 v[52:53], v[52:53], v[54:55], v[118:119]
	v_mul_f32_e32 v54, 0xbfb8aa3b, v120
	v_mul_f32_e32 v55, 0xbfb8aa3b, v121
	v_exp_f32_e32 v54, v54
	v_exp_f32_e32 v55, v55
	v_lshlrev_b32_e32 v62, 16, v63
	v_and_b32_e32 v63, 0xffff0000, v63
	v_add_f32_e32 v54, 1.0, v54
	v_add_f32_e32 v55, 1.0, v55
	v_rcp_f32_e32 v54, v54
	v_rcp_f32_e32 v55, v55
	v_sub_f32_e32 v63, v63, v204
	v_sub_f32_e32 v62, v62, v204
	v_pk_mul_f32 v[62:63], v[206:207], v[62:63] op_sel_hi:[0,1]
	v_pk_fma_f32 v[62:63], v[82:83], v[62:63], v[86:87]
	v_lshlrev_b32_e32 v56, 16, v59
	v_and_b32_e32 v57, 0xffff0000, v59
	v_pk_fma_f32 v[54:55], v[54:55], v[56:57], v[62:63]
	global_store_dwordx4 v[144:145], v[48:51], off offset:512
	global_store_dwordx4 v[144:145], v[52:55], off offset:528
	v_pk_fma_f32 v[62:63], v[202:203], v[40:41], v[68:69] op_sel_hi:[0,1,1]
	v_lshl_add_u64 v[48:49], v[114:115], 0, v[146:147]
	v_lshlrev_b64 v[52:53], 1, v[48:49]
	v_lshl_add_u64 v[48:49], s[26:27], 0, v[52:53]
	v_lshl_add_u64 v[52:53], s[22:23], 0, v[52:53]
	global_load_dwordx4 v[48:51], v[48:49], off
	v_mul_f32_e32 v40, 0xbfb8aa3b, v44
	global_load_dwordx4 v[52:55], v[52:53], off
	v_mul_f32_e32 v41, 0xbfb8aa3b, v45
	v_exp_f32_e32 v40, v40
	v_exp_f32_e32 v41, v41
	v_pk_fma_f32 v[60:61], v[202:203], v[42:43], v[70:71] op_sel_hi:[0,1,1]
	v_add_f32_e32 v40, 1.0, v40
	v_add_f32_e32 v41, 1.0, v41
	v_rcp_f32_e32 v40, v40
	v_rcp_f32_e32 v41, v41
	s_waitcnt vmcnt(0)
; __device__ __forceinline__ f32x4 ln_fix(const f32x4& a, float mu, float rs, const f32x4& cs, const f32x4& cb) { return (a - cs * mu) * rs + cb; }
; __device__ __forceinline__ float bf_lo(unsigned w) { return __uint_as_float(w << 16); }
; __device__ __forceinline__ float bf_hi(unsigned w) { return __uint_as_float(w & 0xffff0000u); }
; __device__ __forceinline__ float fast_sigmoid(float v) { return __builtin_amdgcn_rcpf(1.0f + __builtin_amdgcn_exp2f(-1.4426950408889634f * v)); }
;     __device__ __forceinline__ void operator()(const f32x4 (&acc)[2][2][4][2], const Unit& u, int wr, int wc, int fr_in, int fq_in) const {
;     ...
;                 for (int m = (am * GR) & 3; m < ((am * GR) & 3) + GR; ++m) { const size_t off = (size_t)(row0 + ai * HALF + m * 16) * 1024 + col0 + bj * HALF; ppw[m] = *(const u32x4*)(pexb + off); pzw[m] = *(const u32x4*)(zb + off); }
;                 asm volatile("" ::: "memory");
; #pragma unroll
;                 for (int m = (am * GR) & 3; m < ((am * GR) & 3) + GR; ++m) { const size_t off = (size_t)(row0 + ai * HALF + m * 16) * 1024 + col0 + bj * HALF; const float mu = rst.mu[ai][m], rs = rst.rs[ai][m];
;                     const u32x4 pw = ppw[m]; const u32x4 zw = pzw[m];
;                     const f32x4 x0 = ((f32x4){bf_lo(zw.x), bf_hi(zw.x), bf_lo(zw.y), bf_hi(zw.y)} - mu) * rs * gv[0] + bv[0], x1 = ((f32x4){bf_lo(zw.z), bf_hi(zw.z), bf_lo(zw.w), bf_hi(zw.w)} - mu) * rs * gv[1] + bv[1];
;                     const f32x4 a0 = ln_fix(acc[ai][bj][m][0], mu, rs, csv[0], cbv[0]), a1 = ln_fix(acc[ai][bj][m][1], mu, rs, csv[1], cbv[1]); f32x4 o0, o1;
;                     o0[0] = x0[0] + fast_sigmoid(a0[0]) * bf_lo(pw.x); o0[1] = x0[1] + fast_sigmoid(a0[1]) * bf_hi(pw.x);
;                     o0[2] = x0[2] + fast_sigmoid(a0[2]) * bf_lo(pw.y); o0[3] = x0[3] + fast_sigmoid(a0[3]) * bf_hi(pw.y);
;                     o1[0] = x1[0] + fast_sigmoid(a1[0]) * bf_lo(pw.z); o1[1] = x1[1] + fast_sigmoid(a1[1]) * bf_hi(pw.z);
;                     o1[2] = x1[2] + fast_sigmoid(a1[2]) * bf_lo(pw.w); o1[3] = x1[3] + fast_sigmoid(a1[3]) * bf_hi(pw.w);
;                     if constexpr (FINAL) { *(f32x4*)(outf + off) = o0; *(f32x4*)(outf + off + 4) = o1; }
	v_lshlrev_b32_e32 v42, 16, v48
	v_and_b32_e32 v43, 0xffff0000, v48
	v_lshlrev_b32_e32 v56, 16, v52
	v_and_b32_e32 v57, 0xffff0000, v52
	v_sub_f32_e32 v57, v57, v200
	v_sub_f32_e32 v56, v56, v200
	v_pk_mul_f32 v[56:57], v[202:203], v[56:57] op_sel_hi:[0,1]
	v_pk_fma_f32 v[56:57], v[88:89], v[56:57], v[92:93]
	v_lshlrev_b32_e32 v52, 16, v53
	v_pk_fma_f32 v[40:41], v[40:41], v[42:43], v[56:57]
	v_mul_f32_e32 v42, 0xbfb8aa3b, v46
	v_mul_f32_e32 v43, 0xbfb8aa3b, v47
	v_exp_f32_e32 v42, v42
	v_exp_f32_e32 v43, v43
	v_and_b32_e32 v53, 0xffff0000, v53
	v_sub_f32_e32 v53, v53, v200
	v_add_f32_e32 v42, 1.0, v42
	v_add_f32_e32 v43, 1.0, v43
	v_rcp_f32_e32 v42, v42
	v_rcp_f32_e32 v43, v43
	v_sub_f32_e32 v52, v52, v200
	v_pk_mul_f32 v[52:53], v[202:203], v[52:53] op_sel_hi:[0,1]
	v_pk_fma_f32 v[52:53], v[90:91], v[52:53], v[94:95]
	v_lshlrev_b32_e32 v44, 16, v49
	v_and_b32_e32 v45, 0xffff0000, v49
	v_pk_fma_f32 v[42:43], v[42:43], v[44:45], v[52:53]
	v_mul_f32_e32 v44, 0xbfb8aa3b, v62
	v_mul_f32_e32 v45, 0xbfb8aa3b, v63
	v_exp_f32_e32 v44, v44
	v_exp_f32_e32 v45, v45
	v_lshlrev_b32_e32 v58, 16, v54
	v_and_b32_e32 v59, 0xffff0000, v54
	v_add_f32_e32 v44, 1.0, v44
	v_add_f32_e32 v45, 1.0, v45
	v_rcp_f32_e32 v44, v44
	v_rcp_f32_e32 v45, v45
	v_sub_f32_e32 v59, v59, v200
	v_sub_f32_e32 v58, v58, v200
	v_pk_mul_f32 v[58:59], v[202:203], v[58:59] op_sel_hi:[0,1]
	v_pk_fma_f32 v[58:59], v[80:81], v[58:59], v[84:85]
	v_lshlrev_b32_e32 v46, 16, v50
	v_and_b32_e32 v47, 0xffff0000, v50
	v_pk_fma_f32 v[44:45], v[44:45], v[46:47], v[58:59]
	v_mul_f32_e32 v46, 0xbfb8aa3b, v60
	v_mul_f32_e32 v47, 0xbfb8aa3b, v61
	v_exp_f32_e32 v46, v46
	v_exp_f32_e32 v47, v47
	v_lshlrev_b32_e32 v54, 16, v55
	v_and_b32_e32 v55, 0xffff0000, v55
	v_add_f32_e32 v46, 1.0, v46
	v_add_f32_e32 v47, 1.0, v47
	v_rcp_f32_e32 v46, v46
	v_rcp_f32_e32 v47, v47
	v_sub_f32_e32 v55, v55, v200
	v_sub_f32_e32 v54, v54, v200
	v_pk_mul_f32 v[54:55], v[202:203], v[54:55] op_sel_hi:[0,1]
	v_pk_fma_f32 v[54:55], v[82:83], v[54:55], v[86:87]
	v_lshlrev_b32_e32 v48, 16, v51
	v_and_b32_e32 v49, 0xffff0000, v51
	v_pk_fma_f32 v[46:47], v[46:47], v[48:49], v[54:55]
	global_store_dwordx4 v[104:105], v[40:43], off offset:512
	global_store_dwordx4 v[104:105], v[44:47], off offset:528
	v_pk_fma_f32 v[54:55], v[198:199], v[32:33], v[68:69] op_sel_hi:[0,1,1]
	v_lshl_add_u64 v[40:41], v[114:115], 0, v[106:107]
	v_lshlrev_b64 v[44:45], 1, v[40:41]
	v_lshl_add_u64 v[40:41], s[26:27], 0, v[44:45]
	v_lshl_add_u64 v[44:45], s[22:23], 0, v[44:45]
	global_load_dwordx4 v[40:43], v[40:41], off
	v_mul_f32_e32 v32, 0xbfb8aa3b, v36
	global_load_dwordx4 v[44:47], v[44:45], off
	v_mul_f32_e32 v33, 0xbfb8aa3b, v37
	v_exp_f32_e32 v32, v32
	v_exp_f32_e32 v33, v33
	v_pk_fma_f32 v[52:53], v[198:199], v[34:35], v[70:71] op_sel_hi:[0,1,1]
	v_add_f32_e32 v32, 1.0, v32
	v_add_f32_e32 v33, 1.0, v33
	v_rcp_f32_e32 v32, v32
	v_rcp_f32_e32 v33, v33
	s_waitcnt vmcnt(0)
	v_lshlrev_b32_e32 v34, 16, v40
	v_and_b32_e32 v35, 0xffff0000, v40
	v_lshlrev_b32_e32 v48, 16, v44
	v_and_b32_e32 v49, 0xffff0000, v44
	v_sub_f32_e32 v49, v49, v196
	v_sub_f32_e32 v48, v48, v196
	v_pk_mul_f32 v[48:49], v[198:199], v[48:49] op_sel_hi:[0,1]
	v_pk_fma_f32 v[48:49], v[88:89], v[48:49], v[92:93]
	v_lshlrev_b32_e32 v44, 16, v45
	v_pk_fma_f32 v[32:33], v[32:33], v[34:35], v[48:49]
	v_mul_f32_e32 v34, 0xbfb8aa3b, v38
	v_mul_f32_e32 v35, 0xbfb8aa3b, v39
	v_exp_f32_e32 v34, v34
	v_exp_f32_e32 v35, v35
	v_and_b32_e32 v45, 0xffff0000, v45
	v_sub_f32_e32 v45, v45, v196
	v_add_f32_e32 v34, 1.0, v34
	v_add_f32_e32 v35, 1.0, v35
	v_rcp_f32_e32 v34, v34
	v_rcp_f32_e32 v35, v35
	v_sub_f32_e32 v44, v44, v196
	v_pk_mul_f32 v[44:45], v[198:199], v[44:45] op_sel_hi:[0,1]
	v_pk_fma_f32 v[44:45], v[90:91], v[44:45], v[94:95]
	v_lshlrev_b32_e32 v36, 16, v41
	v_and_b32_e32 v37, 0xffff0000, v41
	v_pk_fma_f32 v[34:35], v[34:35], v[36:37], v[44:45]
	v_mul_f32_e32 v36, 0xbfb8aa3b, v54
	v_mul_f32_e32 v37, 0xbfb8aa3b, v55
	v_exp_f32_e32 v36, v36
	v_exp_f32_e32 v37, v37
	v_lshlrev_b32_e32 v50, 16, v46
	v_and_b32_e32 v51, 0xffff0000, v46
	v_add_f32_e32 v36, 1.0, v36
	v_add_f32_e32 v37, 1.0, v37
	v_rcp_f32_e32 v36, v36
	v_rcp_f32_e32 v37, v37
	v_sub_f32_e32 v51, v51, v196
	v_sub_f32_e32 v50, v50, v196
	v_pk_mul_f32 v[50:51], v[198:199], v[50:51] op_sel_hi:[0,1]
	v_pk_fma_f32 v[50:51], v[80:81], v[50:51], v[84:85]
	v_lshlrev_b32_e32 v38, 16, v42
	v_and_b32_e32 v39, 0xffff0000, v42
	v_pk_fma_f32 v[36:37], v[36:37], v[38:39], v[50:51]
	v_mul_f32_e32 v38, 0xbfb8aa3b, v52
	v_mul_f32_e32 v39, 0xbfb8aa3b, v53
	v_exp_f32_e32 v38, v38
	v_exp_f32_e32 v39, v39
	v_lshlrev_b32_e32 v46, 16, v47
	v_and_b32_e32 v47, 0xffff0000, v47
	v_add_f32_e32 v38, 1.0, v38
	v_add_f32_e32 v39, 1.0, v39
	v_rcp_f32_e32 v38, v38
	v_rcp_f32_e32 v39, v39
	v_sub_f32_e32 v47, v47, v196
	v_sub_f32_e32 v46, v46, v196
	v_pk_mul_f32 v[46:47], v[198:199], v[46:47] op_sel_hi:[0,1]
	v_pk_fma_f32 v[46:47], v[82:83], v[46:47], v[86:87]
	v_lshlrev_b32_e32 v40, 16, v43
	v_and_b32_e32 v41, 0xffff0000, v43
	v_pk_fma_f32 v[38:39], v[38:39], v[40:41], v[46:47]
	global_store_dwordx4 v[96:97], v[32:35], off offset:512
	global_store_dwordx4 v[96:97], v[36:39], off offset:528
	v_pk_fma_f32 v[46:47], v[194:195], v[24:25], v[68:69] op_sel_hi:[0,1,1]
	v_lshl_add_u64 v[32:33], v[114:115], 0, v[98:99]
	v_lshlrev_b64 v[36:37], 1, v[32:33]
	v_lshl_add_u64 v[32:33], s[26:27], 0, v[36:37]
	v_lshl_add_u64 v[36:37], s[22:23], 0, v[36:37]
	global_load_dwordx4 v[32:35], v[32:33], off
	v_mul_f32_e32 v24, 0xbfb8aa3b, v28
	global_load_dwordx4 v[36:39], v[36:37], off
	v_mul_f32_e32 v25, 0xbfb8aa3b, v29
	v_exp_f32_e32 v24, v24
	v_exp_f32_e32 v25, v25
	v_pk_fma_f32 v[44:45], v[194:195], v[26:27], v[70:71] op_sel_hi:[0,1,1]
	v_add_f32_e32 v24, 1.0, v24
	v_add_f32_e32 v25, 1.0, v25
	v_rcp_f32_e32 v24, v24
	v_rcp_f32_e32 v25, v25
	s_waitcnt vmcnt(0)
; __device__ __forceinline__ f32x4 ln_fix(const f32x4& a, float mu, float rs, const f32x4& cs, const f32x4& cb) { return (a - cs * mu) * rs + cb; }
; __device__ __forceinline__ float bf_lo(unsigned w) { return __uint_as_float(w << 16); }
; __device__ __forceinline__ float bf_hi(unsigned w) { return __uint_as_float(w & 0xffff0000u); }
; __device__ __forceinline__ float fast_sigmoid(float v) { return __builtin_amdgcn_rcpf(1.0f + __builtin_amdgcn_exp2f(-1.4426950408889634f * v)); }
;     __device__ __forceinline__ void operator()(const f32x4 (&acc)[2][2][4][2], const Unit& u, int wr, int wc, int fr_in, int fq_in) const {
;     ...
;                 for (int m = (am * GR) & 3; m < ((am * GR) & 3) + GR; ++m) { const size_t off = (size_t)(row0 + ai * HALF + m * 16) * 1024 + col0 + bj * HALF; ppw[m] = *(const u32x4*)(pexb + off); pzw[m] = *(const u32x4*)(zb + off); }
;                 asm volatile("" ::: "memory");
; #pragma unroll
;                 for (int m = (am * GR) & 3; m < ((am * GR) & 3) + GR; ++m) { const size_t off = (size_t)(row0 + ai * HALF + m * 16) * 1024 + col0 + bj * HALF; const float mu = rst.mu[ai][m], rs = rst.rs[ai][m];
;                     const u32x4 pw = ppw[m]; const u32x4 zw = pzw[m];
;                     const f32x4 x0 = ((f32x4){bf_lo(zw.x), bf_hi(zw.x), bf_lo(zw.y), bf_hi(zw.y)} - mu) * rs * gv[0] + bv[0], x1 = ((f32x4){bf_lo(zw.z), bf_hi(zw.z), bf_lo(zw.w), bf_hi(zw.w)} - mu) * rs * gv[1] + bv[1];
;                     const f32x4 a0 = ln_fix(acc[ai][bj][m][0], mu, rs, csv[0], cbv[0]), a1 = ln_fix(acc[ai][bj][m][1], mu, rs, csv[1], cbv[1]); f32x4 o0, o1;
;                     o0[0] = x0[0] + fast_sigmoid(a0[0]) * bf_lo(pw.x); o0[1] = x0[1] + fast_sigmoid(a0[1]) * bf_hi(pw.x);
;                     o0[2] = x0[2] + fast_sigmoid(a0[2]) * bf_lo(pw.y); o0[3] = x0[3] + fast_sigmoid(a0[3]) * bf_hi(pw.y);
;                     o1[0] = x1[0] + fast_sigmoid(a1[0]) * bf_lo(pw.z); o1[1] = x1[1] + fast_sigmoid(a1[1]) * bf_hi(pw.z);
;                     o1[2] = x1[2] + fast_sigmoid(a1[2]) * bf_lo(pw.w); o1[3] = x1[3] + fast_sigmoid(a1[3]) * bf_hi(pw.w);
;                     if constexpr (FINAL) { *(f32x4*)(outf + off) = o0; *(f32x4*)(outf + off + 4) = o1; }
	v_lshlrev_b32_e32 v26, 16, v32
	v_and_b32_e32 v27, 0xffff0000, v32
	v_lshlrev_b32_e32 v40, 16, v36
	v_and_b32_e32 v41, 0xffff0000, v36
	v_sub_f32_e32 v41, v41, v192
	v_sub_f32_e32 v40, v40, v192
	v_pk_mul_f32 v[40:41], v[194:195], v[40:41] op_sel_hi:[0,1]
	v_pk_fma_f32 v[40:41], v[88:89], v[40:41], v[92:93]
	v_lshlrev_b32_e32 v36, 16, v37
	v_pk_fma_f32 v[24:25], v[24:25], v[26:27], v[40:41]
	v_mul_f32_e32 v26, 0xbfb8aa3b, v30
	v_mul_f32_e32 v27, 0xbfb8aa3b, v31
	v_exp_f32_e32 v26, v26
	v_exp_f32_e32 v27, v27
	v_and_b32_e32 v37, 0xffff0000, v37
	v_sub_f32_e32 v37, v37, v192
	v_add_f32_e32 v26, 1.0, v26
	v_add_f32_e32 v27, 1.0, v27
	v_rcp_f32_e32 v26, v26
	v_rcp_f32_e32 v27, v27
	v_sub_f32_e32 v36, v36, v192
	v_pk_mul_f32 v[36:37], v[194:195], v[36:37] op_sel_hi:[0,1]
	v_pk_fma_f32 v[36:37], v[90:91], v[36:37], v[94:95]
	v_lshlrev_b32_e32 v28, 16, v33
	v_and_b32_e32 v29, 0xffff0000, v33
	v_pk_fma_f32 v[26:27], v[26:27], v[28:29], v[36:37]
	v_mul_f32_e32 v28, 0xbfb8aa3b, v46
	v_mul_f32_e32 v29, 0xbfb8aa3b, v47
	v_exp_f32_e32 v28, v28
	v_exp_f32_e32 v29, v29
	v_lshlrev_b32_e32 v42, 16, v38
	v_and_b32_e32 v43, 0xffff0000, v38
	v_add_f32_e32 v28, 1.0, v28
	v_add_f32_e32 v29, 1.0, v29
	v_rcp_f32_e32 v28, v28
	v_rcp_f32_e32 v29, v29
	v_sub_f32_e32 v43, v43, v192
	v_sub_f32_e32 v42, v42, v192
	v_pk_mul_f32 v[42:43], v[194:195], v[42:43] op_sel_hi:[0,1]
	v_pk_fma_f32 v[42:43], v[80:81], v[42:43], v[84:85]
	v_lshlrev_b32_e32 v30, 16, v34
	v_and_b32_e32 v31, 0xffff0000, v34
	v_pk_fma_f32 v[28:29], v[28:29], v[30:31], v[42:43]
	v_mul_f32_e32 v30, 0xbfb8aa3b, v44
	v_mul_f32_e32 v31, 0xbfb8aa3b, v45
	v_exp_f32_e32 v30, v30
	v_exp_f32_e32 v31, v31
	v_lshlrev_b32_e32 v38, 16, v39
	v_and_b32_e32 v39, 0xffff0000, v39
	v_add_f32_e32 v30, 1.0, v30
	v_add_f32_e32 v31, 1.0, v31
	v_rcp_f32_e32 v30, v30
	v_rcp_f32_e32 v31, v31
	v_sub_f32_e32 v39, v39, v192
	v_sub_f32_e32 v38, v38, v192
	v_pk_mul_f32 v[38:39], v[194:195], v[38:39] op_sel_hi:[0,1]
	v_pk_fma_f32 v[38:39], v[82:83], v[38:39], v[86:87]
	v_lshlrev_b32_e32 v32, 16, v35
	v_and_b32_e32 v33, 0xffff0000, v35
	v_pk_fma_f32 v[30:31], v[30:31], v[32:33], v[38:39]
	global_store_dwordx4 v[100:101], v[24:27], off offset:512
	global_store_dwordx4 v[100:101], v[28:31], off offset:528
	v_pk_fma_f32 v[38:39], v[190:191], v[16:17], v[68:69] op_sel_hi:[0,1,1]
	v_lshl_add_u64 v[24:25], v[114:115], 0, v[102:103]
	v_lshlrev_b64 v[28:29], 1, v[24:25]
	v_lshl_add_u64 v[24:25], s[26:27], 0, v[28:29]
	v_lshl_add_u64 v[28:29], s[22:23], 0, v[28:29]
	global_load_dwordx4 v[24:27], v[24:25], off
	v_mul_f32_e32 v16, 0xbfb8aa3b, v20
	global_load_dwordx4 v[28:31], v[28:29], off
	v_mul_f32_e32 v17, 0xbfb8aa3b, v21
	v_exp_f32_e32 v16, v16
	v_exp_f32_e32 v17, v17
	v_pk_fma_f32 v[36:37], v[190:191], v[18:19], v[70:71] op_sel_hi:[0,1,1]
	v_add_f32_e32 v16, 1.0, v16
	v_add_f32_e32 v17, 1.0, v17
	v_rcp_f32_e32 v16, v16
	v_rcp_f32_e32 v17, v17
	s_waitcnt vmcnt(0)
	v_lshlrev_b32_e32 v18, 16, v24
	v_and_b32_e32 v19, 0xffff0000, v24
	v_lshlrev_b32_e32 v32, 16, v28
	v_and_b32_e32 v33, 0xffff0000, v28
	v_sub_f32_e32 v33, v33, v188
	v_sub_f32_e32 v32, v32, v188
	v_pk_mul_f32 v[32:33], v[190:191], v[32:33] op_sel_hi:[0,1]
	v_pk_fma_f32 v[32:33], v[88:89], v[32:33], v[92:93]
	v_lshlrev_b32_e32 v28, 16, v29
	v_pk_fma_f32 v[16:17], v[16:17], v[18:19], v[32:33]
	v_mul_f32_e32 v18, 0xbfb8aa3b, v22
	v_mul_f32_e32 v19, 0xbfb8aa3b, v23
	v_exp_f32_e32 v18, v18
	v_exp_f32_e32 v19, v19
	v_and_b32_e32 v29, 0xffff0000, v29
	v_sub_f32_e32 v29, v29, v188
	v_add_f32_e32 v18, 1.0, v18
	v_add_f32_e32 v19, 1.0, v19
	v_rcp_f32_e32 v18, v18
	v_rcp_f32_e32 v19, v19
	v_sub_f32_e32 v28, v28, v188
	v_pk_mul_f32 v[28:29], v[190:191], v[28:29] op_sel_hi:[0,1]
	v_pk_fma_f32 v[28:29], v[90:91], v[28:29], v[94:95]
	v_lshlrev_b32_e32 v20, 16, v25
	v_and_b32_e32 v21, 0xffff0000, v25
	v_pk_fma_f32 v[18:19], v[18:19], v[20:21], v[28:29]
	v_mul_f32_e32 v20, 0xbfb8aa3b, v38
	v_mul_f32_e32 v21, 0xbfb8aa3b, v39
	v_exp_f32_e32 v20, v20
	v_exp_f32_e32 v21, v21
	v_lshlrev_b32_e32 v34, 16, v30
	v_and_b32_e32 v35, 0xffff0000, v30
	v_add_f32_e32 v20, 1.0, v20
	v_add_f32_e32 v21, 1.0, v21
	v_rcp_f32_e32 v20, v20
	v_rcp_f32_e32 v21, v21
	v_sub_f32_e32 v35, v35, v188
	v_sub_f32_e32 v34, v34, v188
	v_pk_mul_f32 v[34:35], v[190:191], v[34:35] op_sel_hi:[0,1]
	v_pk_fma_f32 v[34:35], v[80:81], v[34:35], v[84:85]
	v_lshlrev_b32_e32 v22, 16, v26
	v_and_b32_e32 v23, 0xffff0000, v26
	v_pk_fma_f32 v[20:21], v[20:21], v[22:23], v[34:35]
	v_mul_f32_e32 v22, 0xbfb8aa3b, v36
	v_mul_f32_e32 v23, 0xbfb8aa3b, v37
	v_exp_f32_e32 v22, v22
	v_exp_f32_e32 v23, v23
	v_lshlrev_b32_e32 v30, 16, v31
	v_and_b32_e32 v31, 0xffff0000, v31
	v_add_f32_e32 v22, 1.0, v22
	v_add_f32_e32 v23, 1.0, v23
	v_rcp_f32_e32 v22, v22
	v_rcp_f32_e32 v23, v23
	v_sub_f32_e32 v31, v31, v188
	v_sub_f32_e32 v30, v30, v188
	v_pk_mul_f32 v[30:31], v[190:191], v[30:31] op_sel_hi:[0,1]
	v_pk_fma_f32 v[30:31], v[82:83], v[30:31], v[86:87]
	v_lshlrev_b32_e32 v24, 16, v27
	v_and_b32_e32 v25, 0xffff0000, v27
	v_pk_fma_f32 v[22:23], v[22:23], v[24:25], v[30:31]
	global_store_dwordx4 v[108:109], v[16:19], off offset:512
	global_store_dwordx4 v[108:109], v[20:23], off offset:528
	v_pk_fma_f32 v[30:31], v[186:187], v[8:9], v[68:69] op_sel_hi:[0,1,1]
	v_lshl_add_u64 v[16:17], v[114:115], 0, v[110:111]
	v_lshlrev_b64 v[20:21], 1, v[16:17]
	v_lshl_add_u64 v[16:17], s[26:27], 0, v[20:21]
	v_lshl_add_u64 v[20:21], s[22:23], 0, v[20:21]
	global_load_dwordx4 v[16:19], v[16:17], off
	v_mul_f32_e32 v8, 0xbfb8aa3b, v12
	global_load_dwordx4 v[20:23], v[20:21], off
	v_mul_f32_e32 v9, 0xbfb8aa3b, v13
	v_exp_f32_e32 v8, v8
	v_exp_f32_e32 v9, v9
	v_pk_fma_f32 v[28:29], v[186:187], v[10:11], v[70:71] op_sel_hi:[0,1,1]
	v_add_f32_e32 v8, 1.0, v8
	v_add_f32_e32 v9, 1.0, v9
	v_rcp_f32_e32 v8, v8
	v_rcp_f32_e32 v9, v9
	s_waitcnt vmcnt(0)
; __device__ __forceinline__ f32x4 ln_fix(const f32x4& a, float mu, float rs, const f32x4& cs, const f32x4& cb) { return (a - cs * mu) * rs + cb; }
; __device__ __forceinline__ float bf_lo(unsigned w) { return __uint_as_float(w << 16); }
; __device__ __forceinline__ float bf_hi(unsigned w) { return __uint_as_float(w & 0xffff0000u); }
; __device__ __forceinline__ float fast_sigmoid(float v) { return __builtin_amdgcn_rcpf(1.0f + __builtin_amdgcn_exp2f(-1.4426950408889634f * v)); }
;     __device__ __forceinline__ void operator()(const f32x4 (&acc)[2][2][4][2], const Unit& u, int wr, int wc, int fr_in, int fq_in) const {
;     ...
;                 for (int m = (am * GR) & 3; m < ((am * GR) & 3) + GR; ++m) { const size_t off = (size_t)(row0 + ai * HALF + m * 16) * 1024 + col0 + bj * HALF; ppw[m] = *(const u32x4*)(pexb + off); pzw[m] = *(const u32x4*)(zb + off); }
;                 asm volatile("" ::: "memory");
; #pragma unroll
;                 for (int m = (am * GR) & 3; m < ((am * GR) & 3) + GR; ++m) { const size_t off = (size_t)(row0 + ai * HALF + m * 16) * 1024 + col0 + bj * HALF; const float mu = rst.mu[ai][m], rs = rst.rs[ai][m];
;                     const u32x4 pw = ppw[m]; const u32x4 zw = pzw[m];
;                     const f32x4 x0 = ((f32x4){bf_lo(zw.x), bf_hi(zw.x), bf_lo(zw.y), bf_hi(zw.y)} - mu) * rs * gv[0] + bv[0], x1 = ((f32x4){bf_lo(zw.z), bf_hi(zw.z), bf_lo(zw.w), bf_hi(zw.w)} - mu) * rs * gv[1] + bv[1];
;                     const f32x4 a0 = ln_fix(acc[ai][bj][m][0], mu, rs, csv[0], cbv[0]), a1 = ln_fix(acc[ai][bj][m][1], mu, rs, csv[1], cbv[1]); f32x4 o0, o1;
;                     o0[0] = x0[0] + fast_sigmoid(a0[0]) * bf_lo(pw.x); o0[1] = x0[1] + fast_sigmoid(a0[1]) * bf_hi(pw.x);
;                     o0[2] = x0[2] + fast_sigmoid(a0[2]) * bf_lo(pw.y); o0[3] = x0[3] + fast_sigmoid(a0[3]) * bf_hi(pw.y);
;                     o1[0] = x1[0] + fast_sigmoid(a1[0]) * bf_lo(pw.z); o1[1] = x1[1] + fast_sigmoid(a1[1]) * bf_hi(pw.z);
;                     o1[2] = x1[2] + fast_sigmoid(a1[2]) * bf_lo(pw.w); o1[3] = x1[3] + fast_sigmoid(a1[3]) * bf_hi(pw.w);
;                     if constexpr (FINAL) { *(f32x4*)(outf + off) = o0; *(f32x4*)(outf + off + 4) = o1; }
	v_lshlrev_b32_e32 v10, 16, v16
	v_and_b32_e32 v11, 0xffff0000, v16
	v_lshlrev_b32_e32 v24, 16, v20
	v_and_b32_e32 v25, 0xffff0000, v20
	v_sub_f32_e32 v25, v25, v184
	v_sub_f32_e32 v24, v24, v184
	v_pk_mul_f32 v[24:25], v[186:187], v[24:25] op_sel_hi:[0,1]
	v_pk_fma_f32 v[24:25], v[88:89], v[24:25], v[92:93]
	v_lshlrev_b32_e32 v20, 16, v21
	v_pk_fma_f32 v[8:9], v[8:9], v[10:11], v[24:25]
	v_mul_f32_e32 v10, 0xbfb8aa3b, v14
	v_mul_f32_e32 v11, 0xbfb8aa3b, v15
	v_exp_f32_e32 v10, v10
	v_exp_f32_e32 v11, v11
	v_and_b32_e32 v21, 0xffff0000, v21
	v_sub_f32_e32 v21, v21, v184
	v_add_f32_e32 v10, 1.0, v10
	v_add_f32_e32 v11, 1.0, v11
	v_rcp_f32_e32 v10, v10
	v_rcp_f32_e32 v11, v11
	v_sub_f32_e32 v20, v20, v184
	v_pk_mul_f32 v[20:21], v[186:187], v[20:21] op_sel_hi:[0,1]
	v_pk_fma_f32 v[20:21], v[90:91], v[20:21], v[94:95]
	v_lshlrev_b32_e32 v12, 16, v17
	v_and_b32_e32 v13, 0xffff0000, v17
	v_pk_fma_f32 v[10:11], v[10:11], v[12:13], v[20:21]
	v_mul_f32_e32 v12, 0xbfb8aa3b, v30
	v_mul_f32_e32 v13, 0xbfb8aa3b, v31
	v_exp_f32_e32 v12, v12
	v_exp_f32_e32 v13, v13
	v_lshlrev_b32_e32 v26, 16, v22
	v_and_b32_e32 v27, 0xffff0000, v22
	v_add_f32_e32 v12, 1.0, v12
	v_add_f32_e32 v13, 1.0, v13
	v_rcp_f32_e32 v12, v12
	v_rcp_f32_e32 v13, v13
	v_sub_f32_e32 v27, v27, v184
	v_sub_f32_e32 v26, v26, v184
	v_pk_mul_f32 v[26:27], v[186:187], v[26:27] op_sel_hi:[0,1]
	v_pk_fma_f32 v[26:27], v[80:81], v[26:27], v[84:85]
	v_lshlrev_b32_e32 v14, 16, v18
	v_and_b32_e32 v15, 0xffff0000, v18
	v_pk_fma_f32 v[12:13], v[12:13], v[14:15], v[26:27]
	v_mul_f32_e32 v14, 0xbfb8aa3b, v28
	v_mul_f32_e32 v15, 0xbfb8aa3b, v29
	v_exp_f32_e32 v14, v14
	v_exp_f32_e32 v15, v15
	v_lshlrev_b32_e32 v22, 16, v23
	v_and_b32_e32 v23, 0xffff0000, v23
	v_add_f32_e32 v14, 1.0, v14
	v_add_f32_e32 v15, 1.0, v15
	v_rcp_f32_e32 v14, v14
	v_rcp_f32_e32 v15, v15
	v_sub_f32_e32 v23, v23, v184
	v_sub_f32_e32 v22, v22, v184
	v_pk_mul_f32 v[22:23], v[186:187], v[22:23] op_sel_hi:[0,1]
	v_pk_fma_f32 v[22:23], v[82:83], v[22:23], v[86:87]
	v_lshlrev_b32_e32 v16, 16, v19
	v_and_b32_e32 v17, 0xffff0000, v19
	v_pk_fma_f32 v[14:15], v[14:15], v[16:17], v[22:23]
	global_store_dwordx4 v[126:127], v[8:11], off offset:512
	global_store_dwordx4 v[126:127], v[12:15], off offset:528
	v_pk_fma_f32 v[22:23], v[182:183], v[0:1], v[68:69] op_sel_hi:[0,1,1]
	v_lshl_add_u64 v[8:9], v[114:115], 0, v[148:149]
	v_lshlrev_b64 v[12:13], 1, v[8:9]
	v_lshl_add_u64 v[8:9], s[26:27], 0, v[12:13]
	v_lshl_add_u64 v[12:13], s[22:23], 0, v[12:13]
	global_load_dwordx4 v[8:11], v[8:9], off
	v_mul_f32_e32 v0, 0xbfb8aa3b, v4
	global_load_dwordx4 v[12:15], v[12:13], off
	v_mul_f32_e32 v1, 0xbfb8aa3b, v5
	v_exp_f32_e32 v0, v0
	v_exp_f32_e32 v1, v1
	v_pk_fma_f32 v[20:21], v[182:183], v[2:3], v[70:71] op_sel_hi:[0,1,1]
	v_add_f32_e32 v0, 1.0, v0
	v_add_f32_e32 v1, 1.0, v1
	v_rcp_f32_e32 v0, v0
	v_rcp_f32_e32 v1, v1
	s_waitcnt vmcnt(0)
	v_lshlrev_b32_e32 v2, 16, v8
	v_and_b32_e32 v3, 0xffff0000, v8
	v_lshlrev_b32_e32 v16, 16, v12
	v_and_b32_e32 v17, 0xffff0000, v12
	v_sub_f32_e32 v17, v17, v180
	v_sub_f32_e32 v16, v16, v180
	v_pk_mul_f32 v[16:17], v[182:183], v[16:17] op_sel_hi:[0,1]
	v_pk_fma_f32 v[16:17], v[88:89], v[16:17], v[92:93]
	v_lshlrev_b32_e32 v12, 16, v13
	v_pk_fma_f32 v[0:1], v[0:1], v[2:3], v[16:17]
	v_mul_f32_e32 v2, 0xbfb8aa3b, v6
	v_mul_f32_e32 v3, 0xbfb8aa3b, v7
	v_exp_f32_e32 v2, v2
	v_exp_f32_e32 v3, v3
	v_and_b32_e32 v13, 0xffff0000, v13
	v_sub_f32_e32 v13, v13, v180
	v_add_f32_e32 v2, 1.0, v2
	v_add_f32_e32 v3, 1.0, v3
	v_rcp_f32_e32 v2, v2
	v_rcp_f32_e32 v3, v3
	v_sub_f32_e32 v12, v12, v180
	v_pk_mul_f32 v[12:13], v[182:183], v[12:13] op_sel_hi:[0,1]
	v_pk_fma_f32 v[12:13], v[90:91], v[12:13], v[94:95]
	v_lshlrev_b32_e32 v4, 16, v9
	v_and_b32_e32 v5, 0xffff0000, v9
	v_pk_fma_f32 v[2:3], v[2:3], v[4:5], v[12:13]
	v_mul_f32_e32 v4, 0xbfb8aa3b, v22
	v_mul_f32_e32 v5, 0xbfb8aa3b, v23
	v_exp_f32_e32 v4, v4
	v_exp_f32_e32 v5, v5
	v_lshlrev_b32_e32 v18, 16, v14
	v_and_b32_e32 v19, 0xffff0000, v14
	v_add_f32_e32 v4, 1.0, v4
	v_add_f32_e32 v5, 1.0, v5
	v_rcp_f32_e32 v4, v4
	v_rcp_f32_e32 v5, v5
	v_sub_f32_e32 v19, v19, v180
	v_sub_f32_e32 v18, v18, v180
	v_pk_mul_f32 v[18:19], v[182:183], v[18:19] op_sel_hi:[0,1]
	v_pk_fma_f32 v[18:19], v[80:81], v[18:19], v[84:85]
	v_lshlrev_b32_e32 v6, 16, v10
	v_and_b32_e32 v7, 0xffff0000, v10
	v_pk_fma_f32 v[4:5], v[4:5], v[6:7], v[18:19]
	v_mul_f32_e32 v6, 0xbfb8aa3b, v20
	v_mul_f32_e32 v7, 0xbfb8aa3b, v21
	v_exp_f32_e32 v6, v6
	v_exp_f32_e32 v7, v7
	v_lshlrev_b32_e32 v14, 16, v15
	v_and_b32_e32 v15, 0xffff0000, v15
	v_add_f32_e32 v6, 1.0, v6
	v_add_f32_e32 v7, 1.0, v7
	v_rcp_f32_e32 v6, v6
	v_rcp_f32_e32 v7, v7
	v_sub_f32_e32 v15, v15, v180
	v_sub_f32_e32 v14, v14, v180
	v_pk_mul_f32 v[14:15], v[182:183], v[14:15] op_sel_hi:[0,1]
	v_pk_fma_f32 v[14:15], v[82:83], v[14:15], v[86:87]
	v_lshlrev_b32_e32 v8, 16, v11
	v_and_b32_e32 v9, 0xffff0000, v11
	v_pk_fma_f32 v[6:7], v[6:7], v[8:9], v[14:15]
	global_store_dwordx4 v[112:113], v[0:3], off offset:512
	global_store_dwordx4 v[112:113], v[4:7], off offset:528
	s_cbranch_vccnz .LBB0_2181
	s_andn2_b64 vcc, exec, s[24:25]
	s_cbranch_vccnz .LBB0_2180
	s_barrier
	s_branch .LBB0_2180
